# GEMM MMA blocks: snake MFMA order (every consecutive MFMA pair shares one source operand)
# baseline (speedup 1.0000x reference)
; #define PG8_STAGE(bufoff, gbase, voff) do { _Pragma("unroll") for (int _i = 0; _i < 2; ++_i) \
;         __builtin_amdgcn_global_load_lds((const unsigned*)((const char*)(gbase) + (voff)[_i]), (LAS unsigned*)(lds + (bufoff) + ldsw + _i * 8192), 16, 0, 0); } while (0)
; #define PG8_LDA(dst, b, h) do { _Pragma("unroll") for (int m = 0; m < 4; ++m) _Pragma("unroll") for (int k = 0; k < 2; ++k) dst[m][k] = *(const LAS bf16x8*)(lds + PG8_SA(b, h) + aoff + m * 2048 + k * 1024); } while (0)
; #define PG8_LDB(dst, b, h) do { _Pragma("unroll") for (int n = 0; n < 2; ++n) _Pragma("unroll") for (int k = 0; k < 2; ++k) dst[n][k] = *(const LAS bf16x8*)(lds + PG8_SB(b, h) + boff + n * 2048 + k * 1024); } while (0)
; #define PG8_MMA(ai, bj, At, Bt) do { __builtin_amdgcn_s_setprio(1); _Pragma("unroll") for (int m = 0; m < 4; ++m) _Pragma("unroll") for (int n = 0; n < 2; ++n) _Pragma("unroll") for (int k = 0; k < 2; ++k) \
;         acc[ai][bj][m][n] = __builtin_amdgcn_mfma_f32_16x16x32_bf16(Bt[n][k], At[m][k], acc[ai][bj][m][n], 0, 0, 0); __builtin_amdgcn_s_setprio(0); } while (0)
; #define PG8_WAIT_L(n) asm volatile("s_waitcnt lgkmcnt(" #n ")" ::: "memory")
; #define PG8_BAR __builtin_amdgcn_s_barrier()
; #define PG8_SCHED __builtin_amdgcn_sched_barrier(0)
; template <class Epi>
; DEVINL void gemm_phase(LAS unsigned char* lds, const Gemm g, const Order& S, const Epi& E) {
;     ...
;         for (int t = 0; t < nt; t += 2) {
;             const bool last = (t == nt - 2);
;             const char* a1 = cA + (size_t)(t + 1) * kstep;
;             const char* a2 = last ? nA : cA + (size_t)(t + 2) * kstep; const char* b2 = last ? nB : cB + (size_t)(t + 2) * kstep;
;             const char* a3 = a2 + kstep; const char* b3 = b2 + kstep;
;             PG8_LDB(B0, 0, 0); PG8_SCHED; PG8_LDA(At, 0, 0); PG8_STAGE(PG8_SA(1, 1), a1 + hstepA, voffA);
;             PG8_WAIT_L(8); PG8_BAR; PG8_WAIT_L(0); PG8_MMA(0, 0, At, B0); PG8_BAR; PG8_SCHED;
;             PG8_LDB(B1, 0, 1); PG8_STAGE(PG8_SB(0, 0), b2, voffB);
;             PG8_BAR; PG8_WAIT_L(0); PG8_MMA(0, 1, At, B1); PG8_BAR;
;             PG8_LDA(At, 0, 1); PG8_STAGE(PG8_SA(0, 0), a2, voffA);
;             PG8_BAR; PG8_WAIT_L(0); PG8_MMA(1, 0, At, B0); PG8_BAR; PG8_SCHED;
.LBB0_340:
	ds_read_b128 v[152:155], v149
	ds_read_b128 v[156:159], v149 offset:1024
	ds_read_b128 v[160:163], v149 offset:2048
	ds_read_b128 v[164:167], v149 offset:3072
	s_add_i32 s93, s10, 2
	s_add_u32 s2, s12, 0xfff80080
	s_addc_u32 s3, s13, -1
	s_cmp_eq_u32 s76, s10
	s_cselect_b32 s10, s85, s86
	s_cselect_b32 s15, s17, s3
	s_cselect_b32 s14, s61, s2
	s_cselect_b32 s11, s84, s87
	v_lshl_add_u64 v[144:145], s[12:13], 0, v[136:137]
	s_add_i32 m0, s67, 0xc000
	ds_read_b128 v[168:171], v150
	ds_read_b128 v[172:175], v150 offset:1024
	ds_read_b128 v[176:179], v150 offset:2048
	ds_read_b128 v[180:183], v150 offset:3072
	ds_read_b128 v[184:187], v150 offset:4096
	ds_read_b128 v[188:191], v150 offset:5120
	ds_read_b128 v[192:195], v150 offset:6144
	ds_read_b128 v[196:199], v150 offset:7168
	global_load_lds_dwordx4 v[144:145], off
	v_lshl_add_u64 v[144:145], s[12:13], 0, v[138:139]
	s_add_i32 m0, s67, 0xe000
	s_nop 0
	global_load_lds_dwordx4 v[144:145], off
	s_waitcnt lgkmcnt(8)
	s_barrier
	s_waitcnt lgkmcnt(0)
	s_setprio 1
	s_waitcnt lgkmcnt(0)
	v_mfma_f32_16x16x32_bf16 v[124:127], v[152:155], v[168:171], v[124:127]
	v_mfma_f32_16x16x32_bf16 v[116:119], v[160:163], v[168:171], v[116:119]
	v_mfma_f32_16x16x32_bf16 v[100:103], v[160:163], v[176:179], v[100:103]
	v_mfma_f32_16x16x32_bf16 v[108:111], v[152:155], v[176:179], v[108:111]
	v_mfma_f32_16x16x32_bf16 v[92:95], v[152:155], v[184:187], v[92:95]
	v_mfma_f32_16x16x32_bf16 v[84:87], v[160:163], v[184:187], v[84:87]
	v_mfma_f32_16x16x32_bf16 v[68:71], v[160:163], v[192:195], v[68:71]
	v_mfma_f32_16x16x32_bf16 v[76:79], v[152:155], v[192:195], v[76:79]
	v_mfma_f32_16x16x32_bf16 v[124:127], v[156:159], v[172:175], v[124:127]
	v_mfma_f32_16x16x32_bf16 v[116:119], v[164:167], v[172:175], v[116:119]
	v_mfma_f32_16x16x32_bf16 v[100:103], v[164:167], v[180:183], v[100:103]
	v_mfma_f32_16x16x32_bf16 v[108:111], v[156:159], v[180:183], v[108:111]
	v_mfma_f32_16x16x32_bf16 v[92:95], v[156:159], v[188:191], v[92:95]
	v_mfma_f32_16x16x32_bf16 v[84:87], v[164:167], v[188:191], v[84:87]
	v_mfma_f32_16x16x32_bf16 v[68:71], v[164:167], v[196:199], v[68:71]
	v_mfma_f32_16x16x32_bf16 v[76:79], v[156:159], v[196:199], v[76:79]
	s_setprio 0
	s_barrier
	s_add_i32 s2, s80, s38
	v_lshl_add_u64 v[144:145], s[10:11], 0, v[132:133]
	s_mov_b32 m0, s2
	ds_read_b128 v[200:203], v151
	ds_read_b128 v[204:207], v151 offset:1024
	ds_read_b128 v[208:211], v151 offset:2048
	ds_read_b128 v[218:221], v151 offset:3072
	global_load_lds_dwordx4 v[144:145], off
	v_lshl_add_u64 v[212:213], s[10:11], 0, v[128:129]
	s_add_i32 m0, s2, 0x2000
	s_nop 0
	global_load_lds_dwordx4 v[212:213], off
	s_barrier
	s_waitcnt lgkmcnt(0)
	s_setprio 1
	s_waitcnt lgkmcnt(0)
	v_mfma_f32_16x16x32_bf16 v[120:123], v[200:203], v[168:171], v[120:123]
	v_mfma_f32_16x16x32_bf16 v[112:115], v[208:211], v[168:171], v[112:115]
	v_mfma_f32_16x16x32_bf16 v[96:99], v[208:211], v[176:179], v[96:99]
	v_mfma_f32_16x16x32_bf16 v[104:107], v[200:203], v[176:179], v[104:107]
	v_mfma_f32_16x16x32_bf16 v[88:91], v[200:203], v[184:187], v[88:91]
	v_mfma_f32_16x16x32_bf16 v[80:83], v[208:211], v[184:187], v[80:83]
	v_mfma_f32_16x16x32_bf16 v[64:67], v[208:211], v[192:195], v[64:67]
	v_mfma_f32_16x16x32_bf16 v[72:75], v[200:203], v[192:195], v[72:75]
	v_mfma_f32_16x16x32_bf16 v[120:123], v[204:207], v[172:175], v[120:123]
	v_mfma_f32_16x16x32_bf16 v[112:115], v[218:221], v[172:175], v[112:115]
	v_mfma_f32_16x16x32_bf16 v[96:99], v[218:221], v[180:183], v[96:99]
	v_mfma_f32_16x16x32_bf16 v[104:107], v[204:207], v[180:183], v[104:107]
	v_mfma_f32_16x16x32_bf16 v[88:91], v[204:207], v[188:191], v[88:91]
	v_mfma_f32_16x16x32_bf16 v[80:83], v[218:221], v[188:191], v[80:83]
	v_mfma_f32_16x16x32_bf16 v[64:67], v[218:221], v[196:199], v[64:67]
	v_mfma_f32_16x16x32_bf16 v[72:75], v[204:207], v[196:199], v[72:75]
	s_setprio 0
	s_mov_b32 m0, s67
	v_lshl_add_u64 v[222:223], s[14:15], 0, v[134:135]
	s_barrier
	ds_read_b128 v[168:171], v150 offset:16384
	ds_read_b128 v[172:175], v150 offset:17408
	ds_read_b128 v[176:179], v150 offset:18432
	ds_read_b128 v[180:183], v150 offset:19456
	ds_read_b128 v[184:187], v150 offset:20480
	ds_read_b128 v[188:191], v150 offset:21504
	ds_read_b128 v[192:195], v150 offset:22528
	ds_read_b128 v[196:199], v150 offset:23552
	global_load_lds_dwordx4 v[222:223], off
	v_lshl_add_u64 v[224:225], s[14:15], 0, v[130:131]
	s_mov_b32 m0, s68
	s_nop 0
	global_load_lds_dwordx4 v[224:225], off
	s_barrier
	s_waitcnt lgkmcnt(0)
	s_setprio 1
	s_waitcnt lgkmcnt(0)
	v_mfma_f32_16x16x32_bf16 v[60:63], v[152:155], v[168:171], v[60:63]
	v_mfma_f32_16x16x32_bf16 v[52:55], v[160:163], v[168:171], v[52:55]
	v_mfma_f32_16x16x32_bf16 v[36:39], v[160:163], v[176:179], v[36:39]
	v_mfma_f32_16x16x32_bf16 v[44:47], v[152:155], v[176:179], v[44:47]
	v_mfma_f32_16x16x32_bf16 v[28:31], v[152:155], v[184:187], v[28:31]
	v_mfma_f32_16x16x32_bf16 v[20:23], v[160:163], v[184:187], v[20:23]
	v_mfma_f32_16x16x32_bf16 v[4:7], v[160:163], v[192:195], v[4:7]
	v_mfma_f32_16x16x32_bf16 v[12:15], v[152:155], v[192:195], v[12:15]
	v_mfma_f32_16x16x32_bf16 v[60:63], v[156:159], v[172:175], v[60:63]
	v_mfma_f32_16x16x32_bf16 v[52:55], v[164:167], v[172:175], v[52:55]
	v_mfma_f32_16x16x32_bf16 v[36:39], v[164:167], v[180:183], v[36:39]
	v_mfma_f32_16x16x32_bf16 v[44:47], v[156:159], v[180:183], v[44:47]
	v_mfma_f32_16x16x32_bf16 v[28:31], v[156:159], v[188:191], v[28:31]
	v_mfma_f32_16x16x32_bf16 v[20:23], v[164:167], v[188:191], v[20:23]
	v_mfma_f32_16x16x32_bf16 v[4:7], v[164:167], v[196:199], v[4:7]
	v_mfma_f32_16x16x32_bf16 v[12:15], v[156:159], v[196:199], v[12:15]
	s_setprio 0
	s_barrier
; #define PG8_STAGE(bufoff, gbase, voff) do { _Pragma("unroll") for (int _i = 0; _i < 2; ++_i) \
;         __builtin_amdgcn_global_load_lds((const unsigned*)((const char*)(gbase) + (voff)[_i]), (LAS unsigned*)(lds + (bufoff) + ldsw + _i * 8192), 16, 0, 0); } while (0)
; #define PG8_LDA(dst, b, h) do { _Pragma("unroll") for (int m = 0; m < 4; ++m) _Pragma("unroll") for (int k = 0; k < 2; ++k) dst[m][k] = *(const LAS bf16x8*)(lds + PG8_SA(b, h) + aoff + m * 2048 + k * 1024); } while (0)
; #define PG8_LDB(dst, b, h) do { _Pragma("unroll") for (int n = 0; n < 2; ++n) _Pragma("unroll") for (int k = 0; k < 2; ++k) dst[n][k] = *(const LAS bf16x8*)(lds + PG8_SB(b, h) + boff + n * 2048 + k * 1024); } while (0)
; #define PG8_MMA(ai, bj, At, Bt) do { __builtin_amdgcn_s_setprio(1); _Pragma("unroll") for (int m = 0; m < 4; ++m) _Pragma("unroll") for (int n = 0; n < 2; ++n) _Pragma("unroll") for (int k = 0; k < 2; ++k) \
;         acc[ai][bj][m][n] = __builtin_amdgcn_mfma_f32_16x16x32_bf16(Bt[n][k], At[m][k], acc[ai][bj][m][n], 0, 0, 0); __builtin_amdgcn_s_setprio(0); } while (0)
; #define PG8_WAIT_V(n) asm volatile("s_waitcnt vmcnt(" #n ")" ::: "memory")
; #define PG8_WAIT_L(n) asm volatile("s_waitcnt lgkmcnt(" #n ")" ::: "memory")
; #define PG8_BAR __builtin_amdgcn_s_barrier()
; #define PG8_SCHED __builtin_amdgcn_sched_barrier(0)
; template <class Epi>
; DEVINL void gemm_phase(LAS unsigned char* lds, const Gemm g, const Order& S, const Epi& E) {
;     ...
;             PG8_STAGE(PG8_SB(0, 1), b2 + hstepB, voffB);
;             PG8_WAIT_V(6); PG8_BAR; PG8_MMA(1, 1, At, B1); PG8_BAR;
;             PG8_LDB(B0, 1, 0); PG8_SCHED; PG8_LDA(At, 1, 0); PG8_STAGE(PG8_SA(0, 1), a2 + hstepA, voffA);
;             PG8_WAIT_L(8); PG8_BAR; PG8_WAIT_L(0); PG8_MMA(0, 0, At, B0); PG8_BAR; PG8_SCHED;
;             PG8_LDB(B1, 1, 1); PG8_STAGE(PG8_SB(1, 0), b3, voffB);
	s_add_u32 s96, s10, 0x80000
	s_addc_u32 s97, s11, 0
	s_add_i32 s2, s81, s38
	v_lshl_add_u64 v[152:153], s[96:97], 0, v[132:133]
	s_mov_b32 m0, s2
	s_nop 0
	global_load_lds_dwordx4 v[152:153], off
	v_lshl_add_u64 v[152:153], s[96:97], 0, v[128:129]
	s_add_i32 m0, s2, 0x2000
	s_nop 0
	global_load_lds_dwordx4 v[152:153], off
	s_waitcnt vmcnt(6)
	s_barrier
	s_setprio 1
	v_mfma_f32_16x16x32_bf16 v[56:59], v[200:203], v[168:171], v[56:59]
	v_mfma_f32_16x16x32_bf16 v[48:51], v[208:211], v[168:171], v[48:51]
	v_mfma_f32_16x16x32_bf16 v[32:35], v[208:211], v[176:179], v[32:35]
	v_mfma_f32_16x16x32_bf16 v[40:43], v[200:203], v[176:179], v[40:43]
	v_mfma_f32_16x16x32_bf16 v[24:27], v[200:203], v[184:187], v[24:27]
	v_mfma_f32_16x16x32_bf16 v[16:19], v[208:211], v[184:187], v[16:19]
	v_mfma_f32_16x16x32_bf16 v[0:3], v[208:211], v[192:195], v[0:3]
	v_mfma_f32_16x16x32_bf16 v[8:11], v[200:203], v[192:195], v[8:11]
	v_mfma_f32_16x16x32_bf16 v[56:59], v[204:207], v[172:175], v[56:59]
	v_mfma_f32_16x16x32_bf16 v[48:51], v[218:221], v[172:175], v[48:51]
	v_mfma_f32_16x16x32_bf16 v[32:35], v[218:221], v[180:183], v[32:35]
	v_mfma_f32_16x16x32_bf16 v[40:43], v[204:207], v[180:183], v[40:43]
	v_mfma_f32_16x16x32_bf16 v[24:27], v[204:207], v[188:191], v[24:27]
	v_mfma_f32_16x16x32_bf16 v[16:19], v[218:221], v[188:191], v[16:19]
	v_mfma_f32_16x16x32_bf16 v[0:3], v[218:221], v[196:199], v[0:3]
	v_mfma_f32_16x16x32_bf16 v[8:11], v[204:207], v[196:199], v[8:11]
	s_setprio 0
	s_add_i32 s2, 16, 0x18000
	v_add_u32_e32 v164, s2, v147
	s_barrier
	ds_read_b128 v[152:155], v164
	ds_read_b128 v[156:159], v164 offset:1024
	ds_read_b128 v[160:163], v164 offset:2048
	ds_read_b128 v[164:167], v164 offset:3072
	s_add_u32 s14, s14, 0x80000
	s_addc_u32 s15, s15, 0
	s_mov_b32 m0, s69
	v_lshl_add_u64 v[200:201], s[14:15], 0, v[134:135]
	ds_read_b128 v[168:171], v150 offset:32768
	ds_read_b128 v[172:175], v150 offset:33792
	ds_read_b128 v[176:179], v150 offset:34816
	ds_read_b128 v[180:183], v150 offset:35840
	ds_read_b128 v[184:187], v150 offset:36864
	ds_read_b128 v[188:191], v150 offset:37888
	ds_read_b128 v[192:195], v150 offset:38912
	ds_read_b128 v[196:199], v150 offset:39936
	global_load_lds_dwordx4 v[200:201], off
	v_lshl_add_u64 v[200:201], s[14:15], 0, v[130:131]
	s_mov_b32 m0, s72
	s_nop 0
	global_load_lds_dwordx4 v[200:201], off
	s_waitcnt lgkmcnt(8)
	s_barrier
	s_waitcnt lgkmcnt(0)
	s_setprio 1
	s_waitcnt lgkmcnt(0)
	v_mfma_f32_16x16x32_bf16 v[124:127], v[152:155], v[168:171], v[124:127]
	v_mfma_f32_16x16x32_bf16 v[116:119], v[160:163], v[168:171], v[116:119]
	v_mfma_f32_16x16x32_bf16 v[100:103], v[160:163], v[176:179], v[100:103]
	v_mfma_f32_16x16x32_bf16 v[108:111], v[152:155], v[176:179], v[108:111]
	v_mfma_f32_16x16x32_bf16 v[92:95], v[152:155], v[184:187], v[92:95]
	v_mfma_f32_16x16x32_bf16 v[84:87], v[160:163], v[184:187], v[84:87]
	v_mfma_f32_16x16x32_bf16 v[68:71], v[160:163], v[192:195], v[68:71]
	v_mfma_f32_16x16x32_bf16 v[76:79], v[152:155], v[192:195], v[76:79]
	v_mfma_f32_16x16x32_bf16 v[124:127], v[156:159], v[172:175], v[124:127]
	v_mfma_f32_16x16x32_bf16 v[116:119], v[164:167], v[172:175], v[116:119]
	v_mfma_f32_16x16x32_bf16 v[100:103], v[164:167], v[180:183], v[100:103]
	v_mfma_f32_16x16x32_bf16 v[108:111], v[156:159], v[180:183], v[108:111]
	v_mfma_f32_16x16x32_bf16 v[92:95], v[156:159], v[188:191], v[92:95]
	v_mfma_f32_16x16x32_bf16 v[84:87], v[164:167], v[188:191], v[84:87]
	v_mfma_f32_16x16x32_bf16 v[68:71], v[164:167], v[196:199], v[68:71]
	v_mfma_f32_16x16x32_bf16 v[76:79], v[156:159], v[196:199], v[76:79]
	s_setprio 0
	s_barrier
	s_add_i32 s3, 16, 0x1c000
	s_add_i32 s2, s2, s38
	v_add_u32_e32 v214, s3, v147
	v_lshl_add_u64 v[144:145], v[144:145], 0, s[6:7]
	s_mov_b32 m0, s2
	ds_read_b128 v[200:203], v214
	ds_read_b128 v[204:207], v214 offset:1024
	ds_read_b128 v[208:211], v214 offset:2048
	ds_read_b128 v[218:221], v214 offset:3072
	global_load_lds_dwordx4 v[144:145], off
	v_lshl_add_u64 v[144:145], v[212:213], 0, s[6:7]
	s_add_i32 m0, s2, 0x2000
	s_nop 0
	global_load_lds_dwordx4 v[144:145], off
	s_barrier
; #define PG8_STAGE(bufoff, gbase, voff) do { _Pragma("unroll") for (int _i = 0; _i < 2; ++_i) \
;         __builtin_amdgcn_global_load_lds((const unsigned*)((const char*)(gbase) + (voff)[_i]), (LAS unsigned*)(lds + (bufoff) + ldsw + _i * 8192), 16, 0, 0); } while (0)
; #define PG8_LDA(dst, b, h) do { _Pragma("unroll") for (int m = 0; m < 4; ++m) _Pragma("unroll") for (int k = 0; k < 2; ++k) dst[m][k] = *(const LAS bf16x8*)(lds + PG8_SA(b, h) + aoff + m * 2048 + k * 1024); } while (0)
; #define PG8_MMA(ai, bj, At, Bt) do { __builtin_amdgcn_s_setprio(1); _Pragma("unroll") for (int m = 0; m < 4; ++m) _Pragma("unroll") for (int n = 0; n < 2; ++n) _Pragma("unroll") for (int k = 0; k < 2; ++k) \
;         acc[ai][bj][m][n] = __builtin_amdgcn_mfma_f32_16x16x32_bf16(Bt[n][k], At[m][k], acc[ai][bj][m][n], 0, 0, 0); __builtin_amdgcn_s_setprio(0); } while (0)
; #define PG8_WAIT_V(n) asm volatile("s_waitcnt vmcnt(" #n ")" ::: "memory")
; #define PG8_WAIT_L(n) asm volatile("s_waitcnt lgkmcnt(" #n ")" ::: "memory")
; #define PG8_BAR __builtin_amdgcn_s_barrier()
; #define PG8_SCHED __builtin_amdgcn_sched_barrier(0)
; template <class Epi>
; DEVINL void gemm_phase(LAS unsigned char* lds, const Gemm g, const Order& S, const Epi& E) {
;     ...
;             PG8_BAR; PG8_WAIT_L(0); PG8_MMA(0, 1, At, B1); PG8_BAR;
;             PG8_LDA(At, 1, 1); PG8_STAGE(PG8_SA(1, 0), a3, voffA);
;             PG8_BAR; PG8_WAIT_L(0); PG8_MMA(1, 0, At, B0); PG8_BAR; PG8_SCHED;
;             PG8_STAGE(PG8_SB(1, 1), b3 + hstepB, voffB);
;             PG8_WAIT_V(6); PG8_BAR; PG8_MMA(1, 1, At, B1); PG8_BAR;
	s_waitcnt lgkmcnt(0)
	s_setprio 1
	s_waitcnt lgkmcnt(0)
	v_mfma_f32_16x16x32_bf16 v[120:123], v[200:203], v[168:171], v[120:123]
	v_mfma_f32_16x16x32_bf16 v[112:115], v[208:211], v[168:171], v[112:115]
	v_mfma_f32_16x16x32_bf16 v[96:99], v[208:211], v[176:179], v[96:99]
	v_mfma_f32_16x16x32_bf16 v[104:107], v[200:203], v[176:179], v[104:107]
	v_mfma_f32_16x16x32_bf16 v[88:91], v[200:203], v[184:187], v[88:91]
	v_mfma_f32_16x16x32_bf16 v[80:83], v[208:211], v[184:187], v[80:83]
	v_mfma_f32_16x16x32_bf16 v[64:67], v[208:211], v[192:195], v[64:67]
	v_mfma_f32_16x16x32_bf16 v[72:75], v[200:203], v[192:195], v[72:75]
	v_mfma_f32_16x16x32_bf16 v[120:123], v[204:207], v[172:175], v[120:123]
	v_mfma_f32_16x16x32_bf16 v[112:115], v[218:221], v[172:175], v[112:115]
	v_mfma_f32_16x16x32_bf16 v[96:99], v[218:221], v[180:183], v[96:99]
	v_mfma_f32_16x16x32_bf16 v[104:107], v[204:207], v[180:183], v[104:107]
	v_mfma_f32_16x16x32_bf16 v[88:91], v[204:207], v[188:191], v[88:91]
	v_mfma_f32_16x16x32_bf16 v[80:83], v[218:221], v[188:191], v[80:83]
	v_mfma_f32_16x16x32_bf16 v[64:67], v[218:221], v[196:199], v[64:67]
	v_mfma_f32_16x16x32_bf16 v[72:75], v[204:207], v[196:199], v[72:75]
	s_setprio 0
	s_mov_b32 m0, s74
	v_lshl_add_u64 v[144:145], v[222:223], 0, s[6:7]
	s_barrier
	ds_read_b128 v[168:171], v150 offset:49152
	ds_read_b128 v[172:175], v150 offset:50176
	ds_read_b128 v[176:179], v150 offset:51200
	ds_read_b128 v[180:183], v150 offset:52224
	ds_read_b128 v[184:187], v150 offset:53248
	ds_read_b128 v[188:191], v150 offset:54272
	ds_read_b128 v[192:195], v150 offset:55296
	ds_read_b128 v[196:199], v150 offset:56320
	global_load_lds_dwordx4 v[144:145], off
	v_lshl_add_u64 v[144:145], v[224:225], 0, s[6:7]
	s_mov_b32 m0, s75
	s_nop 0
	global_load_lds_dwordx4 v[144:145], off
	s_barrier
	s_waitcnt lgkmcnt(0)
	s_setprio 1
	s_waitcnt lgkmcnt(0)
	v_mfma_f32_16x16x32_bf16 v[60:63], v[152:155], v[168:171], v[60:63]
	v_mfma_f32_16x16x32_bf16 v[52:55], v[160:163], v[168:171], v[52:55]
	v_mfma_f32_16x16x32_bf16 v[36:39], v[160:163], v[176:179], v[36:39]
	v_mfma_f32_16x16x32_bf16 v[44:47], v[152:155], v[176:179], v[44:47]
	v_mfma_f32_16x16x32_bf16 v[28:31], v[152:155], v[184:187], v[28:31]
	v_mfma_f32_16x16x32_bf16 v[20:23], v[160:163], v[184:187], v[20:23]
	v_mfma_f32_16x16x32_bf16 v[4:7], v[160:163], v[192:195], v[4:7]
	v_mfma_f32_16x16x32_bf16 v[12:15], v[152:155], v[192:195], v[12:15]
	v_mfma_f32_16x16x32_bf16 v[60:63], v[156:159], v[172:175], v[60:63]
	v_mfma_f32_16x16x32_bf16 v[52:55], v[164:167], v[172:175], v[52:55]
	v_mfma_f32_16x16x32_bf16 v[36:39], v[164:167], v[180:183], v[36:39]
	v_mfma_f32_16x16x32_bf16 v[44:47], v[156:159], v[180:183], v[44:47]
	v_mfma_f32_16x16x32_bf16 v[28:31], v[156:159], v[188:191], v[28:31]
	v_mfma_f32_16x16x32_bf16 v[20:23], v[164:167], v[188:191], v[20:23]
	v_mfma_f32_16x16x32_bf16 v[4:7], v[164:167], v[196:199], v[4:7]
	v_mfma_f32_16x16x32_bf16 v[12:15], v[156:159], v[196:199], v[12:15]
	s_setprio 0
	s_barrier
	s_add_u32 s10, s10, 0x80080
	s_addc_u32 s11, s11, 0
	s_add_i32 s2, s3, s38
	v_lshl_add_u64 v[144:145], s[10:11], 0, v[132:133]
	s_mov_b32 m0, s2
	s_nop 0
	global_load_lds_dwordx4 v[144:145], off
	v_lshl_add_u64 v[144:145], s[10:11], 0, v[128:129]
	s_add_i32 m0, s2, 0x2000
	s_nop 0
	global_load_lds_dwordx4 v[144:145], off
	s_waitcnt vmcnt(6)
	s_barrier
	s_setprio 1
	v_mfma_f32_16x16x32_bf16 v[56:59], v[200:203], v[168:171], v[56:59]
	v_mfma_f32_16x16x32_bf16 v[48:51], v[208:211], v[168:171], v[48:51]
	v_mfma_f32_16x16x32_bf16 v[32:35], v[208:211], v[176:179], v[32:35]
	v_mfma_f32_16x16x32_bf16 v[40:43], v[200:203], v[176:179], v[40:43]
	v_mfma_f32_16x16x32_bf16 v[24:27], v[200:203], v[184:187], v[24:27]
	v_mfma_f32_16x16x32_bf16 v[16:19], v[208:211], v[184:187], v[16:19]
	v_mfma_f32_16x16x32_bf16 v[0:3], v[208:211], v[192:195], v[0:3]
	v_mfma_f32_16x16x32_bf16 v[8:11], v[200:203], v[192:195], v[8:11]
	v_mfma_f32_16x16x32_bf16 v[56:59], v[204:207], v[172:175], v[56:59]
	v_mfma_f32_16x16x32_bf16 v[48:51], v[218:221], v[172:175], v[48:51]
	v_mfma_f32_16x16x32_bf16 v[32:35], v[218:221], v[180:183], v[32:35]
	v_mfma_f32_16x16x32_bf16 v[40:43], v[204:207], v[180:183], v[40:43]
	v_mfma_f32_16x16x32_bf16 v[24:27], v[204:207], v[188:191], v[24:27]
	v_mfma_f32_16x16x32_bf16 v[16:19], v[218:221], v[188:191], v[16:19]
	v_mfma_f32_16x16x32_bf16 v[0:3], v[218:221], v[196:199], v[0:3]
	v_mfma_f32_16x16x32_bf16 v[8:11], v[204:207], v[196:199], v[8:11]
	s_setprio 0
	s_add_u32 s12, s12, 0x100
	s_addc_u32 s13, s13, 0
	s_add_u32 s86, s86, 0x100
	s_addc_u32 s87, s87, 0
	s_cmp_ge_i32 s93, s73
	s_mov_b32 s10, s93
	s_barrier
	s_cbranch_scc0 .LBB0_340
	s_branch .LBB0_335

; #define PG8_STAGE(bufoff, gbase, voff) do { _Pragma("unroll") for (int _i = 0; _i < 2; ++_i) \
;         __builtin_amdgcn_global_load_lds((const unsigned*)((const char*)(gbase) + (voff)[_i]), (LAS unsigned*)(lds + (bufoff) + ldsw + _i * 8192), 16, 0, 0); } while (0)
; #define PG8_LDA(dst, b, h) do { _Pragma("unroll") for (int m = 0; m < 4; ++m) _Pragma("unroll") for (int k = 0; k < 2; ++k) dst[m][k] = *(const LAS bf16x8*)(lds + PG8_SA(b, h) + aoff + m * 2048 + k * 1024); } while (0)
; #define PG8_LDB(dst, b, h) do { _Pragma("unroll") for (int n = 0; n < 2; ++n) _Pragma("unroll") for (int k = 0; k < 2; ++k) dst[n][k] = *(const LAS bf16x8*)(lds + PG8_SB(b, h) + boff + n * 2048 + k * 1024); } while (0)
; #define PG8_MMA(ai, bj, At, Bt) do { __builtin_amdgcn_s_setprio(1); _Pragma("unroll") for (int m = 0; m < 4; ++m) _Pragma("unroll") for (int n = 0; n < 2; ++n) _Pragma("unroll") for (int k = 0; k < 2; ++k) \
;         acc[ai][bj][m][n] = __builtin_amdgcn_mfma_f32_16x16x32_bf16(Bt[n][k], At[m][k], acc[ai][bj][m][n], 0, 0, 0); __builtin_amdgcn_s_setprio(0); } while (0)
; #define PG8_WAIT_L(n) asm volatile("s_waitcnt lgkmcnt(" #n ")" ::: "memory")
; #define PG8_BAR __builtin_amdgcn_s_barrier()
; #define PG8_SCHED __builtin_amdgcn_sched_barrier(0)
; template <class Epi>
; DEVINL void gemm_phase(LAS unsigned char* lds, const Gemm g, const Order& S, const Epi& E) {
;     ...
;         for (int t = 0; t < nt; t += 2) {
;             const bool last = (t == nt - 2);
;             const char* a1 = cA + (size_t)(t + 1) * kstep;
;             const char* a2 = last ? nA : cA + (size_t)(t + 2) * kstep; const char* b2 = last ? nB : cB + (size_t)(t + 2) * kstep;
;             const char* a3 = a2 + kstep; const char* b3 = b2 + kstep;
;             PG8_LDB(B0, 0, 0); PG8_SCHED; PG8_LDA(At, 0, 0); PG8_STAGE(PG8_SA(1, 1), a1 + hstepA, voffA);
;             PG8_WAIT_L(8); PG8_BAR; PG8_WAIT_L(0); PG8_MMA(0, 0, At, B0); PG8_BAR; PG8_SCHED;
;             PG8_LDB(B1, 0, 1); PG8_STAGE(PG8_SB(0, 0), b2, voffB);
;             PG8_BAR; PG8_WAIT_L(0); PG8_MMA(0, 1, At, B1); PG8_BAR;
;             PG8_LDA(At, 0, 1); PG8_STAGE(PG8_SA(0, 0), a2, voffA);
;             PG8_BAR; PG8_WAIT_L(0); PG8_MMA(1, 0, At, B0); PG8_BAR; PG8_SCHED;
.LBB0_361:
	ds_read_b128 v[146:149], v143
	ds_read_b128 v[150:153], v143 offset:1024
	ds_read_b128 v[154:157], v143 offset:2048
	ds_read_b128 v[158:161], v143 offset:3072
	s_add_i32 s87, s10, 2
	s_add_u32 s2, s12, 0xfff80080
	s_addc_u32 s3, s13, -1
	s_cmp_eq_u32 s36, s10
	s_cselect_b32 s10, s84, s85
	s_cselect_b32 s15, s63, s3
	s_cselect_b32 s14, s65, s2
	s_cselect_b32 s11, s83, s86
	v_lshl_add_u64 v[194:195], s[12:13], 0, v[136:137]
	s_add_i32 m0, s5, 0xc000
	ds_read_b128 v[162:165], v144
	ds_read_b128 v[166:169], v144 offset:1024
	ds_read_b128 v[170:173], v144 offset:2048
	ds_read_b128 v[174:177], v144 offset:3072
	ds_read_b128 v[178:181], v144 offset:4096
	ds_read_b128 v[182:185], v144 offset:5120
	ds_read_b128 v[186:189], v144 offset:6144
	ds_read_b128 v[190:193], v144 offset:7168
	global_load_lds_dwordx4 v[194:195], off
	v_lshl_add_u64 v[194:195], s[12:13], 0, v[138:139]
	s_add_i32 m0, s5, 0xe000
	s_nop 0
	global_load_lds_dwordx4 v[194:195], off
	s_waitcnt lgkmcnt(8)
	s_barrier
	s_waitcnt lgkmcnt(0)
	s_setprio 1
	s_waitcnt lgkmcnt(0)
	v_mfma_f32_16x16x32_bf16 v[120:123], v[146:149], v[162:165], v[120:123]
	v_mfma_f32_16x16x32_bf16 v[124:127], v[154:157], v[162:165], v[124:127]
	v_mfma_f32_16x16x32_bf16 v[104:107], v[154:157], v[170:173], v[104:107]
	v_mfma_f32_16x16x32_bf16 v[108:111], v[146:149], v[170:173], v[108:111]
	v_mfma_f32_16x16x32_bf16 v[92:95], v[146:149], v[178:181], v[92:95]
	v_mfma_f32_16x16x32_bf16 v[88:91], v[154:157], v[178:181], v[88:91]
	v_mfma_f32_16x16x32_bf16 v[72:75], v[154:157], v[186:189], v[72:75]
	v_mfma_f32_16x16x32_bf16 v[76:79], v[146:149], v[186:189], v[76:79]
	v_mfma_f32_16x16x32_bf16 v[120:123], v[150:153], v[166:169], v[120:123]
	v_mfma_f32_16x16x32_bf16 v[124:127], v[158:161], v[166:169], v[124:127]
	v_mfma_f32_16x16x32_bf16 v[104:107], v[158:161], v[174:177], v[104:107]
	v_mfma_f32_16x16x32_bf16 v[108:111], v[150:153], v[174:177], v[108:111]
	v_mfma_f32_16x16x32_bf16 v[92:95], v[150:153], v[182:185], v[92:95]
	v_mfma_f32_16x16x32_bf16 v[88:91], v[158:161], v[182:185], v[88:91]
	v_mfma_f32_16x16x32_bf16 v[72:75], v[158:161], v[190:193], v[72:75]
	v_mfma_f32_16x16x32_bf16 v[76:79], v[150:153], v[190:193], v[76:79]
	s_setprio 0
	s_barrier
	s_add_i32 s2, s80, s68
	v_lshl_add_u64 v[210:211], s[10:11], 0, v[130:131]
	s_mov_b32 m0, s2
	ds_read_b128 v[194:197], v145
	ds_read_b128 v[198:201], v145 offset:1024
	ds_read_b128 v[202:205], v145 offset:2048
	ds_read_b128 v[206:209], v145 offset:3072
	global_load_lds_dwordx4 v[210:211], off
	v_lshl_add_u64 v[212:213], s[10:11], 0, v[134:135]
	s_add_i32 m0, s2, 0x2000
	s_nop 0
	global_load_lds_dwordx4 v[212:213], off
	s_barrier
	s_waitcnt lgkmcnt(0)
	s_setprio 1
	s_waitcnt lgkmcnt(0)
	v_mfma_f32_16x16x32_bf16 v[116:119], v[194:197], v[162:165], v[116:119]
	v_mfma_f32_16x16x32_bf16 v[112:115], v[202:205], v[162:165], v[112:115]
	v_mfma_f32_16x16x32_bf16 v[96:99], v[202:205], v[170:173], v[96:99]
	v_mfma_f32_16x16x32_bf16 v[100:103], v[194:197], v[170:173], v[100:103]
	v_mfma_f32_16x16x32_bf16 v[84:87], v[194:197], v[178:181], v[84:87]
	v_mfma_f32_16x16x32_bf16 v[80:83], v[202:205], v[178:181], v[80:83]
	v_mfma_f32_16x16x32_bf16 v[64:67], v[202:205], v[186:189], v[64:67]
	v_mfma_f32_16x16x32_bf16 v[68:71], v[194:197], v[186:189], v[68:71]
	v_mfma_f32_16x16x32_bf16 v[116:119], v[198:201], v[166:169], v[116:119]
	v_mfma_f32_16x16x32_bf16 v[112:115], v[206:209], v[166:169], v[112:115]
	v_mfma_f32_16x16x32_bf16 v[96:99], v[206:209], v[174:177], v[96:99]
	v_mfma_f32_16x16x32_bf16 v[100:103], v[198:201], v[174:177], v[100:103]
	v_mfma_f32_16x16x32_bf16 v[84:87], v[198:201], v[182:185], v[84:87]
	v_mfma_f32_16x16x32_bf16 v[80:83], v[206:209], v[182:185], v[80:83]
	v_mfma_f32_16x16x32_bf16 v[64:67], v[206:209], v[190:193], v[64:67]
	v_mfma_f32_16x16x32_bf16 v[68:71], v[198:201], v[190:193], v[68:71]
	s_setprio 0
	s_mov_b32 m0, s5
	v_lshl_add_u64 v[218:219], s[14:15], 0, v[128:129]
	s_barrier
	ds_read_b128 v[162:165], v144 offset:16384
	ds_read_b128 v[166:169], v144 offset:17408
	ds_read_b128 v[170:173], v144 offset:18432
	ds_read_b128 v[174:177], v144 offset:19456
	ds_read_b128 v[178:181], v144 offset:20480
	ds_read_b128 v[182:185], v144 offset:21504
	ds_read_b128 v[186:189], v144 offset:22528
	ds_read_b128 v[190:193], v144 offset:23552
	global_load_lds_dwordx4 v[218:219], off
	v_lshl_add_u64 v[220:221], s[14:15], 0, v[132:133]
	s_mov_b32 m0, s69
	s_nop 0
	global_load_lds_dwordx4 v[220:221], off
	s_barrier
	s_waitcnt lgkmcnt(0)
	s_setprio 1
	s_waitcnt lgkmcnt(0)
	v_mfma_f32_16x16x32_bf16 v[60:63], v[146:149], v[162:165], v[60:63]
	v_mfma_f32_16x16x32_bf16 v[56:59], v[154:157], v[162:165], v[56:59]
	v_mfma_f32_16x16x32_bf16 v[40:43], v[154:157], v[170:173], v[40:43]
	v_mfma_f32_16x16x32_bf16 v[44:47], v[146:149], v[170:173], v[44:47]
	v_mfma_f32_16x16x32_bf16 v[28:31], v[146:149], v[178:181], v[28:31]
	v_mfma_f32_16x16x32_bf16 v[24:27], v[154:157], v[178:181], v[24:27]
	v_mfma_f32_16x16x32_bf16 v[8:11], v[154:157], v[186:189], v[8:11]
	v_mfma_f32_16x16x32_bf16 v[12:15], v[146:149], v[186:189], v[12:15]
	v_mfma_f32_16x16x32_bf16 v[60:63], v[150:153], v[166:169], v[60:63]
	v_mfma_f32_16x16x32_bf16 v[56:59], v[158:161], v[166:169], v[56:59]
	v_mfma_f32_16x16x32_bf16 v[40:43], v[158:161], v[174:177], v[40:43]
	v_mfma_f32_16x16x32_bf16 v[44:47], v[150:153], v[174:177], v[44:47]
	v_mfma_f32_16x16x32_bf16 v[28:31], v[150:153], v[182:185], v[28:31]
	v_mfma_f32_16x16x32_bf16 v[24:27], v[158:161], v[182:185], v[24:27]
	v_mfma_f32_16x16x32_bf16 v[8:11], v[158:161], v[190:193], v[8:11]
	v_mfma_f32_16x16x32_bf16 v[12:15], v[150:153], v[190:193], v[12:15]
	s_setprio 0
	s_barrier
; #define PG8_STAGE(bufoff, gbase, voff) do { _Pragma("unroll") for (int _i = 0; _i < 2; ++_i) \
;         __builtin_amdgcn_global_load_lds((const unsigned*)((const char*)(gbase) + (voff)[_i]), (LAS unsigned*)(lds + (bufoff) + ldsw + _i * 8192), 16, 0, 0); } while (0)
; #define PG8_LDA(dst, b, h) do { _Pragma("unroll") for (int m = 0; m < 4; ++m) _Pragma("unroll") for (int k = 0; k < 2; ++k) dst[m][k] = *(const LAS bf16x8*)(lds + PG8_SA(b, h) + aoff + m * 2048 + k * 1024); } while (0)
; #define PG8_LDB(dst, b, h) do { _Pragma("unroll") for (int n = 0; n < 2; ++n) _Pragma("unroll") for (int k = 0; k < 2; ++k) dst[n][k] = *(const LAS bf16x8*)(lds + PG8_SB(b, h) + boff + n * 2048 + k * 1024); } while (0)
; #define PG8_MMA(ai, bj, At, Bt) do { __builtin_amdgcn_s_setprio(1); _Pragma("unroll") for (int m = 0; m < 4; ++m) _Pragma("unroll") for (int n = 0; n < 2; ++n) _Pragma("unroll") for (int k = 0; k < 2; ++k) \
;         acc[ai][bj][m][n] = __builtin_amdgcn_mfma_f32_16x16x32_bf16(Bt[n][k], At[m][k], acc[ai][bj][m][n], 0, 0, 0); __builtin_amdgcn_s_setprio(0); } while (0)
; #define PG8_WAIT_V(n) asm volatile("s_waitcnt vmcnt(" #n ")" ::: "memory")
; #define PG8_WAIT_L(n) asm volatile("s_waitcnt lgkmcnt(" #n ")" ::: "memory")
; #define PG8_BAR __builtin_amdgcn_s_barrier()
; #define PG8_SCHED __builtin_amdgcn_sched_barrier(0)
; template <class Epi>
; DEVINL void gemm_phase(LAS unsigned char* lds, const Gemm g, const Order& S, const Epi& E) {
;     ...
;             PG8_STAGE(PG8_SB(0, 1), b2 + hstepB, voffB);
;             PG8_WAIT_V(6); PG8_BAR; PG8_MMA(1, 1, At, B1); PG8_BAR;
;             PG8_LDB(B0, 1, 0); PG8_SCHED; PG8_LDA(At, 1, 0); PG8_STAGE(PG8_SA(0, 1), a2 + hstepA, voffA);
;             PG8_WAIT_L(8); PG8_BAR; PG8_WAIT_L(0); PG8_MMA(0, 0, At, B0); PG8_BAR; PG8_SCHED;
;             PG8_LDB(B1, 1, 1); PG8_STAGE(PG8_SB(1, 0), b3, voffB);
	s_add_u32 vcc_lo, s10, 0x80000
	s_addc_u32 vcc_hi, s11, 0
	s_add_i32 s2, s81, s68
	v_lshl_add_u64 v[146:147], vcc, 0, v[130:131]
	s_mov_b32 m0, s2
	s_nop 0
	global_load_lds_dwordx4 v[146:147], off
	v_lshl_add_u64 v[146:147], vcc, 0, v[134:135]
	s_add_i32 m0, s2, 0x2000
	s_nop 0
	global_load_lds_dwordx4 v[146:147], off
	s_waitcnt vmcnt(6)
	s_barrier
	s_setprio 1
	v_mfma_f32_16x16x32_bf16 v[52:55], v[194:197], v[162:165], v[52:55]
	v_mfma_f32_16x16x32_bf16 v[48:51], v[202:205], v[162:165], v[48:51]
	v_mfma_f32_16x16x32_bf16 v[32:35], v[202:205], v[170:173], v[32:35]
	v_mfma_f32_16x16x32_bf16 v[36:39], v[194:197], v[170:173], v[36:39]
	v_mfma_f32_16x16x32_bf16 v[20:23], v[194:197], v[178:181], v[20:23]
	v_mfma_f32_16x16x32_bf16 v[16:19], v[202:205], v[178:181], v[16:19]
	v_mfma_f32_16x16x32_bf16 v[0:3], v[202:205], v[186:189], v[0:3]
	v_mfma_f32_16x16x32_bf16 v[4:7], v[194:197], v[186:189], v[4:7]
	v_mfma_f32_16x16x32_bf16 v[52:55], v[198:201], v[166:169], v[52:55]
	v_mfma_f32_16x16x32_bf16 v[48:51], v[206:209], v[166:169], v[48:51]
	v_mfma_f32_16x16x32_bf16 v[32:35], v[206:209], v[174:177], v[32:35]
	v_mfma_f32_16x16x32_bf16 v[36:39], v[198:201], v[174:177], v[36:39]
	v_mfma_f32_16x16x32_bf16 v[20:23], v[198:201], v[182:185], v[20:23]
	v_mfma_f32_16x16x32_bf16 v[16:19], v[206:209], v[182:185], v[16:19]
	v_mfma_f32_16x16x32_bf16 v[0:3], v[206:209], v[190:193], v[0:3]
	v_mfma_f32_16x16x32_bf16 v[4:7], v[198:201], v[190:193], v[4:7]
	s_setprio 0
	s_add_i32 s2, 16, 0x18000
	v_add_u32_e32 v158, s2, v141
	s_barrier
	ds_read_b128 v[146:149], v158
	ds_read_b128 v[150:153], v158 offset:1024
	ds_read_b128 v[154:157], v158 offset:2048
	ds_read_b128 v[158:161], v158 offset:3072
	s_add_u32 s14, s14, 0x80000
	s_addc_u32 s15, s15, 0
	s_mov_b32 m0, s72
	v_lshl_add_u64 v[194:195], s[14:15], 0, v[128:129]
	ds_read_b128 v[162:165], v144 offset:32768
	ds_read_b128 v[166:169], v144 offset:33792
	ds_read_b128 v[170:173], v144 offset:34816
	ds_read_b128 v[174:177], v144 offset:35840
	ds_read_b128 v[178:181], v144 offset:36864
	ds_read_b128 v[182:185], v144 offset:37888
	ds_read_b128 v[186:189], v144 offset:38912
	ds_read_b128 v[190:193], v144 offset:39936
	global_load_lds_dwordx4 v[194:195], off
	v_lshl_add_u64 v[194:195], s[14:15], 0, v[132:133]
	s_mov_b32 m0, s73
	s_nop 0
	global_load_lds_dwordx4 v[194:195], off
	s_waitcnt lgkmcnt(8)
	s_barrier
	s_waitcnt lgkmcnt(0)
	s_setprio 1
	s_waitcnt lgkmcnt(0)
	v_mfma_f32_16x16x32_bf16 v[120:123], v[146:149], v[162:165], v[120:123]
	v_mfma_f32_16x16x32_bf16 v[124:127], v[154:157], v[162:165], v[124:127]
	v_mfma_f32_16x16x32_bf16 v[104:107], v[154:157], v[170:173], v[104:107]
	v_mfma_f32_16x16x32_bf16 v[108:111], v[146:149], v[170:173], v[108:111]
	v_mfma_f32_16x16x32_bf16 v[92:95], v[146:149], v[178:181], v[92:95]
	v_mfma_f32_16x16x32_bf16 v[88:91], v[154:157], v[178:181], v[88:91]
	v_mfma_f32_16x16x32_bf16 v[72:75], v[154:157], v[186:189], v[72:75]
	v_mfma_f32_16x16x32_bf16 v[76:79], v[146:149], v[186:189], v[76:79]
	v_mfma_f32_16x16x32_bf16 v[120:123], v[150:153], v[166:169], v[120:123]
	v_mfma_f32_16x16x32_bf16 v[124:127], v[158:161], v[166:169], v[124:127]
	v_mfma_f32_16x16x32_bf16 v[104:107], v[158:161], v[174:177], v[104:107]
	v_mfma_f32_16x16x32_bf16 v[108:111], v[150:153], v[174:177], v[108:111]
	v_mfma_f32_16x16x32_bf16 v[92:95], v[150:153], v[182:185], v[92:95]
	v_mfma_f32_16x16x32_bf16 v[88:91], v[158:161], v[182:185], v[88:91]
	v_mfma_f32_16x16x32_bf16 v[72:75], v[158:161], v[190:193], v[72:75]
	v_mfma_f32_16x16x32_bf16 v[76:79], v[150:153], v[190:193], v[76:79]
	s_setprio 0
	s_barrier
	s_add_i32 s3, 16, 0x1c000
	s_add_i32 s2, s2, s68
	v_add_u32_e32 v206, s3, v141
	v_lshl_add_u64 v[210:211], v[210:211], 0, s[0:1]
	s_mov_b32 m0, s2
	ds_read_b128 v[194:197], v206
	ds_read_b128 v[198:201], v206 offset:1024
	ds_read_b128 v[202:205], v206 offset:2048
	ds_read_b128 v[206:209], v206 offset:3072
	global_load_lds_dwordx4 v[210:211], off
	v_lshl_add_u64 v[210:211], v[212:213], 0, s[0:1]
	s_add_i32 m0, s2, 0x2000
	s_nop 0
	global_load_lds_dwordx4 v[210:211], off
	s_barrier
; #define PG8_STAGE(bufoff, gbase, voff) do { _Pragma("unroll") for (int _i = 0; _i < 2; ++_i) \
;         __builtin_amdgcn_global_load_lds((const unsigned*)((const char*)(gbase) + (voff)[_i]), (LAS unsigned*)(lds + (bufoff) + ldsw + _i * 8192), 16, 0, 0); } while (0)
; #define PG8_LDA(dst, b, h) do { _Pragma("unroll") for (int m = 0; m < 4; ++m) _Pragma("unroll") for (int k = 0; k < 2; ++k) dst[m][k] = *(const LAS bf16x8*)(lds + PG8_SA(b, h) + aoff + m * 2048 + k * 1024); } while (0)
; #define PG8_MMA(ai, bj, At, Bt) do { __builtin_amdgcn_s_setprio(1); _Pragma("unroll") for (int m = 0; m < 4; ++m) _Pragma("unroll") for (int n = 0; n < 2; ++n) _Pragma("unroll") for (int k = 0; k < 2; ++k) \
;         acc[ai][bj][m][n] = __builtin_amdgcn_mfma_f32_16x16x32_bf16(Bt[n][k], At[m][k], acc[ai][bj][m][n], 0, 0, 0); __builtin_amdgcn_s_setprio(0); } while (0)
; #define PG8_WAIT_V(n) asm volatile("s_waitcnt vmcnt(" #n ")" ::: "memory")
; #define PG8_WAIT_L(n) asm volatile("s_waitcnt lgkmcnt(" #n ")" ::: "memory")
; #define PG8_BAR __builtin_amdgcn_s_barrier()
; #define PG8_SCHED __builtin_amdgcn_sched_barrier(0)
; template <class Epi>
; DEVINL void gemm_phase(LAS unsigned char* lds, const Gemm g, const Order& S, const Epi& E) {
;     ...
;             PG8_BAR; PG8_WAIT_L(0); PG8_MMA(0, 1, At, B1); PG8_BAR;
;             PG8_LDA(At, 1, 1); PG8_STAGE(PG8_SA(1, 0), a3, voffA);
;             PG8_BAR; PG8_WAIT_L(0); PG8_MMA(1, 0, At, B0); PG8_BAR; PG8_SCHED;
;             PG8_STAGE(PG8_SB(1, 1), b3 + hstepB, voffB);
;             PG8_WAIT_V(6); PG8_BAR; PG8_MMA(1, 1, At, B1); PG8_BAR;
	s_waitcnt lgkmcnt(0)
	s_setprio 1
	s_waitcnt lgkmcnt(0)
	v_mfma_f32_16x16x32_bf16 v[116:119], v[194:197], v[162:165], v[116:119]
	v_mfma_f32_16x16x32_bf16 v[112:115], v[202:205], v[162:165], v[112:115]
	v_mfma_f32_16x16x32_bf16 v[96:99], v[202:205], v[170:173], v[96:99]
	v_mfma_f32_16x16x32_bf16 v[100:103], v[194:197], v[170:173], v[100:103]
	v_mfma_f32_16x16x32_bf16 v[84:87], v[194:197], v[178:181], v[84:87]
	v_mfma_f32_16x16x32_bf16 v[80:83], v[202:205], v[178:181], v[80:83]
	v_mfma_f32_16x16x32_bf16 v[64:67], v[202:205], v[186:189], v[64:67]
	v_mfma_f32_16x16x32_bf16 v[68:71], v[194:197], v[186:189], v[68:71]
	v_mfma_f32_16x16x32_bf16 v[116:119], v[198:201], v[166:169], v[116:119]
	v_mfma_f32_16x16x32_bf16 v[112:115], v[206:209], v[166:169], v[112:115]
	v_mfma_f32_16x16x32_bf16 v[96:99], v[206:209], v[174:177], v[96:99]
	v_mfma_f32_16x16x32_bf16 v[100:103], v[198:201], v[174:177], v[100:103]
	v_mfma_f32_16x16x32_bf16 v[84:87], v[198:201], v[182:185], v[84:87]
	v_mfma_f32_16x16x32_bf16 v[80:83], v[206:209], v[182:185], v[80:83]
	v_mfma_f32_16x16x32_bf16 v[64:67], v[206:209], v[190:193], v[64:67]
	v_mfma_f32_16x16x32_bf16 v[68:71], v[198:201], v[190:193], v[68:71]
	s_setprio 0
	s_mov_b32 m0, s75
	v_lshl_add_u64 v[210:211], v[218:219], 0, s[0:1]
	s_barrier
	ds_read_b128 v[162:165], v144 offset:49152
	ds_read_b128 v[166:169], v144 offset:50176
	ds_read_b128 v[170:173], v144 offset:51200
	ds_read_b128 v[174:177], v144 offset:52224
	ds_read_b128 v[178:181], v144 offset:53248
	ds_read_b128 v[182:185], v144 offset:54272
	ds_read_b128 v[186:189], v144 offset:55296
	ds_read_b128 v[190:193], v144 offset:56320
	global_load_lds_dwordx4 v[210:211], off
	v_lshl_add_u64 v[210:211], v[220:221], 0, s[0:1]
	s_mov_b32 m0, s76
	s_nop 0
	global_load_lds_dwordx4 v[210:211], off
	s_barrier
	s_waitcnt lgkmcnt(0)
	s_setprio 1
	s_waitcnt lgkmcnt(0)
	v_mfma_f32_16x16x32_bf16 v[60:63], v[146:149], v[162:165], v[60:63]
	v_mfma_f32_16x16x32_bf16 v[56:59], v[154:157], v[162:165], v[56:59]
	v_mfma_f32_16x16x32_bf16 v[40:43], v[154:157], v[170:173], v[40:43]
	v_mfma_f32_16x16x32_bf16 v[44:47], v[146:149], v[170:173], v[44:47]
	v_mfma_f32_16x16x32_bf16 v[28:31], v[146:149], v[178:181], v[28:31]
	v_mfma_f32_16x16x32_bf16 v[24:27], v[154:157], v[178:181], v[24:27]
	v_mfma_f32_16x16x32_bf16 v[8:11], v[154:157], v[186:189], v[8:11]
	v_mfma_f32_16x16x32_bf16 v[12:15], v[146:149], v[186:189], v[12:15]
	v_mfma_f32_16x16x32_bf16 v[60:63], v[150:153], v[166:169], v[60:63]
	v_mfma_f32_16x16x32_bf16 v[56:59], v[158:161], v[166:169], v[56:59]
	v_mfma_f32_16x16x32_bf16 v[40:43], v[158:161], v[174:177], v[40:43]
	v_mfma_f32_16x16x32_bf16 v[44:47], v[150:153], v[174:177], v[44:47]
	v_mfma_f32_16x16x32_bf16 v[28:31], v[150:153], v[182:185], v[28:31]
	v_mfma_f32_16x16x32_bf16 v[24:27], v[158:161], v[182:185], v[24:27]
	v_mfma_f32_16x16x32_bf16 v[8:11], v[158:161], v[190:193], v[8:11]
	v_mfma_f32_16x16x32_bf16 v[12:15], v[150:153], v[190:193], v[12:15]
	s_setprio 0
	s_barrier
	s_add_u32 s10, s10, 0x80080
	s_addc_u32 s11, s11, 0
	s_add_i32 s2, s3, s68
	v_lshl_add_u64 v[146:147], s[10:11], 0, v[130:131]
	s_mov_b32 m0, s2
	s_nop 0
	global_load_lds_dwordx4 v[146:147], off
	v_lshl_add_u64 v[146:147], s[10:11], 0, v[134:135]
	s_add_i32 m0, s2, 0x2000
	s_nop 0
	global_load_lds_dwordx4 v[146:147], off
	s_waitcnt vmcnt(6)
	s_barrier
	s_setprio 1
	v_mfma_f32_16x16x32_bf16 v[52:55], v[194:197], v[162:165], v[52:55]
	v_mfma_f32_16x16x32_bf16 v[48:51], v[202:205], v[162:165], v[48:51]
	v_mfma_f32_16x16x32_bf16 v[32:35], v[202:205], v[170:173], v[32:35]
	v_mfma_f32_16x16x32_bf16 v[36:39], v[194:197], v[170:173], v[36:39]
	v_mfma_f32_16x16x32_bf16 v[20:23], v[194:197], v[178:181], v[20:23]
	v_mfma_f32_16x16x32_bf16 v[16:19], v[202:205], v[178:181], v[16:19]
	v_mfma_f32_16x16x32_bf16 v[0:3], v[202:205], v[186:189], v[0:3]
	v_mfma_f32_16x16x32_bf16 v[4:7], v[194:197], v[186:189], v[4:7]
	v_mfma_f32_16x16x32_bf16 v[52:55], v[198:201], v[166:169], v[52:55]
	v_mfma_f32_16x16x32_bf16 v[48:51], v[206:209], v[166:169], v[48:51]
	v_mfma_f32_16x16x32_bf16 v[32:35], v[206:209], v[174:177], v[32:35]
	v_mfma_f32_16x16x32_bf16 v[36:39], v[198:201], v[174:177], v[36:39]
	v_mfma_f32_16x16x32_bf16 v[20:23], v[198:201], v[182:185], v[20:23]
	v_mfma_f32_16x16x32_bf16 v[16:19], v[206:209], v[182:185], v[16:19]
	v_mfma_f32_16x16x32_bf16 v[0:3], v[206:209], v[190:193], v[0:3]
	v_mfma_f32_16x16x32_bf16 v[4:7], v[198:201], v[190:193], v[4:7]
	s_setprio 0
	s_add_u32 s12, s12, 0x100
	s_addc_u32 s13, s13, 0
	s_add_u32 s85, s85, 0x100
	s_addc_u32 s86, s86, 0
	s_cmp_ge_i32 s87, s74
	s_mov_b32 s10, s87
	s_barrier
	s_cbranch_scc0 .LBB0_361
	s_branch .LBB0_352

; #define PG8_STAGE(bufoff, gbase, voff) do { _Pragma("unroll") for (int _i = 0; _i < 2; ++_i) \
;         __builtin_amdgcn_global_load_lds((const unsigned*)((const char*)(gbase) + (voff)[_i]), (LAS unsigned*)(lds + (bufoff) + ldsw + _i * 8192), 16, 0, 0); } while (0)
; #define PG8_LDA(dst, b, h) do { _Pragma("unroll") for (int m = 0; m < 4; ++m) _Pragma("unroll") for (int k = 0; k < 2; ++k) dst[m][k] = *(const LAS bf16x8*)(lds + PG8_SA(b, h) + aoff + m * 2048 + k * 1024); } while (0)
; #define PG8_LDB(dst, b, h) do { _Pragma("unroll") for (int n = 0; n < 2; ++n) _Pragma("unroll") for (int k = 0; k < 2; ++k) dst[n][k] = *(const LAS bf16x8*)(lds + PG8_SB(b, h) + boff + n * 2048 + k * 1024); } while (0)
; #define PG8_MMA(ai, bj, At, Bt) do { __builtin_amdgcn_s_setprio(1); _Pragma("unroll") for (int m = 0; m < 4; ++m) _Pragma("unroll") for (int n = 0; n < 2; ++n) _Pragma("unroll") for (int k = 0; k < 2; ++k) \
;         acc[ai][bj][m][n] = __builtin_amdgcn_mfma_f32_16x16x32_bf16(Bt[n][k], At[m][k], acc[ai][bj][m][n], 0, 0, 0); __builtin_amdgcn_s_setprio(0); } while (0)
; #define PG8_WAIT_L(n) asm volatile("s_waitcnt lgkmcnt(" #n ")" ::: "memory")
; #define PG8_BAR __builtin_amdgcn_s_barrier()
; #define PG8_SCHED __builtin_amdgcn_sched_barrier(0)
; template <class Epi>
; DEVINL void gemm_phase(LAS unsigned char* lds, const Gemm g, const Order& S, const Epi& E) {
;     ...
;             PG8_LDB(B0, 0, 0); PG8_SCHED; PG8_LDA(At, 0, 0); PG8_STAGE(PG8_SA(1, 1), a1 + hstepA, voffA);
;             PG8_WAIT_L(8); PG8_BAR; PG8_WAIT_L(0); PG8_MMA(0, 0, At, B0); PG8_BAR; PG8_SCHED;
;             PG8_LDB(B1, 0, 1); PG8_STAGE(PG8_SB(0, 0), b2, voffB);
;             PG8_BAR; PG8_WAIT_L(0); PG8_MMA(0, 1, At, B1); PG8_BAR;
;             PG8_LDA(At, 0, 1); PG8_STAGE(PG8_SA(0, 0), a2, voffA);
;             PG8_BAR; PG8_WAIT_L(0); PG8_MMA(1, 0, At, B0); PG8_BAR; PG8_SCHED;
.LBB0_382:
	ds_read_b128 v[146:149], v143
	ds_read_b128 v[150:153], v143 offset:1024
	ds_read_b128 v[154:157], v143 offset:2048
	ds_read_b128 v[158:161], v143 offset:3072
	s_add_i32 s87, s12, 2
	s_add_u32 s2, s14, 0xfff80080
	s_addc_u32 s3, s15, -1
	s_cmp_eq_u32 s78, s12
	s_cselect_b32 s12, s84, s85
	s_cselect_b32 vcc_hi, s65, s3
	s_cselect_b32 vcc_lo, s66, s2
	s_cselect_b32 s13, s67, s86
	v_lshl_add_u64 v[194:195], s[14:15], 0, v[136:137]
	s_add_i32 m0, s5, 0xc000
	ds_read_b128 v[162:165], v144
	ds_read_b128 v[166:169], v144 offset:1024
	ds_read_b128 v[170:173], v144 offset:2048
	ds_read_b128 v[174:177], v144 offset:3072
	ds_read_b128 v[178:181], v144 offset:4096
	ds_read_b128 v[182:185], v144 offset:5120
	ds_read_b128 v[186:189], v144 offset:6144
	ds_read_b128 v[190:193], v144 offset:7168
	global_load_lds_dwordx4 v[194:195], off
	v_lshl_add_u64 v[194:195], s[14:15], 0, v[138:139]
	s_add_i32 m0, s5, 0xe000
	s_nop 0
	global_load_lds_dwordx4 v[194:195], off
	s_waitcnt lgkmcnt(8)
	s_barrier
	s_waitcnt lgkmcnt(0)
	s_setprio 1
	s_waitcnt lgkmcnt(0)
	v_mfma_f32_16x16x32_bf16 v[120:123], v[146:149], v[162:165], v[120:123]
	v_mfma_f32_16x16x32_bf16 v[124:127], v[154:157], v[162:165], v[124:127]
	v_mfma_f32_16x16x32_bf16 v[104:107], v[154:157], v[170:173], v[104:107]
	v_mfma_f32_16x16x32_bf16 v[108:111], v[146:149], v[170:173], v[108:111]
	v_mfma_f32_16x16x32_bf16 v[92:95], v[146:149], v[178:181], v[92:95]
	v_mfma_f32_16x16x32_bf16 v[88:91], v[154:157], v[178:181], v[88:91]
	v_mfma_f32_16x16x32_bf16 v[72:75], v[154:157], v[186:189], v[72:75]
	v_mfma_f32_16x16x32_bf16 v[76:79], v[146:149], v[186:189], v[76:79]
	v_mfma_f32_16x16x32_bf16 v[120:123], v[150:153], v[166:169], v[120:123]
	v_mfma_f32_16x16x32_bf16 v[124:127], v[158:161], v[166:169], v[124:127]
	v_mfma_f32_16x16x32_bf16 v[104:107], v[158:161], v[174:177], v[104:107]
	v_mfma_f32_16x16x32_bf16 v[108:111], v[150:153], v[174:177], v[108:111]
	v_mfma_f32_16x16x32_bf16 v[92:95], v[150:153], v[182:185], v[92:95]
	v_mfma_f32_16x16x32_bf16 v[88:91], v[158:161], v[182:185], v[88:91]
	v_mfma_f32_16x16x32_bf16 v[72:75], v[158:161], v[190:193], v[72:75]
	v_mfma_f32_16x16x32_bf16 v[76:79], v[150:153], v[190:193], v[76:79]
	s_setprio 0
	s_barrier
	s_add_i32 s2, s81, s68
	v_lshl_add_u64 v[210:211], s[12:13], 0, v[130:131]
	s_mov_b32 m0, s2
	ds_read_b128 v[194:197], v145
	ds_read_b128 v[198:201], v145 offset:1024
	ds_read_b128 v[202:205], v145 offset:2048
	ds_read_b128 v[206:209], v145 offset:3072
	global_load_lds_dwordx4 v[210:211], off
	v_lshl_add_u64 v[212:213], s[12:13], 0, v[134:135]
	s_add_i32 m0, s2, 0x2000
	s_nop 0
	global_load_lds_dwordx4 v[212:213], off
	s_barrier
	s_waitcnt lgkmcnt(0)
	s_setprio 1
	s_waitcnt lgkmcnt(0)
	v_mfma_f32_16x16x32_bf16 v[116:119], v[194:197], v[162:165], v[116:119]
	v_mfma_f32_16x16x32_bf16 v[112:115], v[202:205], v[162:165], v[112:115]
	v_mfma_f32_16x16x32_bf16 v[96:99], v[202:205], v[170:173], v[96:99]
	v_mfma_f32_16x16x32_bf16 v[100:103], v[194:197], v[170:173], v[100:103]
	v_mfma_f32_16x16x32_bf16 v[84:87], v[194:197], v[178:181], v[84:87]
	v_mfma_f32_16x16x32_bf16 v[80:83], v[202:205], v[178:181], v[80:83]
	v_mfma_f32_16x16x32_bf16 v[64:67], v[202:205], v[186:189], v[64:67]
	v_mfma_f32_16x16x32_bf16 v[68:71], v[194:197], v[186:189], v[68:71]
	v_mfma_f32_16x16x32_bf16 v[116:119], v[198:201], v[166:169], v[116:119]
	v_mfma_f32_16x16x32_bf16 v[112:115], v[206:209], v[166:169], v[112:115]
	v_mfma_f32_16x16x32_bf16 v[96:99], v[206:209], v[174:177], v[96:99]
	v_mfma_f32_16x16x32_bf16 v[100:103], v[198:201], v[174:177], v[100:103]
	v_mfma_f32_16x16x32_bf16 v[84:87], v[198:201], v[182:185], v[84:87]
	v_mfma_f32_16x16x32_bf16 v[80:83], v[206:209], v[182:185], v[80:83]
	v_mfma_f32_16x16x32_bf16 v[64:67], v[206:209], v[190:193], v[64:67]
	v_mfma_f32_16x16x32_bf16 v[68:71], v[198:201], v[190:193], v[68:71]
	s_setprio 0
	s_mov_b32 m0, s5
	v_lshl_add_u64 v[218:219], vcc, 0, v[128:129]
	s_barrier
	ds_read_b128 v[162:165], v144 offset:16384
	ds_read_b128 v[166:169], v144 offset:17408
	ds_read_b128 v[170:173], v144 offset:18432
	ds_read_b128 v[174:177], v144 offset:19456
	ds_read_b128 v[178:181], v144 offset:20480
	ds_read_b128 v[182:185], v144 offset:21504
	ds_read_b128 v[186:189], v144 offset:22528
	ds_read_b128 v[190:193], v144 offset:23552
	global_load_lds_dwordx4 v[218:219], off
	v_lshl_add_u64 v[220:221], vcc, 0, v[132:133]
	s_mov_b32 m0, s69
	s_nop 0
	global_load_lds_dwordx4 v[220:221], off
	s_barrier
	s_waitcnt lgkmcnt(0)
	s_setprio 1
	s_waitcnt lgkmcnt(0)
	v_mfma_f32_16x16x32_bf16 v[60:63], v[146:149], v[162:165], v[60:63]
	v_mfma_f32_16x16x32_bf16 v[56:59], v[154:157], v[162:165], v[56:59]
	v_mfma_f32_16x16x32_bf16 v[40:43], v[154:157], v[170:173], v[40:43]
	v_mfma_f32_16x16x32_bf16 v[44:47], v[146:149], v[170:173], v[44:47]
	v_mfma_f32_16x16x32_bf16 v[28:31], v[146:149], v[178:181], v[28:31]
	v_mfma_f32_16x16x32_bf16 v[24:27], v[154:157], v[178:181], v[24:27]
	v_mfma_f32_16x16x32_bf16 v[8:11], v[154:157], v[186:189], v[8:11]
	v_mfma_f32_16x16x32_bf16 v[12:15], v[146:149], v[186:189], v[12:15]
	v_mfma_f32_16x16x32_bf16 v[60:63], v[150:153], v[166:169], v[60:63]
	v_mfma_f32_16x16x32_bf16 v[56:59], v[158:161], v[166:169], v[56:59]
	v_mfma_f32_16x16x32_bf16 v[40:43], v[158:161], v[174:177], v[40:43]
	v_mfma_f32_16x16x32_bf16 v[44:47], v[150:153], v[174:177], v[44:47]
	v_mfma_f32_16x16x32_bf16 v[28:31], v[150:153], v[182:185], v[28:31]
	v_mfma_f32_16x16x32_bf16 v[24:27], v[158:161], v[182:185], v[24:27]
	v_mfma_f32_16x16x32_bf16 v[8:11], v[158:161], v[190:193], v[8:11]
	v_mfma_f32_16x16x32_bf16 v[12:15], v[150:153], v[190:193], v[12:15]
	s_setprio 0
	s_barrier
; #define PG8_STAGE(bufoff, gbase, voff) do { _Pragma("unroll") for (int _i = 0; _i < 2; ++_i) \
;         __builtin_amdgcn_global_load_lds((const unsigned*)((const char*)(gbase) + (voff)[_i]), (LAS unsigned*)(lds + (bufoff) + ldsw + _i * 8192), 16, 0, 0); } while (0)
; #define PG8_LDA(dst, b, h) do { _Pragma("unroll") for (int m = 0; m < 4; ++m) _Pragma("unroll") for (int k = 0; k < 2; ++k) dst[m][k] = *(const LAS bf16x8*)(lds + PG8_SA(b, h) + aoff + m * 2048 + k * 1024); } while (0)
; #define PG8_LDB(dst, b, h) do { _Pragma("unroll") for (int n = 0; n < 2; ++n) _Pragma("unroll") for (int k = 0; k < 2; ++k) dst[n][k] = *(const LAS bf16x8*)(lds + PG8_SB(b, h) + boff + n * 2048 + k * 1024); } while (0)
; #define PG8_MMA(ai, bj, At, Bt) do { __builtin_amdgcn_s_setprio(1); _Pragma("unroll") for (int m = 0; m < 4; ++m) _Pragma("unroll") for (int n = 0; n < 2; ++n) _Pragma("unroll") for (int k = 0; k < 2; ++k) \
;         acc[ai][bj][m][n] = __builtin_amdgcn_mfma_f32_16x16x32_bf16(Bt[n][k], At[m][k], acc[ai][bj][m][n], 0, 0, 0); __builtin_amdgcn_s_setprio(0); } while (0)
; #define PG8_WAIT_V(n) asm volatile("s_waitcnt vmcnt(" #n ")" ::: "memory")
; #define PG8_WAIT_L(n) asm volatile("s_waitcnt lgkmcnt(" #n ")" ::: "memory")
; #define PG8_BAR __builtin_amdgcn_s_barrier()
; #define PG8_SCHED __builtin_amdgcn_sched_barrier(0)
; template <class Epi>
; DEVINL void gemm_phase(LAS unsigned char* lds, const Gemm g, const Order& S, const Epi& E) {
;     ...
;             PG8_STAGE(PG8_SB(0, 1), b2 + hstepB, voffB);
;             PG8_WAIT_V(6); PG8_BAR; PG8_MMA(1, 1, At, B1); PG8_BAR;
;             PG8_LDB(B0, 1, 0); PG8_SCHED; PG8_LDA(At, 1, 0); PG8_STAGE(PG8_SA(0, 1), a2 + hstepA, voffA);
;             PG8_WAIT_L(8); PG8_BAR; PG8_WAIT_L(0); PG8_MMA(0, 0, At, B0); PG8_BAR; PG8_SCHED;
;             PG8_LDB(B1, 1, 1); PG8_STAGE(PG8_SB(1, 0), b3, voffB);
	s_add_u32 s2, s12, 0x80000
	s_addc_u32 s3, s13, 0
	s_add_i32 s93, s82, s68
	v_lshl_add_u64 v[146:147], s[2:3], 0, v[130:131]
	s_mov_b32 m0, s93
	s_nop 0
	global_load_lds_dwordx4 v[146:147], off
	v_lshl_add_u64 v[146:147], s[2:3], 0, v[134:135]
	s_add_i32 m0, s93, 0x2000
	s_nop 0
	global_load_lds_dwordx4 v[146:147], off
	s_waitcnt vmcnt(6)
	s_barrier
	s_setprio 1
	v_mfma_f32_16x16x32_bf16 v[52:55], v[194:197], v[162:165], v[52:55]
	v_mfma_f32_16x16x32_bf16 v[48:51], v[202:205], v[162:165], v[48:51]
	v_mfma_f32_16x16x32_bf16 v[32:35], v[202:205], v[170:173], v[32:35]
	v_mfma_f32_16x16x32_bf16 v[36:39], v[194:197], v[170:173], v[36:39]
	v_mfma_f32_16x16x32_bf16 v[20:23], v[194:197], v[178:181], v[20:23]
	v_mfma_f32_16x16x32_bf16 v[16:19], v[202:205], v[178:181], v[16:19]
	v_mfma_f32_16x16x32_bf16 v[0:3], v[202:205], v[186:189], v[0:3]
	v_mfma_f32_16x16x32_bf16 v[4:7], v[194:197], v[186:189], v[4:7]
	v_mfma_f32_16x16x32_bf16 v[52:55], v[198:201], v[166:169], v[52:55]
	v_mfma_f32_16x16x32_bf16 v[48:51], v[206:209], v[166:169], v[48:51]
	v_mfma_f32_16x16x32_bf16 v[32:35], v[206:209], v[174:177], v[32:35]
	v_mfma_f32_16x16x32_bf16 v[36:39], v[198:201], v[174:177], v[36:39]
	v_mfma_f32_16x16x32_bf16 v[20:23], v[198:201], v[182:185], v[20:23]
	v_mfma_f32_16x16x32_bf16 v[16:19], v[206:209], v[182:185], v[16:19]
	v_mfma_f32_16x16x32_bf16 v[0:3], v[206:209], v[190:193], v[0:3]
	v_mfma_f32_16x16x32_bf16 v[4:7], v[198:201], v[190:193], v[4:7]
	s_setprio 0
	s_add_i32 s93, 16, 0x18000
	v_add_u32_e32 v158, s93, v141
	s_barrier
	ds_read_b128 v[146:149], v158
	ds_read_b128 v[150:153], v158 offset:1024
	ds_read_b128 v[154:157], v158 offset:2048
	ds_read_b128 v[158:161], v158 offset:3072
	s_add_u32 s2, vcc_lo, 0x80000
	s_addc_u32 s3, vcc_hi, 0
	s_mov_b32 m0, s72
	v_lshl_add_u64 v[194:195], s[2:3], 0, v[128:129]
	ds_read_b128 v[162:165], v144 offset:32768
	ds_read_b128 v[166:169], v144 offset:33792
	ds_read_b128 v[170:173], v144 offset:34816
	ds_read_b128 v[174:177], v144 offset:35840
	ds_read_b128 v[178:181], v144 offset:36864
	ds_read_b128 v[182:185], v144 offset:37888
	ds_read_b128 v[186:189], v144 offset:38912
	ds_read_b128 v[190:193], v144 offset:39936
	global_load_lds_dwordx4 v[194:195], off
	v_lshl_add_u64 v[194:195], s[2:3], 0, v[132:133]
	s_mov_b32 m0, s73
	s_nop 0
	global_load_lds_dwordx4 v[194:195], off
	s_waitcnt lgkmcnt(8)
	s_barrier
	s_waitcnt lgkmcnt(0)
	s_setprio 1
	s_waitcnt lgkmcnt(0)
	v_mfma_f32_16x16x32_bf16 v[120:123], v[146:149], v[162:165], v[120:123]
	v_mfma_f32_16x16x32_bf16 v[124:127], v[154:157], v[162:165], v[124:127]
	v_mfma_f32_16x16x32_bf16 v[104:107], v[154:157], v[170:173], v[104:107]
	v_mfma_f32_16x16x32_bf16 v[108:111], v[146:149], v[170:173], v[108:111]
	v_mfma_f32_16x16x32_bf16 v[92:95], v[146:149], v[178:181], v[92:95]
	v_mfma_f32_16x16x32_bf16 v[88:91], v[154:157], v[178:181], v[88:91]
	v_mfma_f32_16x16x32_bf16 v[72:75], v[154:157], v[186:189], v[72:75]
	v_mfma_f32_16x16x32_bf16 v[76:79], v[146:149], v[186:189], v[76:79]
	v_mfma_f32_16x16x32_bf16 v[120:123], v[150:153], v[166:169], v[120:123]
	v_mfma_f32_16x16x32_bf16 v[124:127], v[158:161], v[166:169], v[124:127]
	v_mfma_f32_16x16x32_bf16 v[104:107], v[158:161], v[174:177], v[104:107]
	v_mfma_f32_16x16x32_bf16 v[108:111], v[150:153], v[174:177], v[108:111]
	v_mfma_f32_16x16x32_bf16 v[92:95], v[150:153], v[182:185], v[92:95]
	v_mfma_f32_16x16x32_bf16 v[88:91], v[158:161], v[182:185], v[88:91]
	v_mfma_f32_16x16x32_bf16 v[72:75], v[158:161], v[190:193], v[72:75]
	v_mfma_f32_16x16x32_bf16 v[76:79], v[150:153], v[190:193], v[76:79]
	s_setprio 0
	s_barrier
	s_add_i32 vcc_lo, 16, 0x1c000
	s_add_i32 s2, s93, s68
	v_add_u32_e32 v206, vcc_lo, v141
	v_lshl_add_u64 v[210:211], v[210:211], 0, s[0:1]
	s_mov_b32 m0, s2
	ds_read_b128 v[194:197], v206
	ds_read_b128 v[198:201], v206 offset:1024
	ds_read_b128 v[202:205], v206 offset:2048
	ds_read_b128 v[206:209], v206 offset:3072
	global_load_lds_dwordx4 v[210:211], off
	v_lshl_add_u64 v[210:211], v[212:213], 0, s[0:1]
	s_add_i32 m0, s2, 0x2000
	s_nop 0
	global_load_lds_dwordx4 v[210:211], off
	s_barrier
; #define PG8_STAGE(bufoff, gbase, voff) do { _Pragma("unroll") for (int _i = 0; _i < 2; ++_i) \
;         __builtin_amdgcn_global_load_lds((const unsigned*)((const char*)(gbase) + (voff)[_i]), (LAS unsigned*)(lds + (bufoff) + ldsw + _i * 8192), 16, 0, 0); } while (0)
; #define PG8_LDA(dst, b, h) do { _Pragma("unroll") for (int m = 0; m < 4; ++m) _Pragma("unroll") for (int k = 0; k < 2; ++k) dst[m][k] = *(const LAS bf16x8*)(lds + PG8_SA(b, h) + aoff + m * 2048 + k * 1024); } while (0)
; #define PG8_MMA(ai, bj, At, Bt) do { __builtin_amdgcn_s_setprio(1); _Pragma("unroll") for (int m = 0; m < 4; ++m) _Pragma("unroll") for (int n = 0; n < 2; ++n) _Pragma("unroll") for (int k = 0; k < 2; ++k) \
;         acc[ai][bj][m][n] = __builtin_amdgcn_mfma_f32_16x16x32_bf16(Bt[n][k], At[m][k], acc[ai][bj][m][n], 0, 0, 0); __builtin_amdgcn_s_setprio(0); } while (0)
; #define PG8_WAIT_V(n) asm volatile("s_waitcnt vmcnt(" #n ")" ::: "memory")
; #define PG8_WAIT_L(n) asm volatile("s_waitcnt lgkmcnt(" #n ")" ::: "memory")
; #define PG8_BAR __builtin_amdgcn_s_barrier()
; #define PG8_SCHED __builtin_amdgcn_sched_barrier(0)
; template <class Epi>
; DEVINL void gemm_phase(LAS unsigned char* lds, const Gemm g, const Order& S, const Epi& E) {
;     ...
;             PG8_BAR; PG8_WAIT_L(0); PG8_MMA(0, 1, At, B1); PG8_BAR;
;             PG8_LDA(At, 1, 1); PG8_STAGE(PG8_SA(1, 0), a3, voffA);
;             PG8_BAR; PG8_WAIT_L(0); PG8_MMA(1, 0, At, B0); PG8_BAR; PG8_SCHED;
;             PG8_STAGE(PG8_SB(1, 1), b3 + hstepB, voffB);
;             PG8_WAIT_V(6); PG8_BAR; PG8_MMA(1, 1, At, B1); PG8_BAR;
;         }
	s_waitcnt lgkmcnt(0)
	s_setprio 1
	s_waitcnt lgkmcnt(0)
	v_mfma_f32_16x16x32_bf16 v[116:119], v[194:197], v[162:165], v[116:119]
	v_mfma_f32_16x16x32_bf16 v[112:115], v[202:205], v[162:165], v[112:115]
	v_mfma_f32_16x16x32_bf16 v[96:99], v[202:205], v[170:173], v[96:99]
	v_mfma_f32_16x16x32_bf16 v[100:103], v[194:197], v[170:173], v[100:103]
	v_mfma_f32_16x16x32_bf16 v[84:87], v[194:197], v[178:181], v[84:87]
	v_mfma_f32_16x16x32_bf16 v[80:83], v[202:205], v[178:181], v[80:83]
	v_mfma_f32_16x16x32_bf16 v[64:67], v[202:205], v[186:189], v[64:67]
	v_mfma_f32_16x16x32_bf16 v[68:71], v[194:197], v[186:189], v[68:71]
	v_mfma_f32_16x16x32_bf16 v[116:119], v[198:201], v[166:169], v[116:119]
	v_mfma_f32_16x16x32_bf16 v[112:115], v[206:209], v[166:169], v[112:115]
	v_mfma_f32_16x16x32_bf16 v[96:99], v[206:209], v[174:177], v[96:99]
	v_mfma_f32_16x16x32_bf16 v[100:103], v[198:201], v[174:177], v[100:103]
	v_mfma_f32_16x16x32_bf16 v[84:87], v[198:201], v[182:185], v[84:87]
	v_mfma_f32_16x16x32_bf16 v[80:83], v[206:209], v[182:185], v[80:83]
	v_mfma_f32_16x16x32_bf16 v[64:67], v[206:209], v[190:193], v[64:67]
	v_mfma_f32_16x16x32_bf16 v[68:71], v[198:201], v[190:193], v[68:71]
	s_setprio 0
	s_mov_b32 m0, s76
	v_lshl_add_u64 v[210:211], v[218:219], 0, s[0:1]
	s_barrier
	ds_read_b128 v[162:165], v144 offset:49152
	ds_read_b128 v[166:169], v144 offset:50176
	ds_read_b128 v[170:173], v144 offset:51200
	ds_read_b128 v[174:177], v144 offset:52224
	ds_read_b128 v[178:181], v144 offset:53248
	ds_read_b128 v[182:185], v144 offset:54272
	ds_read_b128 v[186:189], v144 offset:55296
	ds_read_b128 v[190:193], v144 offset:56320
	global_load_lds_dwordx4 v[210:211], off
	v_lshl_add_u64 v[210:211], v[220:221], 0, s[0:1]
	s_mov_b32 m0, s77
	s_nop 0
	global_load_lds_dwordx4 v[210:211], off
	s_barrier
	s_waitcnt lgkmcnt(0)
	s_setprio 1
	s_waitcnt lgkmcnt(0)
	v_mfma_f32_16x16x32_bf16 v[60:63], v[146:149], v[162:165], v[60:63]
	v_mfma_f32_16x16x32_bf16 v[56:59], v[154:157], v[162:165], v[56:59]
	v_mfma_f32_16x16x32_bf16 v[40:43], v[154:157], v[170:173], v[40:43]
	v_mfma_f32_16x16x32_bf16 v[44:47], v[146:149], v[170:173], v[44:47]
	v_mfma_f32_16x16x32_bf16 v[28:31], v[146:149], v[178:181], v[28:31]
	v_mfma_f32_16x16x32_bf16 v[24:27], v[154:157], v[178:181], v[24:27]
	v_mfma_f32_16x16x32_bf16 v[8:11], v[154:157], v[186:189], v[8:11]
	v_mfma_f32_16x16x32_bf16 v[12:15], v[146:149], v[186:189], v[12:15]
	v_mfma_f32_16x16x32_bf16 v[60:63], v[150:153], v[166:169], v[60:63]
	v_mfma_f32_16x16x32_bf16 v[56:59], v[158:161], v[166:169], v[56:59]
	v_mfma_f32_16x16x32_bf16 v[40:43], v[158:161], v[174:177], v[40:43]
	v_mfma_f32_16x16x32_bf16 v[44:47], v[150:153], v[174:177], v[44:47]
	v_mfma_f32_16x16x32_bf16 v[28:31], v[150:153], v[182:185], v[28:31]
	v_mfma_f32_16x16x32_bf16 v[24:27], v[158:161], v[182:185], v[24:27]
	v_mfma_f32_16x16x32_bf16 v[8:11], v[158:161], v[190:193], v[8:11]
	v_mfma_f32_16x16x32_bf16 v[12:15], v[150:153], v[190:193], v[12:15]
	s_setprio 0
	s_barrier
	s_add_u32 s2, s12, 0x80080
	s_addc_u32 s3, s13, 0
	s_add_i32 s12, vcc_lo, s68
	v_lshl_add_u64 v[146:147], s[2:3], 0, v[130:131]
	s_mov_b32 m0, s12
	s_nop 0
	global_load_lds_dwordx4 v[146:147], off
	v_lshl_add_u64 v[146:147], s[2:3], 0, v[134:135]
	s_add_i32 m0, s12, 0x2000
	s_nop 0
	global_load_lds_dwordx4 v[146:147], off
	s_waitcnt vmcnt(6)
	s_barrier
	s_setprio 1
	v_mfma_f32_16x16x32_bf16 v[52:55], v[194:197], v[162:165], v[52:55]
	v_mfma_f32_16x16x32_bf16 v[48:51], v[202:205], v[162:165], v[48:51]
	v_mfma_f32_16x16x32_bf16 v[32:35], v[202:205], v[170:173], v[32:35]
	v_mfma_f32_16x16x32_bf16 v[36:39], v[194:197], v[170:173], v[36:39]
	v_mfma_f32_16x16x32_bf16 v[20:23], v[194:197], v[178:181], v[20:23]
	v_mfma_f32_16x16x32_bf16 v[16:19], v[202:205], v[178:181], v[16:19]
	v_mfma_f32_16x16x32_bf16 v[0:3], v[202:205], v[186:189], v[0:3]
	v_mfma_f32_16x16x32_bf16 v[4:7], v[194:197], v[186:189], v[4:7]
	v_mfma_f32_16x16x32_bf16 v[52:55], v[198:201], v[166:169], v[52:55]
	v_mfma_f32_16x16x32_bf16 v[48:51], v[206:209], v[166:169], v[48:51]
	v_mfma_f32_16x16x32_bf16 v[32:35], v[206:209], v[174:177], v[32:35]
	v_mfma_f32_16x16x32_bf16 v[36:39], v[198:201], v[174:177], v[36:39]
	v_mfma_f32_16x16x32_bf16 v[20:23], v[198:201], v[182:185], v[20:23]
	v_mfma_f32_16x16x32_bf16 v[16:19], v[206:209], v[182:185], v[16:19]
	v_mfma_f32_16x16x32_bf16 v[0:3], v[206:209], v[190:193], v[0:3]
	v_mfma_f32_16x16x32_bf16 v[4:7], v[198:201], v[190:193], v[4:7]
	s_setprio 0
	s_add_u32 s14, s14, 0x100
	s_addc_u32 s15, s15, 0
	s_add_u32 s85, s85, 0x100
	s_addc_u32 s86, s86, 0
	s_cmp_ge_i32 s87, s75
	s_mov_b32 s12, s87
	s_barrier
	s_cbranch_scc0 .LBB0_382
	s_branch .LBB0_373

; #define PG8_STAGE(bufoff, gbase, voff) do { _Pragma("unroll") for (int _i = 0; _i < 2; ++_i) \
;         __builtin_amdgcn_global_load_lds((const unsigned*)((const char*)(gbase) + (voff)[_i]), (LAS unsigned*)(lds + (bufoff) + ldsw + _i * 8192), 16, 0, 0); } while (0)
; #define PG8_LDA(dst, b, h) do { _Pragma("unroll") for (int m = 0; m < 4; ++m) _Pragma("unroll") for (int k = 0; k < 2; ++k) dst[m][k] = *(const LAS bf16x8*)(lds + PG8_SA(b, h) + aoff + m * 2048 + k * 1024); } while (0)
; #define PG8_LDB(dst, b, h) do { _Pragma("unroll") for (int n = 0; n < 2; ++n) _Pragma("unroll") for (int k = 0; k < 2; ++k) dst[n][k] = *(const LAS bf16x8*)(lds + PG8_SB(b, h) + boff + n * 2048 + k * 1024); } while (0)
; #define PG8_MMA(ai, bj, At, Bt) do { __builtin_amdgcn_s_setprio(1); _Pragma("unroll") for (int m = 0; m < 4; ++m) _Pragma("unroll") for (int n = 0; n < 2; ++n) _Pragma("unroll") for (int k = 0; k < 2; ++k) \
;         acc[ai][bj][m][n] = __builtin_amdgcn_mfma_f32_16x16x32_bf16(Bt[n][k], At[m][k], acc[ai][bj][m][n], 0, 0, 0); __builtin_amdgcn_s_setprio(0); } while (0)
; #define PG8_WAIT_L(n) asm volatile("s_waitcnt lgkmcnt(" #n ")" ::: "memory")
; #define PG8_BAR __builtin_amdgcn_s_barrier()
; #define PG8_SCHED __builtin_amdgcn_sched_barrier(0)
; template <class Epi>
; DEVINL void gemm_phase(LAS unsigned char* lds, const Gemm g, const Order& S, const Epi& E) {
;     ...
;             PG8_LDB(B0, 0, 0); PG8_SCHED; PG8_LDA(At, 0, 0); PG8_STAGE(PG8_SA(1, 1), a1 + hstepA, voffA);
;             PG8_WAIT_L(8); PG8_BAR; PG8_WAIT_L(0); PG8_MMA(0, 0, At, B0); PG8_BAR; PG8_SCHED;
;             PG8_LDB(B1, 0, 1); PG8_STAGE(PG8_SB(0, 0), b2, voffB);
;             PG8_BAR; PG8_WAIT_L(0); PG8_MMA(0, 1, At, B1); PG8_BAR;
;             PG8_LDA(At, 0, 1); PG8_STAGE(PG8_SA(0, 0), a2, voffA);
;             PG8_BAR; PG8_WAIT_L(0); PG8_MMA(1, 0, At, B0); PG8_BAR; PG8_SCHED;
.LBB0_459:
	ds_read_b128 v[150:153], v147
	ds_read_b128 v[154:157], v147 offset:1024
	ds_read_b128 v[158:161], v147 offset:2048
	ds_read_b128 v[162:165], v147 offset:3072
	s_add_i32 s85, s14, 2
	s_add_u32 s10, s12, 0x100
	s_addc_u32 s11, s13, 0
	s_cmp_eq_u32 s74, s14
	s_cselect_b32 s14, s4, s83
	s_cselect_b32 s65, s9, s11
	s_cselect_b32 s64, s8, s10
	s_cselect_b32 s15, s5, s84
	v_lshl_add_u64 v[198:199], s[12:13], 0, v[136:137]
	s_add_i32 m0, s38, 0xc000
	ds_read_b128 v[166:169], v148
	ds_read_b128 v[170:173], v148 offset:1024
	ds_read_b128 v[174:177], v148 offset:2048
	ds_read_b128 v[178:181], v148 offset:3072
	ds_read_b128 v[182:185], v148 offset:4096
	ds_read_b128 v[186:189], v148 offset:5120
	ds_read_b128 v[190:193], v148 offset:6144
	ds_read_b128 v[194:197], v148 offset:7168
	global_load_lds_dwordx4 v[198:199], off
	v_lshl_add_u64 v[198:199], s[12:13], 0, v[138:139]
	s_add_i32 m0, s38, 0xe000
	s_nop 0
	global_load_lds_dwordx4 v[198:199], off
	s_waitcnt lgkmcnt(8)
	s_barrier
	s_waitcnt lgkmcnt(0)
	s_setprio 1
	s_waitcnt lgkmcnt(0)
	v_mfma_f32_16x16x32_bf16 v[120:123], v[150:153], v[166:169], v[120:123]
	v_mfma_f32_16x16x32_bf16 v[124:127], v[158:161], v[166:169], v[124:127]
	v_mfma_f32_16x16x32_bf16 v[104:107], v[158:161], v[174:177], v[104:107]
	v_mfma_f32_16x16x32_bf16 v[108:111], v[150:153], v[174:177], v[108:111]
	v_mfma_f32_16x16x32_bf16 v[92:95], v[150:153], v[182:185], v[92:95]
	v_mfma_f32_16x16x32_bf16 v[88:91], v[158:161], v[182:185], v[88:91]
	v_mfma_f32_16x16x32_bf16 v[72:75], v[158:161], v[190:193], v[72:75]
	v_mfma_f32_16x16x32_bf16 v[76:79], v[150:153], v[190:193], v[76:79]
	v_mfma_f32_16x16x32_bf16 v[120:123], v[154:157], v[170:173], v[120:123]
	v_mfma_f32_16x16x32_bf16 v[124:127], v[162:165], v[170:173], v[124:127]
	v_mfma_f32_16x16x32_bf16 v[104:107], v[162:165], v[178:181], v[104:107]
	v_mfma_f32_16x16x32_bf16 v[108:111], v[154:157], v[178:181], v[108:111]
	v_mfma_f32_16x16x32_bf16 v[92:95], v[154:157], v[186:189], v[92:95]
	v_mfma_f32_16x16x32_bf16 v[88:91], v[162:165], v[186:189], v[88:91]
	v_mfma_f32_16x16x32_bf16 v[72:75], v[162:165], v[194:197], v[72:75]
	v_mfma_f32_16x16x32_bf16 v[76:79], v[154:157], v[194:197], v[76:79]
	s_setprio 0
	s_barrier
	s_add_i32 s2, s78, s37
	v_lshl_add_u64 v[218:219], s[14:15], 0, v[130:131]
	s_mov_b32 m0, s2
	ds_read_b128 v[198:201], v149
	ds_read_b128 v[202:205], v149 offset:1024
	ds_read_b128 v[206:209], v149 offset:2048
	ds_read_b128 v[210:213], v149 offset:3072
	global_load_lds_dwordx4 v[218:219], off
	v_lshl_add_u64 v[220:221], s[14:15], 0, v[134:135]
	s_add_i32 m0, s2, 0x2000
	s_nop 0
	global_load_lds_dwordx4 v[220:221], off
	s_barrier
	s_waitcnt lgkmcnt(0)
	s_setprio 1
	s_waitcnt lgkmcnt(0)
	v_mfma_f32_16x16x32_bf16 v[116:119], v[198:201], v[166:169], v[116:119]
	v_mfma_f32_16x16x32_bf16 v[112:115], v[206:209], v[166:169], v[112:115]
	v_mfma_f32_16x16x32_bf16 v[96:99], v[206:209], v[174:177], v[96:99]
	v_mfma_f32_16x16x32_bf16 v[100:103], v[198:201], v[174:177], v[100:103]
	v_mfma_f32_16x16x32_bf16 v[84:87], v[198:201], v[182:185], v[84:87]
	v_mfma_f32_16x16x32_bf16 v[80:83], v[206:209], v[182:185], v[80:83]
	v_mfma_f32_16x16x32_bf16 v[64:67], v[206:209], v[190:193], v[64:67]
	v_mfma_f32_16x16x32_bf16 v[68:71], v[198:201], v[190:193], v[68:71]
	v_mfma_f32_16x16x32_bf16 v[116:119], v[202:205], v[170:173], v[116:119]
	v_mfma_f32_16x16x32_bf16 v[112:115], v[210:213], v[170:173], v[112:115]
	v_mfma_f32_16x16x32_bf16 v[96:99], v[210:213], v[178:181], v[96:99]
	v_mfma_f32_16x16x32_bf16 v[100:103], v[202:205], v[178:181], v[100:103]
	v_mfma_f32_16x16x32_bf16 v[84:87], v[202:205], v[186:189], v[84:87]
	v_mfma_f32_16x16x32_bf16 v[80:83], v[210:213], v[186:189], v[80:83]
	v_mfma_f32_16x16x32_bf16 v[64:67], v[210:213], v[194:197], v[64:67]
	v_mfma_f32_16x16x32_bf16 v[68:71], v[202:205], v[194:197], v[68:71]
	s_setprio 0
	s_mov_b32 m0, s38
	v_lshl_add_u64 v[222:223], s[64:65], 0, v[128:129]
	s_barrier
	ds_read_b128 v[166:169], v148 offset:16384
	ds_read_b128 v[170:173], v148 offset:17408
	ds_read_b128 v[174:177], v148 offset:18432
	ds_read_b128 v[178:181], v148 offset:19456
	ds_read_b128 v[182:185], v148 offset:20480
	ds_read_b128 v[186:189], v148 offset:21504
	ds_read_b128 v[190:193], v148 offset:22528
	ds_read_b128 v[194:197], v148 offset:23552
	global_load_lds_dwordx4 v[222:223], off
	v_lshl_add_u64 v[224:225], s[64:65], 0, v[132:133]
	s_mov_b32 m0, s39
	s_nop 0
	global_load_lds_dwordx4 v[224:225], off
	s_barrier
	s_waitcnt lgkmcnt(0)
	s_setprio 1
	s_waitcnt lgkmcnt(0)
	v_mfma_f32_16x16x32_bf16 v[60:63], v[150:153], v[166:169], v[60:63]
	v_mfma_f32_16x16x32_bf16 v[56:59], v[158:161], v[166:169], v[56:59]
	v_mfma_f32_16x16x32_bf16 v[40:43], v[158:161], v[174:177], v[40:43]
	v_mfma_f32_16x16x32_bf16 v[44:47], v[150:153], v[174:177], v[44:47]
	v_mfma_f32_16x16x32_bf16 v[28:31], v[150:153], v[182:185], v[28:31]
	v_mfma_f32_16x16x32_bf16 v[24:27], v[158:161], v[182:185], v[24:27]
	v_mfma_f32_16x16x32_bf16 v[8:11], v[158:161], v[190:193], v[8:11]
	v_mfma_f32_16x16x32_bf16 v[12:15], v[150:153], v[190:193], v[12:15]
	v_mfma_f32_16x16x32_bf16 v[60:63], v[154:157], v[170:173], v[60:63]
	v_mfma_f32_16x16x32_bf16 v[56:59], v[162:165], v[170:173], v[56:59]
	v_mfma_f32_16x16x32_bf16 v[40:43], v[162:165], v[178:181], v[40:43]
	v_mfma_f32_16x16x32_bf16 v[44:47], v[154:157], v[178:181], v[44:47]
	v_mfma_f32_16x16x32_bf16 v[28:31], v[154:157], v[186:189], v[28:31]
	v_mfma_f32_16x16x32_bf16 v[24:27], v[162:165], v[186:189], v[24:27]
	v_mfma_f32_16x16x32_bf16 v[8:11], v[162:165], v[194:197], v[8:11]
	v_mfma_f32_16x16x32_bf16 v[12:15], v[154:157], v[194:197], v[12:15]
	s_setprio 0
	s_barrier
; #define PG8_STAGE(bufoff, gbase, voff) do { _Pragma("unroll") for (int _i = 0; _i < 2; ++_i) \
;         __builtin_amdgcn_global_load_lds((const unsigned*)((const char*)(gbase) + (voff)[_i]), (LAS unsigned*)(lds + (bufoff) + ldsw + _i * 8192), 16, 0, 0); } while (0)
; #define PG8_LDA(dst, b, h) do { _Pragma("unroll") for (int m = 0; m < 4; ++m) _Pragma("unroll") for (int k = 0; k < 2; ++k) dst[m][k] = *(const LAS bf16x8*)(lds + PG8_SA(b, h) + aoff + m * 2048 + k * 1024); } while (0)
; #define PG8_LDB(dst, b, h) do { _Pragma("unroll") for (int n = 0; n < 2; ++n) _Pragma("unroll") for (int k = 0; k < 2; ++k) dst[n][k] = *(const LAS bf16x8*)(lds + PG8_SB(b, h) + boff + n * 2048 + k * 1024); } while (0)
; #define PG8_MMA(ai, bj, At, Bt) do { __builtin_amdgcn_s_setprio(1); _Pragma("unroll") for (int m = 0; m < 4; ++m) _Pragma("unroll") for (int n = 0; n < 2; ++n) _Pragma("unroll") for (int k = 0; k < 2; ++k) \
;         acc[ai][bj][m][n] = __builtin_amdgcn_mfma_f32_16x16x32_bf16(Bt[n][k], At[m][k], acc[ai][bj][m][n], 0, 0, 0); __builtin_amdgcn_s_setprio(0); } while (0)
; #define PG8_WAIT_V(n) asm volatile("s_waitcnt vmcnt(" #n ")" ::: "memory")
; #define PG8_WAIT_L(n) asm volatile("s_waitcnt lgkmcnt(" #n ")" ::: "memory")
; #define PG8_BAR __builtin_amdgcn_s_barrier()
; #define PG8_SCHED __builtin_amdgcn_sched_barrier(0)
; template <class Epi>
; DEVINL void gemm_phase(LAS unsigned char* lds, const Gemm g, const Order& S, const Epi& E) {
;     ...
;             PG8_STAGE(PG8_SB(0, 1), b2 + hstepB, voffB);
;             PG8_WAIT_V(6); PG8_BAR; PG8_MMA(1, 1, At, B1); PG8_BAR;
;             PG8_LDB(B0, 1, 0); PG8_SCHED; PG8_LDA(At, 1, 0); PG8_STAGE(PG8_SA(0, 1), a2 + hstepA, voffA);
;             PG8_WAIT_L(8); PG8_BAR; PG8_WAIT_L(0); PG8_MMA(0, 0, At, B0); PG8_BAR; PG8_SCHED;
;             PG8_LDB(B1, 1, 1); PG8_STAGE(PG8_SB(1, 0), b3, voffB);
	s_add_u32 s2, s14, 0x158000
	s_addc_u32 s3, s15, 0
	s_add_i32 s12, s79, s37
	v_lshl_add_u64 v[150:151], s[2:3], 0, v[130:131]
	s_mov_b32 m0, s12
	s_nop 0
	global_load_lds_dwordx4 v[150:151], off
	v_lshl_add_u64 v[150:151], s[2:3], 0, v[134:135]
	s_add_i32 m0, s12, 0x2000
	s_nop 0
	global_load_lds_dwordx4 v[150:151], off
	s_waitcnt vmcnt(6)
	s_barrier
	s_setprio 1
	v_mfma_f32_16x16x32_bf16 v[52:55], v[198:201], v[166:169], v[52:55]
	v_mfma_f32_16x16x32_bf16 v[48:51], v[206:209], v[166:169], v[48:51]
	v_mfma_f32_16x16x32_bf16 v[32:35], v[206:209], v[174:177], v[32:35]
	v_mfma_f32_16x16x32_bf16 v[36:39], v[198:201], v[174:177], v[36:39]
	v_mfma_f32_16x16x32_bf16 v[20:23], v[198:201], v[182:185], v[20:23]
	v_mfma_f32_16x16x32_bf16 v[16:19], v[206:209], v[182:185], v[16:19]
	v_mfma_f32_16x16x32_bf16 v[0:3], v[206:209], v[190:193], v[0:3]
	v_mfma_f32_16x16x32_bf16 v[4:7], v[198:201], v[190:193], v[4:7]
	v_mfma_f32_16x16x32_bf16 v[52:55], v[202:205], v[170:173], v[52:55]
	v_mfma_f32_16x16x32_bf16 v[48:51], v[210:213], v[170:173], v[48:51]
	v_mfma_f32_16x16x32_bf16 v[32:35], v[210:213], v[178:181], v[32:35]
	v_mfma_f32_16x16x32_bf16 v[36:39], v[202:205], v[178:181], v[36:39]
	v_mfma_f32_16x16x32_bf16 v[20:23], v[202:205], v[186:189], v[20:23]
	v_mfma_f32_16x16x32_bf16 v[16:19], v[210:213], v[186:189], v[16:19]
	v_mfma_f32_16x16x32_bf16 v[0:3], v[210:213], v[194:197], v[0:3]
	v_mfma_f32_16x16x32_bf16 v[4:7], v[202:205], v[194:197], v[4:7]
	s_setprio 0
	s_add_i32 s12, 16, 0x18000
	v_add_u32_e32 v162, s12, v145
	s_barrier
	ds_read_b128 v[150:153], v162
	ds_read_b128 v[154:157], v162 offset:1024
	ds_read_b128 v[158:161], v162 offset:2048
	ds_read_b128 v[162:165], v162 offset:3072
	s_add_u32 s2, s64, 0x158000
	s_addc_u32 s3, s65, 0
	s_mov_b32 m0, s66
	v_lshl_add_u64 v[198:199], s[2:3], 0, v[128:129]
	ds_read_b128 v[166:169], v148 offset:32768
	ds_read_b128 v[170:173], v148 offset:33792
	ds_read_b128 v[174:177], v148 offset:34816
	ds_read_b128 v[178:181], v148 offset:35840
	ds_read_b128 v[182:185], v148 offset:36864
	ds_read_b128 v[186:189], v148 offset:37888
	ds_read_b128 v[190:193], v148 offset:38912
	ds_read_b128 v[194:197], v148 offset:39936
	global_load_lds_dwordx4 v[198:199], off
	v_lshl_add_u64 v[198:199], s[2:3], 0, v[132:133]
	s_mov_b32 m0, s67
	s_nop 0
	global_load_lds_dwordx4 v[198:199], off
	s_waitcnt lgkmcnt(8)
	s_barrier
	s_waitcnt lgkmcnt(0)
	s_setprio 1
	s_waitcnt lgkmcnt(0)
	v_mfma_f32_16x16x32_bf16 v[120:123], v[150:153], v[166:169], v[120:123]
	v_mfma_f32_16x16x32_bf16 v[124:127], v[158:161], v[166:169], v[124:127]
	v_mfma_f32_16x16x32_bf16 v[104:107], v[158:161], v[174:177], v[104:107]
	v_mfma_f32_16x16x32_bf16 v[108:111], v[150:153], v[174:177], v[108:111]
	v_mfma_f32_16x16x32_bf16 v[92:95], v[150:153], v[182:185], v[92:95]
	v_mfma_f32_16x16x32_bf16 v[88:91], v[158:161], v[182:185], v[88:91]
	v_mfma_f32_16x16x32_bf16 v[72:75], v[158:161], v[190:193], v[72:75]
	v_mfma_f32_16x16x32_bf16 v[76:79], v[150:153], v[190:193], v[76:79]
	v_mfma_f32_16x16x32_bf16 v[120:123], v[154:157], v[170:173], v[120:123]
	v_mfma_f32_16x16x32_bf16 v[124:127], v[162:165], v[170:173], v[124:127]
	v_mfma_f32_16x16x32_bf16 v[104:107], v[162:165], v[178:181], v[104:107]
	v_mfma_f32_16x16x32_bf16 v[108:111], v[154:157], v[178:181], v[108:111]
	v_mfma_f32_16x16x32_bf16 v[92:95], v[154:157], v[186:189], v[92:95]
	v_mfma_f32_16x16x32_bf16 v[88:91], v[162:165], v[186:189], v[88:91]
	v_mfma_f32_16x16x32_bf16 v[72:75], v[162:165], v[194:197], v[72:75]
	v_mfma_f32_16x16x32_bf16 v[76:79], v[154:157], v[194:197], v[76:79]
	s_setprio 0
	s_barrier
	s_add_i32 s13, 16, 0x1c000
	s_add_i32 s2, s12, s37
	v_add_u32_e32 v210, s13, v145
	v_lshl_add_u64 v[218:219], v[218:219], 0, s[6:7]
	s_mov_b32 m0, s2
	ds_read_b128 v[198:201], v210
	ds_read_b128 v[202:205], v210 offset:1024
	ds_read_b128 v[206:209], v210 offset:2048
	ds_read_b128 v[210:213], v210 offset:3072
	global_load_lds_dwordx4 v[218:219], off
	v_lshl_add_u64 v[218:219], v[220:221], 0, s[6:7]
	s_add_i32 m0, s2, 0x2000
	s_nop 0
	global_load_lds_dwordx4 v[218:219], off
	s_barrier
; #define PG8_STAGE(bufoff, gbase, voff) do { _Pragma("unroll") for (int _i = 0; _i < 2; ++_i) \
;         __builtin_amdgcn_global_load_lds((const unsigned*)((const char*)(gbase) + (voff)[_i]), (LAS unsigned*)(lds + (bufoff) + ldsw + _i * 8192), 16, 0, 0); } while (0)
; #define PG8_LDA(dst, b, h) do { _Pragma("unroll") for (int m = 0; m < 4; ++m) _Pragma("unroll") for (int k = 0; k < 2; ++k) dst[m][k] = *(const LAS bf16x8*)(lds + PG8_SA(b, h) + aoff + m * 2048 + k * 1024); } while (0)
; #define PG8_MMA(ai, bj, At, Bt) do { __builtin_amdgcn_s_setprio(1); _Pragma("unroll") for (int m = 0; m < 4; ++m) _Pragma("unroll") for (int n = 0; n < 2; ++n) _Pragma("unroll") for (int k = 0; k < 2; ++k) \
;         acc[ai][bj][m][n] = __builtin_amdgcn_mfma_f32_16x16x32_bf16(Bt[n][k], At[m][k], acc[ai][bj][m][n], 0, 0, 0); __builtin_amdgcn_s_setprio(0); } while (0)
; #define PG8_WAIT_V(n) asm volatile("s_waitcnt vmcnt(" #n ")" ::: "memory")
; #define PG8_WAIT_L(n) asm volatile("s_waitcnt lgkmcnt(" #n ")" ::: "memory")
; #define PG8_BAR __builtin_amdgcn_s_barrier()
; #define PG8_SCHED __builtin_amdgcn_sched_barrier(0)
; template <class Epi>
; DEVINL void gemm_phase(LAS unsigned char* lds, const Gemm g, const Order& S, const Epi& E) {
;     ...
;             PG8_BAR; PG8_WAIT_L(0); PG8_MMA(0, 1, At, B1); PG8_BAR;
;             PG8_LDA(At, 1, 1); PG8_STAGE(PG8_SA(1, 0), a3, voffA);
;             PG8_BAR; PG8_WAIT_L(0); PG8_MMA(1, 0, At, B0); PG8_BAR; PG8_SCHED;
;             PG8_STAGE(PG8_SB(1, 1), b3 + hstepB, voffB);
;             PG8_WAIT_V(6); PG8_BAR; PG8_MMA(1, 1, At, B1); PG8_BAR;
;         }
	s_waitcnt lgkmcnt(0)
	s_setprio 1
	s_waitcnt lgkmcnt(0)
	v_mfma_f32_16x16x32_bf16 v[116:119], v[198:201], v[166:169], v[116:119]
	v_mfma_f32_16x16x32_bf16 v[112:115], v[206:209], v[166:169], v[112:115]
	v_mfma_f32_16x16x32_bf16 v[96:99], v[206:209], v[174:177], v[96:99]
	v_mfma_f32_16x16x32_bf16 v[100:103], v[198:201], v[174:177], v[100:103]
	v_mfma_f32_16x16x32_bf16 v[84:87], v[198:201], v[182:185], v[84:87]
	v_mfma_f32_16x16x32_bf16 v[80:83], v[206:209], v[182:185], v[80:83]
	v_mfma_f32_16x16x32_bf16 v[64:67], v[206:209], v[190:193], v[64:67]
	v_mfma_f32_16x16x32_bf16 v[68:71], v[198:201], v[190:193], v[68:71]
	v_mfma_f32_16x16x32_bf16 v[116:119], v[202:205], v[170:173], v[116:119]
	v_mfma_f32_16x16x32_bf16 v[112:115], v[210:213], v[170:173], v[112:115]
	v_mfma_f32_16x16x32_bf16 v[96:99], v[210:213], v[178:181], v[96:99]
	v_mfma_f32_16x16x32_bf16 v[100:103], v[202:205], v[178:181], v[100:103]
	v_mfma_f32_16x16x32_bf16 v[84:87], v[202:205], v[186:189], v[84:87]
	v_mfma_f32_16x16x32_bf16 v[80:83], v[210:213], v[186:189], v[80:83]
	v_mfma_f32_16x16x32_bf16 v[64:67], v[210:213], v[194:197], v[64:67]
	v_mfma_f32_16x16x32_bf16 v[68:71], v[202:205], v[194:197], v[68:71]
	s_setprio 0
	s_mov_b32 m0, s69
	v_lshl_add_u64 v[218:219], v[222:223], 0, s[6:7]
	s_barrier
	ds_read_b128 v[166:169], v148 offset:49152
	ds_read_b128 v[170:173], v148 offset:50176
	ds_read_b128 v[174:177], v148 offset:51200
	ds_read_b128 v[178:181], v148 offset:52224
	ds_read_b128 v[182:185], v148 offset:53248
	ds_read_b128 v[186:189], v148 offset:54272
	ds_read_b128 v[190:193], v148 offset:55296
	ds_read_b128 v[194:197], v148 offset:56320
	global_load_lds_dwordx4 v[218:219], off
	v_lshl_add_u64 v[218:219], v[224:225], 0, s[6:7]
	s_mov_b32 m0, s72
	s_nop 0
	global_load_lds_dwordx4 v[218:219], off
	s_barrier
	s_waitcnt lgkmcnt(0)
	s_setprio 1
	s_waitcnt lgkmcnt(0)
	v_mfma_f32_16x16x32_bf16 v[60:63], v[150:153], v[166:169], v[60:63]
	v_mfma_f32_16x16x32_bf16 v[56:59], v[158:161], v[166:169], v[56:59]
	v_mfma_f32_16x16x32_bf16 v[40:43], v[158:161], v[174:177], v[40:43]
	v_mfma_f32_16x16x32_bf16 v[44:47], v[150:153], v[174:177], v[44:47]
	v_mfma_f32_16x16x32_bf16 v[28:31], v[150:153], v[182:185], v[28:31]
	v_mfma_f32_16x16x32_bf16 v[24:27], v[158:161], v[182:185], v[24:27]
	v_mfma_f32_16x16x32_bf16 v[8:11], v[158:161], v[190:193], v[8:11]
	v_mfma_f32_16x16x32_bf16 v[12:15], v[150:153], v[190:193], v[12:15]
	v_mfma_f32_16x16x32_bf16 v[60:63], v[154:157], v[170:173], v[60:63]
	v_mfma_f32_16x16x32_bf16 v[56:59], v[162:165], v[170:173], v[56:59]
	v_mfma_f32_16x16x32_bf16 v[40:43], v[162:165], v[178:181], v[40:43]
	v_mfma_f32_16x16x32_bf16 v[44:47], v[154:157], v[178:181], v[44:47]
	v_mfma_f32_16x16x32_bf16 v[28:31], v[154:157], v[186:189], v[28:31]
	v_mfma_f32_16x16x32_bf16 v[24:27], v[162:165], v[186:189], v[24:27]
	v_mfma_f32_16x16x32_bf16 v[8:11], v[162:165], v[194:197], v[8:11]
	v_mfma_f32_16x16x32_bf16 v[12:15], v[154:157], v[194:197], v[12:15]
	s_setprio 0
	s_barrier
	s_add_u32 s2, s14, 0x158080
	s_addc_u32 s3, s15, 0
	s_add_i32 s12, s13, s37
	v_lshl_add_u64 v[150:151], s[2:3], 0, v[130:131]
	s_mov_b32 m0, s12
	s_nop 0
	global_load_lds_dwordx4 v[150:151], off
	v_lshl_add_u64 v[150:151], s[2:3], 0, v[134:135]
	s_add_i32 m0, s12, 0x2000
	s_nop 0
	global_load_lds_dwordx4 v[150:151], off
	s_waitcnt vmcnt(6)
	s_barrier
	s_setprio 1
	v_mfma_f32_16x16x32_bf16 v[52:55], v[198:201], v[166:169], v[52:55]
	v_mfma_f32_16x16x32_bf16 v[48:51], v[206:209], v[166:169], v[48:51]
	v_mfma_f32_16x16x32_bf16 v[32:35], v[206:209], v[174:177], v[32:35]
	v_mfma_f32_16x16x32_bf16 v[36:39], v[198:201], v[174:177], v[36:39]
	v_mfma_f32_16x16x32_bf16 v[20:23], v[198:201], v[182:185], v[20:23]
	v_mfma_f32_16x16x32_bf16 v[16:19], v[206:209], v[182:185], v[16:19]
	v_mfma_f32_16x16x32_bf16 v[0:3], v[206:209], v[190:193], v[0:3]
	v_mfma_f32_16x16x32_bf16 v[4:7], v[198:201], v[190:193], v[4:7]
	v_mfma_f32_16x16x32_bf16 v[52:55], v[202:205], v[170:173], v[52:55]
	v_mfma_f32_16x16x32_bf16 v[48:51], v[210:213], v[170:173], v[48:51]
	v_mfma_f32_16x16x32_bf16 v[32:35], v[210:213], v[178:181], v[32:35]
	v_mfma_f32_16x16x32_bf16 v[36:39], v[202:205], v[178:181], v[36:39]
	v_mfma_f32_16x16x32_bf16 v[20:23], v[202:205], v[186:189], v[20:23]
	v_mfma_f32_16x16x32_bf16 v[16:19], v[210:213], v[186:189], v[16:19]
	v_mfma_f32_16x16x32_bf16 v[0:3], v[210:213], v[194:197], v[0:3]
	v_mfma_f32_16x16x32_bf16 v[4:7], v[202:205], v[194:197], v[4:7]
	s_setprio 0
	s_add_u32 s83, s83, 0x100
	s_addc_u32 s84, s84, 0
	s_cmp_ge_i32 s85, s68
	s_mov_b64 s[12:13], s[10:11]
	s_mov_b32 s14, s85
	s_barrier
	s_cbranch_scc0 .LBB0_459
	s_branch .LBB0_446

; #define PG8_STAGE(bufoff, gbase, voff) do { _Pragma("unroll") for (int _i = 0; _i < 2; ++_i) \
;         __builtin_amdgcn_global_load_lds((const unsigned*)((const char*)(gbase) + (voff)[_i]), (LAS unsigned*)(lds + (bufoff) + ldsw + _i * 8192), 16, 0, 0); } while (0)
; #define PG8_LDA(dst, b, h) do { _Pragma("unroll") for (int m = 0; m < 4; ++m) _Pragma("unroll") for (int k = 0; k < 2; ++k) dst[m][k] = *(const LAS bf16x8*)(lds + PG8_SA(b, h) + aoff + m * 2048 + k * 1024); } while (0)
; #define PG8_LDB(dst, b, h) do { _Pragma("unroll") for (int n = 0; n < 2; ++n) _Pragma("unroll") for (int k = 0; k < 2; ++k) dst[n][k] = *(const LAS bf16x8*)(lds + PG8_SB(b, h) + boff + n * 2048 + k * 1024); } while (0)
; #define PG8_MMA(ai, bj, At, Bt) do { __builtin_amdgcn_s_setprio(1); _Pragma("unroll") for (int m = 0; m < 4; ++m) _Pragma("unroll") for (int n = 0; n < 2; ++n) _Pragma("unroll") for (int k = 0; k < 2; ++k) \
;         acc[ai][bj][m][n] = __builtin_amdgcn_mfma_f32_16x16x32_bf16(Bt[n][k], At[m][k], acc[ai][bj][m][n], 0, 0, 0); __builtin_amdgcn_s_setprio(0); } while (0)
; #define PG8_WAIT_L(n) asm volatile("s_waitcnt lgkmcnt(" #n ")" ::: "memory")
; #define PG8_BAR __builtin_amdgcn_s_barrier()
; #define PG8_SCHED __builtin_amdgcn_sched_barrier(0)
; template <class Epi>
; DEVINL void gemm_phase(LAS unsigned char* lds, const Gemm g, const Order& S, const Epi& E) {
;     ...
;             PG8_LDB(B0, 0, 0); PG8_SCHED; PG8_LDA(At, 0, 0); PG8_STAGE(PG8_SA(1, 1), a1 + hstepA, voffA);
;             PG8_WAIT_L(8); PG8_BAR; PG8_WAIT_L(0); PG8_MMA(0, 0, At, B0); PG8_BAR; PG8_SCHED;
;             PG8_LDB(B1, 0, 1); PG8_STAGE(PG8_SB(0, 0), b2, voffB);
;             PG8_BAR; PG8_WAIT_L(0); PG8_MMA(0, 1, At, B1); PG8_BAR;
;             PG8_LDA(At, 0, 1); PG8_STAGE(PG8_SA(0, 0), a2, voffA);
;             PG8_BAR; PG8_WAIT_L(0); PG8_MMA(1, 0, At, B0); PG8_BAR; PG8_SCHED;
.LBB0_650:
	ds_read_b128 v[128:131], v175
	ds_read_b128 v[132:135], v175 offset:1024
	ds_read_b128 v[136:139], v175 offset:2048
	ds_read_b128 v[140:143], v175 offset:3072
	s_add_i32 s64, s14, 2
	s_add_u32 s2, s12, 0xfff80080
	s_addc_u32 s3, s13, -1
	s_cmp_eq_u32 s49, s14
	s_cselect_b32 s14, s57, s58
	s_cselect_b32 s45, s11, s3
	s_cselect_b32 s44, s17, s2
	s_cselect_b32 s15, s56, s59
	v_lshl_add_u64 v[170:171], s[12:13], 0, v[156:157]
	s_add_i32 m0, s29, 0xc000
	ds_read_b128 v[166:169], v176
	ds_read_b128 v[178:181], v176 offset:1024
	ds_read_b128 v[182:185], v176 offset:2048
	ds_read_b128 v[186:189], v176 offset:3072
	ds_read_b128 v[190:193], v176 offset:4096
	ds_read_b128 v[194:197], v176 offset:5120
	ds_read_b128 v[198:201], v176 offset:6144
	ds_read_b128 v[202:205], v176 offset:7168
	global_load_lds_dwordx4 v[170:171], off
	v_lshl_add_u64 v[170:171], s[12:13], 0, v[158:159]
	s_add_i32 m0, s29, 0xe000
	s_nop 0
	global_load_lds_dwordx4 v[170:171], off
	s_waitcnt lgkmcnt(8)
	s_barrier
	s_waitcnt lgkmcnt(0)
	s_setprio 1
	s_waitcnt lgkmcnt(0)
	v_mfma_f32_16x16x32_bf16 v[124:127], v[128:131], v[166:169], v[124:127]
	v_mfma_f32_16x16x32_bf16 v[120:123], v[136:139], v[166:169], v[120:123]
	v_mfma_f32_16x16x32_bf16 v[104:107], v[136:139], v[182:185], v[104:107]
	v_mfma_f32_16x16x32_bf16 v[108:111], v[128:131], v[182:185], v[108:111]
	v_mfma_f32_16x16x32_bf16 v[92:95], v[128:131], v[190:193], v[92:95]
	v_mfma_f32_16x16x32_bf16 v[88:91], v[136:139], v[190:193], v[88:91]
	v_mfma_f32_16x16x32_bf16 v[72:75], v[136:139], v[198:201], v[72:75]
	v_mfma_f32_16x16x32_bf16 v[76:79], v[128:131], v[198:201], v[76:79]
	v_mfma_f32_16x16x32_bf16 v[124:127], v[132:135], v[178:181], v[124:127]
	v_mfma_f32_16x16x32_bf16 v[120:123], v[140:143], v[178:181], v[120:123]
	v_mfma_f32_16x16x32_bf16 v[104:107], v[140:143], v[186:189], v[104:107]
	v_mfma_f32_16x16x32_bf16 v[108:111], v[132:135], v[186:189], v[108:111]
	v_mfma_f32_16x16x32_bf16 v[92:95], v[132:135], v[194:197], v[92:95]
	v_mfma_f32_16x16x32_bf16 v[88:91], v[140:143], v[194:197], v[88:91]
	v_mfma_f32_16x16x32_bf16 v[72:75], v[140:143], v[202:205], v[72:75]
	v_mfma_f32_16x16x32_bf16 v[76:79], v[132:135], v[202:205], v[76:79]
	s_setprio 0
	s_barrier
	s_add_i32 s2, s52, s26
	v_lshl_add_u64 v[170:171], s[14:15], 0, v[148:149]
	s_mov_b32 m0, s2
	ds_read_b128 v[206:209], v177
	ds_read_b128 v[210:213], v177 offset:1024
	ds_read_b128 v[218:221], v177 offset:2048
	ds_read_b128 v[222:225], v177 offset:3072
	global_load_lds_dwordx4 v[170:171], off
	v_lshl_add_u64 v[226:227], s[14:15], 0, v[144:145]
	s_add_i32 m0, s2, 0x2000
	s_nop 0
	global_load_lds_dwordx4 v[226:227], off
	s_barrier
	s_waitcnt lgkmcnt(0)
	s_setprio 1
	s_waitcnt lgkmcnt(0)
	v_mfma_f32_16x16x32_bf16 v[116:119], v[206:209], v[166:169], v[116:119]
	v_mfma_f32_16x16x32_bf16 v[112:115], v[218:221], v[166:169], v[112:115]
	v_mfma_f32_16x16x32_bf16 v[96:99], v[218:221], v[182:185], v[96:99]
	v_mfma_f32_16x16x32_bf16 v[100:103], v[206:209], v[182:185], v[100:103]
	v_mfma_f32_16x16x32_bf16 v[84:87], v[206:209], v[190:193], v[84:87]
	v_mfma_f32_16x16x32_bf16 v[80:83], v[218:221], v[190:193], v[80:83]
	v_mfma_f32_16x16x32_bf16 v[64:67], v[218:221], v[198:201], v[64:67]
	v_mfma_f32_16x16x32_bf16 v[68:71], v[206:209], v[198:201], v[68:71]
	v_mfma_f32_16x16x32_bf16 v[116:119], v[210:213], v[178:181], v[116:119]
	v_mfma_f32_16x16x32_bf16 v[112:115], v[222:225], v[178:181], v[112:115]
	v_mfma_f32_16x16x32_bf16 v[96:99], v[222:225], v[186:189], v[96:99]
	v_mfma_f32_16x16x32_bf16 v[100:103], v[210:213], v[186:189], v[100:103]
	v_mfma_f32_16x16x32_bf16 v[84:87], v[210:213], v[194:197], v[84:87]
	v_mfma_f32_16x16x32_bf16 v[80:83], v[222:225], v[194:197], v[80:83]
	v_mfma_f32_16x16x32_bf16 v[64:67], v[222:225], v[202:205], v[64:67]
	v_mfma_f32_16x16x32_bf16 v[68:71], v[210:213], v[202:205], v[68:71]
	s_setprio 0
	s_mov_b32 m0, s29
	v_lshl_add_u64 v[228:229], s[44:45], 0, v[150:151]
	s_barrier
	ds_read_b128 v[166:169], v176 offset:16384
	ds_read_b128 v[178:181], v176 offset:17408
	ds_read_b128 v[182:185], v176 offset:18432
	ds_read_b128 v[186:189], v176 offset:19456
	ds_read_b128 v[190:193], v176 offset:20480
	ds_read_b128 v[194:197], v176 offset:21504
	ds_read_b128 v[198:201], v176 offset:22528
	ds_read_b128 v[202:205], v176 offset:23552
	global_load_lds_dwordx4 v[228:229], off
	v_lshl_add_u64 v[230:231], s[44:45], 0, v[146:147]
	s_mov_b32 m0, s30
	s_nop 0
	global_load_lds_dwordx4 v[230:231], off
	s_barrier
	s_waitcnt lgkmcnt(0)
	s_setprio 1
	s_waitcnt lgkmcnt(0)
	v_mfma_f32_16x16x32_bf16 v[60:63], v[128:131], v[166:169], v[60:63]
	v_mfma_f32_16x16x32_bf16 v[56:59], v[136:139], v[166:169], v[56:59]
	v_mfma_f32_16x16x32_bf16 v[40:43], v[136:139], v[182:185], v[40:43]
	v_mfma_f32_16x16x32_bf16 v[44:47], v[128:131], v[182:185], v[44:47]
	v_mfma_f32_16x16x32_bf16 v[28:31], v[128:131], v[190:193], v[28:31]
	v_mfma_f32_16x16x32_bf16 v[24:27], v[136:139], v[190:193], v[24:27]
	v_mfma_f32_16x16x32_bf16 v[8:11], v[136:139], v[198:201], v[8:11]
	v_mfma_f32_16x16x32_bf16 v[12:15], v[128:131], v[198:201], v[12:15]
	v_mfma_f32_16x16x32_bf16 v[60:63], v[132:135], v[178:181], v[60:63]
	v_mfma_f32_16x16x32_bf16 v[56:59], v[140:143], v[178:181], v[56:59]
	v_mfma_f32_16x16x32_bf16 v[40:43], v[140:143], v[186:189], v[40:43]
	v_mfma_f32_16x16x32_bf16 v[44:47], v[132:135], v[186:189], v[44:47]
	v_mfma_f32_16x16x32_bf16 v[28:31], v[132:135], v[194:197], v[28:31]
	v_mfma_f32_16x16x32_bf16 v[24:27], v[140:143], v[194:197], v[24:27]
	v_mfma_f32_16x16x32_bf16 v[8:11], v[140:143], v[202:205], v[8:11]
	v_mfma_f32_16x16x32_bf16 v[12:15], v[132:135], v[202:205], v[12:15]
	s_setprio 0
	s_barrier
; #define PG8_STAGE(bufoff, gbase, voff) do { _Pragma("unroll") for (int _i = 0; _i < 2; ++_i) \
;         __builtin_amdgcn_global_load_lds((const unsigned*)((const char*)(gbase) + (voff)[_i]), (LAS unsigned*)(lds + (bufoff) + ldsw + _i * 8192), 16, 0, 0); } while (0)
; #define PG8_LDA(dst, b, h) do { _Pragma("unroll") for (int m = 0; m < 4; ++m) _Pragma("unroll") for (int k = 0; k < 2; ++k) dst[m][k] = *(const LAS bf16x8*)(lds + PG8_SA(b, h) + aoff + m * 2048 + k * 1024); } while (0)
; #define PG8_LDB(dst, b, h) do { _Pragma("unroll") for (int n = 0; n < 2; ++n) _Pragma("unroll") for (int k = 0; k < 2; ++k) dst[n][k] = *(const LAS bf16x8*)(lds + PG8_SB(b, h) + boff + n * 2048 + k * 1024); } while (0)
; #define PG8_MMA(ai, bj, At, Bt) do { __builtin_amdgcn_s_setprio(1); _Pragma("unroll") for (int m = 0; m < 4; ++m) _Pragma("unroll") for (int n = 0; n < 2; ++n) _Pragma("unroll") for (int k = 0; k < 2; ++k) \
;         acc[ai][bj][m][n] = __builtin_amdgcn_mfma_f32_16x16x32_bf16(Bt[n][k], At[m][k], acc[ai][bj][m][n], 0, 0, 0); __builtin_amdgcn_s_setprio(0); } while (0)
; #define PG8_WAIT_V(n) asm volatile("s_waitcnt vmcnt(" #n ")" ::: "memory")
; #define PG8_WAIT_L(n) asm volatile("s_waitcnt lgkmcnt(" #n ")" ::: "memory")
; #define PG8_BAR __builtin_amdgcn_s_barrier()
; #define PG8_SCHED __builtin_amdgcn_sched_barrier(0)
; template <class Epi>
; DEVINL void gemm_phase(LAS unsigned char* lds, const Gemm g, const Order& S, const Epi& E) {
;     ...
;             PG8_STAGE(PG8_SB(0, 1), b2 + hstepB, voffB);
;             PG8_WAIT_V(6); PG8_BAR; PG8_MMA(1, 1, At, B1); PG8_BAR;
;             PG8_LDB(B0, 1, 0); PG8_SCHED; PG8_LDA(At, 1, 0); PG8_STAGE(PG8_SA(0, 1), a2 + hstepA, voffA);
;             PG8_WAIT_L(8); PG8_BAR; PG8_WAIT_L(0); PG8_MMA(0, 0, At, B0); PG8_BAR; PG8_SCHED;
;             PG8_LDB(B1, 1, 1); PG8_STAGE(PG8_SB(1, 0), b3, voffB);
	s_add_u32 s2, s14, 0x80000
	s_addc_u32 s3, s15, 0
	s_add_i32 s65, s53, s26
	v_lshl_add_u64 v[128:129], s[2:3], 0, v[148:149]
	s_mov_b32 m0, s65
	s_nop 0
	global_load_lds_dwordx4 v[128:129], off
	v_lshl_add_u64 v[128:129], s[2:3], 0, v[144:145]
	s_add_i32 m0, s65, 0x2000
	s_nop 0
	global_load_lds_dwordx4 v[128:129], off
	s_waitcnt vmcnt(6)
	s_barrier
	s_setprio 1
	v_mfma_f32_16x16x32_bf16 v[52:55], v[206:209], v[166:169], v[52:55]
	v_mfma_f32_16x16x32_bf16 v[48:51], v[218:221], v[166:169], v[48:51]
	v_mfma_f32_16x16x32_bf16 v[32:35], v[218:221], v[182:185], v[32:35]
	v_mfma_f32_16x16x32_bf16 v[36:39], v[206:209], v[182:185], v[36:39]
	v_mfma_f32_16x16x32_bf16 v[20:23], v[206:209], v[190:193], v[20:23]
	v_mfma_f32_16x16x32_bf16 v[16:19], v[218:221], v[190:193], v[16:19]
	v_mfma_f32_16x16x32_bf16 v[0:3], v[218:221], v[198:201], v[0:3]
	v_mfma_f32_16x16x32_bf16 v[4:7], v[206:209], v[198:201], v[4:7]
	v_mfma_f32_16x16x32_bf16 v[52:55], v[210:213], v[178:181], v[52:55]
	v_mfma_f32_16x16x32_bf16 v[48:51], v[222:225], v[178:181], v[48:51]
	v_mfma_f32_16x16x32_bf16 v[32:35], v[222:225], v[186:189], v[32:35]
	v_mfma_f32_16x16x32_bf16 v[36:39], v[210:213], v[186:189], v[36:39]
	v_mfma_f32_16x16x32_bf16 v[20:23], v[210:213], v[194:197], v[20:23]
	v_mfma_f32_16x16x32_bf16 v[16:19], v[222:225], v[194:197], v[16:19]
	v_mfma_f32_16x16x32_bf16 v[0:3], v[222:225], v[202:205], v[0:3]
	v_mfma_f32_16x16x32_bf16 v[4:7], v[210:213], v[202:205], v[4:7]
	s_setprio 0
	s_add_i32 s65, 16, 0x18000
	v_add_u32_e32 v140, s65, v173
	s_barrier
	ds_read_b128 v[128:131], v140
	ds_read_b128 v[132:135], v140 offset:1024
	ds_read_b128 v[136:139], v140 offset:2048
	ds_read_b128 v[140:143], v140 offset:3072
	s_add_u32 s2, s44, 0x80000
	s_addc_u32 s3, s45, 0
	s_mov_b32 m0, s31
	v_lshl_add_u64 v[206:207], s[2:3], 0, v[150:151]
	ds_read_b128 v[166:169], v176 offset:32768
	ds_read_b128 v[178:181], v176 offset:33792
	ds_read_b128 v[182:185], v176 offset:34816
	ds_read_b128 v[186:189], v176 offset:35840
	ds_read_b128 v[190:193], v176 offset:36864
	ds_read_b128 v[194:197], v176 offset:37888
	ds_read_b128 v[198:201], v176 offset:38912
	ds_read_b128 v[202:205], v176 offset:39936
	global_load_lds_dwordx4 v[206:207], off
	v_lshl_add_u64 v[206:207], s[2:3], 0, v[146:147]
	s_mov_b32 m0, s43
	s_nop 0
	global_load_lds_dwordx4 v[206:207], off
	s_waitcnt lgkmcnt(8)
	s_barrier
	s_waitcnt lgkmcnt(0)
	s_setprio 1
	s_waitcnt lgkmcnt(0)
	v_mfma_f32_16x16x32_bf16 v[124:127], v[128:131], v[166:169], v[124:127]
	v_mfma_f32_16x16x32_bf16 v[120:123], v[136:139], v[166:169], v[120:123]
	v_mfma_f32_16x16x32_bf16 v[104:107], v[136:139], v[182:185], v[104:107]
	v_mfma_f32_16x16x32_bf16 v[108:111], v[128:131], v[182:185], v[108:111]
	v_mfma_f32_16x16x32_bf16 v[92:95], v[128:131], v[190:193], v[92:95]
	v_mfma_f32_16x16x32_bf16 v[88:91], v[136:139], v[190:193], v[88:91]
	v_mfma_f32_16x16x32_bf16 v[72:75], v[136:139], v[198:201], v[72:75]
	v_mfma_f32_16x16x32_bf16 v[76:79], v[128:131], v[198:201], v[76:79]
	v_mfma_f32_16x16x32_bf16 v[124:127], v[132:135], v[178:181], v[124:127]
	v_mfma_f32_16x16x32_bf16 v[120:123], v[140:143], v[178:181], v[120:123]
	v_mfma_f32_16x16x32_bf16 v[104:107], v[140:143], v[186:189], v[104:107]
	v_mfma_f32_16x16x32_bf16 v[108:111], v[132:135], v[186:189], v[108:111]
	v_mfma_f32_16x16x32_bf16 v[92:95], v[132:135], v[194:197], v[92:95]
	v_mfma_f32_16x16x32_bf16 v[88:91], v[140:143], v[194:197], v[88:91]
	v_mfma_f32_16x16x32_bf16 v[72:75], v[140:143], v[202:205], v[72:75]
	v_mfma_f32_16x16x32_bf16 v[76:79], v[132:135], v[202:205], v[76:79]
	s_setprio 0
	s_barrier
	s_add_i32 s44, 16, 0x1c000
	s_add_i32 s2, s65, s26
	v_add_u32_e32 v152, s44, v173
	v_lshl_add_u64 v[170:171], v[170:171], 0, s[4:5]
	s_mov_b32 m0, s2
	ds_read_b128 v[206:209], v152
	ds_read_b128 v[210:213], v152 offset:1024
	ds_read_b128 v[218:221], v152 offset:2048
	ds_read_b128 v[222:225], v152 offset:3072
	global_load_lds_dwordx4 v[170:171], off
	v_lshl_add_u64 v[170:171], v[226:227], 0, s[4:5]
	s_add_i32 m0, s2, 0x2000
	s_nop 0
	global_load_lds_dwordx4 v[170:171], off
	s_barrier
; #define PG8_STAGE(bufoff, gbase, voff) do { _Pragma("unroll") for (int _i = 0; _i < 2; ++_i) \
;         __builtin_amdgcn_global_load_lds((const unsigned*)((const char*)(gbase) + (voff)[_i]), (LAS unsigned*)(lds + (bufoff) + ldsw + _i * 8192), 16, 0, 0); } while (0)
; #define PG8_LDA(dst, b, h) do { _Pragma("unroll") for (int m = 0; m < 4; ++m) _Pragma("unroll") for (int k = 0; k < 2; ++k) dst[m][k] = *(const LAS bf16x8*)(lds + PG8_SA(b, h) + aoff + m * 2048 + k * 1024); } while (0)
; #define PG8_MMA(ai, bj, At, Bt) do { __builtin_amdgcn_s_setprio(1); _Pragma("unroll") for (int m = 0; m < 4; ++m) _Pragma("unroll") for (int n = 0; n < 2; ++n) _Pragma("unroll") for (int k = 0; k < 2; ++k) \
;         acc[ai][bj][m][n] = __builtin_amdgcn_mfma_f32_16x16x32_bf16(Bt[n][k], At[m][k], acc[ai][bj][m][n], 0, 0, 0); __builtin_amdgcn_s_setprio(0); } while (0)
; #define PG8_WAIT_V(n) asm volatile("s_waitcnt vmcnt(" #n ")" ::: "memory")
; #define PG8_WAIT_L(n) asm volatile("s_waitcnt lgkmcnt(" #n ")" ::: "memory")
; #define PG8_BAR __builtin_amdgcn_s_barrier()
; #define PG8_SCHED __builtin_amdgcn_sched_barrier(0)
; template <class Epi>
; DEVINL void gemm_phase(LAS unsigned char* lds, const Gemm g, const Order& S, const Epi& E) {
;     ...
;             PG8_BAR; PG8_WAIT_L(0); PG8_MMA(0, 1, At, B1); PG8_BAR;
;             PG8_LDA(At, 1, 1); PG8_STAGE(PG8_SA(1, 0), a3, voffA);
;             PG8_BAR; PG8_WAIT_L(0); PG8_MMA(1, 0, At, B0); PG8_BAR; PG8_SCHED;
;             PG8_STAGE(PG8_SB(1, 1), b3 + hstepB, voffB);
;             PG8_WAIT_V(6); PG8_BAR; PG8_MMA(1, 1, At, B1); PG8_BAR;
;         }
	s_waitcnt lgkmcnt(0)
	s_setprio 1
	s_waitcnt lgkmcnt(0)
	v_mfma_f32_16x16x32_bf16 v[116:119], v[206:209], v[166:169], v[116:119]
	v_mfma_f32_16x16x32_bf16 v[112:115], v[218:221], v[166:169], v[112:115]
	v_mfma_f32_16x16x32_bf16 v[96:99], v[218:221], v[182:185], v[96:99]
	v_mfma_f32_16x16x32_bf16 v[100:103], v[206:209], v[182:185], v[100:103]
	v_mfma_f32_16x16x32_bf16 v[84:87], v[206:209], v[190:193], v[84:87]
	v_mfma_f32_16x16x32_bf16 v[80:83], v[218:221], v[190:193], v[80:83]
	v_mfma_f32_16x16x32_bf16 v[64:67], v[218:221], v[198:201], v[64:67]
	v_mfma_f32_16x16x32_bf16 v[68:71], v[206:209], v[198:201], v[68:71]
	v_mfma_f32_16x16x32_bf16 v[116:119], v[210:213], v[178:181], v[116:119]
	v_mfma_f32_16x16x32_bf16 v[112:115], v[222:225], v[178:181], v[112:115]
	v_mfma_f32_16x16x32_bf16 v[96:99], v[222:225], v[186:189], v[96:99]
	v_mfma_f32_16x16x32_bf16 v[100:103], v[210:213], v[186:189], v[100:103]
	v_mfma_f32_16x16x32_bf16 v[84:87], v[210:213], v[194:197], v[84:87]
	v_mfma_f32_16x16x32_bf16 v[80:83], v[222:225], v[194:197], v[80:83]
	v_mfma_f32_16x16x32_bf16 v[64:67], v[222:225], v[202:205], v[64:67]
	v_mfma_f32_16x16x32_bf16 v[68:71], v[210:213], v[202:205], v[68:71]
	s_setprio 0
	s_mov_b32 m0, s47
	v_lshl_add_u64 v[170:171], v[228:229], 0, s[4:5]
	s_barrier
	ds_read_b128 v[166:169], v176 offset:49152
	ds_read_b128 v[178:181], v176 offset:50176
	ds_read_b128 v[182:185], v176 offset:51200
	ds_read_b128 v[186:189], v176 offset:52224
	ds_read_b128 v[190:193], v176 offset:53248
	ds_read_b128 v[194:197], v176 offset:54272
	ds_read_b128 v[198:201], v176 offset:55296
	ds_read_b128 v[202:205], v176 offset:56320
	global_load_lds_dwordx4 v[170:171], off
	v_lshl_add_u64 v[170:171], v[230:231], 0, s[4:5]
	s_mov_b32 m0, s48
	s_nop 0
	global_load_lds_dwordx4 v[170:171], off
	s_barrier
	s_waitcnt lgkmcnt(0)
	s_setprio 1
	s_waitcnt lgkmcnt(0)
	v_mfma_f32_16x16x32_bf16 v[60:63], v[128:131], v[166:169], v[60:63]
	v_mfma_f32_16x16x32_bf16 v[56:59], v[136:139], v[166:169], v[56:59]
	v_mfma_f32_16x16x32_bf16 v[40:43], v[136:139], v[182:185], v[40:43]
	v_mfma_f32_16x16x32_bf16 v[44:47], v[128:131], v[182:185], v[44:47]
	v_mfma_f32_16x16x32_bf16 v[28:31], v[128:131], v[190:193], v[28:31]
	v_mfma_f32_16x16x32_bf16 v[24:27], v[136:139], v[190:193], v[24:27]
	v_mfma_f32_16x16x32_bf16 v[8:11], v[136:139], v[198:201], v[8:11]
	v_mfma_f32_16x16x32_bf16 v[12:15], v[128:131], v[198:201], v[12:15]
	v_mfma_f32_16x16x32_bf16 v[60:63], v[132:135], v[178:181], v[60:63]
	v_mfma_f32_16x16x32_bf16 v[56:59], v[140:143], v[178:181], v[56:59]
	v_mfma_f32_16x16x32_bf16 v[40:43], v[140:143], v[186:189], v[40:43]
	v_mfma_f32_16x16x32_bf16 v[44:47], v[132:135], v[186:189], v[44:47]
	v_mfma_f32_16x16x32_bf16 v[28:31], v[132:135], v[194:197], v[28:31]
	v_mfma_f32_16x16x32_bf16 v[24:27], v[140:143], v[194:197], v[24:27]
	v_mfma_f32_16x16x32_bf16 v[8:11], v[140:143], v[202:205], v[8:11]
	v_mfma_f32_16x16x32_bf16 v[12:15], v[132:135], v[202:205], v[12:15]
	s_setprio 0
	s_barrier
	s_add_u32 s2, s14, 0x80080
	s_addc_u32 s3, s15, 0
	s_add_i32 s14, s44, s26
	v_lshl_add_u64 v[128:129], s[2:3], 0, v[148:149]
	s_mov_b32 m0, s14
	s_nop 0
	global_load_lds_dwordx4 v[128:129], off
	v_lshl_add_u64 v[128:129], s[2:3], 0, v[144:145]
	s_add_i32 m0, s14, 0x2000
	s_nop 0
	global_load_lds_dwordx4 v[128:129], off
	s_waitcnt vmcnt(6)
	s_barrier
	s_setprio 1
	v_mfma_f32_16x16x32_bf16 v[52:55], v[206:209], v[166:169], v[52:55]
	v_mfma_f32_16x16x32_bf16 v[48:51], v[218:221], v[166:169], v[48:51]
	v_mfma_f32_16x16x32_bf16 v[32:35], v[218:221], v[182:185], v[32:35]
	v_mfma_f32_16x16x32_bf16 v[36:39], v[206:209], v[182:185], v[36:39]
	v_mfma_f32_16x16x32_bf16 v[20:23], v[206:209], v[190:193], v[20:23]
	v_mfma_f32_16x16x32_bf16 v[16:19], v[218:221], v[190:193], v[16:19]
	v_mfma_f32_16x16x32_bf16 v[0:3], v[218:221], v[198:201], v[0:3]
	v_mfma_f32_16x16x32_bf16 v[4:7], v[206:209], v[198:201], v[4:7]
	v_mfma_f32_16x16x32_bf16 v[52:55], v[210:213], v[178:181], v[52:55]
	v_mfma_f32_16x16x32_bf16 v[48:51], v[222:225], v[178:181], v[48:51]
	v_mfma_f32_16x16x32_bf16 v[32:35], v[222:225], v[186:189], v[32:35]
	v_mfma_f32_16x16x32_bf16 v[36:39], v[210:213], v[186:189], v[36:39]
	v_mfma_f32_16x16x32_bf16 v[20:23], v[210:213], v[194:197], v[20:23]
	v_mfma_f32_16x16x32_bf16 v[16:19], v[222:225], v[194:197], v[16:19]
	v_mfma_f32_16x16x32_bf16 v[0:3], v[222:225], v[202:205], v[0:3]
	v_mfma_f32_16x16x32_bf16 v[4:7], v[210:213], v[202:205], v[4:7]
	s_setprio 0
	s_add_u32 s12, s12, 0x100
	s_addc_u32 s13, s13, 0
	s_add_u32 s58, s58, 0x100
	s_addc_u32 s59, s59, 0
	s_cmp_ge_i32 s64, s46
	s_mov_b32 s14, s64
	s_barrier
	s_cbranch_scc0 .LBB0_650

; #define PG8_STAGE(bufoff, gbase, voff) do { _Pragma("unroll") for (int _i = 0; _i < 2; ++_i) \
;         __builtin_amdgcn_global_load_lds((const unsigned*)((const char*)(gbase) + (voff)[_i]), (LAS unsigned*)(lds + (bufoff) + ldsw + _i * 8192), 16, 0, 0); } while (0)
; #define PG8_LDA(dst, b, h) do { _Pragma("unroll") for (int m = 0; m < 4; ++m) _Pragma("unroll") for (int k = 0; k < 2; ++k) dst[m][k] = *(const LAS bf16x8*)(lds + PG8_SA(b, h) + aoff + m * 2048 + k * 1024); } while (0)
; #define PG8_LDB(dst, b, h) do { _Pragma("unroll") for (int n = 0; n < 2; ++n) _Pragma("unroll") for (int k = 0; k < 2; ++k) dst[n][k] = *(const LAS bf16x8*)(lds + PG8_SB(b, h) + boff + n * 2048 + k * 1024); } while (0)
; #define PG8_MMA(ai, bj, At, Bt) do { __builtin_amdgcn_s_setprio(1); _Pragma("unroll") for (int m = 0; m < 4; ++m) _Pragma("unroll") for (int n = 0; n < 2; ++n) _Pragma("unroll") for (int k = 0; k < 2; ++k) \
;         acc[ai][bj][m][n] = __builtin_amdgcn_mfma_f32_16x16x32_bf16(Bt[n][k], At[m][k], acc[ai][bj][m][n], 0, 0, 0); __builtin_amdgcn_s_setprio(0); } while (0)
; #define PG8_WAIT_L(n) asm volatile("s_waitcnt lgkmcnt(" #n ")" ::: "memory")
; #define PG8_BAR __builtin_amdgcn_s_barrier()
; #define PG8_SCHED __builtin_amdgcn_sched_barrier(0)
; template <class Epi>
; DEVINL void gemm_phase(LAS unsigned char* lds, const Gemm g, const Order& S, const Epi& E) {
;     ...
;             PG8_LDB(B0, 0, 0); PG8_SCHED; PG8_LDA(At, 0, 0); PG8_STAGE(PG8_SA(1, 1), a1 + hstepA, voffA);
;             PG8_WAIT_L(8); PG8_BAR; PG8_WAIT_L(0); PG8_MMA(0, 0, At, B0); PG8_BAR; PG8_SCHED;
;             PG8_LDB(B1, 0, 1); PG8_STAGE(PG8_SB(0, 0), b2, voffB);
;             PG8_BAR; PG8_WAIT_L(0); PG8_MMA(0, 1, At, B1); PG8_BAR;
;             PG8_LDA(At, 0, 1); PG8_STAGE(PG8_SA(0, 0), a2, voffA);
;             PG8_BAR; PG8_WAIT_L(0); PG8_MMA(1, 0, At, B0); PG8_BAR; PG8_SCHED;
.LBB0_802:
	ds_read_b128 v[150:153], v147
	ds_read_b128 v[154:157], v147 offset:1024
	ds_read_b128 v[158:161], v147 offset:2048
	ds_read_b128 v[162:165], v147 offset:3072
	s_add_i32 s65, s38, 2
	s_add_u32 s4, s16, 0x100
	s_addc_u32 s5, s17, 0
	s_cmp_eq_u32 s49, s38
	s_cselect_b32 s38, s58, s59
	s_cselect_b32 s41, s13, s5
	s_cselect_b32 s40, s12, s4
	s_cselect_b32 s39, s11, s64
	v_lshl_add_u64 v[198:199], s[16:17], 0, v[136:137]
	s_add_i32 m0, s31, 0xc000
	ds_read_b128 v[166:169], v148
	ds_read_b128 v[170:173], v148 offset:1024
	ds_read_b128 v[174:177], v148 offset:2048
	ds_read_b128 v[178:181], v148 offset:3072
	ds_read_b128 v[182:185], v148 offset:4096
	ds_read_b128 v[186:189], v148 offset:5120
	ds_read_b128 v[190:193], v148 offset:6144
	ds_read_b128 v[194:197], v148 offset:7168
	global_load_lds_dwordx4 v[198:199], off
	v_lshl_add_u64 v[198:199], s[16:17], 0, v[138:139]
	s_add_i32 m0, s31, 0xe000
	s_nop 0
	global_load_lds_dwordx4 v[198:199], off
	s_waitcnt lgkmcnt(8)
	s_barrier
	s_waitcnt lgkmcnt(0)
	s_setprio 1
	s_waitcnt lgkmcnt(0)
	v_mfma_f32_16x16x32_bf16 v[120:123], v[150:153], v[166:169], v[120:123]
	v_mfma_f32_16x16x32_bf16 v[124:127], v[158:161], v[166:169], v[124:127]
	v_mfma_f32_16x16x32_bf16 v[104:107], v[158:161], v[174:177], v[104:107]
	v_mfma_f32_16x16x32_bf16 v[108:111], v[150:153], v[174:177], v[108:111]
	v_mfma_f32_16x16x32_bf16 v[92:95], v[150:153], v[182:185], v[92:95]
	v_mfma_f32_16x16x32_bf16 v[88:91], v[158:161], v[182:185], v[88:91]
	v_mfma_f32_16x16x32_bf16 v[72:75], v[158:161], v[190:193], v[72:75]
	v_mfma_f32_16x16x32_bf16 v[76:79], v[150:153], v[190:193], v[76:79]
	v_mfma_f32_16x16x32_bf16 v[120:123], v[154:157], v[170:173], v[120:123]
	v_mfma_f32_16x16x32_bf16 v[124:127], v[162:165], v[170:173], v[124:127]
	v_mfma_f32_16x16x32_bf16 v[104:107], v[162:165], v[178:181], v[104:107]
	v_mfma_f32_16x16x32_bf16 v[108:111], v[154:157], v[178:181], v[108:111]
	v_mfma_f32_16x16x32_bf16 v[92:95], v[154:157], v[186:189], v[92:95]
	v_mfma_f32_16x16x32_bf16 v[88:91], v[162:165], v[186:189], v[88:91]
	v_mfma_f32_16x16x32_bf16 v[72:75], v[162:165], v[194:197], v[72:75]
	v_mfma_f32_16x16x32_bf16 v[76:79], v[154:157], v[194:197], v[76:79]
	s_setprio 0
	s_barrier
	s_add_i32 s2, s52, s28
	v_lshl_add_u64 v[218:219], s[38:39], 0, v[132:133]
	s_mov_b32 m0, s2
	ds_read_b128 v[198:201], v149
	ds_read_b128 v[202:205], v149 offset:1024
	ds_read_b128 v[206:209], v149 offset:2048
	ds_read_b128 v[210:213], v149 offset:3072
	global_load_lds_dwordx4 v[218:219], off
	v_lshl_add_u64 v[220:221], s[38:39], 0, v[128:129]
	s_add_i32 m0, s2, 0x2000
	s_nop 0
	global_load_lds_dwordx4 v[220:221], off
	s_barrier
	s_waitcnt lgkmcnt(0)
	s_setprio 1
	s_waitcnt lgkmcnt(0)
	v_mfma_f32_16x16x32_bf16 v[116:119], v[198:201], v[166:169], v[116:119]
	v_mfma_f32_16x16x32_bf16 v[112:115], v[206:209], v[166:169], v[112:115]
	v_mfma_f32_16x16x32_bf16 v[96:99], v[206:209], v[174:177], v[96:99]
	v_mfma_f32_16x16x32_bf16 v[100:103], v[198:201], v[174:177], v[100:103]
	v_mfma_f32_16x16x32_bf16 v[84:87], v[198:201], v[182:185], v[84:87]
	v_mfma_f32_16x16x32_bf16 v[80:83], v[206:209], v[182:185], v[80:83]
	v_mfma_f32_16x16x32_bf16 v[64:67], v[206:209], v[190:193], v[64:67]
	v_mfma_f32_16x16x32_bf16 v[68:71], v[198:201], v[190:193], v[68:71]
	v_mfma_f32_16x16x32_bf16 v[116:119], v[202:205], v[170:173], v[116:119]
	v_mfma_f32_16x16x32_bf16 v[112:115], v[210:213], v[170:173], v[112:115]
	v_mfma_f32_16x16x32_bf16 v[96:99], v[210:213], v[178:181], v[96:99]
	v_mfma_f32_16x16x32_bf16 v[100:103], v[202:205], v[178:181], v[100:103]
	v_mfma_f32_16x16x32_bf16 v[84:87], v[202:205], v[186:189], v[84:87]
	v_mfma_f32_16x16x32_bf16 v[80:83], v[210:213], v[186:189], v[80:83]
	v_mfma_f32_16x16x32_bf16 v[64:67], v[210:213], v[194:197], v[64:67]
	v_mfma_f32_16x16x32_bf16 v[68:71], v[202:205], v[194:197], v[68:71]
	s_setprio 0
	s_mov_b32 m0, s31
	v_lshl_add_u64 v[222:223], s[40:41], 0, v[134:135]
	s_barrier
	ds_read_b128 v[166:169], v148 offset:16384
	ds_read_b128 v[170:173], v148 offset:17408
	ds_read_b128 v[174:177], v148 offset:18432
	ds_read_b128 v[178:181], v148 offset:19456
	ds_read_b128 v[182:185], v148 offset:20480
	ds_read_b128 v[186:189], v148 offset:21504
	ds_read_b128 v[190:193], v148 offset:22528
	ds_read_b128 v[194:197], v148 offset:23552
	global_load_lds_dwordx4 v[222:223], off
	v_lshl_add_u64 v[224:225], s[40:41], 0, v[130:131]
	s_mov_b32 m0, s42
	s_nop 0
	global_load_lds_dwordx4 v[224:225], off
	s_barrier
	s_waitcnt lgkmcnt(0)
	s_setprio 1
	s_waitcnt lgkmcnt(0)
	v_mfma_f32_16x16x32_bf16 v[60:63], v[150:153], v[166:169], v[60:63]
	v_mfma_f32_16x16x32_bf16 v[56:59], v[158:161], v[166:169], v[56:59]
	v_mfma_f32_16x16x32_bf16 v[40:43], v[158:161], v[174:177], v[40:43]
	v_mfma_f32_16x16x32_bf16 v[44:47], v[150:153], v[174:177], v[44:47]
	v_mfma_f32_16x16x32_bf16 v[28:31], v[150:153], v[182:185], v[28:31]
	v_mfma_f32_16x16x32_bf16 v[24:27], v[158:161], v[182:185], v[24:27]
	v_mfma_f32_16x16x32_bf16 v[8:11], v[158:161], v[190:193], v[8:11]
	v_mfma_f32_16x16x32_bf16 v[12:15], v[150:153], v[190:193], v[12:15]
	v_mfma_f32_16x16x32_bf16 v[60:63], v[154:157], v[170:173], v[60:63]
	v_mfma_f32_16x16x32_bf16 v[56:59], v[162:165], v[170:173], v[56:59]
	v_mfma_f32_16x16x32_bf16 v[40:43], v[162:165], v[178:181], v[40:43]
	v_mfma_f32_16x16x32_bf16 v[44:47], v[154:157], v[178:181], v[44:47]
	v_mfma_f32_16x16x32_bf16 v[28:31], v[154:157], v[186:189], v[28:31]
	v_mfma_f32_16x16x32_bf16 v[24:27], v[162:165], v[186:189], v[24:27]
	v_mfma_f32_16x16x32_bf16 v[8:11], v[162:165], v[194:197], v[8:11]
	v_mfma_f32_16x16x32_bf16 v[12:15], v[154:157], v[194:197], v[12:15]
	s_setprio 0
	s_barrier
; #define PG8_STAGE(bufoff, gbase, voff) do { _Pragma("unroll") for (int _i = 0; _i < 2; ++_i) \
;         __builtin_amdgcn_global_load_lds((const unsigned*)((const char*)(gbase) + (voff)[_i]), (LAS unsigned*)(lds + (bufoff) + ldsw + _i * 8192), 16, 0, 0); } while (0)
; #define PG8_LDA(dst, b, h) do { _Pragma("unroll") for (int m = 0; m < 4; ++m) _Pragma("unroll") for (int k = 0; k < 2; ++k) dst[m][k] = *(const LAS bf16x8*)(lds + PG8_SA(b, h) + aoff + m * 2048 + k * 1024); } while (0)
; #define PG8_LDB(dst, b, h) do { _Pragma("unroll") for (int n = 0; n < 2; ++n) _Pragma("unroll") for (int k = 0; k < 2; ++k) dst[n][k] = *(const LAS bf16x8*)(lds + PG8_SB(b, h) + boff + n * 2048 + k * 1024); } while (0)
; #define PG8_MMA(ai, bj, At, Bt) do { __builtin_amdgcn_s_setprio(1); _Pragma("unroll") for (int m = 0; m < 4; ++m) _Pragma("unroll") for (int n = 0; n < 2; ++n) _Pragma("unroll") for (int k = 0; k < 2; ++k) \
;         acc[ai][bj][m][n] = __builtin_amdgcn_mfma_f32_16x16x32_bf16(Bt[n][k], At[m][k], acc[ai][bj][m][n], 0, 0, 0); __builtin_amdgcn_s_setprio(0); } while (0)
; #define PG8_WAIT_V(n) asm volatile("s_waitcnt vmcnt(" #n ")" ::: "memory")
; #define PG8_WAIT_L(n) asm volatile("s_waitcnt lgkmcnt(" #n ")" ::: "memory")
; #define PG8_BAR __builtin_amdgcn_s_barrier()
; #define PG8_SCHED __builtin_amdgcn_sched_barrier(0)
; template <class Epi>
; DEVINL void gemm_phase(LAS unsigned char* lds, const Gemm g, const Order& S, const Epi& E) {
;     ...
;             PG8_STAGE(PG8_SB(0, 1), b2 + hstepB, voffB);
;             PG8_WAIT_V(6); PG8_BAR; PG8_MMA(1, 1, At, B1); PG8_BAR;
;             PG8_LDB(B0, 1, 0); PG8_SCHED; PG8_LDA(At, 1, 0); PG8_STAGE(PG8_SA(0, 1), a2 + hstepA, voffA);
;             PG8_WAIT_L(8); PG8_BAR; PG8_WAIT_L(0); PG8_MMA(0, 0, At, B0); PG8_BAR; PG8_SCHED;
;             PG8_LDB(B1, 1, 1); PG8_STAGE(PG8_SB(1, 0), b3, voffB);
	s_add_u32 s2, s38, 0x20000
	s_addc_u32 s3, s39, 0
	s_add_i32 s16, s53, s28
	v_lshl_add_u64 v[150:151], s[2:3], 0, v[132:133]
	s_mov_b32 m0, s16
	s_nop 0
	global_load_lds_dwordx4 v[150:151], off
	v_lshl_add_u64 v[150:151], s[2:3], 0, v[128:129]
	s_add_i32 m0, s16, 0x2000
	s_nop 0
	global_load_lds_dwordx4 v[150:151], off
	s_waitcnt vmcnt(6)
	s_barrier
	s_setprio 1
	v_mfma_f32_16x16x32_bf16 v[52:55], v[198:201], v[166:169], v[52:55]
	v_mfma_f32_16x16x32_bf16 v[48:51], v[206:209], v[166:169], v[48:51]
	v_mfma_f32_16x16x32_bf16 v[32:35], v[206:209], v[174:177], v[32:35]
	v_mfma_f32_16x16x32_bf16 v[36:39], v[198:201], v[174:177], v[36:39]
	v_mfma_f32_16x16x32_bf16 v[20:23], v[198:201], v[182:185], v[20:23]
	v_mfma_f32_16x16x32_bf16 v[16:19], v[206:209], v[182:185], v[16:19]
	v_mfma_f32_16x16x32_bf16 v[0:3], v[206:209], v[190:193], v[0:3]
	v_mfma_f32_16x16x32_bf16 v[4:7], v[198:201], v[190:193], v[4:7]
	v_mfma_f32_16x16x32_bf16 v[52:55], v[202:205], v[170:173], v[52:55]
	v_mfma_f32_16x16x32_bf16 v[48:51], v[210:213], v[170:173], v[48:51]
	v_mfma_f32_16x16x32_bf16 v[32:35], v[210:213], v[178:181], v[32:35]
	v_mfma_f32_16x16x32_bf16 v[36:39], v[202:205], v[178:181], v[36:39]
	v_mfma_f32_16x16x32_bf16 v[20:23], v[202:205], v[186:189], v[20:23]
	v_mfma_f32_16x16x32_bf16 v[16:19], v[210:213], v[186:189], v[16:19]
	v_mfma_f32_16x16x32_bf16 v[0:3], v[210:213], v[194:197], v[0:3]
	v_mfma_f32_16x16x32_bf16 v[4:7], v[202:205], v[194:197], v[4:7]
	s_setprio 0
	s_add_i32 s16, 16, 0x18000
	v_add_u32_e32 v162, s16, v145
	s_barrier
	ds_read_b128 v[150:153], v162
	ds_read_b128 v[154:157], v162 offset:1024
	ds_read_b128 v[158:161], v162 offset:2048
	ds_read_b128 v[162:165], v162 offset:3072
	s_add_u32 s2, s40, 0x30000
	s_addc_u32 s3, s41, 0
	s_mov_b32 m0, s43
	v_lshl_add_u64 v[198:199], s[2:3], 0, v[134:135]
	ds_read_b128 v[166:169], v148 offset:32768
	ds_read_b128 v[170:173], v148 offset:33792
	ds_read_b128 v[174:177], v148 offset:34816
	ds_read_b128 v[178:181], v148 offset:35840
	ds_read_b128 v[182:185], v148 offset:36864
	ds_read_b128 v[186:189], v148 offset:37888
	ds_read_b128 v[190:193], v148 offset:38912
	ds_read_b128 v[194:197], v148 offset:39936
	global_load_lds_dwordx4 v[198:199], off
	v_lshl_add_u64 v[198:199], s[2:3], 0, v[130:131]
	s_mov_b32 m0, s44
	s_nop 0
	global_load_lds_dwordx4 v[198:199], off
	s_waitcnt lgkmcnt(8)
	s_barrier
	s_waitcnt lgkmcnt(0)
	s_setprio 1
	s_waitcnt lgkmcnt(0)
	v_mfma_f32_16x16x32_bf16 v[120:123], v[150:153], v[166:169], v[120:123]
	v_mfma_f32_16x16x32_bf16 v[124:127], v[158:161], v[166:169], v[124:127]
	v_mfma_f32_16x16x32_bf16 v[104:107], v[158:161], v[174:177], v[104:107]
	v_mfma_f32_16x16x32_bf16 v[108:111], v[150:153], v[174:177], v[108:111]
	v_mfma_f32_16x16x32_bf16 v[92:95], v[150:153], v[182:185], v[92:95]
	v_mfma_f32_16x16x32_bf16 v[88:91], v[158:161], v[182:185], v[88:91]
	v_mfma_f32_16x16x32_bf16 v[72:75], v[158:161], v[190:193], v[72:75]
	v_mfma_f32_16x16x32_bf16 v[76:79], v[150:153], v[190:193], v[76:79]
	v_mfma_f32_16x16x32_bf16 v[120:123], v[154:157], v[170:173], v[120:123]
	v_mfma_f32_16x16x32_bf16 v[124:127], v[162:165], v[170:173], v[124:127]
	v_mfma_f32_16x16x32_bf16 v[104:107], v[162:165], v[178:181], v[104:107]
	v_mfma_f32_16x16x32_bf16 v[108:111], v[154:157], v[178:181], v[108:111]
	v_mfma_f32_16x16x32_bf16 v[92:95], v[154:157], v[186:189], v[92:95]
	v_mfma_f32_16x16x32_bf16 v[88:91], v[162:165], v[186:189], v[88:91]
	v_mfma_f32_16x16x32_bf16 v[72:75], v[162:165], v[194:197], v[72:75]
	v_mfma_f32_16x16x32_bf16 v[76:79], v[154:157], v[194:197], v[76:79]
	s_setprio 0
	s_barrier
	s_add_i32 s17, 16, 0x1c000
	s_add_i32 s2, s16, s28
	v_add_u32_e32 v210, s17, v145
	v_lshl_add_u64 v[218:219], v[218:219], 0, s[6:7]
	s_mov_b32 m0, s2
	ds_read_b128 v[198:201], v210
	ds_read_b128 v[202:205], v210 offset:1024
	ds_read_b128 v[206:209], v210 offset:2048
	ds_read_b128 v[210:213], v210 offset:3072
	global_load_lds_dwordx4 v[218:219], off
	v_lshl_add_u64 v[218:219], v[220:221], 0, s[6:7]
	s_add_i32 m0, s2, 0x2000
	s_nop 0
	global_load_lds_dwordx4 v[218:219], off
	s_barrier
; #define PG8_STAGE(bufoff, gbase, voff) do { _Pragma("unroll") for (int _i = 0; _i < 2; ++_i) \
;         __builtin_amdgcn_global_load_lds((const unsigned*)((const char*)(gbase) + (voff)[_i]), (LAS unsigned*)(lds + (bufoff) + ldsw + _i * 8192), 16, 0, 0); } while (0)
; #define PG8_LDA(dst, b, h) do { _Pragma("unroll") for (int m = 0; m < 4; ++m) _Pragma("unroll") for (int k = 0; k < 2; ++k) dst[m][k] = *(const LAS bf16x8*)(lds + PG8_SA(b, h) + aoff + m * 2048 + k * 1024); } while (0)
; #define PG8_MMA(ai, bj, At, Bt) do { __builtin_amdgcn_s_setprio(1); _Pragma("unroll") for (int m = 0; m < 4; ++m) _Pragma("unroll") for (int n = 0; n < 2; ++n) _Pragma("unroll") for (int k = 0; k < 2; ++k) \
;         acc[ai][bj][m][n] = __builtin_amdgcn_mfma_f32_16x16x32_bf16(Bt[n][k], At[m][k], acc[ai][bj][m][n], 0, 0, 0); __builtin_amdgcn_s_setprio(0); } while (0)
; #define PG8_WAIT_V(n) asm volatile("s_waitcnt vmcnt(" #n ")" ::: "memory")
; #define PG8_WAIT_L(n) asm volatile("s_waitcnt lgkmcnt(" #n ")" ::: "memory")
; #define PG8_BAR __builtin_amdgcn_s_barrier()
; #define PG8_SCHED __builtin_amdgcn_sched_barrier(0)
; template <class Epi>
; DEVINL void gemm_phase(LAS unsigned char* lds, const Gemm g, const Order& S, const Epi& E) {
;     ...
;             PG8_BAR; PG8_WAIT_L(0); PG8_MMA(0, 1, At, B1); PG8_BAR;
;             PG8_LDA(At, 1, 1); PG8_STAGE(PG8_SA(1, 0), a3, voffA);
;             PG8_BAR; PG8_WAIT_L(0); PG8_MMA(1, 0, At, B0); PG8_BAR; PG8_SCHED;
;             PG8_STAGE(PG8_SB(1, 1), b3 + hstepB, voffB);
;             PG8_WAIT_V(6); PG8_BAR; PG8_MMA(1, 1, At, B1); PG8_BAR;
;         }
	s_waitcnt lgkmcnt(0)
	s_setprio 1
	s_waitcnt lgkmcnt(0)
	v_mfma_f32_16x16x32_bf16 v[116:119], v[198:201], v[166:169], v[116:119]
	v_mfma_f32_16x16x32_bf16 v[112:115], v[206:209], v[166:169], v[112:115]
	v_mfma_f32_16x16x32_bf16 v[96:99], v[206:209], v[174:177], v[96:99]
	v_mfma_f32_16x16x32_bf16 v[100:103], v[198:201], v[174:177], v[100:103]
	v_mfma_f32_16x16x32_bf16 v[84:87], v[198:201], v[182:185], v[84:87]
	v_mfma_f32_16x16x32_bf16 v[80:83], v[206:209], v[182:185], v[80:83]
	v_mfma_f32_16x16x32_bf16 v[64:67], v[206:209], v[190:193], v[64:67]
	v_mfma_f32_16x16x32_bf16 v[68:71], v[198:201], v[190:193], v[68:71]
	v_mfma_f32_16x16x32_bf16 v[116:119], v[202:205], v[170:173], v[116:119]
	v_mfma_f32_16x16x32_bf16 v[112:115], v[210:213], v[170:173], v[112:115]
	v_mfma_f32_16x16x32_bf16 v[96:99], v[210:213], v[178:181], v[96:99]
	v_mfma_f32_16x16x32_bf16 v[100:103], v[202:205], v[178:181], v[100:103]
	v_mfma_f32_16x16x32_bf16 v[84:87], v[202:205], v[186:189], v[84:87]
	v_mfma_f32_16x16x32_bf16 v[80:83], v[210:213], v[186:189], v[80:83]
	v_mfma_f32_16x16x32_bf16 v[64:67], v[210:213], v[194:197], v[64:67]
	v_mfma_f32_16x16x32_bf16 v[68:71], v[202:205], v[194:197], v[68:71]
	s_setprio 0
	s_mov_b32 m0, s47
	v_lshl_add_u64 v[218:219], v[222:223], 0, s[6:7]
	s_barrier
	ds_read_b128 v[166:169], v148 offset:49152
	ds_read_b128 v[170:173], v148 offset:50176
	ds_read_b128 v[174:177], v148 offset:51200
	ds_read_b128 v[178:181], v148 offset:52224
	ds_read_b128 v[182:185], v148 offset:53248
	ds_read_b128 v[186:189], v148 offset:54272
	ds_read_b128 v[190:193], v148 offset:55296
	ds_read_b128 v[194:197], v148 offset:56320
	global_load_lds_dwordx4 v[218:219], off
	v_lshl_add_u64 v[218:219], v[224:225], 0, s[6:7]
	s_mov_b32 m0, s48
	s_nop 0
	global_load_lds_dwordx4 v[218:219], off
	s_barrier
	s_waitcnt lgkmcnt(0)
	s_setprio 1
	s_waitcnt lgkmcnt(0)
	v_mfma_f32_16x16x32_bf16 v[60:63], v[150:153], v[166:169], v[60:63]
	v_mfma_f32_16x16x32_bf16 v[56:59], v[158:161], v[166:169], v[56:59]
	v_mfma_f32_16x16x32_bf16 v[40:43], v[158:161], v[174:177], v[40:43]
	v_mfma_f32_16x16x32_bf16 v[44:47], v[150:153], v[174:177], v[44:47]
	v_mfma_f32_16x16x32_bf16 v[28:31], v[150:153], v[182:185], v[28:31]
	v_mfma_f32_16x16x32_bf16 v[24:27], v[158:161], v[182:185], v[24:27]
	v_mfma_f32_16x16x32_bf16 v[8:11], v[158:161], v[190:193], v[8:11]
	v_mfma_f32_16x16x32_bf16 v[12:15], v[150:153], v[190:193], v[12:15]
	v_mfma_f32_16x16x32_bf16 v[60:63], v[154:157], v[170:173], v[60:63]
	v_mfma_f32_16x16x32_bf16 v[56:59], v[162:165], v[170:173], v[56:59]
	v_mfma_f32_16x16x32_bf16 v[40:43], v[162:165], v[178:181], v[40:43]
	v_mfma_f32_16x16x32_bf16 v[44:47], v[154:157], v[178:181], v[44:47]
	v_mfma_f32_16x16x32_bf16 v[28:31], v[154:157], v[186:189], v[28:31]
	v_mfma_f32_16x16x32_bf16 v[24:27], v[162:165], v[186:189], v[24:27]
	v_mfma_f32_16x16x32_bf16 v[8:11], v[162:165], v[194:197], v[8:11]
	v_mfma_f32_16x16x32_bf16 v[12:15], v[154:157], v[194:197], v[12:15]
	s_setprio 0
	s_barrier
	s_add_u32 s2, s38, 0x20080
	s_addc_u32 s3, s39, 0
	s_add_i32 s16, s17, s28
	v_lshl_add_u64 v[150:151], s[2:3], 0, v[132:133]
	s_mov_b32 m0, s16
	s_nop 0
	global_load_lds_dwordx4 v[150:151], off
	v_lshl_add_u64 v[150:151], s[2:3], 0, v[128:129]
	s_add_i32 m0, s16, 0x2000
	s_nop 0
	global_load_lds_dwordx4 v[150:151], off
	s_waitcnt vmcnt(6)
	s_barrier
	s_setprio 1
	v_mfma_f32_16x16x32_bf16 v[52:55], v[198:201], v[166:169], v[52:55]
	v_mfma_f32_16x16x32_bf16 v[48:51], v[206:209], v[166:169], v[48:51]
	v_mfma_f32_16x16x32_bf16 v[32:35], v[206:209], v[174:177], v[32:35]
	v_mfma_f32_16x16x32_bf16 v[36:39], v[198:201], v[174:177], v[36:39]
	v_mfma_f32_16x16x32_bf16 v[20:23], v[198:201], v[182:185], v[20:23]
	v_mfma_f32_16x16x32_bf16 v[16:19], v[206:209], v[182:185], v[16:19]
	v_mfma_f32_16x16x32_bf16 v[0:3], v[206:209], v[190:193], v[0:3]
	v_mfma_f32_16x16x32_bf16 v[4:7], v[198:201], v[190:193], v[4:7]
	v_mfma_f32_16x16x32_bf16 v[52:55], v[202:205], v[170:173], v[52:55]
	v_mfma_f32_16x16x32_bf16 v[48:51], v[210:213], v[170:173], v[48:51]
	v_mfma_f32_16x16x32_bf16 v[32:35], v[210:213], v[178:181], v[32:35]
	v_mfma_f32_16x16x32_bf16 v[36:39], v[202:205], v[178:181], v[36:39]
	v_mfma_f32_16x16x32_bf16 v[20:23], v[202:205], v[186:189], v[20:23]
	v_mfma_f32_16x16x32_bf16 v[16:19], v[210:213], v[186:189], v[16:19]
	v_mfma_f32_16x16x32_bf16 v[0:3], v[210:213], v[194:197], v[0:3]
	v_mfma_f32_16x16x32_bf16 v[4:7], v[202:205], v[194:197], v[4:7]
	s_setprio 0
	s_add_u32 s59, s59, 0x100
	s_addc_u32 s64, s64, 0
	s_cmp_ge_i32 s65, s46
	s_mov_b64 s[16:17], s[4:5]
	s_mov_b32 s38, s65
	s_barrier
	s_cbranch_scc0 .LBB0_802
	s_branch .LBB0_795

; #define PG8_STAGE(bufoff, gbase, voff) do { _Pragma("unroll") for (int _i = 0; _i < 2; ++_i) \
;         __builtin_amdgcn_global_load_lds((const unsigned*)((const char*)(gbase) + (voff)[_i]), (LAS unsigned*)(lds + (bufoff) + ldsw + _i * 8192), 16, 0, 0); } while (0)
; #define PG8_LDA(dst, b, h) do { _Pragma("unroll") for (int m = 0; m < 4; ++m) _Pragma("unroll") for (int k = 0; k < 2; ++k) dst[m][k] = *(const LAS bf16x8*)(lds + PG8_SA(b, h) + aoff + m * 2048 + k * 1024); } while (0)
; #define PG8_LDB(dst, b, h) do { _Pragma("unroll") for (int n = 0; n < 2; ++n) _Pragma("unroll") for (int k = 0; k < 2; ++k) dst[n][k] = *(const LAS bf16x8*)(lds + PG8_SB(b, h) + boff + n * 2048 + k * 1024); } while (0)
; #define PG8_MMA(ai, bj, At, Bt) do { __builtin_amdgcn_s_setprio(1); _Pragma("unroll") for (int m = 0; m < 4; ++m) _Pragma("unroll") for (int n = 0; n < 2; ++n) _Pragma("unroll") for (int k = 0; k < 2; ++k) \
;         acc[ai][bj][m][n] = __builtin_amdgcn_mfma_f32_16x16x32_bf16(Bt[n][k], At[m][k], acc[ai][bj][m][n], 0, 0, 0); __builtin_amdgcn_s_setprio(0); } while (0)
; #define PG8_WAIT_L(n) asm volatile("s_waitcnt lgkmcnt(" #n ")" ::: "memory")
; #define PG8_BAR __builtin_amdgcn_s_barrier()
; #define PG8_SCHED __builtin_amdgcn_sched_barrier(0)
; template <class Epi>
; DEVINL void gemm_phase(LAS unsigned char* lds, const Gemm g, const Order& S, const Epi& E) {
;     ...
;             PG8_LDB(B0, 0, 0); PG8_SCHED; PG8_LDA(At, 0, 0); PG8_STAGE(PG8_SA(1, 1), a1 + hstepA, voffA);
;             PG8_WAIT_L(8); PG8_BAR; PG8_WAIT_L(0); PG8_MMA(0, 0, At, B0); PG8_BAR; PG8_SCHED;
;             PG8_LDB(B1, 0, 1); PG8_STAGE(PG8_SB(0, 0), b2, voffB);
;             PG8_BAR; PG8_WAIT_L(0); PG8_MMA(0, 1, At, B1); PG8_BAR;
;             PG8_LDA(At, 0, 1); PG8_STAGE(PG8_SA(0, 0), a2, voffA);
;             PG8_BAR; PG8_WAIT_L(0); PG8_MMA(1, 0, At, B0); PG8_BAR; PG8_SCHED;
.LBB0_825:
	ds_read_b128 v[150:153], v147
	ds_read_b128 v[154:157], v147 offset:1024
	ds_read_b128 v[158:161], v147 offset:2048
	ds_read_b128 v[162:165], v147 offset:3072
	s_add_i32 s68, s42, 2
	s_add_u32 s4, s38, 0x100
	s_addc_u32 s5, s39, 0
	s_cmp_eq_u32 s53, s42
	s_cselect_b32 s42, s65, s66
	s_cselect_b32 s45, s15, s5
	s_cselect_b32 s44, s14, s4
	s_cselect_b32 s43, s13, s67
	v_lshl_add_u64 v[198:199], s[38:39], 0, v[136:137]
	s_add_i32 m0, s31, 0xc000
	ds_read_b128 v[166:169], v148
	ds_read_b128 v[170:173], v148 offset:1024
	ds_read_b128 v[174:177], v148 offset:2048
	ds_read_b128 v[178:181], v148 offset:3072
	ds_read_b128 v[182:185], v148 offset:4096
	ds_read_b128 v[186:189], v148 offset:5120
	ds_read_b128 v[190:193], v148 offset:6144
	ds_read_b128 v[194:197], v148 offset:7168
	global_load_lds_dwordx4 v[198:199], off
	v_lshl_add_u64 v[198:199], s[38:39], 0, v[138:139]
	s_add_i32 m0, s31, 0xe000
	s_nop 0
	global_load_lds_dwordx4 v[198:199], off
	s_waitcnt lgkmcnt(8)
	s_barrier
	s_waitcnt lgkmcnt(0)
	s_setprio 1
	s_waitcnt lgkmcnt(0)
	v_mfma_f32_16x16x32_bf16 v[120:123], v[150:153], v[166:169], v[120:123]
	v_mfma_f32_16x16x32_bf16 v[124:127], v[158:161], v[166:169], v[124:127]
	v_mfma_f32_16x16x32_bf16 v[104:107], v[158:161], v[174:177], v[104:107]
	v_mfma_f32_16x16x32_bf16 v[108:111], v[150:153], v[174:177], v[108:111]
	v_mfma_f32_16x16x32_bf16 v[92:95], v[150:153], v[182:185], v[92:95]
	v_mfma_f32_16x16x32_bf16 v[88:91], v[158:161], v[182:185], v[88:91]
	v_mfma_f32_16x16x32_bf16 v[72:75], v[158:161], v[190:193], v[72:75]
	v_mfma_f32_16x16x32_bf16 v[76:79], v[150:153], v[190:193], v[76:79]
	v_mfma_f32_16x16x32_bf16 v[120:123], v[154:157], v[170:173], v[120:123]
	v_mfma_f32_16x16x32_bf16 v[124:127], v[162:165], v[170:173], v[124:127]
	v_mfma_f32_16x16x32_bf16 v[104:107], v[162:165], v[178:181], v[104:107]
	v_mfma_f32_16x16x32_bf16 v[108:111], v[154:157], v[178:181], v[108:111]
	v_mfma_f32_16x16x32_bf16 v[92:95], v[154:157], v[186:189], v[92:95]
	v_mfma_f32_16x16x32_bf16 v[88:91], v[162:165], v[186:189], v[88:91]
	v_mfma_f32_16x16x32_bf16 v[72:75], v[162:165], v[194:197], v[72:75]
	v_mfma_f32_16x16x32_bf16 v[76:79], v[154:157], v[194:197], v[76:79]
	s_setprio 0
	s_barrier
	s_add_i32 s2, s57, s30
	v_lshl_add_u64 v[218:219], s[42:43], 0, v[130:131]
	s_mov_b32 m0, s2
	ds_read_b128 v[198:201], v149
	ds_read_b128 v[202:205], v149 offset:1024
	ds_read_b128 v[206:209], v149 offset:2048
	ds_read_b128 v[210:213], v149 offset:3072
	global_load_lds_dwordx4 v[218:219], off
	v_lshl_add_u64 v[220:221], s[42:43], 0, v[134:135]
	s_add_i32 m0, s2, 0x2000
	s_nop 0
	global_load_lds_dwordx4 v[220:221], off
	s_barrier
	s_waitcnt lgkmcnt(0)
	s_setprio 1
	s_waitcnt lgkmcnt(0)
	v_mfma_f32_16x16x32_bf16 v[116:119], v[198:201], v[166:169], v[116:119]
	v_mfma_f32_16x16x32_bf16 v[112:115], v[206:209], v[166:169], v[112:115]
	v_mfma_f32_16x16x32_bf16 v[96:99], v[206:209], v[174:177], v[96:99]
	v_mfma_f32_16x16x32_bf16 v[100:103], v[198:201], v[174:177], v[100:103]
	v_mfma_f32_16x16x32_bf16 v[84:87], v[198:201], v[182:185], v[84:87]
	v_mfma_f32_16x16x32_bf16 v[80:83], v[206:209], v[182:185], v[80:83]
	v_mfma_f32_16x16x32_bf16 v[64:67], v[206:209], v[190:193], v[64:67]
	v_mfma_f32_16x16x32_bf16 v[68:71], v[198:201], v[190:193], v[68:71]
	v_mfma_f32_16x16x32_bf16 v[116:119], v[202:205], v[170:173], v[116:119]
	v_mfma_f32_16x16x32_bf16 v[112:115], v[210:213], v[170:173], v[112:115]
	v_mfma_f32_16x16x32_bf16 v[96:99], v[210:213], v[178:181], v[96:99]
	v_mfma_f32_16x16x32_bf16 v[100:103], v[202:205], v[178:181], v[100:103]
	v_mfma_f32_16x16x32_bf16 v[84:87], v[202:205], v[186:189], v[84:87]
	v_mfma_f32_16x16x32_bf16 v[80:83], v[210:213], v[186:189], v[80:83]
	v_mfma_f32_16x16x32_bf16 v[64:67], v[210:213], v[194:197], v[64:67]
	v_mfma_f32_16x16x32_bf16 v[68:71], v[202:205], v[194:197], v[68:71]
	s_setprio 0
	s_mov_b32 m0, s31
	v_lshl_add_u64 v[222:223], s[44:45], 0, v[128:129]
	s_barrier
	ds_read_b128 v[166:169], v148 offset:16384
	ds_read_b128 v[170:173], v148 offset:17408
	ds_read_b128 v[174:177], v148 offset:18432
	ds_read_b128 v[178:181], v148 offset:19456
	ds_read_b128 v[182:185], v148 offset:20480
	ds_read_b128 v[186:189], v148 offset:21504
	ds_read_b128 v[190:193], v148 offset:22528
	ds_read_b128 v[194:197], v148 offset:23552
	global_load_lds_dwordx4 v[222:223], off
	v_lshl_add_u64 v[224:225], s[44:45], 0, v[132:133]
	s_mov_b32 m0, s46
	s_nop 0
	global_load_lds_dwordx4 v[224:225], off
	s_barrier
	s_waitcnt lgkmcnt(0)
	s_setprio 1
	s_waitcnt lgkmcnt(0)
	v_mfma_f32_16x16x32_bf16 v[60:63], v[150:153], v[166:169], v[60:63]
	v_mfma_f32_16x16x32_bf16 v[56:59], v[158:161], v[166:169], v[56:59]
	v_mfma_f32_16x16x32_bf16 v[40:43], v[158:161], v[174:177], v[40:43]
	v_mfma_f32_16x16x32_bf16 v[44:47], v[150:153], v[174:177], v[44:47]
	v_mfma_f32_16x16x32_bf16 v[28:31], v[150:153], v[182:185], v[28:31]
	v_mfma_f32_16x16x32_bf16 v[24:27], v[158:161], v[182:185], v[24:27]
	v_mfma_f32_16x16x32_bf16 v[8:11], v[158:161], v[190:193], v[8:11]
	v_mfma_f32_16x16x32_bf16 v[12:15], v[150:153], v[190:193], v[12:15]
	v_mfma_f32_16x16x32_bf16 v[60:63], v[154:157], v[170:173], v[60:63]
	v_mfma_f32_16x16x32_bf16 v[56:59], v[162:165], v[170:173], v[56:59]
	v_mfma_f32_16x16x32_bf16 v[40:43], v[162:165], v[178:181], v[40:43]
	v_mfma_f32_16x16x32_bf16 v[44:47], v[154:157], v[178:181], v[44:47]
	v_mfma_f32_16x16x32_bf16 v[28:31], v[154:157], v[186:189], v[28:31]
	v_mfma_f32_16x16x32_bf16 v[24:27], v[162:165], v[186:189], v[24:27]
	v_mfma_f32_16x16x32_bf16 v[8:11], v[162:165], v[194:197], v[8:11]
	v_mfma_f32_16x16x32_bf16 v[12:15], v[154:157], v[194:197], v[12:15]
	s_setprio 0
	s_barrier
; #define PG8_STAGE(bufoff, gbase, voff) do { _Pragma("unroll") for (int _i = 0; _i < 2; ++_i) \
;         __builtin_amdgcn_global_load_lds((const unsigned*)((const char*)(gbase) + (voff)[_i]), (LAS unsigned*)(lds + (bufoff) + ldsw + _i * 8192), 16, 0, 0); } while (0)
; #define PG8_LDA(dst, b, h) do { _Pragma("unroll") for (int m = 0; m < 4; ++m) _Pragma("unroll") for (int k = 0; k < 2; ++k) dst[m][k] = *(const LAS bf16x8*)(lds + PG8_SA(b, h) + aoff + m * 2048 + k * 1024); } while (0)
; #define PG8_LDB(dst, b, h) do { _Pragma("unroll") for (int n = 0; n < 2; ++n) _Pragma("unroll") for (int k = 0; k < 2; ++k) dst[n][k] = *(const LAS bf16x8*)(lds + PG8_SB(b, h) + boff + n * 2048 + k * 1024); } while (0)
; #define PG8_MMA(ai, bj, At, Bt) do { __builtin_amdgcn_s_setprio(1); _Pragma("unroll") for (int m = 0; m < 4; ++m) _Pragma("unroll") for (int n = 0; n < 2; ++n) _Pragma("unroll") for (int k = 0; k < 2; ++k) \
;         acc[ai][bj][m][n] = __builtin_amdgcn_mfma_f32_16x16x32_bf16(Bt[n][k], At[m][k], acc[ai][bj][m][n], 0, 0, 0); __builtin_amdgcn_s_setprio(0); } while (0)
; #define PG8_WAIT_V(n) asm volatile("s_waitcnt vmcnt(" #n ")" ::: "memory")
; #define PG8_WAIT_L(n) asm volatile("s_waitcnt lgkmcnt(" #n ")" ::: "memory")
; #define PG8_BAR __builtin_amdgcn_s_barrier()
; #define PG8_SCHED __builtin_amdgcn_sched_barrier(0)
; template <class Epi>
; DEVINL void gemm_phase(LAS unsigned char* lds, const Gemm g, const Order& S, const Epi& E) {
;     ...
;             PG8_STAGE(PG8_SB(0, 1), b2 + hstepB, voffB);
;             PG8_WAIT_V(6); PG8_BAR; PG8_MMA(1, 1, At, B1); PG8_BAR;
;             PG8_LDB(B0, 1, 0); PG8_SCHED; PG8_LDA(At, 1, 0); PG8_STAGE(PG8_SA(0, 1), a2 + hstepA, voffA);
;             PG8_WAIT_L(8); PG8_BAR; PG8_WAIT_L(0); PG8_MMA(0, 0, At, B0); PG8_BAR; PG8_SCHED;
;             PG8_LDB(B1, 1, 1); PG8_STAGE(PG8_SB(1, 0), b3, voffB);
	s_add_u32 s2, s42, 0x10000
	s_addc_u32 s3, s43, 0
	s_add_i32 s38, s58, s30
	v_lshl_add_u64 v[150:151], s[2:3], 0, v[130:131]
	s_mov_b32 m0, s38
	s_nop 0
	global_load_lds_dwordx4 v[150:151], off
	v_lshl_add_u64 v[150:151], s[2:3], 0, v[134:135]
	s_add_i32 m0, s38, 0x2000
	s_nop 0
	global_load_lds_dwordx4 v[150:151], off
	s_waitcnt vmcnt(6)
	s_barrier
	s_setprio 1
	v_mfma_f32_16x16x32_bf16 v[52:55], v[198:201], v[166:169], v[52:55]
	v_mfma_f32_16x16x32_bf16 v[48:51], v[206:209], v[166:169], v[48:51]
	v_mfma_f32_16x16x32_bf16 v[32:35], v[206:209], v[174:177], v[32:35]
	v_mfma_f32_16x16x32_bf16 v[36:39], v[198:201], v[174:177], v[36:39]
	v_mfma_f32_16x16x32_bf16 v[20:23], v[198:201], v[182:185], v[20:23]
	v_mfma_f32_16x16x32_bf16 v[16:19], v[206:209], v[182:185], v[16:19]
	v_mfma_f32_16x16x32_bf16 v[0:3], v[206:209], v[190:193], v[0:3]
	v_mfma_f32_16x16x32_bf16 v[4:7], v[198:201], v[190:193], v[4:7]
	v_mfma_f32_16x16x32_bf16 v[52:55], v[202:205], v[170:173], v[52:55]
	v_mfma_f32_16x16x32_bf16 v[48:51], v[210:213], v[170:173], v[48:51]
	v_mfma_f32_16x16x32_bf16 v[32:35], v[210:213], v[178:181], v[32:35]
	v_mfma_f32_16x16x32_bf16 v[36:39], v[202:205], v[178:181], v[36:39]
	v_mfma_f32_16x16x32_bf16 v[20:23], v[202:205], v[186:189], v[20:23]
	v_mfma_f32_16x16x32_bf16 v[16:19], v[210:213], v[186:189], v[16:19]
	v_mfma_f32_16x16x32_bf16 v[0:3], v[210:213], v[194:197], v[0:3]
	v_mfma_f32_16x16x32_bf16 v[4:7], v[202:205], v[194:197], v[4:7]
	s_setprio 0
	s_add_i32 s38, 16, 0x18000
	v_add_u32_e32 v162, s38, v145
	s_barrier
	ds_read_b128 v[150:153], v162
	ds_read_b128 v[154:157], v162 offset:1024
	ds_read_b128 v[158:161], v162 offset:2048
	ds_read_b128 v[162:165], v162 offset:3072
	s_add_u32 s2, s44, 0x30000
	s_addc_u32 s3, s45, 0
	s_mov_b32 m0, s47
	v_lshl_add_u64 v[198:199], s[2:3], 0, v[128:129]
	ds_read_b128 v[166:169], v148 offset:32768
	ds_read_b128 v[170:173], v148 offset:33792
	ds_read_b128 v[174:177], v148 offset:34816
	ds_read_b128 v[178:181], v148 offset:35840
	ds_read_b128 v[182:185], v148 offset:36864
	ds_read_b128 v[186:189], v148 offset:37888
	ds_read_b128 v[190:193], v148 offset:38912
	ds_read_b128 v[194:197], v148 offset:39936
	global_load_lds_dwordx4 v[198:199], off
	v_lshl_add_u64 v[198:199], s[2:3], 0, v[132:133]
	s_mov_b32 m0, s48
	s_nop 0
	global_load_lds_dwordx4 v[198:199], off
	s_waitcnt lgkmcnt(8)
	s_barrier
	s_waitcnt lgkmcnt(0)
	s_setprio 1
	s_waitcnt lgkmcnt(0)
	v_mfma_f32_16x16x32_bf16 v[120:123], v[150:153], v[166:169], v[120:123]
	v_mfma_f32_16x16x32_bf16 v[124:127], v[158:161], v[166:169], v[124:127]
	v_mfma_f32_16x16x32_bf16 v[104:107], v[158:161], v[174:177], v[104:107]
	v_mfma_f32_16x16x32_bf16 v[108:111], v[150:153], v[174:177], v[108:111]
	v_mfma_f32_16x16x32_bf16 v[92:95], v[150:153], v[182:185], v[92:95]
	v_mfma_f32_16x16x32_bf16 v[88:91], v[158:161], v[182:185], v[88:91]
	v_mfma_f32_16x16x32_bf16 v[72:75], v[158:161], v[190:193], v[72:75]
	v_mfma_f32_16x16x32_bf16 v[76:79], v[150:153], v[190:193], v[76:79]
	v_mfma_f32_16x16x32_bf16 v[120:123], v[154:157], v[170:173], v[120:123]
	v_mfma_f32_16x16x32_bf16 v[124:127], v[162:165], v[170:173], v[124:127]
	v_mfma_f32_16x16x32_bf16 v[104:107], v[162:165], v[178:181], v[104:107]
	v_mfma_f32_16x16x32_bf16 v[108:111], v[154:157], v[178:181], v[108:111]
	v_mfma_f32_16x16x32_bf16 v[92:95], v[154:157], v[186:189], v[92:95]
	v_mfma_f32_16x16x32_bf16 v[88:91], v[162:165], v[186:189], v[88:91]
	v_mfma_f32_16x16x32_bf16 v[72:75], v[162:165], v[194:197], v[72:75]
	v_mfma_f32_16x16x32_bf16 v[76:79], v[154:157], v[194:197], v[76:79]
	s_setprio 0
	s_barrier
	s_add_i32 s39, 16, 0x1c000
	s_add_i32 s2, s38, s30
	v_add_u32_e32 v210, s39, v145
	v_lshl_add_u64 v[218:219], v[218:219], 0, s[8:9]
	s_mov_b32 m0, s2
	ds_read_b128 v[198:201], v210
	ds_read_b128 v[202:205], v210 offset:1024
	ds_read_b128 v[206:209], v210 offset:2048
	ds_read_b128 v[210:213], v210 offset:3072
	global_load_lds_dwordx4 v[218:219], off
	v_lshl_add_u64 v[218:219], v[220:221], 0, s[8:9]
	s_add_i32 m0, s2, 0x2000
	s_nop 0
	global_load_lds_dwordx4 v[218:219], off
	s_barrier
; #define PG8_STAGE(bufoff, gbase, voff) do { _Pragma("unroll") for (int _i = 0; _i < 2; ++_i) \
;         __builtin_amdgcn_global_load_lds((const unsigned*)((const char*)(gbase) + (voff)[_i]), (LAS unsigned*)(lds + (bufoff) + ldsw + _i * 8192), 16, 0, 0); } while (0)
; #define PG8_LDA(dst, b, h) do { _Pragma("unroll") for (int m = 0; m < 4; ++m) _Pragma("unroll") for (int k = 0; k < 2; ++k) dst[m][k] = *(const LAS bf16x8*)(lds + PG8_SA(b, h) + aoff + m * 2048 + k * 1024); } while (0)
; #define PG8_MMA(ai, bj, At, Bt) do { __builtin_amdgcn_s_setprio(1); _Pragma("unroll") for (int m = 0; m < 4; ++m) _Pragma("unroll") for (int n = 0; n < 2; ++n) _Pragma("unroll") for (int k = 0; k < 2; ++k) \
;         acc[ai][bj][m][n] = __builtin_amdgcn_mfma_f32_16x16x32_bf16(Bt[n][k], At[m][k], acc[ai][bj][m][n], 0, 0, 0); __builtin_amdgcn_s_setprio(0); } while (0)
; #define PG8_WAIT_V(n) asm volatile("s_waitcnt vmcnt(" #n ")" ::: "memory")
; #define PG8_WAIT_L(n) asm volatile("s_waitcnt lgkmcnt(" #n ")" ::: "memory")
; #define PG8_BAR __builtin_amdgcn_s_barrier()
; #define PG8_SCHED __builtin_amdgcn_sched_barrier(0)
; template <class Epi>
; DEVINL void gemm_phase(LAS unsigned char* lds, const Gemm g, const Order& S, const Epi& E) {
;     ...
;             PG8_BAR; PG8_WAIT_L(0); PG8_MMA(0, 1, At, B1); PG8_BAR;
;             PG8_LDA(At, 1, 1); PG8_STAGE(PG8_SA(1, 0), a3, voffA);
;             PG8_BAR; PG8_WAIT_L(0); PG8_MMA(1, 0, At, B0); PG8_BAR; PG8_SCHED;
;             PG8_STAGE(PG8_SB(1, 1), b3 + hstepB, voffB);
;             PG8_WAIT_V(6); PG8_BAR; PG8_MMA(1, 1, At, B1); PG8_BAR;
;         }
	s_waitcnt lgkmcnt(0)
	s_setprio 1
	s_waitcnt lgkmcnt(0)
	v_mfma_f32_16x16x32_bf16 v[116:119], v[198:201], v[166:169], v[116:119]
	v_mfma_f32_16x16x32_bf16 v[112:115], v[206:209], v[166:169], v[112:115]
	v_mfma_f32_16x16x32_bf16 v[96:99], v[206:209], v[174:177], v[96:99]
	v_mfma_f32_16x16x32_bf16 v[100:103], v[198:201], v[174:177], v[100:103]
	v_mfma_f32_16x16x32_bf16 v[84:87], v[198:201], v[182:185], v[84:87]
	v_mfma_f32_16x16x32_bf16 v[80:83], v[206:209], v[182:185], v[80:83]
	v_mfma_f32_16x16x32_bf16 v[64:67], v[206:209], v[190:193], v[64:67]
	v_mfma_f32_16x16x32_bf16 v[68:71], v[198:201], v[190:193], v[68:71]
	v_mfma_f32_16x16x32_bf16 v[116:119], v[202:205], v[170:173], v[116:119]
	v_mfma_f32_16x16x32_bf16 v[112:115], v[210:213], v[170:173], v[112:115]
	v_mfma_f32_16x16x32_bf16 v[96:99], v[210:213], v[178:181], v[96:99]
	v_mfma_f32_16x16x32_bf16 v[100:103], v[202:205], v[178:181], v[100:103]
	v_mfma_f32_16x16x32_bf16 v[84:87], v[202:205], v[186:189], v[84:87]
	v_mfma_f32_16x16x32_bf16 v[80:83], v[210:213], v[186:189], v[80:83]
	v_mfma_f32_16x16x32_bf16 v[64:67], v[210:213], v[194:197], v[64:67]
	v_mfma_f32_16x16x32_bf16 v[68:71], v[202:205], v[194:197], v[68:71]
	s_setprio 0
	s_mov_b32 m0, s50
	v_lshl_add_u64 v[218:219], v[222:223], 0, s[8:9]
	s_barrier
	ds_read_b128 v[166:169], v148 offset:49152
	ds_read_b128 v[170:173], v148 offset:50176
	ds_read_b128 v[174:177], v148 offset:51200
	ds_read_b128 v[178:181], v148 offset:52224
	ds_read_b128 v[182:185], v148 offset:53248
	ds_read_b128 v[186:189], v148 offset:54272
	ds_read_b128 v[190:193], v148 offset:55296
	ds_read_b128 v[194:197], v148 offset:56320
	global_load_lds_dwordx4 v[218:219], off
	v_lshl_add_u64 v[218:219], v[224:225], 0, s[8:9]
	s_mov_b32 m0, s51
	s_nop 0
	global_load_lds_dwordx4 v[218:219], off
	s_barrier
	s_waitcnt lgkmcnt(0)
	s_setprio 1
	s_waitcnt lgkmcnt(0)
	v_mfma_f32_16x16x32_bf16 v[60:63], v[150:153], v[166:169], v[60:63]
	v_mfma_f32_16x16x32_bf16 v[56:59], v[158:161], v[166:169], v[56:59]
	v_mfma_f32_16x16x32_bf16 v[40:43], v[158:161], v[174:177], v[40:43]
	v_mfma_f32_16x16x32_bf16 v[44:47], v[150:153], v[174:177], v[44:47]
	v_mfma_f32_16x16x32_bf16 v[28:31], v[150:153], v[182:185], v[28:31]
	v_mfma_f32_16x16x32_bf16 v[24:27], v[158:161], v[182:185], v[24:27]
	v_mfma_f32_16x16x32_bf16 v[8:11], v[158:161], v[190:193], v[8:11]
	v_mfma_f32_16x16x32_bf16 v[12:15], v[150:153], v[190:193], v[12:15]
	v_mfma_f32_16x16x32_bf16 v[60:63], v[154:157], v[170:173], v[60:63]
	v_mfma_f32_16x16x32_bf16 v[56:59], v[162:165], v[170:173], v[56:59]
	v_mfma_f32_16x16x32_bf16 v[40:43], v[162:165], v[178:181], v[40:43]
	v_mfma_f32_16x16x32_bf16 v[44:47], v[154:157], v[178:181], v[44:47]
	v_mfma_f32_16x16x32_bf16 v[28:31], v[154:157], v[186:189], v[28:31]
	v_mfma_f32_16x16x32_bf16 v[24:27], v[162:165], v[186:189], v[24:27]
	v_mfma_f32_16x16x32_bf16 v[8:11], v[162:165], v[194:197], v[8:11]
	v_mfma_f32_16x16x32_bf16 v[12:15], v[154:157], v[194:197], v[12:15]
	s_setprio 0
	s_barrier
	s_add_u32 s2, s42, 0x10080
	s_addc_u32 s3, s43, 0
	s_add_i32 s38, s39, s30
	v_lshl_add_u64 v[150:151], s[2:3], 0, v[130:131]
	s_mov_b32 m0, s38
	s_nop 0
	global_load_lds_dwordx4 v[150:151], off
	v_lshl_add_u64 v[150:151], s[2:3], 0, v[134:135]
	s_add_i32 m0, s38, 0x2000
	s_nop 0
	global_load_lds_dwordx4 v[150:151], off
	s_waitcnt vmcnt(6)
	s_barrier
	s_setprio 1
	v_mfma_f32_16x16x32_bf16 v[52:55], v[198:201], v[166:169], v[52:55]
	v_mfma_f32_16x16x32_bf16 v[48:51], v[206:209], v[166:169], v[48:51]
	v_mfma_f32_16x16x32_bf16 v[32:35], v[206:209], v[174:177], v[32:35]
	v_mfma_f32_16x16x32_bf16 v[36:39], v[198:201], v[174:177], v[36:39]
	v_mfma_f32_16x16x32_bf16 v[20:23], v[198:201], v[182:185], v[20:23]
	v_mfma_f32_16x16x32_bf16 v[16:19], v[206:209], v[182:185], v[16:19]
	v_mfma_f32_16x16x32_bf16 v[0:3], v[206:209], v[190:193], v[0:3]
	v_mfma_f32_16x16x32_bf16 v[4:7], v[198:201], v[190:193], v[4:7]
	v_mfma_f32_16x16x32_bf16 v[52:55], v[202:205], v[170:173], v[52:55]
	v_mfma_f32_16x16x32_bf16 v[48:51], v[210:213], v[170:173], v[48:51]
	v_mfma_f32_16x16x32_bf16 v[32:35], v[210:213], v[178:181], v[32:35]
	v_mfma_f32_16x16x32_bf16 v[36:39], v[202:205], v[178:181], v[36:39]
	v_mfma_f32_16x16x32_bf16 v[20:23], v[202:205], v[186:189], v[20:23]
	v_mfma_f32_16x16x32_bf16 v[16:19], v[210:213], v[186:189], v[16:19]
	v_mfma_f32_16x16x32_bf16 v[0:3], v[210:213], v[194:197], v[0:3]
	v_mfma_f32_16x16x32_bf16 v[4:7], v[202:205], v[194:197], v[4:7]
	s_setprio 0
	s_add_u32 s66, s66, 0x100
	s_addc_u32 s67, s67, 0
	s_cmp_ge_i32 s68, s49
	s_mov_b64 s[38:39], s[4:5]
	s_mov_b32 s42, s68
	s_barrier
	s_cbranch_scc0 .LBB0_825
	s_branch .LBB0_814

; #define PG8_STAGE(bufoff, gbase, voff) do { _Pragma("unroll") for (int _i = 0; _i < 2; ++_i) \
;         __builtin_amdgcn_global_load_lds((const unsigned*)((const char*)(gbase) + (voff)[_i]), (LAS unsigned*)(lds + (bufoff) + ldsw + _i * 8192), 16, 0, 0); } while (0)
; #define PG8_LDA(dst, b, h) do { _Pragma("unroll") for (int m = 0; m < 4; ++m) _Pragma("unroll") for (int k = 0; k < 2; ++k) dst[m][k] = *(const LAS bf16x8*)(lds + PG8_SA(b, h) + aoff + m * 2048 + k * 1024); } while (0)
; #define PG8_LDB(dst, b, h) do { _Pragma("unroll") for (int n = 0; n < 2; ++n) _Pragma("unroll") for (int k = 0; k < 2; ++k) dst[n][k] = *(const LAS bf16x8*)(lds + PG8_SB(b, h) + boff + n * 2048 + k * 1024); } while (0)
; #define PG8_MMA(ai, bj, At, Bt) do { __builtin_amdgcn_s_setprio(1); _Pragma("unroll") for (int m = 0; m < 4; ++m) _Pragma("unroll") for (int n = 0; n < 2; ++n) _Pragma("unroll") for (int k = 0; k < 2; ++k) \
;         acc[ai][bj][m][n] = __builtin_amdgcn_mfma_f32_16x16x32_bf16(Bt[n][k], At[m][k], acc[ai][bj][m][n], 0, 0, 0); __builtin_amdgcn_s_setprio(0); } while (0)
; #define PG8_WAIT_L(n) asm volatile("s_waitcnt lgkmcnt(" #n ")" ::: "memory")
; #define PG8_BAR __builtin_amdgcn_s_barrier()
; #define PG8_SCHED __builtin_amdgcn_sched_barrier(0)
; template <class Epi>
; DEVINL void gemm_phase(LAS unsigned char* lds, const Gemm g, const Order& S, const Epi& E) {
;     ...
;             PG8_LDB(B0, 0, 0); PG8_SCHED; PG8_LDA(At, 0, 0); PG8_STAGE(PG8_SA(1, 1), a1 + hstepA, voffA);
;             PG8_WAIT_L(8); PG8_BAR; PG8_WAIT_L(0); PG8_MMA(0, 0, At, B0); PG8_BAR; PG8_SCHED;
;             PG8_LDB(B1, 0, 1); PG8_STAGE(PG8_SB(0, 0), b2, voffB);
;             PG8_BAR; PG8_WAIT_L(0); PG8_MMA(0, 1, At, B1); PG8_BAR;
;             PG8_LDA(At, 0, 1); PG8_STAGE(PG8_SA(0, 0), a2, voffA);
;             PG8_BAR; PG8_WAIT_L(0); PG8_MMA(1, 0, At, B0); PG8_BAR; PG8_SCHED;
.LBB0_848:
	ds_read_b128 v[150:153], v147
	ds_read_b128 v[154:157], v147 offset:1024
	ds_read_b128 v[158:161], v147 offset:2048
	ds_read_b128 v[162:165], v147 offset:3072
	s_add_i32 s67, s44, 2
	s_add_u32 s2, s4, 0xffff0080
	s_addc_u32 s3, s5, -1
	s_cmp_eq_u32 s25, s44
	s_cselect_b32 s44, s16, s65
	s_cselect_b32 s47, s13, s3
	s_cselect_b32 s46, s64, s2
	s_cselect_b32 s45, s17, s66
	v_lshl_add_u64 v[198:199], s[4:5], 0, v[136:137]
	s_add_i32 m0, s9, 0xc000
	ds_read_b128 v[166:169], v148
	ds_read_b128 v[170:173], v148 offset:1024
	ds_read_b128 v[174:177], v148 offset:2048
	ds_read_b128 v[178:181], v148 offset:3072
	ds_read_b128 v[182:185], v148 offset:4096
	ds_read_b128 v[186:189], v148 offset:5120
	ds_read_b128 v[190:193], v148 offset:6144
	ds_read_b128 v[194:197], v148 offset:7168
	global_load_lds_dwordx4 v[198:199], off
	v_lshl_add_u64 v[198:199], s[4:5], 0, v[138:139]
	s_add_i32 m0, s9, 0xe000
	s_nop 0
	global_load_lds_dwordx4 v[198:199], off
	s_waitcnt lgkmcnt(8)
	s_barrier
	s_waitcnt lgkmcnt(0)
	s_setprio 1
	s_waitcnt lgkmcnt(0)
	v_mfma_f32_16x16x32_bf16 v[120:123], v[150:153], v[166:169], v[120:123]
	v_mfma_f32_16x16x32_bf16 v[124:127], v[158:161], v[166:169], v[124:127]
	v_mfma_f32_16x16x32_bf16 v[104:107], v[158:161], v[174:177], v[104:107]
	v_mfma_f32_16x16x32_bf16 v[108:111], v[150:153], v[174:177], v[108:111]
	v_mfma_f32_16x16x32_bf16 v[92:95], v[150:153], v[182:185], v[92:95]
	v_mfma_f32_16x16x32_bf16 v[88:91], v[158:161], v[182:185], v[88:91]
	v_mfma_f32_16x16x32_bf16 v[72:75], v[158:161], v[190:193], v[72:75]
	v_mfma_f32_16x16x32_bf16 v[76:79], v[150:153], v[190:193], v[76:79]
	v_mfma_f32_16x16x32_bf16 v[120:123], v[154:157], v[170:173], v[120:123]
	v_mfma_f32_16x16x32_bf16 v[124:127], v[162:165], v[170:173], v[124:127]
	v_mfma_f32_16x16x32_bf16 v[104:107], v[162:165], v[178:181], v[104:107]
	v_mfma_f32_16x16x32_bf16 v[108:111], v[154:157], v[178:181], v[108:111]
	v_mfma_f32_16x16x32_bf16 v[92:95], v[154:157], v[186:189], v[92:95]
	v_mfma_f32_16x16x32_bf16 v[88:91], v[162:165], v[186:189], v[88:91]
	v_mfma_f32_16x16x32_bf16 v[72:75], v[162:165], v[194:197], v[72:75]
	v_mfma_f32_16x16x32_bf16 v[76:79], v[154:157], v[194:197], v[76:79]
	s_setprio 0
	s_barrier
	s_add_i32 s2, s56, s30
	v_lshl_add_u64 v[218:219], s[44:45], 0, v[130:131]
	s_mov_b32 m0, s2
	ds_read_b128 v[198:201], v149
	ds_read_b128 v[202:205], v149 offset:1024
	ds_read_b128 v[206:209], v149 offset:2048
	ds_read_b128 v[210:213], v149 offset:3072
	global_load_lds_dwordx4 v[218:219], off
	v_lshl_add_u64 v[220:221], s[44:45], 0, v[134:135]
	s_add_i32 m0, s2, 0x2000
	s_nop 0
	global_load_lds_dwordx4 v[220:221], off
	s_barrier
	s_waitcnt lgkmcnt(0)
	s_setprio 1
	s_waitcnt lgkmcnt(0)
	v_mfma_f32_16x16x32_bf16 v[116:119], v[198:201], v[166:169], v[116:119]
	v_mfma_f32_16x16x32_bf16 v[112:115], v[206:209], v[166:169], v[112:115]
	v_mfma_f32_16x16x32_bf16 v[96:99], v[206:209], v[174:177], v[96:99]
	v_mfma_f32_16x16x32_bf16 v[100:103], v[198:201], v[174:177], v[100:103]
	v_mfma_f32_16x16x32_bf16 v[84:87], v[198:201], v[182:185], v[84:87]
	v_mfma_f32_16x16x32_bf16 v[80:83], v[206:209], v[182:185], v[80:83]
	v_mfma_f32_16x16x32_bf16 v[64:67], v[206:209], v[190:193], v[64:67]
	v_mfma_f32_16x16x32_bf16 v[68:71], v[198:201], v[190:193], v[68:71]
	v_mfma_f32_16x16x32_bf16 v[116:119], v[202:205], v[170:173], v[116:119]
	v_mfma_f32_16x16x32_bf16 v[112:115], v[210:213], v[170:173], v[112:115]
	v_mfma_f32_16x16x32_bf16 v[96:99], v[210:213], v[178:181], v[96:99]
	v_mfma_f32_16x16x32_bf16 v[100:103], v[202:205], v[178:181], v[100:103]
	v_mfma_f32_16x16x32_bf16 v[84:87], v[202:205], v[186:189], v[84:87]
	v_mfma_f32_16x16x32_bf16 v[80:83], v[210:213], v[186:189], v[80:83]
	v_mfma_f32_16x16x32_bf16 v[64:67], v[210:213], v[194:197], v[64:67]
	v_mfma_f32_16x16x32_bf16 v[68:71], v[202:205], v[194:197], v[68:71]
	s_setprio 0
	s_mov_b32 m0, s9
	v_lshl_add_u64 v[222:223], s[46:47], 0, v[128:129]
	s_barrier
	ds_read_b128 v[166:169], v148 offset:16384
	ds_read_b128 v[170:173], v148 offset:17408
	ds_read_b128 v[174:177], v148 offset:18432
	ds_read_b128 v[178:181], v148 offset:19456
	ds_read_b128 v[182:185], v148 offset:20480
	ds_read_b128 v[186:189], v148 offset:21504
	ds_read_b128 v[190:193], v148 offset:22528
	ds_read_b128 v[194:197], v148 offset:23552
	global_load_lds_dwordx4 v[222:223], off
	v_lshl_add_u64 v[224:225], s[46:47], 0, v[132:133]
	s_mov_b32 m0, s31
	s_nop 0
	global_load_lds_dwordx4 v[224:225], off
	s_barrier
	s_waitcnt lgkmcnt(0)
	s_setprio 1
	s_waitcnt lgkmcnt(0)
	v_mfma_f32_16x16x32_bf16 v[60:63], v[150:153], v[166:169], v[60:63]
	v_mfma_f32_16x16x32_bf16 v[56:59], v[158:161], v[166:169], v[56:59]
	v_mfma_f32_16x16x32_bf16 v[40:43], v[158:161], v[174:177], v[40:43]
	v_mfma_f32_16x16x32_bf16 v[44:47], v[150:153], v[174:177], v[44:47]
	v_mfma_f32_16x16x32_bf16 v[28:31], v[150:153], v[182:185], v[28:31]
	v_mfma_f32_16x16x32_bf16 v[24:27], v[158:161], v[182:185], v[24:27]
	v_mfma_f32_16x16x32_bf16 v[8:11], v[158:161], v[190:193], v[8:11]
	v_mfma_f32_16x16x32_bf16 v[12:15], v[150:153], v[190:193], v[12:15]
	v_mfma_f32_16x16x32_bf16 v[60:63], v[154:157], v[170:173], v[60:63]
	v_mfma_f32_16x16x32_bf16 v[56:59], v[162:165], v[170:173], v[56:59]
	v_mfma_f32_16x16x32_bf16 v[40:43], v[162:165], v[178:181], v[40:43]
	v_mfma_f32_16x16x32_bf16 v[44:47], v[154:157], v[178:181], v[44:47]
	v_mfma_f32_16x16x32_bf16 v[28:31], v[154:157], v[186:189], v[28:31]
	v_mfma_f32_16x16x32_bf16 v[24:27], v[162:165], v[186:189], v[24:27]
	v_mfma_f32_16x16x32_bf16 v[8:11], v[162:165], v[194:197], v[8:11]
	v_mfma_f32_16x16x32_bf16 v[12:15], v[154:157], v[194:197], v[12:15]
	s_setprio 0
	s_barrier
; #define PG8_STAGE(bufoff, gbase, voff) do { _Pragma("unroll") for (int _i = 0; _i < 2; ++_i) \
;         __builtin_amdgcn_global_load_lds((const unsigned*)((const char*)(gbase) + (voff)[_i]), (LAS unsigned*)(lds + (bufoff) + ldsw + _i * 8192), 16, 0, 0); } while (0)
; #define PG8_LDA(dst, b, h) do { _Pragma("unroll") for (int m = 0; m < 4; ++m) _Pragma("unroll") for (int k = 0; k < 2; ++k) dst[m][k] = *(const LAS bf16x8*)(lds + PG8_SA(b, h) + aoff + m * 2048 + k * 1024); } while (0)
; #define PG8_LDB(dst, b, h) do { _Pragma("unroll") for (int n = 0; n < 2; ++n) _Pragma("unroll") for (int k = 0; k < 2; ++k) dst[n][k] = *(const LAS bf16x8*)(lds + PG8_SB(b, h) + boff + n * 2048 + k * 1024); } while (0)
; #define PG8_MMA(ai, bj, At, Bt) do { __builtin_amdgcn_s_setprio(1); _Pragma("unroll") for (int m = 0; m < 4; ++m) _Pragma("unroll") for (int n = 0; n < 2; ++n) _Pragma("unroll") for (int k = 0; k < 2; ++k) \
;         acc[ai][bj][m][n] = __builtin_amdgcn_mfma_f32_16x16x32_bf16(Bt[n][k], At[m][k], acc[ai][bj][m][n], 0, 0, 0); __builtin_amdgcn_s_setprio(0); } while (0)
; #define PG8_WAIT_V(n) asm volatile("s_waitcnt vmcnt(" #n ")" ::: "memory")
; #define PG8_WAIT_L(n) asm volatile("s_waitcnt lgkmcnt(" #n ")" ::: "memory")
; #define PG8_BAR __builtin_amdgcn_s_barrier()
; #define PG8_SCHED __builtin_amdgcn_sched_barrier(0)
; template <class Epi>
; DEVINL void gemm_phase(LAS unsigned char* lds, const Gemm g, const Order& S, const Epi& E) {
;     ...
;             PG8_STAGE(PG8_SB(0, 1), b2 + hstepB, voffB);
;             PG8_WAIT_V(6); PG8_BAR; PG8_MMA(1, 1, At, B1); PG8_BAR;
;             PG8_LDB(B0, 1, 0); PG8_SCHED; PG8_LDA(At, 1, 0); PG8_STAGE(PG8_SA(0, 1), a2 + hstepA, voffA);
;             PG8_WAIT_L(8); PG8_BAR; PG8_WAIT_L(0); PG8_MMA(0, 0, At, B0); PG8_BAR; PG8_SCHED;
;             PG8_LDB(B1, 1, 1); PG8_STAGE(PG8_SB(1, 0), b3, voffB);
	s_add_u32 s2, s44, 0x30000
	s_addc_u32 s3, s45, 0
	s_add_i32 s68, s57, s30
	v_lshl_add_u64 v[150:151], s[2:3], 0, v[130:131]
	s_mov_b32 m0, s68
	s_nop 0
	global_load_lds_dwordx4 v[150:151], off
	v_lshl_add_u64 v[150:151], s[2:3], 0, v[134:135]
	s_add_i32 m0, s68, 0x2000
	s_nop 0
	global_load_lds_dwordx4 v[150:151], off
	s_waitcnt vmcnt(6)
	s_barrier
	s_setprio 1
	v_mfma_f32_16x16x32_bf16 v[52:55], v[198:201], v[166:169], v[52:55]
	v_mfma_f32_16x16x32_bf16 v[48:51], v[206:209], v[166:169], v[48:51]
	v_mfma_f32_16x16x32_bf16 v[32:35], v[206:209], v[174:177], v[32:35]
	v_mfma_f32_16x16x32_bf16 v[36:39], v[198:201], v[174:177], v[36:39]
	v_mfma_f32_16x16x32_bf16 v[20:23], v[198:201], v[182:185], v[20:23]
	v_mfma_f32_16x16x32_bf16 v[16:19], v[206:209], v[182:185], v[16:19]
	v_mfma_f32_16x16x32_bf16 v[0:3], v[206:209], v[190:193], v[0:3]
	v_mfma_f32_16x16x32_bf16 v[4:7], v[198:201], v[190:193], v[4:7]
	v_mfma_f32_16x16x32_bf16 v[52:55], v[202:205], v[170:173], v[52:55]
	v_mfma_f32_16x16x32_bf16 v[48:51], v[210:213], v[170:173], v[48:51]
	v_mfma_f32_16x16x32_bf16 v[32:35], v[210:213], v[178:181], v[32:35]
	v_mfma_f32_16x16x32_bf16 v[36:39], v[202:205], v[178:181], v[36:39]
	v_mfma_f32_16x16x32_bf16 v[20:23], v[202:205], v[186:189], v[20:23]
	v_mfma_f32_16x16x32_bf16 v[16:19], v[210:213], v[186:189], v[16:19]
	v_mfma_f32_16x16x32_bf16 v[0:3], v[210:213], v[194:197], v[0:3]
	v_mfma_f32_16x16x32_bf16 v[4:7], v[202:205], v[194:197], v[4:7]
	s_setprio 0
	s_add_i32 s68, 16, 0x18000
	v_add_u32_e32 v162, s68, v145
	s_barrier
	ds_read_b128 v[150:153], v162
	ds_read_b128 v[154:157], v162 offset:1024
	ds_read_b128 v[158:161], v162 offset:2048
	ds_read_b128 v[162:165], v162 offset:3072
	s_add_u32 s2, s46, 0x10000
	s_addc_u32 s3, s47, 0
	s_mov_b32 m0, s48
	v_lshl_add_u64 v[198:199], s[2:3], 0, v[128:129]
	ds_read_b128 v[166:169], v148 offset:32768
	ds_read_b128 v[170:173], v148 offset:33792
	ds_read_b128 v[174:177], v148 offset:34816
	ds_read_b128 v[178:181], v148 offset:35840
	ds_read_b128 v[182:185], v148 offset:36864
	ds_read_b128 v[186:189], v148 offset:37888
	ds_read_b128 v[190:193], v148 offset:38912
	ds_read_b128 v[194:197], v148 offset:39936
	global_load_lds_dwordx4 v[198:199], off
	v_lshl_add_u64 v[198:199], s[2:3], 0, v[132:133]
	s_mov_b32 m0, s49
	s_nop 0
	global_load_lds_dwordx4 v[198:199], off
	s_waitcnt lgkmcnt(8)
	s_barrier
	s_waitcnt lgkmcnt(0)
	s_setprio 1
	s_waitcnt lgkmcnt(0)
	v_mfma_f32_16x16x32_bf16 v[120:123], v[150:153], v[166:169], v[120:123]
	v_mfma_f32_16x16x32_bf16 v[124:127], v[158:161], v[166:169], v[124:127]
	v_mfma_f32_16x16x32_bf16 v[104:107], v[158:161], v[174:177], v[104:107]
	v_mfma_f32_16x16x32_bf16 v[108:111], v[150:153], v[174:177], v[108:111]
	v_mfma_f32_16x16x32_bf16 v[92:95], v[150:153], v[182:185], v[92:95]
	v_mfma_f32_16x16x32_bf16 v[88:91], v[158:161], v[182:185], v[88:91]
	v_mfma_f32_16x16x32_bf16 v[72:75], v[158:161], v[190:193], v[72:75]
	v_mfma_f32_16x16x32_bf16 v[76:79], v[150:153], v[190:193], v[76:79]
	v_mfma_f32_16x16x32_bf16 v[120:123], v[154:157], v[170:173], v[120:123]
	v_mfma_f32_16x16x32_bf16 v[124:127], v[162:165], v[170:173], v[124:127]
	v_mfma_f32_16x16x32_bf16 v[104:107], v[162:165], v[178:181], v[104:107]
	v_mfma_f32_16x16x32_bf16 v[108:111], v[154:157], v[178:181], v[108:111]
	v_mfma_f32_16x16x32_bf16 v[92:95], v[154:157], v[186:189], v[92:95]
	v_mfma_f32_16x16x32_bf16 v[88:91], v[162:165], v[186:189], v[88:91]
	v_mfma_f32_16x16x32_bf16 v[72:75], v[162:165], v[194:197], v[72:75]
	v_mfma_f32_16x16x32_bf16 v[76:79], v[154:157], v[194:197], v[76:79]
	s_setprio 0
	s_barrier
	s_add_i32 s46, 16, 0x1c000
	s_add_i32 s2, s68, s30
	v_add_u32_e32 v210, s46, v145
	v_lshl_add_u64 v[218:219], v[218:219], 0, s[6:7]
	s_mov_b32 m0, s2
	ds_read_b128 v[198:201], v210
	ds_read_b128 v[202:205], v210 offset:1024
	ds_read_b128 v[206:209], v210 offset:2048
	ds_read_b128 v[210:213], v210 offset:3072
	global_load_lds_dwordx4 v[218:219], off
	v_lshl_add_u64 v[218:219], v[220:221], 0, s[6:7]
	s_add_i32 m0, s2, 0x2000
	s_nop 0
	global_load_lds_dwordx4 v[218:219], off
	s_barrier
; #define PG8_STAGE(bufoff, gbase, voff) do { _Pragma("unroll") for (int _i = 0; _i < 2; ++_i) \
;         __builtin_amdgcn_global_load_lds((const unsigned*)((const char*)(gbase) + (voff)[_i]), (LAS unsigned*)(lds + (bufoff) + ldsw + _i * 8192), 16, 0, 0); } while (0)
; #define PG8_LDA(dst, b, h) do { _Pragma("unroll") for (int m = 0; m < 4; ++m) _Pragma("unroll") for (int k = 0; k < 2; ++k) dst[m][k] = *(const LAS bf16x8*)(lds + PG8_SA(b, h) + aoff + m * 2048 + k * 1024); } while (0)
; #define PG8_MMA(ai, bj, At, Bt) do { __builtin_amdgcn_s_setprio(1); _Pragma("unroll") for (int m = 0; m < 4; ++m) _Pragma("unroll") for (int n = 0; n < 2; ++n) _Pragma("unroll") for (int k = 0; k < 2; ++k) \
;         acc[ai][bj][m][n] = __builtin_amdgcn_mfma_f32_16x16x32_bf16(Bt[n][k], At[m][k], acc[ai][bj][m][n], 0, 0, 0); __builtin_amdgcn_s_setprio(0); } while (0)
; #define PG8_WAIT_V(n) asm volatile("s_waitcnt vmcnt(" #n ")" ::: "memory")
; #define PG8_WAIT_L(n) asm volatile("s_waitcnt lgkmcnt(" #n ")" ::: "memory")
; #define PG8_BAR __builtin_amdgcn_s_barrier()
; #define PG8_SCHED __builtin_amdgcn_sched_barrier(0)
; template <class Epi>
; DEVINL void gemm_phase(LAS unsigned char* lds, const Gemm g, const Order& S, const Epi& E) {
;     ...
;             PG8_BAR; PG8_WAIT_L(0); PG8_MMA(0, 1, At, B1); PG8_BAR;
;             PG8_LDA(At, 1, 1); PG8_STAGE(PG8_SA(1, 0), a3, voffA);
;             PG8_BAR; PG8_WAIT_L(0); PG8_MMA(1, 0, At, B0); PG8_BAR; PG8_SCHED;
;             PG8_STAGE(PG8_SB(1, 1), b3 + hstepB, voffB);
;             PG8_WAIT_V(6); PG8_BAR; PG8_MMA(1, 1, At, B1); PG8_BAR;
;         }
	s_waitcnt lgkmcnt(0)
	s_setprio 1
	s_waitcnt lgkmcnt(0)
	v_mfma_f32_16x16x32_bf16 v[116:119], v[198:201], v[166:169], v[116:119]
	v_mfma_f32_16x16x32_bf16 v[112:115], v[206:209], v[166:169], v[112:115]
	v_mfma_f32_16x16x32_bf16 v[96:99], v[206:209], v[174:177], v[96:99]
	v_mfma_f32_16x16x32_bf16 v[100:103], v[198:201], v[174:177], v[100:103]
	v_mfma_f32_16x16x32_bf16 v[84:87], v[198:201], v[182:185], v[84:87]
	v_mfma_f32_16x16x32_bf16 v[80:83], v[206:209], v[182:185], v[80:83]
	v_mfma_f32_16x16x32_bf16 v[64:67], v[206:209], v[190:193], v[64:67]
	v_mfma_f32_16x16x32_bf16 v[68:71], v[198:201], v[190:193], v[68:71]
	v_mfma_f32_16x16x32_bf16 v[116:119], v[202:205], v[170:173], v[116:119]
	v_mfma_f32_16x16x32_bf16 v[112:115], v[210:213], v[170:173], v[112:115]
	v_mfma_f32_16x16x32_bf16 v[96:99], v[210:213], v[178:181], v[96:99]
	v_mfma_f32_16x16x32_bf16 v[100:103], v[202:205], v[178:181], v[100:103]
	v_mfma_f32_16x16x32_bf16 v[84:87], v[202:205], v[186:189], v[84:87]
	v_mfma_f32_16x16x32_bf16 v[80:83], v[210:213], v[186:189], v[80:83]
	v_mfma_f32_16x16x32_bf16 v[64:67], v[210:213], v[194:197], v[64:67]
	v_mfma_f32_16x16x32_bf16 v[68:71], v[202:205], v[194:197], v[68:71]
	s_setprio 0
	s_mov_b32 m0, s52
	v_lshl_add_u64 v[218:219], v[222:223], 0, s[6:7]
	s_barrier
	ds_read_b128 v[166:169], v148 offset:49152
	ds_read_b128 v[170:173], v148 offset:50176
	ds_read_b128 v[174:177], v148 offset:51200
	ds_read_b128 v[178:181], v148 offset:52224
	ds_read_b128 v[182:185], v148 offset:53248
	ds_read_b128 v[186:189], v148 offset:54272
	ds_read_b128 v[190:193], v148 offset:55296
	ds_read_b128 v[194:197], v148 offset:56320
	global_load_lds_dwordx4 v[218:219], off
	v_lshl_add_u64 v[218:219], v[224:225], 0, s[6:7]
	s_mov_b32 m0, s53
	s_nop 0
	global_load_lds_dwordx4 v[218:219], off
	s_barrier
	s_waitcnt lgkmcnt(0)
	s_setprio 1
	s_waitcnt lgkmcnt(0)
	v_mfma_f32_16x16x32_bf16 v[60:63], v[150:153], v[166:169], v[60:63]
	v_mfma_f32_16x16x32_bf16 v[56:59], v[158:161], v[166:169], v[56:59]
	v_mfma_f32_16x16x32_bf16 v[40:43], v[158:161], v[174:177], v[40:43]
	v_mfma_f32_16x16x32_bf16 v[44:47], v[150:153], v[174:177], v[44:47]
	v_mfma_f32_16x16x32_bf16 v[28:31], v[150:153], v[182:185], v[28:31]
	v_mfma_f32_16x16x32_bf16 v[24:27], v[158:161], v[182:185], v[24:27]
	v_mfma_f32_16x16x32_bf16 v[8:11], v[158:161], v[190:193], v[8:11]
	v_mfma_f32_16x16x32_bf16 v[12:15], v[150:153], v[190:193], v[12:15]
	v_mfma_f32_16x16x32_bf16 v[60:63], v[154:157], v[170:173], v[60:63]
	v_mfma_f32_16x16x32_bf16 v[56:59], v[162:165], v[170:173], v[56:59]
	v_mfma_f32_16x16x32_bf16 v[40:43], v[162:165], v[178:181], v[40:43]
	v_mfma_f32_16x16x32_bf16 v[44:47], v[154:157], v[178:181], v[44:47]
	v_mfma_f32_16x16x32_bf16 v[28:31], v[154:157], v[186:189], v[28:31]
	v_mfma_f32_16x16x32_bf16 v[24:27], v[162:165], v[186:189], v[24:27]
	v_mfma_f32_16x16x32_bf16 v[8:11], v[162:165], v[194:197], v[8:11]
	v_mfma_f32_16x16x32_bf16 v[12:15], v[154:157], v[194:197], v[12:15]
	s_setprio 0
	s_barrier
	s_add_u32 s2, s44, 0x30080
	s_addc_u32 s3, s45, 0
	s_add_i32 s44, s46, s30
	v_lshl_add_u64 v[150:151], s[2:3], 0, v[130:131]
	s_mov_b32 m0, s44
	s_nop 0
	global_load_lds_dwordx4 v[150:151], off
	v_lshl_add_u64 v[150:151], s[2:3], 0, v[134:135]
	s_add_i32 m0, s44, 0x2000
	s_nop 0
	global_load_lds_dwordx4 v[150:151], off
	s_waitcnt vmcnt(6)
	s_barrier
	s_setprio 1
	v_mfma_f32_16x16x32_bf16 v[52:55], v[198:201], v[166:169], v[52:55]
	v_mfma_f32_16x16x32_bf16 v[48:51], v[206:209], v[166:169], v[48:51]
	v_mfma_f32_16x16x32_bf16 v[32:35], v[206:209], v[174:177], v[32:35]
	v_mfma_f32_16x16x32_bf16 v[36:39], v[198:201], v[174:177], v[36:39]
	v_mfma_f32_16x16x32_bf16 v[20:23], v[198:201], v[182:185], v[20:23]
	v_mfma_f32_16x16x32_bf16 v[16:19], v[206:209], v[182:185], v[16:19]
	v_mfma_f32_16x16x32_bf16 v[0:3], v[206:209], v[190:193], v[0:3]
	v_mfma_f32_16x16x32_bf16 v[4:7], v[198:201], v[190:193], v[4:7]
	v_mfma_f32_16x16x32_bf16 v[52:55], v[202:205], v[170:173], v[52:55]
	v_mfma_f32_16x16x32_bf16 v[48:51], v[210:213], v[170:173], v[48:51]
	v_mfma_f32_16x16x32_bf16 v[32:35], v[210:213], v[178:181], v[32:35]
	v_mfma_f32_16x16x32_bf16 v[36:39], v[202:205], v[178:181], v[36:39]
	v_mfma_f32_16x16x32_bf16 v[20:23], v[202:205], v[186:189], v[20:23]
	v_mfma_f32_16x16x32_bf16 v[16:19], v[210:213], v[186:189], v[16:19]
	v_mfma_f32_16x16x32_bf16 v[0:3], v[210:213], v[194:197], v[0:3]
	v_mfma_f32_16x16x32_bf16 v[4:7], v[202:205], v[194:197], v[4:7]
	s_setprio 0
	s_add_u32 s4, s4, 0x100
	s_addc_u32 s5, s5, 0
	s_add_u32 s65, s65, 0x100
	s_addc_u32 s66, s66, 0
	s_cmp_ge_i32 s67, s51
	s_mov_b32 s44, s67
	s_barrier
	s_cbranch_scc0 .LBB0_848
	s_branch .LBB0_837

; #define PG8_STAGE(bufoff, gbase, voff) do { _Pragma("unroll") for (int _i = 0; _i < 2; ++_i) \
;         __builtin_amdgcn_global_load_lds((const unsigned*)((const char*)(gbase) + (voff)[_i]), (LAS unsigned*)(lds + (bufoff) + ldsw + _i * 8192), 16, 0, 0); } while (0)
; #define PG8_LDA(dst, b, h) do { _Pragma("unroll") for (int m = 0; m < 4; ++m) _Pragma("unroll") for (int k = 0; k < 2; ++k) dst[m][k] = *(const LAS bf16x8*)(lds + PG8_SA(b, h) + aoff + m * 2048 + k * 1024); } while (0)
; #define PG8_LDB(dst, b, h) do { _Pragma("unroll") for (int n = 0; n < 2; ++n) _Pragma("unroll") for (int k = 0; k < 2; ++k) dst[n][k] = *(const LAS bf16x8*)(lds + PG8_SB(b, h) + boff + n * 2048 + k * 1024); } while (0)
; #define PG8_MMA(ai, bj, At, Bt) do { __builtin_amdgcn_s_setprio(1); _Pragma("unroll") for (int m = 0; m < 4; ++m) _Pragma("unroll") for (int n = 0; n < 2; ++n) _Pragma("unroll") for (int k = 0; k < 2; ++k) \
;         acc[ai][bj][m][n] = __builtin_amdgcn_mfma_f32_16x16x32_bf16(Bt[n][k], At[m][k], acc[ai][bj][m][n], 0, 0, 0); __builtin_amdgcn_s_setprio(0); } while (0)
; #define PG8_WAIT_L(n) asm volatile("s_waitcnt lgkmcnt(" #n ")" ::: "memory")
; #define PG8_BAR __builtin_amdgcn_s_barrier()
; #define PG8_SCHED __builtin_amdgcn_sched_barrier(0)
; template <class Epi>
; DEVINL void gemm_phase(LAS unsigned char* lds, const Gemm g, const Order& S, const Epi& E) {
;     ...
;             PG8_LDB(B0, 0, 0); PG8_SCHED; PG8_LDA(At, 0, 0); PG8_STAGE(PG8_SA(1, 1), a1 + hstepA, voffA);
;             PG8_WAIT_L(8); PG8_BAR; PG8_WAIT_L(0); PG8_MMA(0, 0, At, B0); PG8_BAR; PG8_SCHED;
;             PG8_LDB(B1, 0, 1); PG8_STAGE(PG8_SB(0, 0), b2, voffB);
;             PG8_BAR; PG8_WAIT_L(0); PG8_MMA(0, 1, At, B1); PG8_BAR;
;             PG8_LDA(At, 0, 1); PG8_STAGE(PG8_SA(0, 0), a2, voffA);
;             PG8_BAR; PG8_WAIT_L(0); PG8_MMA(1, 0, At, B0); PG8_BAR; PG8_SCHED;
.LBB0_986:
	ds_read_b128 v[150:153], v147
	ds_read_b128 v[154:157], v147 offset:1024
	ds_read_b128 v[158:161], v147 offset:2048
	ds_read_b128 v[162:165], v147 offset:3072
	s_add_i32 s69, s46, 2
	s_add_u32 s2, s4, 0xffff0080
	s_addc_u32 s3, s5, -1
	s_cmp_eq_u32 s54, s46
	s_cselect_b32 s46, s66, s67
	s_cselect_b32 s49, s11, s3
	s_cselect_b32 s48, s13, s2
	s_cselect_b32 s47, s65, s68
	v_lshl_add_u64 v[198:199], s[4:5], 0, v[136:137]
	s_add_i32 m0, s30, 0xc000
	ds_read_b128 v[166:169], v148
	ds_read_b128 v[170:173], v148 offset:1024
	ds_read_b128 v[174:177], v148 offset:2048
	ds_read_b128 v[178:181], v148 offset:3072
	ds_read_b128 v[182:185], v148 offset:4096
	ds_read_b128 v[186:189], v148 offset:5120
	ds_read_b128 v[190:193], v148 offset:6144
	ds_read_b128 v[194:197], v148 offset:7168
	global_load_lds_dwordx4 v[198:199], off
	v_lshl_add_u64 v[198:199], s[4:5], 0, v[138:139]
	s_add_i32 m0, s30, 0xe000
	s_nop 0
	global_load_lds_dwordx4 v[198:199], off
	s_waitcnt lgkmcnt(8)
	s_barrier
	s_waitcnt lgkmcnt(0)
	s_setprio 1
	s_waitcnt lgkmcnt(0)
	v_mfma_f32_16x16x32_bf16 v[124:127], v[150:153], v[166:169], v[124:127]
	v_mfma_f32_16x16x32_bf16 v[120:123], v[158:161], v[166:169], v[120:123]
	v_mfma_f32_16x16x32_bf16 v[112:115], v[158:161], v[174:177], v[112:115]
	v_mfma_f32_16x16x32_bf16 v[116:119], v[150:153], v[174:177], v[116:119]
	v_mfma_f32_16x16x32_bf16 v[108:111], v[150:153], v[182:185], v[108:111]
	v_mfma_f32_16x16x32_bf16 v[104:107], v[158:161], v[182:185], v[104:107]
	v_mfma_f32_16x16x32_bf16 v[96:99], v[158:161], v[190:193], v[96:99]
	v_mfma_f32_16x16x32_bf16 v[100:103], v[150:153], v[190:193], v[100:103]
	v_mfma_f32_16x16x32_bf16 v[124:127], v[154:157], v[170:173], v[124:127]
	v_mfma_f32_16x16x32_bf16 v[120:123], v[162:165], v[170:173], v[120:123]
	v_mfma_f32_16x16x32_bf16 v[112:115], v[162:165], v[178:181], v[112:115]
	v_mfma_f32_16x16x32_bf16 v[116:119], v[154:157], v[178:181], v[116:119]
	v_mfma_f32_16x16x32_bf16 v[108:111], v[154:157], v[186:189], v[108:111]
	v_mfma_f32_16x16x32_bf16 v[104:107], v[162:165], v[186:189], v[104:107]
	v_mfma_f32_16x16x32_bf16 v[96:99], v[162:165], v[194:197], v[96:99]
	v_mfma_f32_16x16x32_bf16 v[100:103], v[154:157], v[194:197], v[100:103]
	s_setprio 0
	s_barrier
	s_add_i32 s2, s58, s29
	v_lshl_add_u64 v[218:219], s[46:47], 0, v[130:131]
	s_mov_b32 m0, s2
	ds_read_b128 v[198:201], v149
	ds_read_b128 v[202:205], v149 offset:1024
	ds_read_b128 v[206:209], v149 offset:2048
	ds_read_b128 v[210:213], v149 offset:3072
	global_load_lds_dwordx4 v[218:219], off
	v_lshl_add_u64 v[220:221], s[46:47], 0, v[134:135]
	s_add_i32 m0, s2, 0x2000
	s_nop 0
	global_load_lds_dwordx4 v[220:221], off
	s_barrier
	s_waitcnt lgkmcnt(0)
	s_setprio 1
	s_waitcnt lgkmcnt(0)
	v_mfma_f32_16x16x32_bf16 v[60:63], v[198:201], v[166:169], v[60:63]
	v_mfma_f32_16x16x32_bf16 v[56:59], v[206:209], v[166:169], v[56:59]
	v_mfma_f32_16x16x32_bf16 v[48:51], v[206:209], v[174:177], v[48:51]
	v_mfma_f32_16x16x32_bf16 v[52:55], v[198:201], v[174:177], v[52:55]
	v_mfma_f32_16x16x32_bf16 v[44:47], v[198:201], v[182:185], v[44:47]
	v_mfma_f32_16x16x32_bf16 v[40:43], v[206:209], v[182:185], v[40:43]
	v_mfma_f32_16x16x32_bf16 v[32:35], v[206:209], v[190:193], v[32:35]
	v_mfma_f32_16x16x32_bf16 v[36:39], v[198:201], v[190:193], v[36:39]
	v_mfma_f32_16x16x32_bf16 v[60:63], v[202:205], v[170:173], v[60:63]
	v_mfma_f32_16x16x32_bf16 v[56:59], v[210:213], v[170:173], v[56:59]
	v_mfma_f32_16x16x32_bf16 v[48:51], v[210:213], v[178:181], v[48:51]
	v_mfma_f32_16x16x32_bf16 v[52:55], v[202:205], v[178:181], v[52:55]
	v_mfma_f32_16x16x32_bf16 v[44:47], v[202:205], v[186:189], v[44:47]
	v_mfma_f32_16x16x32_bf16 v[40:43], v[210:213], v[186:189], v[40:43]
	v_mfma_f32_16x16x32_bf16 v[32:35], v[210:213], v[194:197], v[32:35]
	v_mfma_f32_16x16x32_bf16 v[36:39], v[202:205], v[194:197], v[36:39]
	s_setprio 0
	s_mov_b32 m0, s30
	v_lshl_add_u64 v[222:223], s[48:49], 0, v[128:129]
	s_barrier
	ds_read_b128 v[166:169], v148 offset:16384
	ds_read_b128 v[170:173], v148 offset:17408
	ds_read_b128 v[174:177], v148 offset:18432
	ds_read_b128 v[178:181], v148 offset:19456
	ds_read_b128 v[182:185], v148 offset:20480
	ds_read_b128 v[186:189], v148 offset:21504
	ds_read_b128 v[190:193], v148 offset:22528
	ds_read_b128 v[194:197], v148 offset:23552
	global_load_lds_dwordx4 v[222:223], off
	v_lshl_add_u64 v[224:225], s[48:49], 0, v[132:133]
	s_mov_b32 m0, s31
	s_nop 0
	global_load_lds_dwordx4 v[224:225], off
	s_barrier
	s_waitcnt lgkmcnt(0)
	s_setprio 1
	s_waitcnt lgkmcnt(0)
	v_mfma_f32_16x16x32_bf16 v[92:95], v[150:153], v[166:169], v[92:95]
	v_mfma_f32_16x16x32_bf16 v[88:91], v[158:161], v[166:169], v[88:91]
	v_mfma_f32_16x16x32_bf16 v[80:83], v[158:161], v[174:177], v[80:83]
	v_mfma_f32_16x16x32_bf16 v[84:87], v[150:153], v[174:177], v[84:87]
	v_mfma_f32_16x16x32_bf16 v[76:79], v[150:153], v[182:185], v[76:79]
	v_mfma_f32_16x16x32_bf16 v[72:75], v[158:161], v[182:185], v[72:75]
	v_mfma_f32_16x16x32_bf16 v[64:67], v[158:161], v[190:193], v[64:67]
	v_mfma_f32_16x16x32_bf16 v[68:71], v[150:153], v[190:193], v[68:71]
	v_mfma_f32_16x16x32_bf16 v[92:95], v[154:157], v[170:173], v[92:95]
	v_mfma_f32_16x16x32_bf16 v[88:91], v[162:165], v[170:173], v[88:91]
	v_mfma_f32_16x16x32_bf16 v[80:83], v[162:165], v[178:181], v[80:83]
	v_mfma_f32_16x16x32_bf16 v[84:87], v[154:157], v[178:181], v[84:87]
	v_mfma_f32_16x16x32_bf16 v[76:79], v[154:157], v[186:189], v[76:79]
	v_mfma_f32_16x16x32_bf16 v[72:75], v[162:165], v[186:189], v[72:75]
	v_mfma_f32_16x16x32_bf16 v[64:67], v[162:165], v[194:197], v[64:67]
	v_mfma_f32_16x16x32_bf16 v[68:71], v[154:157], v[194:197], v[68:71]
	s_setprio 0
	s_barrier
; #define PG8_STAGE(bufoff, gbase, voff) do { _Pragma("unroll") for (int _i = 0; _i < 2; ++_i) \
;         __builtin_amdgcn_global_load_lds((const unsigned*)((const char*)(gbase) + (voff)[_i]), (LAS unsigned*)(lds + (bufoff) + ldsw + _i * 8192), 16, 0, 0); } while (0)
; #define PG8_LDA(dst, b, h) do { _Pragma("unroll") for (int m = 0; m < 4; ++m) _Pragma("unroll") for (int k = 0; k < 2; ++k) dst[m][k] = *(const LAS bf16x8*)(lds + PG8_SA(b, h) + aoff + m * 2048 + k * 1024); } while (0)
; #define PG8_LDB(dst, b, h) do { _Pragma("unroll") for (int n = 0; n < 2; ++n) _Pragma("unroll") for (int k = 0; k < 2; ++k) dst[n][k] = *(const LAS bf16x8*)(lds + PG8_SB(b, h) + boff + n * 2048 + k * 1024); } while (0)
; #define PG8_MMA(ai, bj, At, Bt) do { __builtin_amdgcn_s_setprio(1); _Pragma("unroll") for (int m = 0; m < 4; ++m) _Pragma("unroll") for (int n = 0; n < 2; ++n) _Pragma("unroll") for (int k = 0; k < 2; ++k) \
;         acc[ai][bj][m][n] = __builtin_amdgcn_mfma_f32_16x16x32_bf16(Bt[n][k], At[m][k], acc[ai][bj][m][n], 0, 0, 0); __builtin_amdgcn_s_setprio(0); } while (0)
; #define PG8_WAIT_V(n) asm volatile("s_waitcnt vmcnt(" #n ")" ::: "memory")
; #define PG8_WAIT_L(n) asm volatile("s_waitcnt lgkmcnt(" #n ")" ::: "memory")
; #define PG8_BAR __builtin_amdgcn_s_barrier()
; #define PG8_SCHED __builtin_amdgcn_sched_barrier(0)
; template <class Epi>
; DEVINL void gemm_phase(LAS unsigned char* lds, const Gemm g, const Order& S, const Epi& E) {
;     ...
;             PG8_STAGE(PG8_SB(0, 1), b2 + hstepB, voffB);
;             PG8_WAIT_V(6); PG8_BAR; PG8_MMA(1, 1, At, B1); PG8_BAR;
;             PG8_LDB(B0, 1, 0); PG8_SCHED; PG8_LDA(At, 1, 0); PG8_STAGE(PG8_SA(0, 1), a2 + hstepA, voffA);
;             PG8_WAIT_L(8); PG8_BAR; PG8_WAIT_L(0); PG8_MMA(0, 0, At, B0); PG8_BAR; PG8_SCHED;
;             PG8_LDB(B1, 1, 1); PG8_STAGE(PG8_SB(1, 0), b3, voffB);
	s_add_u32 s2, s46, 0x10000
	s_addc_u32 s3, s47, 0
	s_add_i32 s70, s59, s29
	v_lshl_add_u64 v[150:151], s[2:3], 0, v[130:131]
	s_mov_b32 m0, s70
	s_nop 0
	global_load_lds_dwordx4 v[150:151], off
	v_lshl_add_u64 v[150:151], s[2:3], 0, v[134:135]
	s_add_i32 m0, s70, 0x2000
	s_nop 0
	global_load_lds_dwordx4 v[150:151], off
	s_waitcnt vmcnt(6)
	s_barrier
	s_setprio 1
	v_mfma_f32_16x16x32_bf16 v[28:31], v[198:201], v[166:169], v[28:31]
	v_mfma_f32_16x16x32_bf16 v[24:27], v[206:209], v[166:169], v[24:27]
	v_mfma_f32_16x16x32_bf16 v[16:19], v[206:209], v[174:177], v[16:19]
	v_mfma_f32_16x16x32_bf16 v[20:23], v[198:201], v[174:177], v[20:23]
	v_mfma_f32_16x16x32_bf16 v[12:15], v[198:201], v[182:185], v[12:15]
	v_mfma_f32_16x16x32_bf16 v[8:11], v[206:209], v[182:185], v[8:11]
	v_mfma_f32_16x16x32_bf16 v[0:3], v[206:209], v[190:193], v[0:3]
	v_mfma_f32_16x16x32_bf16 v[4:7], v[198:201], v[190:193], v[4:7]
	v_mfma_f32_16x16x32_bf16 v[28:31], v[202:205], v[170:173], v[28:31]
	v_mfma_f32_16x16x32_bf16 v[24:27], v[210:213], v[170:173], v[24:27]
	v_mfma_f32_16x16x32_bf16 v[16:19], v[210:213], v[178:181], v[16:19]
	v_mfma_f32_16x16x32_bf16 v[20:23], v[202:205], v[178:181], v[20:23]
	v_mfma_f32_16x16x32_bf16 v[12:15], v[202:205], v[186:189], v[12:15]
	v_mfma_f32_16x16x32_bf16 v[8:11], v[210:213], v[186:189], v[8:11]
	v_mfma_f32_16x16x32_bf16 v[0:3], v[210:213], v[194:197], v[0:3]
	v_mfma_f32_16x16x32_bf16 v[4:7], v[202:205], v[194:197], v[4:7]
	s_setprio 0
	s_add_i32 s70, 16, 0x18000
	v_add_u32_e32 v162, s70, v145
	s_barrier
	ds_read_b128 v[150:153], v162
	ds_read_b128 v[154:157], v162 offset:1024
	ds_read_b128 v[158:161], v162 offset:2048
	ds_read_b128 v[162:165], v162 offset:3072
	s_add_u32 s2, s48, 0x10000
	s_addc_u32 s3, s49, 0
	s_mov_b32 m0, s45
	v_lshl_add_u64 v[198:199], s[2:3], 0, v[128:129]
	ds_read_b128 v[166:169], v148 offset:32768
	ds_read_b128 v[170:173], v148 offset:33792
	ds_read_b128 v[174:177], v148 offset:34816
	ds_read_b128 v[178:181], v148 offset:35840
	ds_read_b128 v[182:185], v148 offset:36864
	ds_read_b128 v[186:189], v148 offset:37888
	ds_read_b128 v[190:193], v148 offset:38912
	ds_read_b128 v[194:197], v148 offset:39936
	global_load_lds_dwordx4 v[198:199], off
	v_lshl_add_u64 v[198:199], s[2:3], 0, v[132:133]
	s_mov_b32 m0, s50
	s_nop 0
	global_load_lds_dwordx4 v[198:199], off
	s_waitcnt lgkmcnt(8)
	s_barrier
	s_waitcnt lgkmcnt(0)
	s_setprio 1
	s_waitcnt lgkmcnt(0)
	v_mfma_f32_16x16x32_bf16 v[124:127], v[150:153], v[166:169], v[124:127]
	v_mfma_f32_16x16x32_bf16 v[120:123], v[158:161], v[166:169], v[120:123]
	v_mfma_f32_16x16x32_bf16 v[112:115], v[158:161], v[174:177], v[112:115]
	v_mfma_f32_16x16x32_bf16 v[116:119], v[150:153], v[174:177], v[116:119]
	v_mfma_f32_16x16x32_bf16 v[108:111], v[150:153], v[182:185], v[108:111]
	v_mfma_f32_16x16x32_bf16 v[104:107], v[158:161], v[182:185], v[104:107]
	v_mfma_f32_16x16x32_bf16 v[96:99], v[158:161], v[190:193], v[96:99]
	v_mfma_f32_16x16x32_bf16 v[100:103], v[150:153], v[190:193], v[100:103]
	v_mfma_f32_16x16x32_bf16 v[124:127], v[154:157], v[170:173], v[124:127]
	v_mfma_f32_16x16x32_bf16 v[120:123], v[162:165], v[170:173], v[120:123]
	v_mfma_f32_16x16x32_bf16 v[112:115], v[162:165], v[178:181], v[112:115]
	v_mfma_f32_16x16x32_bf16 v[116:119], v[154:157], v[178:181], v[116:119]
	v_mfma_f32_16x16x32_bf16 v[108:111], v[154:157], v[186:189], v[108:111]
	v_mfma_f32_16x16x32_bf16 v[104:107], v[162:165], v[186:189], v[104:107]
	v_mfma_f32_16x16x32_bf16 v[96:99], v[162:165], v[194:197], v[96:99]
	v_mfma_f32_16x16x32_bf16 v[100:103], v[154:157], v[194:197], v[100:103]
	s_setprio 0
	s_barrier
	s_add_i32 s48, 16, 0x1c000
	s_add_i32 s2, s70, s29
	v_add_u32_e32 v210, s48, v145
	v_lshl_add_u64 v[218:219], v[218:219], 0, s[6:7]
	s_mov_b32 m0, s2
	ds_read_b128 v[198:201], v210
	ds_read_b128 v[202:205], v210 offset:1024
	ds_read_b128 v[206:209], v210 offset:2048
	ds_read_b128 v[210:213], v210 offset:3072
	global_load_lds_dwordx4 v[218:219], off
	v_lshl_add_u64 v[218:219], v[220:221], 0, s[6:7]
	s_add_i32 m0, s2, 0x2000
	s_nop 0
	global_load_lds_dwordx4 v[218:219], off
	s_barrier
; #define PG8_STAGE(bufoff, gbase, voff) do { _Pragma("unroll") for (int _i = 0; _i < 2; ++_i) \
;         __builtin_amdgcn_global_load_lds((const unsigned*)((const char*)(gbase) + (voff)[_i]), (LAS unsigned*)(lds + (bufoff) + ldsw + _i * 8192), 16, 0, 0); } while (0)
; #define PG8_LDA(dst, b, h) do { _Pragma("unroll") for (int m = 0; m < 4; ++m) _Pragma("unroll") for (int k = 0; k < 2; ++k) dst[m][k] = *(const LAS bf16x8*)(lds + PG8_SA(b, h) + aoff + m * 2048 + k * 1024); } while (0)
; #define PG8_MMA(ai, bj, At, Bt) do { __builtin_amdgcn_s_setprio(1); _Pragma("unroll") for (int m = 0; m < 4; ++m) _Pragma("unroll") for (int n = 0; n < 2; ++n) _Pragma("unroll") for (int k = 0; k < 2; ++k) \
;         acc[ai][bj][m][n] = __builtin_amdgcn_mfma_f32_16x16x32_bf16(Bt[n][k], At[m][k], acc[ai][bj][m][n], 0, 0, 0); __builtin_amdgcn_s_setprio(0); } while (0)
; #define PG8_WAIT_V(n) asm volatile("s_waitcnt vmcnt(" #n ")" ::: "memory")
; #define PG8_WAIT_L(n) asm volatile("s_waitcnt lgkmcnt(" #n ")" ::: "memory")
; #define PG8_BAR __builtin_amdgcn_s_barrier()
; #define PG8_SCHED __builtin_amdgcn_sched_barrier(0)
; template <class Epi>
; DEVINL void gemm_phase(LAS unsigned char* lds, const Gemm g, const Order& S, const Epi& E) {
;     ...
;             PG8_BAR; PG8_WAIT_L(0); PG8_MMA(0, 1, At, B1); PG8_BAR;
;             PG8_LDA(At, 1, 1); PG8_STAGE(PG8_SA(1, 0), a3, voffA);
;             PG8_BAR; PG8_WAIT_L(0); PG8_MMA(1, 0, At, B0); PG8_BAR; PG8_SCHED;
;             PG8_STAGE(PG8_SB(1, 1), b3 + hstepB, voffB);
;             PG8_WAIT_V(6); PG8_BAR; PG8_MMA(1, 1, At, B1); PG8_BAR;
;         }
	s_waitcnt lgkmcnt(0)
	s_setprio 1
	s_waitcnt lgkmcnt(0)
	v_mfma_f32_16x16x32_bf16 v[60:63], v[198:201], v[166:169], v[60:63]
	v_mfma_f32_16x16x32_bf16 v[56:59], v[206:209], v[166:169], v[56:59]
	v_mfma_f32_16x16x32_bf16 v[48:51], v[206:209], v[174:177], v[48:51]
	v_mfma_f32_16x16x32_bf16 v[52:55], v[198:201], v[174:177], v[52:55]
	v_mfma_f32_16x16x32_bf16 v[44:47], v[198:201], v[182:185], v[44:47]
	v_mfma_f32_16x16x32_bf16 v[40:43], v[206:209], v[182:185], v[40:43]
	v_mfma_f32_16x16x32_bf16 v[32:35], v[206:209], v[190:193], v[32:35]
	v_mfma_f32_16x16x32_bf16 v[36:39], v[198:201], v[190:193], v[36:39]
	v_mfma_f32_16x16x32_bf16 v[60:63], v[202:205], v[170:173], v[60:63]
	v_mfma_f32_16x16x32_bf16 v[56:59], v[210:213], v[170:173], v[56:59]
	v_mfma_f32_16x16x32_bf16 v[48:51], v[210:213], v[178:181], v[48:51]
	v_mfma_f32_16x16x32_bf16 v[52:55], v[202:205], v[178:181], v[52:55]
	v_mfma_f32_16x16x32_bf16 v[44:47], v[202:205], v[186:189], v[44:47]
	v_mfma_f32_16x16x32_bf16 v[40:43], v[210:213], v[186:189], v[40:43]
	v_mfma_f32_16x16x32_bf16 v[32:35], v[210:213], v[194:197], v[32:35]
	v_mfma_f32_16x16x32_bf16 v[36:39], v[202:205], v[194:197], v[36:39]
	s_setprio 0
	s_mov_b32 m0, s52
	v_lshl_add_u64 v[218:219], v[222:223], 0, s[6:7]
	s_barrier
	ds_read_b128 v[166:169], v148 offset:49152
	ds_read_b128 v[170:173], v148 offset:50176
	ds_read_b128 v[174:177], v148 offset:51200
	ds_read_b128 v[178:181], v148 offset:52224
	ds_read_b128 v[182:185], v148 offset:53248
	ds_read_b128 v[186:189], v148 offset:54272
	ds_read_b128 v[190:193], v148 offset:55296
	ds_read_b128 v[194:197], v148 offset:56320
	global_load_lds_dwordx4 v[218:219], off
	v_lshl_add_u64 v[218:219], v[224:225], 0, s[6:7]
	s_mov_b32 m0, s53
	s_nop 0
	global_load_lds_dwordx4 v[218:219], off
	s_barrier
	s_waitcnt lgkmcnt(0)
	s_setprio 1
	s_waitcnt lgkmcnt(0)
	v_mfma_f32_16x16x32_bf16 v[92:95], v[150:153], v[166:169], v[92:95]
	v_mfma_f32_16x16x32_bf16 v[88:91], v[158:161], v[166:169], v[88:91]
	v_mfma_f32_16x16x32_bf16 v[80:83], v[158:161], v[174:177], v[80:83]
	v_mfma_f32_16x16x32_bf16 v[84:87], v[150:153], v[174:177], v[84:87]
	v_mfma_f32_16x16x32_bf16 v[76:79], v[150:153], v[182:185], v[76:79]
	v_mfma_f32_16x16x32_bf16 v[72:75], v[158:161], v[182:185], v[72:75]
	v_mfma_f32_16x16x32_bf16 v[64:67], v[158:161], v[190:193], v[64:67]
	v_mfma_f32_16x16x32_bf16 v[68:71], v[150:153], v[190:193], v[68:71]
	v_mfma_f32_16x16x32_bf16 v[92:95], v[154:157], v[170:173], v[92:95]
	v_mfma_f32_16x16x32_bf16 v[88:91], v[162:165], v[170:173], v[88:91]
	v_mfma_f32_16x16x32_bf16 v[80:83], v[162:165], v[178:181], v[80:83]
	v_mfma_f32_16x16x32_bf16 v[84:87], v[154:157], v[178:181], v[84:87]
	v_mfma_f32_16x16x32_bf16 v[76:79], v[154:157], v[186:189], v[76:79]
	v_mfma_f32_16x16x32_bf16 v[72:75], v[162:165], v[186:189], v[72:75]
	v_mfma_f32_16x16x32_bf16 v[64:67], v[162:165], v[194:197], v[64:67]
	v_mfma_f32_16x16x32_bf16 v[68:71], v[154:157], v[194:197], v[68:71]
	s_setprio 0
	s_barrier
	s_add_u32 s2, s46, 0x10080
	s_addc_u32 s3, s47, 0
	s_add_i32 s46, s48, s29
	v_lshl_add_u64 v[150:151], s[2:3], 0, v[130:131]
	s_mov_b32 m0, s46
	s_nop 0
	global_load_lds_dwordx4 v[150:151], off
	v_lshl_add_u64 v[150:151], s[2:3], 0, v[134:135]
	s_add_i32 m0, s46, 0x2000
	s_nop 0
	global_load_lds_dwordx4 v[150:151], off
	s_waitcnt vmcnt(6)
	s_barrier
	s_setprio 1
	v_mfma_f32_16x16x32_bf16 v[28:31], v[198:201], v[166:169], v[28:31]
	v_mfma_f32_16x16x32_bf16 v[24:27], v[206:209], v[166:169], v[24:27]
	v_mfma_f32_16x16x32_bf16 v[16:19], v[206:209], v[174:177], v[16:19]
	v_mfma_f32_16x16x32_bf16 v[20:23], v[198:201], v[174:177], v[20:23]
	v_mfma_f32_16x16x32_bf16 v[12:15], v[198:201], v[182:185], v[12:15]
	v_mfma_f32_16x16x32_bf16 v[8:11], v[206:209], v[182:185], v[8:11]
	v_mfma_f32_16x16x32_bf16 v[0:3], v[206:209], v[190:193], v[0:3]
	v_mfma_f32_16x16x32_bf16 v[4:7], v[198:201], v[190:193], v[4:7]
	v_mfma_f32_16x16x32_bf16 v[28:31], v[202:205], v[170:173], v[28:31]
	v_mfma_f32_16x16x32_bf16 v[24:27], v[210:213], v[170:173], v[24:27]
	v_mfma_f32_16x16x32_bf16 v[16:19], v[210:213], v[178:181], v[16:19]
	v_mfma_f32_16x16x32_bf16 v[20:23], v[202:205], v[178:181], v[20:23]
	v_mfma_f32_16x16x32_bf16 v[12:15], v[202:205], v[186:189], v[12:15]
	v_mfma_f32_16x16x32_bf16 v[8:11], v[210:213], v[186:189], v[8:11]
	v_mfma_f32_16x16x32_bf16 v[0:3], v[210:213], v[194:197], v[0:3]
	v_mfma_f32_16x16x32_bf16 v[4:7], v[202:205], v[194:197], v[4:7]
	s_setprio 0
	s_add_u32 s4, s4, 0x100
	s_addc_u32 s5, s5, 0
	s_add_u32 s67, s67, 0x100
	s_addc_u32 s68, s68, 0
	s_cmp_ge_i32 s69, s51
	s_mov_b32 s46, s69
	s_barrier
	s_cbranch_scc0 .LBB0_986
	v_readlane_b32 s66, v251, 56
	v_readlane_b32 s67, v251, 57
	s_branch .LBB0_977

; #define PG8_STAGE(bufoff, gbase, voff) do { _Pragma("unroll") for (int _i = 0; _i < 2; ++_i) \
;         __builtin_amdgcn_global_load_lds((const unsigned*)((const char*)(gbase) + (voff)[_i]), (LAS unsigned*)(lds + (bufoff) + ldsw + _i * 8192), 16, 0, 0); } while (0)
; #define PG8_LDA(dst, b, h) do { _Pragma("unroll") for (int m = 0; m < 4; ++m) _Pragma("unroll") for (int k = 0; k < 2; ++k) dst[m][k] = *(const LAS bf16x8*)(lds + PG8_SA(b, h) + aoff + m * 2048 + k * 1024); } while (0)
; #define PG8_LDB(dst, b, h) do { _Pragma("unroll") for (int n = 0; n < 2; ++n) _Pragma("unroll") for (int k = 0; k < 2; ++k) dst[n][k] = *(const LAS bf16x8*)(lds + PG8_SB(b, h) + boff + n * 2048 + k * 1024); } while (0)
; #define PG8_MMA(ai, bj, At, Bt) do { __builtin_amdgcn_s_setprio(1); _Pragma("unroll") for (int m = 0; m < 4; ++m) _Pragma("unroll") for (int n = 0; n < 2; ++n) _Pragma("unroll") for (int k = 0; k < 2; ++k) \
;         acc[ai][bj][m][n] = __builtin_amdgcn_mfma_f32_16x16x32_bf16(Bt[n][k], At[m][k], acc[ai][bj][m][n], 0, 0, 0); __builtin_amdgcn_s_setprio(0); } while (0)
; #define PG8_WAIT_L(n) asm volatile("s_waitcnt lgkmcnt(" #n ")" ::: "memory")
; #define PG8_BAR __builtin_amdgcn_s_barrier()
; #define PG8_SCHED __builtin_amdgcn_sched_barrier(0)
; template <class Epi>
; DEVINL void gemm_phase(LAS unsigned char* lds, const Gemm g, const Order& S, const Epi& E) {
;     ...
;             PG8_LDB(B0, 0, 0); PG8_SCHED; PG8_LDA(At, 0, 0); PG8_STAGE(PG8_SA(1, 1), a1 + hstepA, voffA);
;             PG8_WAIT_L(8); PG8_BAR; PG8_WAIT_L(0); PG8_MMA(0, 0, At, B0); PG8_BAR; PG8_SCHED;
;             PG8_LDB(B1, 0, 1); PG8_STAGE(PG8_SB(0, 0), b2, voffB);
;             PG8_BAR; PG8_WAIT_L(0); PG8_MMA(0, 1, At, B1); PG8_BAR;
;             PG8_LDA(At, 0, 1); PG8_STAGE(PG8_SA(0, 0), a2, voffA);
;             PG8_BAR; PG8_WAIT_L(0); PG8_MMA(1, 0, At, B0); PG8_BAR; PG8_SCHED;
.LBB0_1008:
	ds_read_b128 v[150:153], v147
	ds_read_b128 v[154:157], v147 offset:1024
	ds_read_b128 v[158:161], v147 offset:2048
	ds_read_b128 v[162:165], v147 offset:3072
	s_add_i32 s68, s46, 2
	s_add_u32 s47, s4, 0xffff0080
	s_addc_u32 s48, s5, -1
	s_cmp_eq_u32 s26, s46
	s_cselect_b32 s46, s13, s66
	s_cselect_b32 s49, s2, s48
	s_cselect_b32 s48, s3, s47
	s_cselect_b32 s47, s11, s67
	v_lshl_add_u64 v[198:199], s[4:5], 0, v[136:137]
	s_add_i32 m0, s45, 0xc000
	ds_read_b128 v[166:169], v148
	ds_read_b128 v[170:173], v148 offset:1024
	ds_read_b128 v[174:177], v148 offset:2048
	ds_read_b128 v[178:181], v148 offset:3072
	ds_read_b128 v[182:185], v148 offset:4096
	ds_read_b128 v[186:189], v148 offset:5120
	ds_read_b128 v[190:193], v148 offset:6144
	ds_read_b128 v[194:197], v148 offset:7168
	global_load_lds_dwordx4 v[198:199], off
	v_lshl_add_u64 v[198:199], s[4:5], 0, v[138:139]
	s_add_i32 m0, s45, 0xe000
	s_nop 0
	global_load_lds_dwordx4 v[198:199], off
	s_waitcnt lgkmcnt(8)
	s_barrier
	s_waitcnt lgkmcnt(0)
	s_setprio 1
	s_waitcnt lgkmcnt(0)
	v_mfma_f32_16x16x32_bf16 v[124:127], v[150:153], v[166:169], v[124:127]
	v_mfma_f32_16x16x32_bf16 v[120:123], v[158:161], v[166:169], v[120:123]
	v_mfma_f32_16x16x32_bf16 v[112:115], v[158:161], v[174:177], v[112:115]
	v_mfma_f32_16x16x32_bf16 v[116:119], v[150:153], v[174:177], v[116:119]
	v_mfma_f32_16x16x32_bf16 v[108:111], v[150:153], v[182:185], v[108:111]
	v_mfma_f32_16x16x32_bf16 v[104:107], v[158:161], v[182:185], v[104:107]
	v_mfma_f32_16x16x32_bf16 v[96:99], v[158:161], v[190:193], v[96:99]
	v_mfma_f32_16x16x32_bf16 v[100:103], v[150:153], v[190:193], v[100:103]
	v_mfma_f32_16x16x32_bf16 v[124:127], v[154:157], v[170:173], v[124:127]
	v_mfma_f32_16x16x32_bf16 v[120:123], v[162:165], v[170:173], v[120:123]
	v_mfma_f32_16x16x32_bf16 v[112:115], v[162:165], v[178:181], v[112:115]
	v_mfma_f32_16x16x32_bf16 v[116:119], v[154:157], v[178:181], v[116:119]
	v_mfma_f32_16x16x32_bf16 v[108:111], v[154:157], v[186:189], v[108:111]
	v_mfma_f32_16x16x32_bf16 v[104:107], v[162:165], v[186:189], v[104:107]
	v_mfma_f32_16x16x32_bf16 v[96:99], v[162:165], v[194:197], v[96:99]
	v_mfma_f32_16x16x32_bf16 v[100:103], v[154:157], v[194:197], v[100:103]
	s_setprio 0
	s_barrier
	s_add_i32 s69, s59, s31
	v_lshl_add_u64 v[218:219], s[46:47], 0, v[130:131]
	s_mov_b32 m0, s69
	ds_read_b128 v[198:201], v149
	ds_read_b128 v[202:205], v149 offset:1024
	ds_read_b128 v[206:209], v149 offset:2048
	ds_read_b128 v[210:213], v149 offset:3072
	global_load_lds_dwordx4 v[218:219], off
	v_lshl_add_u64 v[220:221], s[46:47], 0, v[134:135]
	s_add_i32 m0, s69, 0x2000
	s_nop 0
	global_load_lds_dwordx4 v[220:221], off
	s_barrier
	s_waitcnt lgkmcnt(0)
	s_setprio 1
	s_waitcnt lgkmcnt(0)
	v_mfma_f32_16x16x32_bf16 v[60:63], v[198:201], v[166:169], v[60:63]
	v_mfma_f32_16x16x32_bf16 v[56:59], v[206:209], v[166:169], v[56:59]
	v_mfma_f32_16x16x32_bf16 v[48:51], v[206:209], v[174:177], v[48:51]
	v_mfma_f32_16x16x32_bf16 v[52:55], v[198:201], v[174:177], v[52:55]
	v_mfma_f32_16x16x32_bf16 v[44:47], v[198:201], v[182:185], v[44:47]
	v_mfma_f32_16x16x32_bf16 v[40:43], v[206:209], v[182:185], v[40:43]
	v_mfma_f32_16x16x32_bf16 v[32:35], v[206:209], v[190:193], v[32:35]
	v_mfma_f32_16x16x32_bf16 v[36:39], v[198:201], v[190:193], v[36:39]
	v_mfma_f32_16x16x32_bf16 v[60:63], v[202:205], v[170:173], v[60:63]
	v_mfma_f32_16x16x32_bf16 v[56:59], v[210:213], v[170:173], v[56:59]
	v_mfma_f32_16x16x32_bf16 v[48:51], v[210:213], v[178:181], v[48:51]
	v_mfma_f32_16x16x32_bf16 v[52:55], v[202:205], v[178:181], v[52:55]
	v_mfma_f32_16x16x32_bf16 v[44:47], v[202:205], v[186:189], v[44:47]
	v_mfma_f32_16x16x32_bf16 v[40:43], v[210:213], v[186:189], v[40:43]
	v_mfma_f32_16x16x32_bf16 v[32:35], v[210:213], v[194:197], v[32:35]
	v_mfma_f32_16x16x32_bf16 v[36:39], v[202:205], v[194:197], v[36:39]
	s_setprio 0
	s_mov_b32 m0, s45
	v_lshl_add_u64 v[222:223], s[48:49], 0, v[128:129]
	s_barrier
	ds_read_b128 v[166:169], v148 offset:16384
	ds_read_b128 v[170:173], v148 offset:17408
	ds_read_b128 v[174:177], v148 offset:18432
	ds_read_b128 v[178:181], v148 offset:19456
	ds_read_b128 v[182:185], v148 offset:20480
	ds_read_b128 v[186:189], v148 offset:21504
	ds_read_b128 v[190:193], v148 offset:22528
	ds_read_b128 v[194:197], v148 offset:23552
	global_load_lds_dwordx4 v[222:223], off
	v_lshl_add_u64 v[224:225], s[48:49], 0, v[132:133]
	s_mov_b32 m0, s50
	s_nop 0
	global_load_lds_dwordx4 v[224:225], off
	s_barrier
	s_waitcnt lgkmcnt(0)
	s_setprio 1
	s_waitcnt lgkmcnt(0)
	v_mfma_f32_16x16x32_bf16 v[92:95], v[150:153], v[166:169], v[92:95]
	v_mfma_f32_16x16x32_bf16 v[88:91], v[158:161], v[166:169], v[88:91]
	v_mfma_f32_16x16x32_bf16 v[80:83], v[158:161], v[174:177], v[80:83]
	v_mfma_f32_16x16x32_bf16 v[84:87], v[150:153], v[174:177], v[84:87]
	v_mfma_f32_16x16x32_bf16 v[76:79], v[150:153], v[182:185], v[76:79]
	v_mfma_f32_16x16x32_bf16 v[72:75], v[158:161], v[182:185], v[72:75]
	v_mfma_f32_16x16x32_bf16 v[64:67], v[158:161], v[190:193], v[64:67]
	v_mfma_f32_16x16x32_bf16 v[68:71], v[150:153], v[190:193], v[68:71]
	v_mfma_f32_16x16x32_bf16 v[92:95], v[154:157], v[170:173], v[92:95]
	v_mfma_f32_16x16x32_bf16 v[88:91], v[162:165], v[170:173], v[88:91]
	v_mfma_f32_16x16x32_bf16 v[80:83], v[162:165], v[178:181], v[80:83]
	v_mfma_f32_16x16x32_bf16 v[84:87], v[154:157], v[178:181], v[84:87]
	v_mfma_f32_16x16x32_bf16 v[76:79], v[154:157], v[186:189], v[76:79]
	v_mfma_f32_16x16x32_bf16 v[72:75], v[162:165], v[186:189], v[72:75]
	v_mfma_f32_16x16x32_bf16 v[64:67], v[162:165], v[194:197], v[64:67]
	v_mfma_f32_16x16x32_bf16 v[68:71], v[154:157], v[194:197], v[68:71]
	s_setprio 0
	s_barrier
; #define PG8_STAGE(bufoff, gbase, voff) do { _Pragma("unroll") for (int _i = 0; _i < 2; ++_i) \
;         __builtin_amdgcn_global_load_lds((const unsigned*)((const char*)(gbase) + (voff)[_i]), (LAS unsigned*)(lds + (bufoff) + ldsw + _i * 8192), 16, 0, 0); } while (0)
; #define PG8_LDA(dst, b, h) do { _Pragma("unroll") for (int m = 0; m < 4; ++m) _Pragma("unroll") for (int k = 0; k < 2; ++k) dst[m][k] = *(const LAS bf16x8*)(lds + PG8_SA(b, h) + aoff + m * 2048 + k * 1024); } while (0)
; #define PG8_LDB(dst, b, h) do { _Pragma("unroll") for (int n = 0; n < 2; ++n) _Pragma("unroll") for (int k = 0; k < 2; ++k) dst[n][k] = *(const LAS bf16x8*)(lds + PG8_SB(b, h) + boff + n * 2048 + k * 1024); } while (0)
; #define PG8_MMA(ai, bj, At, Bt) do { __builtin_amdgcn_s_setprio(1); _Pragma("unroll") for (int m = 0; m < 4; ++m) _Pragma("unroll") for (int n = 0; n < 2; ++n) _Pragma("unroll") for (int k = 0; k < 2; ++k) \
;         acc[ai][bj][m][n] = __builtin_amdgcn_mfma_f32_16x16x32_bf16(Bt[n][k], At[m][k], acc[ai][bj][m][n], 0, 0, 0); __builtin_amdgcn_s_setprio(0); } while (0)
; #define PG8_WAIT_V(n) asm volatile("s_waitcnt vmcnt(" #n ")" ::: "memory")
; #define PG8_WAIT_L(n) asm volatile("s_waitcnt lgkmcnt(" #n ")" ::: "memory")
; #define PG8_BAR __builtin_amdgcn_s_barrier()
; #define PG8_SCHED __builtin_amdgcn_sched_barrier(0)
; template <class Epi>
; DEVINL void gemm_phase(LAS unsigned char* lds, const Gemm g, const Order& S, const Epi& E) {
;     ...
;             PG8_STAGE(PG8_SB(0, 1), b2 + hstepB, voffB);
;             PG8_WAIT_V(6); PG8_BAR; PG8_MMA(1, 1, At, B1); PG8_BAR;
;             PG8_LDB(B0, 1, 0); PG8_SCHED; PG8_LDA(At, 1, 0); PG8_STAGE(PG8_SA(0, 1), a2 + hstepA, voffA);
;             PG8_WAIT_L(8); PG8_BAR; PG8_WAIT_L(0); PG8_MMA(0, 0, At, B0); PG8_BAR; PG8_SCHED;
;             PG8_LDB(B1, 1, 1); PG8_STAGE(PG8_SB(1, 0), b3, voffB);
;             PG8_BAR; PG8_WAIT_L(0); PG8_MMA(0, 1, At, B1); PG8_BAR;
;             PG8_LDA(At, 1, 1); PG8_STAGE(PG8_SA(1, 0), a3, voffA);
	s_add_u32 s70, s46, 0x10000
	s_addc_u32 s71, s47, 0
	s_add_i32 s69, s64, s31
	v_lshl_add_u64 v[150:151], s[70:71], 0, v[130:131]
	s_mov_b32 m0, s69
	s_nop 0
	global_load_lds_dwordx4 v[150:151], off
	v_lshl_add_u64 v[150:151], s[70:71], 0, v[134:135]
	s_add_i32 m0, s69, 0x2000
	s_nop 0
	global_load_lds_dwordx4 v[150:151], off
	s_waitcnt vmcnt(6)
	s_barrier
	s_setprio 1
	v_mfma_f32_16x16x32_bf16 v[28:31], v[198:201], v[166:169], v[28:31]
	v_mfma_f32_16x16x32_bf16 v[24:27], v[206:209], v[166:169], v[24:27]
	v_mfma_f32_16x16x32_bf16 v[16:19], v[206:209], v[174:177], v[16:19]
	v_mfma_f32_16x16x32_bf16 v[20:23], v[198:201], v[174:177], v[20:23]
	v_mfma_f32_16x16x32_bf16 v[12:15], v[198:201], v[182:185], v[12:15]
	v_mfma_f32_16x16x32_bf16 v[8:11], v[206:209], v[182:185], v[8:11]
	v_mfma_f32_16x16x32_bf16 v[0:3], v[206:209], v[190:193], v[0:3]
	v_mfma_f32_16x16x32_bf16 v[4:7], v[198:201], v[190:193], v[4:7]
	v_mfma_f32_16x16x32_bf16 v[28:31], v[202:205], v[170:173], v[28:31]
	v_mfma_f32_16x16x32_bf16 v[24:27], v[210:213], v[170:173], v[24:27]
	v_mfma_f32_16x16x32_bf16 v[16:19], v[210:213], v[178:181], v[16:19]
	v_mfma_f32_16x16x32_bf16 v[20:23], v[202:205], v[178:181], v[20:23]
	v_mfma_f32_16x16x32_bf16 v[12:15], v[202:205], v[186:189], v[12:15]
	v_mfma_f32_16x16x32_bf16 v[8:11], v[210:213], v[186:189], v[8:11]
	v_mfma_f32_16x16x32_bf16 v[0:3], v[210:213], v[194:197], v[0:3]
	v_mfma_f32_16x16x32_bf16 v[4:7], v[202:205], v[194:197], v[4:7]
	s_setprio 0
	s_add_i32 s69, 16, 0x18000
	v_add_u32_e32 v162, s69, v145
	s_barrier
	ds_read_b128 v[150:153], v162
	ds_read_b128 v[154:157], v162 offset:1024
	ds_read_b128 v[158:161], v162 offset:2048
	ds_read_b128 v[162:165], v162 offset:3072
	s_add_u32 s48, s48, 0x10000
	s_addc_u32 s49, s49, 0
	s_mov_b32 m0, s51
	v_lshl_add_u64 v[198:199], s[48:49], 0, v[128:129]
	ds_read_b128 v[166:169], v148 offset:32768
	ds_read_b128 v[170:173], v148 offset:33792
	ds_read_b128 v[174:177], v148 offset:34816
	ds_read_b128 v[178:181], v148 offset:35840
	ds_read_b128 v[182:185], v148 offset:36864
	ds_read_b128 v[186:189], v148 offset:37888
	ds_read_b128 v[190:193], v148 offset:38912
	ds_read_b128 v[194:197], v148 offset:39936
	global_load_lds_dwordx4 v[198:199], off
	v_lshl_add_u64 v[198:199], s[48:49], 0, v[132:133]
	s_mov_b32 m0, s52
	s_nop 0
	global_load_lds_dwordx4 v[198:199], off
	s_waitcnt lgkmcnt(8)
	s_barrier
	s_waitcnt lgkmcnt(0)
	s_setprio 1
	s_waitcnt lgkmcnt(0)
	v_mfma_f32_16x16x32_bf16 v[124:127], v[150:153], v[166:169], v[124:127]
	v_mfma_f32_16x16x32_bf16 v[120:123], v[158:161], v[166:169], v[120:123]
	v_mfma_f32_16x16x32_bf16 v[112:115], v[158:161], v[174:177], v[112:115]
	v_mfma_f32_16x16x32_bf16 v[116:119], v[150:153], v[174:177], v[116:119]
	v_mfma_f32_16x16x32_bf16 v[108:111], v[150:153], v[182:185], v[108:111]
	v_mfma_f32_16x16x32_bf16 v[104:107], v[158:161], v[182:185], v[104:107]
	v_mfma_f32_16x16x32_bf16 v[96:99], v[158:161], v[190:193], v[96:99]
	v_mfma_f32_16x16x32_bf16 v[100:103], v[150:153], v[190:193], v[100:103]
	v_mfma_f32_16x16x32_bf16 v[124:127], v[154:157], v[170:173], v[124:127]
	v_mfma_f32_16x16x32_bf16 v[120:123], v[162:165], v[170:173], v[120:123]
	v_mfma_f32_16x16x32_bf16 v[112:115], v[162:165], v[178:181], v[112:115]
	v_mfma_f32_16x16x32_bf16 v[116:119], v[154:157], v[178:181], v[116:119]
	v_mfma_f32_16x16x32_bf16 v[108:111], v[154:157], v[186:189], v[108:111]
	v_mfma_f32_16x16x32_bf16 v[104:107], v[162:165], v[186:189], v[104:107]
	v_mfma_f32_16x16x32_bf16 v[96:99], v[162:165], v[194:197], v[96:99]
	v_mfma_f32_16x16x32_bf16 v[100:103], v[154:157], v[194:197], v[100:103]
	s_setprio 0
	s_barrier
	s_add_i32 s48, 16, 0x1c000
	s_add_i32 s49, s69, s31
	v_add_u32_e32 v210, s48, v145
	v_lshl_add_u64 v[218:219], v[218:219], 0, s[6:7]
	s_mov_b32 m0, s49
	ds_read_b128 v[198:201], v210
	ds_read_b128 v[202:205], v210 offset:1024
	ds_read_b128 v[206:209], v210 offset:2048
	ds_read_b128 v[210:213], v210 offset:3072
	global_load_lds_dwordx4 v[218:219], off
	v_lshl_add_u64 v[218:219], v[220:221], 0, s[6:7]
	s_add_i32 m0, s49, 0x2000
	s_nop 0
	global_load_lds_dwordx4 v[218:219], off
	s_barrier
; #define PG8_STAGE(bufoff, gbase, voff) do { _Pragma("unroll") for (int _i = 0; _i < 2; ++_i) \
;         __builtin_amdgcn_global_load_lds((const unsigned*)((const char*)(gbase) + (voff)[_i]), (LAS unsigned*)(lds + (bufoff) + ldsw + _i * 8192), 16, 0, 0); } while (0)
; #define PG8_MMA(ai, bj, At, Bt) do { __builtin_amdgcn_s_setprio(1); _Pragma("unroll") for (int m = 0; m < 4; ++m) _Pragma("unroll") for (int n = 0; n < 2; ++n) _Pragma("unroll") for (int k = 0; k < 2; ++k) \
;         acc[ai][bj][m][n] = __builtin_amdgcn_mfma_f32_16x16x32_bf16(Bt[n][k], At[m][k], acc[ai][bj][m][n], 0, 0, 0); __builtin_amdgcn_s_setprio(0); } while (0)
; #define PG8_WAIT_V(n) asm volatile("s_waitcnt vmcnt(" #n ")" ::: "memory")
; #define PG8_WAIT_L(n) asm volatile("s_waitcnt lgkmcnt(" #n ")" ::: "memory")
; #define PG8_BAR __builtin_amdgcn_s_barrier()
; #define PG8_SCHED __builtin_amdgcn_sched_barrier(0)
; template <class Epi>
; DEVINL void gemm_phase(LAS unsigned char* lds, const Gemm g, const Order& S, const Epi& E) {
;     ...
;             PG8_BAR; PG8_WAIT_L(0); PG8_MMA(1, 0, At, B0); PG8_BAR; PG8_SCHED;
;             PG8_STAGE(PG8_SB(1, 1), b3 + hstepB, voffB);
;             PG8_WAIT_V(6); PG8_BAR; PG8_MMA(1, 1, At, B1); PG8_BAR;
;         }
	s_waitcnt lgkmcnt(0)
	s_setprio 1
	s_waitcnt lgkmcnt(0)
	v_mfma_f32_16x16x32_bf16 v[60:63], v[198:201], v[166:169], v[60:63]
	v_mfma_f32_16x16x32_bf16 v[56:59], v[206:209], v[166:169], v[56:59]
	v_mfma_f32_16x16x32_bf16 v[48:51], v[206:209], v[174:177], v[48:51]
	v_mfma_f32_16x16x32_bf16 v[52:55], v[198:201], v[174:177], v[52:55]
	v_mfma_f32_16x16x32_bf16 v[44:47], v[198:201], v[182:185], v[44:47]
	v_mfma_f32_16x16x32_bf16 v[40:43], v[206:209], v[182:185], v[40:43]
	v_mfma_f32_16x16x32_bf16 v[32:35], v[206:209], v[190:193], v[32:35]
	v_mfma_f32_16x16x32_bf16 v[36:39], v[198:201], v[190:193], v[36:39]
	v_mfma_f32_16x16x32_bf16 v[60:63], v[202:205], v[170:173], v[60:63]
	v_mfma_f32_16x16x32_bf16 v[56:59], v[210:213], v[170:173], v[56:59]
	v_mfma_f32_16x16x32_bf16 v[48:51], v[210:213], v[178:181], v[48:51]
	v_mfma_f32_16x16x32_bf16 v[52:55], v[202:205], v[178:181], v[52:55]
	v_mfma_f32_16x16x32_bf16 v[44:47], v[202:205], v[186:189], v[44:47]
	v_mfma_f32_16x16x32_bf16 v[40:43], v[210:213], v[186:189], v[40:43]
	v_mfma_f32_16x16x32_bf16 v[32:35], v[210:213], v[194:197], v[32:35]
	v_mfma_f32_16x16x32_bf16 v[36:39], v[202:205], v[194:197], v[36:39]
	s_setprio 0
	s_mov_b32 m0, s54
	v_lshl_add_u64 v[218:219], v[222:223], 0, s[6:7]
	s_barrier
	ds_read_b128 v[166:169], v148 offset:49152
	ds_read_b128 v[170:173], v148 offset:50176
	ds_read_b128 v[174:177], v148 offset:51200
	ds_read_b128 v[178:181], v148 offset:52224
	ds_read_b128 v[182:185], v148 offset:53248
	ds_read_b128 v[186:189], v148 offset:54272
	ds_read_b128 v[190:193], v148 offset:55296
	ds_read_b128 v[194:197], v148 offset:56320
	global_load_lds_dwordx4 v[218:219], off
	v_lshl_add_u64 v[218:219], v[224:225], 0, s[6:7]
	s_mov_b32 m0, s55
	s_nop 0
	global_load_lds_dwordx4 v[218:219], off
	s_barrier
	s_waitcnt lgkmcnt(0)
	s_setprio 1
	s_waitcnt lgkmcnt(0)
	v_mfma_f32_16x16x32_bf16 v[92:95], v[150:153], v[166:169], v[92:95]
	v_mfma_f32_16x16x32_bf16 v[88:91], v[158:161], v[166:169], v[88:91]
	v_mfma_f32_16x16x32_bf16 v[80:83], v[158:161], v[174:177], v[80:83]
	v_mfma_f32_16x16x32_bf16 v[84:87], v[150:153], v[174:177], v[84:87]
	v_mfma_f32_16x16x32_bf16 v[76:79], v[150:153], v[182:185], v[76:79]
	v_mfma_f32_16x16x32_bf16 v[72:75], v[158:161], v[182:185], v[72:75]
	v_mfma_f32_16x16x32_bf16 v[64:67], v[158:161], v[190:193], v[64:67]
	v_mfma_f32_16x16x32_bf16 v[68:71], v[150:153], v[190:193], v[68:71]
	v_mfma_f32_16x16x32_bf16 v[92:95], v[154:157], v[170:173], v[92:95]
	v_mfma_f32_16x16x32_bf16 v[88:91], v[162:165], v[170:173], v[88:91]
	v_mfma_f32_16x16x32_bf16 v[80:83], v[162:165], v[178:181], v[80:83]
	v_mfma_f32_16x16x32_bf16 v[84:87], v[154:157], v[178:181], v[84:87]
	v_mfma_f32_16x16x32_bf16 v[76:79], v[154:157], v[186:189], v[76:79]
	v_mfma_f32_16x16x32_bf16 v[72:75], v[162:165], v[186:189], v[72:75]
	v_mfma_f32_16x16x32_bf16 v[64:67], v[162:165], v[194:197], v[64:67]
	v_mfma_f32_16x16x32_bf16 v[68:71], v[154:157], v[194:197], v[68:71]
	s_setprio 0
	s_barrier
	s_add_u32 s46, s46, 0x10080
	s_addc_u32 s47, s47, 0
	s_add_i32 s48, s48, s31
	v_lshl_add_u64 v[150:151], s[46:47], 0, v[130:131]
	s_mov_b32 m0, s48
	s_nop 0
	global_load_lds_dwordx4 v[150:151], off
	v_lshl_add_u64 v[150:151], s[46:47], 0, v[134:135]
	s_add_i32 m0, s48, 0x2000
	s_nop 0
	global_load_lds_dwordx4 v[150:151], off
	s_waitcnt vmcnt(6)
	s_barrier
	s_setprio 1
	v_mfma_f32_16x16x32_bf16 v[28:31], v[198:201], v[166:169], v[28:31]
	v_mfma_f32_16x16x32_bf16 v[24:27], v[206:209], v[166:169], v[24:27]
	v_mfma_f32_16x16x32_bf16 v[16:19], v[206:209], v[174:177], v[16:19]
	v_mfma_f32_16x16x32_bf16 v[20:23], v[198:201], v[174:177], v[20:23]
	v_mfma_f32_16x16x32_bf16 v[12:15], v[198:201], v[182:185], v[12:15]
	v_mfma_f32_16x16x32_bf16 v[8:11], v[206:209], v[182:185], v[8:11]
	v_mfma_f32_16x16x32_bf16 v[0:3], v[206:209], v[190:193], v[0:3]
	v_mfma_f32_16x16x32_bf16 v[4:7], v[198:201], v[190:193], v[4:7]
	v_mfma_f32_16x16x32_bf16 v[28:31], v[202:205], v[170:173], v[28:31]
	v_mfma_f32_16x16x32_bf16 v[24:27], v[210:213], v[170:173], v[24:27]
	v_mfma_f32_16x16x32_bf16 v[16:19], v[210:213], v[178:181], v[16:19]
	v_mfma_f32_16x16x32_bf16 v[20:23], v[202:205], v[178:181], v[20:23]
	v_mfma_f32_16x16x32_bf16 v[12:15], v[202:205], v[186:189], v[12:15]
	v_mfma_f32_16x16x32_bf16 v[8:11], v[210:213], v[186:189], v[8:11]
	v_mfma_f32_16x16x32_bf16 v[0:3], v[210:213], v[194:197], v[0:3]
	v_mfma_f32_16x16x32_bf16 v[4:7], v[202:205], v[194:197], v[4:7]
	s_setprio 0
	s_add_u32 s4, s4, 0x100
	s_addc_u32 s5, s5, 0
	s_add_u32 s66, s66, 0x100
	s_addc_u32 s67, s67, 0
	s_cmp_ge_i32 s68, s53
	s_mov_b32 s46, s68
	s_barrier
	s_cbranch_scc0 .LBB0_1008
	s_branch .LBB0_999

; #define PG8_STAGE(bufoff, gbase, voff) do { _Pragma("unroll") for (int _i = 0; _i < 2; ++_i) \
;         __builtin_amdgcn_global_load_lds((const unsigned*)((const char*)(gbase) + (voff)[_i]), (LAS unsigned*)(lds + (bufoff) + ldsw + _i * 8192), 16, 0, 0); } while (0)
; #define PG8_LDA(dst, b, h) do { _Pragma("unroll") for (int m = 0; m < 4; ++m) _Pragma("unroll") for (int k = 0; k < 2; ++k) dst[m][k] = *(const LAS bf16x8*)(lds + PG8_SA(b, h) + aoff + m * 2048 + k * 1024); } while (0)
; #define PG8_LDB(dst, b, h) do { _Pragma("unroll") for (int n = 0; n < 2; ++n) _Pragma("unroll") for (int k = 0; k < 2; ++k) dst[n][k] = *(const LAS bf16x8*)(lds + PG8_SB(b, h) + boff + n * 2048 + k * 1024); } while (0)
; #define PG8_MMA(ai, bj, At, Bt) do { __builtin_amdgcn_s_setprio(1); _Pragma("unroll") for (int m = 0; m < 4; ++m) _Pragma("unroll") for (int n = 0; n < 2; ++n) _Pragma("unroll") for (int k = 0; k < 2; ++k) \
;         acc[ai][bj][m][n] = __builtin_amdgcn_mfma_f32_16x16x32_bf16(Bt[n][k], At[m][k], acc[ai][bj][m][n], 0, 0, 0); __builtin_amdgcn_s_setprio(0); } while (0)
; #define PG8_WAIT_L(n) asm volatile("s_waitcnt lgkmcnt(" #n ")" ::: "memory")
; #define PG8_BAR __builtin_amdgcn_s_barrier()
; #define PG8_SCHED __builtin_amdgcn_sched_barrier(0)
; template <class Epi>
; DEVINL void gemm_phase(LAS unsigned char* lds, const Gemm g, const Order& S, const Epi& E) {
;     ...
;         for (int t = 0; t < nt; t += 2) {
;             const bool last = (t == nt - 2);
;             const char* a1 = cA + (size_t)(t + 1) * kstep;
;             const char* a2 = last ? nA : cA + (size_t)(t + 2) * kstep; const char* b2 = last ? nB : cB + (size_t)(t + 2) * kstep;
;             const char* a3 = a2 + kstep; const char* b3 = b2 + kstep;
;             PG8_LDB(B0, 0, 0); PG8_SCHED; PG8_LDA(At, 0, 0); PG8_STAGE(PG8_SA(1, 1), a1 + hstepA, voffA);
;             PG8_WAIT_L(8); PG8_BAR; PG8_WAIT_L(0); PG8_MMA(0, 0, At, B0); PG8_BAR; PG8_SCHED;
;             PG8_LDB(B1, 0, 1); PG8_STAGE(PG8_SB(0, 0), b2, voffB);
;             PG8_BAR; PG8_WAIT_L(0); PG8_MMA(0, 1, At, B1); PG8_BAR;
;             PG8_LDA(At, 0, 1); PG8_STAGE(PG8_SA(0, 0), a2, voffA);
;             PG8_BAR; PG8_WAIT_L(0); PG8_MMA(1, 0, At, B0); PG8_BAR; PG8_SCHED;
.LBB0_1029:
	ds_read_b128 v[150:153], v147
	ds_read_b128 v[154:157], v147 offset:1024
	ds_read_b128 v[158:161], v147 offset:2048
	ds_read_b128 v[162:165], v147 offset:3072
	s_add_i32 s70, s48, 2
	s_add_u32 s49, s4, 0xffff0080
	s_addc_u32 s50, s5, -1
	s_cmp_eq_u32 s57, s48
	s_cselect_b32 s48, s13, s68
	s_cselect_b32 s51, s2, s50
	s_cselect_b32 s50, s3, s49
	s_cselect_b32 s49, s11, s69
	v_lshl_add_u64 v[198:199], s[4:5], 0, v[136:137]
	s_add_i32 m0, s31, 0xc000
	ds_read_b128 v[166:169], v148
	ds_read_b128 v[170:173], v148 offset:1024
	ds_read_b128 v[174:177], v148 offset:2048
	ds_read_b128 v[178:181], v148 offset:3072
	ds_read_b128 v[182:185], v148 offset:4096
	ds_read_b128 v[186:189], v148 offset:5120
	ds_read_b128 v[190:193], v148 offset:6144
	ds_read_b128 v[194:197], v148 offset:7168
	global_load_lds_dwordx4 v[198:199], off
	v_lshl_add_u64 v[198:199], s[4:5], 0, v[138:139]
	s_add_i32 m0, s31, 0xe000
	s_nop 0
	global_load_lds_dwordx4 v[198:199], off
	s_waitcnt lgkmcnt(8)
	s_barrier
	s_waitcnt lgkmcnt(0)
	s_setprio 1
	s_waitcnt lgkmcnt(0)
	v_mfma_f32_16x16x32_bf16 v[124:127], v[150:153], v[166:169], v[124:127]
	v_mfma_f32_16x16x32_bf16 v[120:123], v[158:161], v[166:169], v[120:123]
	v_mfma_f32_16x16x32_bf16 v[112:115], v[158:161], v[174:177], v[112:115]
	v_mfma_f32_16x16x32_bf16 v[116:119], v[150:153], v[174:177], v[116:119]
	v_mfma_f32_16x16x32_bf16 v[108:111], v[150:153], v[182:185], v[108:111]
	v_mfma_f32_16x16x32_bf16 v[104:107], v[158:161], v[182:185], v[104:107]
	v_mfma_f32_16x16x32_bf16 v[96:99], v[158:161], v[190:193], v[96:99]
	v_mfma_f32_16x16x32_bf16 v[100:103], v[150:153], v[190:193], v[100:103]
	v_mfma_f32_16x16x32_bf16 v[124:127], v[154:157], v[170:173], v[124:127]
	v_mfma_f32_16x16x32_bf16 v[120:123], v[162:165], v[170:173], v[120:123]
	v_mfma_f32_16x16x32_bf16 v[112:115], v[162:165], v[178:181], v[112:115]
	v_mfma_f32_16x16x32_bf16 v[116:119], v[154:157], v[178:181], v[116:119]
	v_mfma_f32_16x16x32_bf16 v[108:111], v[154:157], v[186:189], v[108:111]
	v_mfma_f32_16x16x32_bf16 v[104:107], v[162:165], v[186:189], v[104:107]
	v_mfma_f32_16x16x32_bf16 v[96:99], v[162:165], v[194:197], v[96:99]
	v_mfma_f32_16x16x32_bf16 v[100:103], v[154:157], v[194:197], v[100:103]
	s_setprio 0
	s_barrier
	s_add_i32 s71, s65, s30
	v_lshl_add_u64 v[218:219], s[48:49], 0, v[130:131]
	s_mov_b32 m0, s71
	ds_read_b128 v[198:201], v149
	ds_read_b128 v[202:205], v149 offset:1024
	ds_read_b128 v[206:209], v149 offset:2048
	ds_read_b128 v[210:213], v149 offset:3072
	global_load_lds_dwordx4 v[218:219], off
	v_lshl_add_u64 v[220:221], s[48:49], 0, v[134:135]
	s_add_i32 m0, s71, 0x2000
	s_nop 0
	global_load_lds_dwordx4 v[220:221], off
	s_barrier
	s_waitcnt lgkmcnt(0)
	s_setprio 1
	s_waitcnt lgkmcnt(0)
	v_mfma_f32_16x16x32_bf16 v[60:63], v[198:201], v[166:169], v[60:63]
	v_mfma_f32_16x16x32_bf16 v[56:59], v[206:209], v[166:169], v[56:59]
	v_mfma_f32_16x16x32_bf16 v[48:51], v[206:209], v[174:177], v[48:51]
	v_mfma_f32_16x16x32_bf16 v[52:55], v[198:201], v[174:177], v[52:55]
	v_mfma_f32_16x16x32_bf16 v[44:47], v[198:201], v[182:185], v[44:47]
	v_mfma_f32_16x16x32_bf16 v[40:43], v[206:209], v[182:185], v[40:43]
	v_mfma_f32_16x16x32_bf16 v[32:35], v[206:209], v[190:193], v[32:35]
	v_mfma_f32_16x16x32_bf16 v[36:39], v[198:201], v[190:193], v[36:39]
	v_mfma_f32_16x16x32_bf16 v[60:63], v[202:205], v[170:173], v[60:63]
	v_mfma_f32_16x16x32_bf16 v[56:59], v[210:213], v[170:173], v[56:59]
	v_mfma_f32_16x16x32_bf16 v[48:51], v[210:213], v[178:181], v[48:51]
	v_mfma_f32_16x16x32_bf16 v[52:55], v[202:205], v[178:181], v[52:55]
	v_mfma_f32_16x16x32_bf16 v[44:47], v[202:205], v[186:189], v[44:47]
	v_mfma_f32_16x16x32_bf16 v[40:43], v[210:213], v[186:189], v[40:43]
	v_mfma_f32_16x16x32_bf16 v[32:35], v[210:213], v[194:197], v[32:35]
	v_mfma_f32_16x16x32_bf16 v[36:39], v[202:205], v[194:197], v[36:39]
	s_setprio 0
	s_mov_b32 m0, s31
	v_lshl_add_u64 v[222:223], s[50:51], 0, v[128:129]
	s_barrier
	ds_read_b128 v[166:169], v148 offset:16384
	ds_read_b128 v[170:173], v148 offset:17408
	ds_read_b128 v[174:177], v148 offset:18432
	ds_read_b128 v[178:181], v148 offset:19456
	ds_read_b128 v[182:185], v148 offset:20480
	ds_read_b128 v[186:189], v148 offset:21504
	ds_read_b128 v[190:193], v148 offset:22528
	ds_read_b128 v[194:197], v148 offset:23552
	global_load_lds_dwordx4 v[222:223], off
	v_lshl_add_u64 v[224:225], s[50:51], 0, v[132:133]
	s_mov_b32 m0, s47
	s_nop 0
	global_load_lds_dwordx4 v[224:225], off
	s_barrier
	s_waitcnt lgkmcnt(0)
	s_setprio 1
	s_waitcnt lgkmcnt(0)
	v_mfma_f32_16x16x32_bf16 v[92:95], v[150:153], v[166:169], v[92:95]
	v_mfma_f32_16x16x32_bf16 v[88:91], v[158:161], v[166:169], v[88:91]
	v_mfma_f32_16x16x32_bf16 v[80:83], v[158:161], v[174:177], v[80:83]
	v_mfma_f32_16x16x32_bf16 v[84:87], v[150:153], v[174:177], v[84:87]
	v_mfma_f32_16x16x32_bf16 v[76:79], v[150:153], v[182:185], v[76:79]
	v_mfma_f32_16x16x32_bf16 v[72:75], v[158:161], v[182:185], v[72:75]
	v_mfma_f32_16x16x32_bf16 v[64:67], v[158:161], v[190:193], v[64:67]
	v_mfma_f32_16x16x32_bf16 v[68:71], v[150:153], v[190:193], v[68:71]
	v_mfma_f32_16x16x32_bf16 v[92:95], v[154:157], v[170:173], v[92:95]
	v_mfma_f32_16x16x32_bf16 v[88:91], v[162:165], v[170:173], v[88:91]
	v_mfma_f32_16x16x32_bf16 v[80:83], v[162:165], v[178:181], v[80:83]
	v_mfma_f32_16x16x32_bf16 v[84:87], v[154:157], v[178:181], v[84:87]
	v_mfma_f32_16x16x32_bf16 v[76:79], v[154:157], v[186:189], v[76:79]
	v_mfma_f32_16x16x32_bf16 v[72:75], v[162:165], v[186:189], v[72:75]
	v_mfma_f32_16x16x32_bf16 v[64:67], v[162:165], v[194:197], v[64:67]
	v_mfma_f32_16x16x32_bf16 v[68:71], v[154:157], v[194:197], v[68:71]
	s_setprio 0
	s_barrier
; #define PG8_STAGE(bufoff, gbase, voff) do { _Pragma("unroll") for (int _i = 0; _i < 2; ++_i) \
;         __builtin_amdgcn_global_load_lds((const unsigned*)((const char*)(gbase) + (voff)[_i]), (LAS unsigned*)(lds + (bufoff) + ldsw + _i * 8192), 16, 0, 0); } while (0)
; #define PG8_LDA(dst, b, h) do { _Pragma("unroll") for (int m = 0; m < 4; ++m) _Pragma("unroll") for (int k = 0; k < 2; ++k) dst[m][k] = *(const LAS bf16x8*)(lds + PG8_SA(b, h) + aoff + m * 2048 + k * 1024); } while (0)
; #define PG8_LDB(dst, b, h) do { _Pragma("unroll") for (int n = 0; n < 2; ++n) _Pragma("unroll") for (int k = 0; k < 2; ++k) dst[n][k] = *(const LAS bf16x8*)(lds + PG8_SB(b, h) + boff + n * 2048 + k * 1024); } while (0)
; #define PG8_MMA(ai, bj, At, Bt) do { __builtin_amdgcn_s_setprio(1); _Pragma("unroll") for (int m = 0; m < 4; ++m) _Pragma("unroll") for (int n = 0; n < 2; ++n) _Pragma("unroll") for (int k = 0; k < 2; ++k) \
;         acc[ai][bj][m][n] = __builtin_amdgcn_mfma_f32_16x16x32_bf16(Bt[n][k], At[m][k], acc[ai][bj][m][n], 0, 0, 0); __builtin_amdgcn_s_setprio(0); } while (0)
; #define PG8_WAIT_V(n) asm volatile("s_waitcnt vmcnt(" #n ")" ::: "memory")
; #define PG8_WAIT_L(n) asm volatile("s_waitcnt lgkmcnt(" #n ")" ::: "memory")
; #define PG8_BAR __builtin_amdgcn_s_barrier()
; #define PG8_SCHED __builtin_amdgcn_sched_barrier(0)
; template <class Epi>
; DEVINL void gemm_phase(LAS unsigned char* lds, const Gemm g, const Order& S, const Epi& E) {
;     ...
;             PG8_STAGE(PG8_SB(0, 1), b2 + hstepB, voffB);
;             PG8_WAIT_V(6); PG8_BAR; PG8_MMA(1, 1, At, B1); PG8_BAR;
;             PG8_LDB(B0, 1, 0); PG8_SCHED; PG8_LDA(At, 1, 0); PG8_STAGE(PG8_SA(0, 1), a2 + hstepA, voffA);
;             PG8_WAIT_L(8); PG8_BAR; PG8_WAIT_L(0); PG8_MMA(0, 0, At, B0); PG8_BAR; PG8_SCHED;
;             PG8_LDB(B1, 1, 1); PG8_STAGE(PG8_SB(1, 0), b3, voffB);
;             PG8_BAR; PG8_WAIT_L(0); PG8_MMA(0, 1, At, B1); PG8_BAR;
;             PG8_LDA(At, 1, 1); PG8_STAGE(PG8_SA(1, 0), a3, voffA);
	s_add_u32 s72, s48, 0x10000
	s_addc_u32 s73, s49, 0
	s_add_i32 s71, s66, s30
	v_lshl_add_u64 v[150:151], s[72:73], 0, v[130:131]
	s_mov_b32 m0, s71
	s_nop 0
	global_load_lds_dwordx4 v[150:151], off
	v_lshl_add_u64 v[150:151], s[72:73], 0, v[134:135]
	s_add_i32 m0, s71, 0x2000
	s_nop 0
	global_load_lds_dwordx4 v[150:151], off
	s_waitcnt vmcnt(6)
	s_barrier
	s_setprio 1
	v_mfma_f32_16x16x32_bf16 v[28:31], v[198:201], v[166:169], v[28:31]
	v_mfma_f32_16x16x32_bf16 v[24:27], v[206:209], v[166:169], v[24:27]
	v_mfma_f32_16x16x32_bf16 v[16:19], v[206:209], v[174:177], v[16:19]
	v_mfma_f32_16x16x32_bf16 v[20:23], v[198:201], v[174:177], v[20:23]
	v_mfma_f32_16x16x32_bf16 v[12:15], v[198:201], v[182:185], v[12:15]
	v_mfma_f32_16x16x32_bf16 v[8:11], v[206:209], v[182:185], v[8:11]
	v_mfma_f32_16x16x32_bf16 v[0:3], v[206:209], v[190:193], v[0:3]
	v_mfma_f32_16x16x32_bf16 v[4:7], v[198:201], v[190:193], v[4:7]
	v_mfma_f32_16x16x32_bf16 v[28:31], v[202:205], v[170:173], v[28:31]
	v_mfma_f32_16x16x32_bf16 v[24:27], v[210:213], v[170:173], v[24:27]
	v_mfma_f32_16x16x32_bf16 v[16:19], v[210:213], v[178:181], v[16:19]
	v_mfma_f32_16x16x32_bf16 v[20:23], v[202:205], v[178:181], v[20:23]
	v_mfma_f32_16x16x32_bf16 v[12:15], v[202:205], v[186:189], v[12:15]
	v_mfma_f32_16x16x32_bf16 v[8:11], v[210:213], v[186:189], v[8:11]
	v_mfma_f32_16x16x32_bf16 v[0:3], v[210:213], v[194:197], v[0:3]
	v_mfma_f32_16x16x32_bf16 v[4:7], v[202:205], v[194:197], v[4:7]
	s_setprio 0
	s_add_i32 s71, 16, 0x18000
	v_add_u32_e32 v162, s71, v145
	s_barrier
	ds_read_b128 v[150:153], v162
	ds_read_b128 v[154:157], v162 offset:1024
	ds_read_b128 v[158:161], v162 offset:2048
	ds_read_b128 v[162:165], v162 offset:3072
	s_add_u32 s50, s50, 0x10000
	s_addc_u32 s51, s51, 0
	s_mov_b32 m0, s52
	v_lshl_add_u64 v[198:199], s[50:51], 0, v[128:129]
	ds_read_b128 v[166:169], v148 offset:32768
	ds_read_b128 v[170:173], v148 offset:33792
	ds_read_b128 v[174:177], v148 offset:34816
	ds_read_b128 v[178:181], v148 offset:35840
	ds_read_b128 v[182:185], v148 offset:36864
	ds_read_b128 v[186:189], v148 offset:37888
	ds_read_b128 v[190:193], v148 offset:38912
	ds_read_b128 v[194:197], v148 offset:39936
	global_load_lds_dwordx4 v[198:199], off
	v_lshl_add_u64 v[198:199], s[50:51], 0, v[132:133]
	s_mov_b32 m0, s53
	s_nop 0
	global_load_lds_dwordx4 v[198:199], off
	s_waitcnt lgkmcnt(8)
	s_barrier
	s_waitcnt lgkmcnt(0)
	s_setprio 1
	s_waitcnt lgkmcnt(0)
	v_mfma_f32_16x16x32_bf16 v[124:127], v[150:153], v[166:169], v[124:127]
	v_mfma_f32_16x16x32_bf16 v[120:123], v[158:161], v[166:169], v[120:123]
	v_mfma_f32_16x16x32_bf16 v[112:115], v[158:161], v[174:177], v[112:115]
	v_mfma_f32_16x16x32_bf16 v[116:119], v[150:153], v[174:177], v[116:119]
	v_mfma_f32_16x16x32_bf16 v[108:111], v[150:153], v[182:185], v[108:111]
	v_mfma_f32_16x16x32_bf16 v[104:107], v[158:161], v[182:185], v[104:107]
	v_mfma_f32_16x16x32_bf16 v[96:99], v[158:161], v[190:193], v[96:99]
	v_mfma_f32_16x16x32_bf16 v[100:103], v[150:153], v[190:193], v[100:103]
	v_mfma_f32_16x16x32_bf16 v[124:127], v[154:157], v[170:173], v[124:127]
	v_mfma_f32_16x16x32_bf16 v[120:123], v[162:165], v[170:173], v[120:123]
	v_mfma_f32_16x16x32_bf16 v[112:115], v[162:165], v[178:181], v[112:115]
	v_mfma_f32_16x16x32_bf16 v[116:119], v[154:157], v[178:181], v[116:119]
	v_mfma_f32_16x16x32_bf16 v[108:111], v[154:157], v[186:189], v[108:111]
	v_mfma_f32_16x16x32_bf16 v[104:107], v[162:165], v[186:189], v[104:107]
	v_mfma_f32_16x16x32_bf16 v[96:99], v[162:165], v[194:197], v[96:99]
	v_mfma_f32_16x16x32_bf16 v[100:103], v[154:157], v[194:197], v[100:103]
	s_setprio 0
	s_barrier
	s_add_i32 s50, 16, 0x1c000
	s_add_i32 s51, s71, s30
	v_add_u32_e32 v210, s50, v145
	v_lshl_add_u64 v[218:219], v[218:219], 0, s[6:7]
	s_mov_b32 m0, s51
	ds_read_b128 v[198:201], v210
	ds_read_b128 v[202:205], v210 offset:1024
	ds_read_b128 v[206:209], v210 offset:2048
	ds_read_b128 v[210:213], v210 offset:3072
	global_load_lds_dwordx4 v[218:219], off
	v_lshl_add_u64 v[218:219], v[220:221], 0, s[6:7]
	s_add_i32 m0, s51, 0x2000
	s_nop 0
	global_load_lds_dwordx4 v[218:219], off
	s_barrier
; #define PG8_STAGE(bufoff, gbase, voff) do { _Pragma("unroll") for (int _i = 0; _i < 2; ++_i) \
;         __builtin_amdgcn_global_load_lds((const unsigned*)((const char*)(gbase) + (voff)[_i]), (LAS unsigned*)(lds + (bufoff) + ldsw + _i * 8192), 16, 0, 0); } while (0)
; #define PG8_MMA(ai, bj, At, Bt) do { __builtin_amdgcn_s_setprio(1); _Pragma("unroll") for (int m = 0; m < 4; ++m) _Pragma("unroll") for (int n = 0; n < 2; ++n) _Pragma("unroll") for (int k = 0; k < 2; ++k) \
;         acc[ai][bj][m][n] = __builtin_amdgcn_mfma_f32_16x16x32_bf16(Bt[n][k], At[m][k], acc[ai][bj][m][n], 0, 0, 0); __builtin_amdgcn_s_setprio(0); } while (0)
; #define PG8_WAIT_V(n) asm volatile("s_waitcnt vmcnt(" #n ")" ::: "memory")
; #define PG8_WAIT_L(n) asm volatile("s_waitcnt lgkmcnt(" #n ")" ::: "memory")
; #define PG8_BAR __builtin_amdgcn_s_barrier()
; #define PG8_SCHED __builtin_amdgcn_sched_barrier(0)
; template <class Epi>
; DEVINL void gemm_phase(LAS unsigned char* lds, const Gemm g, const Order& S, const Epi& E) {
;     ...
;             PG8_BAR; PG8_WAIT_L(0); PG8_MMA(1, 0, At, B0); PG8_BAR; PG8_SCHED;
;             PG8_STAGE(PG8_SB(1, 1), b3 + hstepB, voffB);
;             PG8_WAIT_V(6); PG8_BAR; PG8_MMA(1, 1, At, B1); PG8_BAR;
;         }
	s_waitcnt lgkmcnt(0)
	s_setprio 1
	s_waitcnt lgkmcnt(0)
	v_mfma_f32_16x16x32_bf16 v[60:63], v[198:201], v[166:169], v[60:63]
	v_mfma_f32_16x16x32_bf16 v[56:59], v[206:209], v[166:169], v[56:59]
	v_mfma_f32_16x16x32_bf16 v[48:51], v[206:209], v[174:177], v[48:51]
	v_mfma_f32_16x16x32_bf16 v[52:55], v[198:201], v[174:177], v[52:55]
	v_mfma_f32_16x16x32_bf16 v[44:47], v[198:201], v[182:185], v[44:47]
	v_mfma_f32_16x16x32_bf16 v[40:43], v[206:209], v[182:185], v[40:43]
	v_mfma_f32_16x16x32_bf16 v[32:35], v[206:209], v[190:193], v[32:35]
	v_mfma_f32_16x16x32_bf16 v[36:39], v[198:201], v[190:193], v[36:39]
	v_mfma_f32_16x16x32_bf16 v[60:63], v[202:205], v[170:173], v[60:63]
	v_mfma_f32_16x16x32_bf16 v[56:59], v[210:213], v[170:173], v[56:59]
	v_mfma_f32_16x16x32_bf16 v[48:51], v[210:213], v[178:181], v[48:51]
	v_mfma_f32_16x16x32_bf16 v[52:55], v[202:205], v[178:181], v[52:55]
	v_mfma_f32_16x16x32_bf16 v[44:47], v[202:205], v[186:189], v[44:47]
	v_mfma_f32_16x16x32_bf16 v[40:43], v[210:213], v[186:189], v[40:43]
	v_mfma_f32_16x16x32_bf16 v[32:35], v[210:213], v[194:197], v[32:35]
	v_mfma_f32_16x16x32_bf16 v[36:39], v[202:205], v[194:197], v[36:39]
	s_setprio 0
	s_mov_b32 m0, s55
	v_lshl_add_u64 v[218:219], v[222:223], 0, s[6:7]
	s_barrier
	ds_read_b128 v[166:169], v148 offset:49152
	ds_read_b128 v[170:173], v148 offset:50176
	ds_read_b128 v[174:177], v148 offset:51200
	ds_read_b128 v[178:181], v148 offset:52224
	ds_read_b128 v[182:185], v148 offset:53248
	ds_read_b128 v[186:189], v148 offset:54272
	ds_read_b128 v[190:193], v148 offset:55296
	ds_read_b128 v[194:197], v148 offset:56320
	global_load_lds_dwordx4 v[218:219], off
	v_lshl_add_u64 v[218:219], v[224:225], 0, s[6:7]
	s_mov_b32 m0, s56
	s_nop 0
	global_load_lds_dwordx4 v[218:219], off
	s_barrier
	s_waitcnt lgkmcnt(0)
	s_setprio 1
	s_waitcnt lgkmcnt(0)
	v_mfma_f32_16x16x32_bf16 v[92:95], v[150:153], v[166:169], v[92:95]
	v_mfma_f32_16x16x32_bf16 v[88:91], v[158:161], v[166:169], v[88:91]
	v_mfma_f32_16x16x32_bf16 v[80:83], v[158:161], v[174:177], v[80:83]
	v_mfma_f32_16x16x32_bf16 v[84:87], v[150:153], v[174:177], v[84:87]
	v_mfma_f32_16x16x32_bf16 v[76:79], v[150:153], v[182:185], v[76:79]
	v_mfma_f32_16x16x32_bf16 v[72:75], v[158:161], v[182:185], v[72:75]
	v_mfma_f32_16x16x32_bf16 v[64:67], v[158:161], v[190:193], v[64:67]
	v_mfma_f32_16x16x32_bf16 v[68:71], v[150:153], v[190:193], v[68:71]
	v_mfma_f32_16x16x32_bf16 v[92:95], v[154:157], v[170:173], v[92:95]
	v_mfma_f32_16x16x32_bf16 v[88:91], v[162:165], v[170:173], v[88:91]
	v_mfma_f32_16x16x32_bf16 v[80:83], v[162:165], v[178:181], v[80:83]
	v_mfma_f32_16x16x32_bf16 v[84:87], v[154:157], v[178:181], v[84:87]
	v_mfma_f32_16x16x32_bf16 v[76:79], v[154:157], v[186:189], v[76:79]
	v_mfma_f32_16x16x32_bf16 v[72:75], v[162:165], v[186:189], v[72:75]
	v_mfma_f32_16x16x32_bf16 v[64:67], v[162:165], v[194:197], v[64:67]
	v_mfma_f32_16x16x32_bf16 v[68:71], v[154:157], v[194:197], v[68:71]
	s_setprio 0
	s_barrier
	s_add_u32 s48, s48, 0x10080
	s_addc_u32 s49, s49, 0
	s_add_i32 s50, s50, s30
	v_lshl_add_u64 v[150:151], s[48:49], 0, v[130:131]
	s_mov_b32 m0, s50
	s_nop 0
	global_load_lds_dwordx4 v[150:151], off
	v_lshl_add_u64 v[150:151], s[48:49], 0, v[134:135]
	s_add_i32 m0, s50, 0x2000
	s_nop 0
	global_load_lds_dwordx4 v[150:151], off
	s_waitcnt vmcnt(6)
	s_barrier
	s_setprio 1
	v_mfma_f32_16x16x32_bf16 v[28:31], v[198:201], v[166:169], v[28:31]
	v_mfma_f32_16x16x32_bf16 v[24:27], v[206:209], v[166:169], v[24:27]
	v_mfma_f32_16x16x32_bf16 v[16:19], v[206:209], v[174:177], v[16:19]
	v_mfma_f32_16x16x32_bf16 v[20:23], v[198:201], v[174:177], v[20:23]
	v_mfma_f32_16x16x32_bf16 v[12:15], v[198:201], v[182:185], v[12:15]
	v_mfma_f32_16x16x32_bf16 v[8:11], v[206:209], v[182:185], v[8:11]
	v_mfma_f32_16x16x32_bf16 v[0:3], v[206:209], v[190:193], v[0:3]
	v_mfma_f32_16x16x32_bf16 v[4:7], v[198:201], v[190:193], v[4:7]
	v_mfma_f32_16x16x32_bf16 v[28:31], v[202:205], v[170:173], v[28:31]
	v_mfma_f32_16x16x32_bf16 v[24:27], v[210:213], v[170:173], v[24:27]
	v_mfma_f32_16x16x32_bf16 v[16:19], v[210:213], v[178:181], v[16:19]
	v_mfma_f32_16x16x32_bf16 v[20:23], v[202:205], v[178:181], v[20:23]
	v_mfma_f32_16x16x32_bf16 v[12:15], v[202:205], v[186:189], v[12:15]
	v_mfma_f32_16x16x32_bf16 v[8:11], v[210:213], v[186:189], v[8:11]
	v_mfma_f32_16x16x32_bf16 v[0:3], v[210:213], v[194:197], v[0:3]
	v_mfma_f32_16x16x32_bf16 v[4:7], v[202:205], v[194:197], v[4:7]
	s_setprio 0
	s_add_u32 s4, s4, 0x100
	s_addc_u32 s5, s5, 0
	s_add_u32 s68, s68, 0x100
	s_addc_u32 s69, s69, 0
	s_cmp_ge_i32 s70, s54
	s_mov_b32 s48, s70
	s_barrier
	s_cbranch_scc0 .LBB0_1029
	s_branch .LBB0_1020

; #define PG8_STAGE(bufoff, gbase, voff) do { _Pragma("unroll") for (int _i = 0; _i < 2; ++_i) \
;         __builtin_amdgcn_global_load_lds((const unsigned*)((const char*)(gbase) + (voff)[_i]), (LAS unsigned*)(lds + (bufoff) + ldsw + _i * 8192), 16, 0, 0); } while (0)
; #define PG8_LDA(dst, b, h) do { _Pragma("unroll") for (int m = 0; m < 4; ++m) _Pragma("unroll") for (int k = 0; k < 2; ++k) dst[m][k] = *(const LAS bf16x8*)(lds + PG8_SA(b, h) + aoff + m * 2048 + k * 1024); } while (0)
; #define PG8_LDB(dst, b, h) do { _Pragma("unroll") for (int n = 0; n < 2; ++n) _Pragma("unroll") for (int k = 0; k < 2; ++k) dst[n][k] = *(const LAS bf16x8*)(lds + PG8_SB(b, h) + boff + n * 2048 + k * 1024); } while (0)
; #define PG8_MMA(ai, bj, At, Bt) do { __builtin_amdgcn_s_setprio(1); _Pragma("unroll") for (int m = 0; m < 4; ++m) _Pragma("unroll") for (int n = 0; n < 2; ++n) _Pragma("unroll") for (int k = 0; k < 2; ++k) \
;         acc[ai][bj][m][n] = __builtin_amdgcn_mfma_f32_16x16x32_bf16(Bt[n][k], At[m][k], acc[ai][bj][m][n], 0, 0, 0); __builtin_amdgcn_s_setprio(0); } while (0)
; #define PG8_WAIT_L(n) asm volatile("s_waitcnt lgkmcnt(" #n ")" ::: "memory")
; #define PG8_BAR __builtin_amdgcn_s_barrier()
; #define PG8_SCHED __builtin_amdgcn_sched_barrier(0)
; template <class Epi>
; DEVINL void gemm_phase(LAS unsigned char* lds, const Gemm g, const Order& S, const Epi& E) {
;     ...
;         for (int t = 0; t < nt; t += 2) {
;             const bool last = (t == nt - 2);
;             const char* a1 = cA + (size_t)(t + 1) * kstep;
;             const char* a2 = last ? nA : cA + (size_t)(t + 2) * kstep; const char* b2 = last ? nB : cB + (size_t)(t + 2) * kstep;
;             const char* a3 = a2 + kstep; const char* b3 = b2 + kstep;
;             PG8_LDB(B0, 0, 0); PG8_SCHED; PG8_LDA(At, 0, 0); PG8_STAGE(PG8_SA(1, 1), a1 + hstepA, voffA);
;             PG8_WAIT_L(8); PG8_BAR; PG8_WAIT_L(0); PG8_MMA(0, 0, At, B0); PG8_BAR; PG8_SCHED;
;             PG8_LDB(B1, 0, 1); PG8_STAGE(PG8_SB(0, 0), b2, voffB);
;             PG8_BAR; PG8_WAIT_L(0); PG8_MMA(0, 1, At, B1); PG8_BAR;
;             PG8_LDA(At, 0, 1); PG8_STAGE(PG8_SA(0, 0), a2, voffA);
;             PG8_BAR; PG8_WAIT_L(0); PG8_MMA(1, 0, At, B0); PG8_BAR; PG8_SCHED;
.LBB0_1186:
	ds_read_b128 v[128:131], v159
	ds_read_b128 v[148:151], v159 offset:1024
	ds_read_b128 v[152:155], v159 offset:2048
	ds_read_b128 v[162:165], v159 offset:3072
	s_add_i32 s66, s30, 2
	s_add_u32 s31, s10, 0xfffc0080
	s_addc_u32 s40, s11, -1
	s_cmp_eq_u32 s53, s30
	s_cselect_b32 s30, s17, s64
	s_cselect_b32 s41, s2, s40
	s_cselect_b32 s40, s3, s31
	s_cselect_b32 s31, s13, s65
	v_lshl_add_u64 v[198:199], s[10:11], 0, v[140:141]
	s_add_i32 m0, s29, 0xc000
	ds_read_b128 v[166:169], v160
	ds_read_b128 v[170:173], v160 offset:1024
	ds_read_b128 v[174:177], v160 offset:2048
	ds_read_b128 v[178:181], v160 offset:3072
	ds_read_b128 v[182:185], v160 offset:4096
	ds_read_b128 v[186:189], v160 offset:5120
	ds_read_b128 v[190:193], v160 offset:6144
	ds_read_b128 v[194:197], v160 offset:7168
	global_load_lds_dwordx4 v[198:199], off
	v_lshl_add_u64 v[198:199], s[10:11], 0, v[142:143]
	s_add_i32 m0, s29, 0xe000
	s_nop 0
	global_load_lds_dwordx4 v[198:199], off
	s_waitcnt lgkmcnt(8)
	s_barrier
	s_waitcnt lgkmcnt(0)
	s_setprio 1
	s_waitcnt lgkmcnt(0)
	v_mfma_f32_16x16x32_bf16 v[124:127], v[128:131], v[166:169], v[124:127]
	v_mfma_f32_16x16x32_bf16 v[120:123], v[152:155], v[166:169], v[120:123]
	v_mfma_f32_16x16x32_bf16 v[104:107], v[152:155], v[174:177], v[104:107]
	v_mfma_f32_16x16x32_bf16 v[108:111], v[128:131], v[174:177], v[108:111]
	v_mfma_f32_16x16x32_bf16 v[92:95], v[128:131], v[182:185], v[92:95]
	v_mfma_f32_16x16x32_bf16 v[88:91], v[152:155], v[182:185], v[88:91]
	v_mfma_f32_16x16x32_bf16 v[72:75], v[152:155], v[190:193], v[72:75]
	v_mfma_f32_16x16x32_bf16 v[76:79], v[128:131], v[190:193], v[76:79]
	v_mfma_f32_16x16x32_bf16 v[124:127], v[148:151], v[170:173], v[124:127]
	v_mfma_f32_16x16x32_bf16 v[120:123], v[162:165], v[170:173], v[120:123]
	v_mfma_f32_16x16x32_bf16 v[104:107], v[162:165], v[178:181], v[104:107]
	v_mfma_f32_16x16x32_bf16 v[108:111], v[148:151], v[178:181], v[108:111]
	v_mfma_f32_16x16x32_bf16 v[92:95], v[148:151], v[186:189], v[92:95]
	v_mfma_f32_16x16x32_bf16 v[88:91], v[162:165], v[186:189], v[88:91]
	v_mfma_f32_16x16x32_bf16 v[72:75], v[162:165], v[194:197], v[72:75]
	v_mfma_f32_16x16x32_bf16 v[76:79], v[148:151], v[194:197], v[76:79]
	s_setprio 0
	s_barrier
	s_add_i32 s67, s57, s46
	v_lshl_add_u64 v[218:219], s[30:31], 0, v[134:135]
	s_mov_b32 m0, s67
	ds_read_b128 v[198:201], v161
	ds_read_b128 v[202:205], v161 offset:1024
	ds_read_b128 v[206:209], v161 offset:2048
	ds_read_b128 v[210:213], v161 offset:3072
	global_load_lds_dwordx4 v[218:219], off
	v_lshl_add_u64 v[220:221], s[30:31], 0, v[138:139]
	s_add_i32 m0, s67, 0x2000
	s_nop 0
	global_load_lds_dwordx4 v[220:221], off
	s_barrier
	s_waitcnt lgkmcnt(0)
	s_setprio 1
	s_waitcnt lgkmcnt(0)
	v_mfma_f32_16x16x32_bf16 v[116:119], v[198:201], v[166:169], v[116:119]
	v_mfma_f32_16x16x32_bf16 v[112:115], v[206:209], v[166:169], v[112:115]
	v_mfma_f32_16x16x32_bf16 v[96:99], v[206:209], v[174:177], v[96:99]
	v_mfma_f32_16x16x32_bf16 v[100:103], v[198:201], v[174:177], v[100:103]
	v_mfma_f32_16x16x32_bf16 v[84:87], v[198:201], v[182:185], v[84:87]
	v_mfma_f32_16x16x32_bf16 v[80:83], v[206:209], v[182:185], v[80:83]
	v_mfma_f32_16x16x32_bf16 v[64:67], v[206:209], v[190:193], v[64:67]
	v_mfma_f32_16x16x32_bf16 v[68:71], v[198:201], v[190:193], v[68:71]
	v_mfma_f32_16x16x32_bf16 v[116:119], v[202:205], v[170:173], v[116:119]
	v_mfma_f32_16x16x32_bf16 v[112:115], v[210:213], v[170:173], v[112:115]
	v_mfma_f32_16x16x32_bf16 v[96:99], v[210:213], v[178:181], v[96:99]
	v_mfma_f32_16x16x32_bf16 v[100:103], v[202:205], v[178:181], v[100:103]
	v_mfma_f32_16x16x32_bf16 v[84:87], v[202:205], v[186:189], v[84:87]
	v_mfma_f32_16x16x32_bf16 v[80:83], v[210:213], v[186:189], v[80:83]
	v_mfma_f32_16x16x32_bf16 v[64:67], v[210:213], v[194:197], v[64:67]
	v_mfma_f32_16x16x32_bf16 v[68:71], v[202:205], v[194:197], v[68:71]
	s_setprio 0
	s_mov_b32 m0, s29
	v_lshl_add_u64 v[222:223], s[40:41], 0, v[132:133]
	s_barrier
	ds_read_b128 v[166:169], v160 offset:16384
	ds_read_b128 v[170:173], v160 offset:17408
	ds_read_b128 v[174:177], v160 offset:18432
	ds_read_b128 v[178:181], v160 offset:19456
	ds_read_b128 v[182:185], v160 offset:20480
	ds_read_b128 v[186:189], v160 offset:21504
	ds_read_b128 v[190:193], v160 offset:22528
	ds_read_b128 v[194:197], v160 offset:23552
	global_load_lds_dwordx4 v[222:223], off
	v_lshl_add_u64 v[224:225], s[40:41], 0, v[136:137]
	s_mov_b32 m0, s47
	s_nop 0
	global_load_lds_dwordx4 v[224:225], off
	s_barrier
	s_waitcnt lgkmcnt(0)
	s_setprio 1
	s_waitcnt lgkmcnt(0)
	v_mfma_f32_16x16x32_bf16 v[60:63], v[128:131], v[166:169], v[60:63]
	v_mfma_f32_16x16x32_bf16 v[56:59], v[152:155], v[166:169], v[56:59]
	v_mfma_f32_16x16x32_bf16 v[40:43], v[152:155], v[174:177], v[40:43]
	v_mfma_f32_16x16x32_bf16 v[44:47], v[128:131], v[174:177], v[44:47]
	v_mfma_f32_16x16x32_bf16 v[28:31], v[128:131], v[182:185], v[28:31]
	v_mfma_f32_16x16x32_bf16 v[24:27], v[152:155], v[182:185], v[24:27]
	v_mfma_f32_16x16x32_bf16 v[8:11], v[152:155], v[190:193], v[8:11]
	v_mfma_f32_16x16x32_bf16 v[12:15], v[128:131], v[190:193], v[12:15]
	v_mfma_f32_16x16x32_bf16 v[60:63], v[148:151], v[170:173], v[60:63]
	v_mfma_f32_16x16x32_bf16 v[56:59], v[162:165], v[170:173], v[56:59]
	v_mfma_f32_16x16x32_bf16 v[40:43], v[162:165], v[178:181], v[40:43]
	v_mfma_f32_16x16x32_bf16 v[44:47], v[148:151], v[178:181], v[44:47]
	v_mfma_f32_16x16x32_bf16 v[28:31], v[148:151], v[186:189], v[28:31]
	v_mfma_f32_16x16x32_bf16 v[24:27], v[162:165], v[186:189], v[24:27]
	v_mfma_f32_16x16x32_bf16 v[8:11], v[162:165], v[194:197], v[8:11]
	v_mfma_f32_16x16x32_bf16 v[12:15], v[148:151], v[194:197], v[12:15]
	s_setprio 0
	s_barrier
; #define PG8_STAGE(bufoff, gbase, voff) do { _Pragma("unroll") for (int _i = 0; _i < 2; ++_i) \
;         __builtin_amdgcn_global_load_lds((const unsigned*)((const char*)(gbase) + (voff)[_i]), (LAS unsigned*)(lds + (bufoff) + ldsw + _i * 8192), 16, 0, 0); } while (0)
; #define PG8_LDA(dst, b, h) do { _Pragma("unroll") for (int m = 0; m < 4; ++m) _Pragma("unroll") for (int k = 0; k < 2; ++k) dst[m][k] = *(const LAS bf16x8*)(lds + PG8_SA(b, h) + aoff + m * 2048 + k * 1024); } while (0)
; #define PG8_LDB(dst, b, h) do { _Pragma("unroll") for (int n = 0; n < 2; ++n) _Pragma("unroll") for (int k = 0; k < 2; ++k) dst[n][k] = *(const LAS bf16x8*)(lds + PG8_SB(b, h) + boff + n * 2048 + k * 1024); } while (0)
; #define PG8_MMA(ai, bj, At, Bt) do { __builtin_amdgcn_s_setprio(1); _Pragma("unroll") for (int m = 0; m < 4; ++m) _Pragma("unroll") for (int n = 0; n < 2; ++n) _Pragma("unroll") for (int k = 0; k < 2; ++k) \
;         acc[ai][bj][m][n] = __builtin_amdgcn_mfma_f32_16x16x32_bf16(Bt[n][k], At[m][k], acc[ai][bj][m][n], 0, 0, 0); __builtin_amdgcn_s_setprio(0); } while (0)
; #define PG8_WAIT_V(n) asm volatile("s_waitcnt vmcnt(" #n ")" ::: "memory")
; #define PG8_WAIT_L(n) asm volatile("s_waitcnt lgkmcnt(" #n ")" ::: "memory")
; #define PG8_BAR __builtin_amdgcn_s_barrier()
; #define PG8_SCHED __builtin_amdgcn_sched_barrier(0)
; template <class Epi>
; DEVINL void gemm_phase(LAS unsigned char* lds, const Gemm g, const Order& S, const Epi& E) {
;     ...
;             PG8_STAGE(PG8_SB(0, 1), b2 + hstepB, voffB);
;             PG8_WAIT_V(6); PG8_BAR; PG8_MMA(1, 1, At, B1); PG8_BAR;
;             PG8_LDB(B0, 1, 0); PG8_SCHED; PG8_LDA(At, 1, 0); PG8_STAGE(PG8_SA(0, 1), a2 + hstepA, voffA);
;             PG8_WAIT_L(8); PG8_BAR; PG8_WAIT_L(0); PG8_MMA(0, 0, At, B0); PG8_BAR; PG8_SCHED;
;             PG8_LDB(B1, 1, 1); PG8_STAGE(PG8_SB(1, 0), b3, voffB);
;             PG8_BAR; PG8_WAIT_L(0); PG8_MMA(0, 1, At, B1); PG8_BAR;
;             PG8_LDA(At, 1, 1); PG8_STAGE(PG8_SA(1, 0), a3, voffA);
	s_add_u32 s68, s30, 0x40000
	s_addc_u32 s69, s31, 0
	s_add_i32 s67, s58, s46
	v_lshl_add_u64 v[128:129], s[68:69], 0, v[134:135]
	s_mov_b32 m0, s67
	s_nop 0
	global_load_lds_dwordx4 v[128:129], off
	v_lshl_add_u64 v[128:129], s[68:69], 0, v[138:139]
	s_add_i32 m0, s67, 0x2000
	s_nop 0
	global_load_lds_dwordx4 v[128:129], off
	s_waitcnt vmcnt(6)
	s_barrier
	s_setprio 1
	v_mfma_f32_16x16x32_bf16 v[52:55], v[198:201], v[166:169], v[52:55]
	v_mfma_f32_16x16x32_bf16 v[48:51], v[206:209], v[166:169], v[48:51]
	v_mfma_f32_16x16x32_bf16 v[32:35], v[206:209], v[174:177], v[32:35]
	v_mfma_f32_16x16x32_bf16 v[36:39], v[198:201], v[174:177], v[36:39]
	v_mfma_f32_16x16x32_bf16 v[20:23], v[198:201], v[182:185], v[20:23]
	v_mfma_f32_16x16x32_bf16 v[16:19], v[206:209], v[182:185], v[16:19]
	v_mfma_f32_16x16x32_bf16 v[0:3], v[206:209], v[190:193], v[0:3]
	v_mfma_f32_16x16x32_bf16 v[4:7], v[198:201], v[190:193], v[4:7]
	v_mfma_f32_16x16x32_bf16 v[52:55], v[202:205], v[170:173], v[52:55]
	v_mfma_f32_16x16x32_bf16 v[48:51], v[210:213], v[170:173], v[48:51]
	v_mfma_f32_16x16x32_bf16 v[32:35], v[210:213], v[178:181], v[32:35]
	v_mfma_f32_16x16x32_bf16 v[36:39], v[202:205], v[178:181], v[36:39]
	v_mfma_f32_16x16x32_bf16 v[20:23], v[202:205], v[186:189], v[20:23]
	v_mfma_f32_16x16x32_bf16 v[16:19], v[210:213], v[186:189], v[16:19]
	v_mfma_f32_16x16x32_bf16 v[0:3], v[210:213], v[194:197], v[0:3]
	v_mfma_f32_16x16x32_bf16 v[4:7], v[202:205], v[194:197], v[4:7]
	s_setprio 0
	s_add_i32 s67, 16, 0x18000
	v_add_u32_e32 v162, s67, v157
	s_barrier
	ds_read_b128 v[128:131], v162
	ds_read_b128 v[148:151], v162 offset:1024
	ds_read_b128 v[152:155], v162 offset:2048
	ds_read_b128 v[162:165], v162 offset:3072
	s_add_u32 s40, s40, 0x40000
	s_addc_u32 s41, s41, 0
	s_mov_b32 m0, s48
	v_lshl_add_u64 v[198:199], s[40:41], 0, v[132:133]
	ds_read_b128 v[166:169], v160 offset:32768
	ds_read_b128 v[170:173], v160 offset:33792
	ds_read_b128 v[174:177], v160 offset:34816
	ds_read_b128 v[178:181], v160 offset:35840
	ds_read_b128 v[182:185], v160 offset:36864
	ds_read_b128 v[186:189], v160 offset:37888
	ds_read_b128 v[190:193], v160 offset:38912
	ds_read_b128 v[194:197], v160 offset:39936
	global_load_lds_dwordx4 v[198:199], off
	v_lshl_add_u64 v[198:199], s[40:41], 0, v[136:137]
	s_mov_b32 m0, s49
	s_nop 0
	global_load_lds_dwordx4 v[198:199], off
	s_waitcnt lgkmcnt(8)
	s_barrier
	s_waitcnt lgkmcnt(0)
	s_setprio 1
	s_waitcnt lgkmcnt(0)
	v_mfma_f32_16x16x32_bf16 v[124:127], v[128:131], v[166:169], v[124:127]
	v_mfma_f32_16x16x32_bf16 v[120:123], v[152:155], v[166:169], v[120:123]
	v_mfma_f32_16x16x32_bf16 v[104:107], v[152:155], v[174:177], v[104:107]
	v_mfma_f32_16x16x32_bf16 v[108:111], v[128:131], v[174:177], v[108:111]
	v_mfma_f32_16x16x32_bf16 v[92:95], v[128:131], v[182:185], v[92:95]
	v_mfma_f32_16x16x32_bf16 v[88:91], v[152:155], v[182:185], v[88:91]
	v_mfma_f32_16x16x32_bf16 v[72:75], v[152:155], v[190:193], v[72:75]
	v_mfma_f32_16x16x32_bf16 v[76:79], v[128:131], v[190:193], v[76:79]
	v_mfma_f32_16x16x32_bf16 v[124:127], v[148:151], v[170:173], v[124:127]
	v_mfma_f32_16x16x32_bf16 v[120:123], v[162:165], v[170:173], v[120:123]
	v_mfma_f32_16x16x32_bf16 v[104:107], v[162:165], v[178:181], v[104:107]
	v_mfma_f32_16x16x32_bf16 v[108:111], v[148:151], v[178:181], v[108:111]
	v_mfma_f32_16x16x32_bf16 v[92:95], v[148:151], v[186:189], v[92:95]
	v_mfma_f32_16x16x32_bf16 v[88:91], v[162:165], v[186:189], v[88:91]
	v_mfma_f32_16x16x32_bf16 v[72:75], v[162:165], v[194:197], v[72:75]
	v_mfma_f32_16x16x32_bf16 v[76:79], v[148:151], v[194:197], v[76:79]
	s_setprio 0
	s_barrier
	s_add_i32 s40, 16, 0x1c000
	s_add_i32 s41, s67, s46
	v_add_u32_e32 v210, s40, v157
	v_lshl_add_u64 v[218:219], v[218:219], 0, s[6:7]
	s_mov_b32 m0, s41
	ds_read_b128 v[198:201], v210
	ds_read_b128 v[202:205], v210 offset:1024
	ds_read_b128 v[206:209], v210 offset:2048
	ds_read_b128 v[210:213], v210 offset:3072
	global_load_lds_dwordx4 v[218:219], off
	v_lshl_add_u64 v[218:219], v[220:221], 0, s[6:7]
	s_add_i32 m0, s41, 0x2000
	s_nop 0
	global_load_lds_dwordx4 v[218:219], off
	s_barrier
; #define PG8_STAGE(bufoff, gbase, voff) do { _Pragma("unroll") for (int _i = 0; _i < 2; ++_i) \
;         __builtin_amdgcn_global_load_lds((const unsigned*)((const char*)(gbase) + (voff)[_i]), (LAS unsigned*)(lds + (bufoff) + ldsw + _i * 8192), 16, 0, 0); } while (0)
; #define PG8_MMA(ai, bj, At, Bt) do { __builtin_amdgcn_s_setprio(1); _Pragma("unroll") for (int m = 0; m < 4; ++m) _Pragma("unroll") for (int n = 0; n < 2; ++n) _Pragma("unroll") for (int k = 0; k < 2; ++k) \
;         acc[ai][bj][m][n] = __builtin_amdgcn_mfma_f32_16x16x32_bf16(Bt[n][k], At[m][k], acc[ai][bj][m][n], 0, 0, 0); __builtin_amdgcn_s_setprio(0); } while (0)
; #define PG8_WAIT_V(n) asm volatile("s_waitcnt vmcnt(" #n ")" ::: "memory")
; #define PG8_WAIT_L(n) asm volatile("s_waitcnt lgkmcnt(" #n ")" ::: "memory")
; #define PG8_BAR __builtin_amdgcn_s_barrier()
; #define PG8_SCHED __builtin_amdgcn_sched_barrier(0)
; template <class Epi>
; DEVINL void gemm_phase(LAS unsigned char* lds, const Gemm g, const Order& S, const Epi& E) {
;     ...
;             PG8_BAR; PG8_WAIT_L(0); PG8_MMA(1, 0, At, B0); PG8_BAR; PG8_SCHED;
;             PG8_STAGE(PG8_SB(1, 1), b3 + hstepB, voffB);
;             PG8_WAIT_V(6); PG8_BAR; PG8_MMA(1, 1, At, B1); PG8_BAR;
;         }
	s_waitcnt lgkmcnt(0)
	s_setprio 1
	s_waitcnt lgkmcnt(0)
	v_mfma_f32_16x16x32_bf16 v[116:119], v[198:201], v[166:169], v[116:119]
	v_mfma_f32_16x16x32_bf16 v[112:115], v[206:209], v[166:169], v[112:115]
	v_mfma_f32_16x16x32_bf16 v[96:99], v[206:209], v[174:177], v[96:99]
	v_mfma_f32_16x16x32_bf16 v[100:103], v[198:201], v[174:177], v[100:103]
	v_mfma_f32_16x16x32_bf16 v[84:87], v[198:201], v[182:185], v[84:87]
	v_mfma_f32_16x16x32_bf16 v[80:83], v[206:209], v[182:185], v[80:83]
	v_mfma_f32_16x16x32_bf16 v[64:67], v[206:209], v[190:193], v[64:67]
	v_mfma_f32_16x16x32_bf16 v[68:71], v[198:201], v[190:193], v[68:71]
	v_mfma_f32_16x16x32_bf16 v[116:119], v[202:205], v[170:173], v[116:119]
	v_mfma_f32_16x16x32_bf16 v[112:115], v[210:213], v[170:173], v[112:115]
	v_mfma_f32_16x16x32_bf16 v[96:99], v[210:213], v[178:181], v[96:99]
	v_mfma_f32_16x16x32_bf16 v[100:103], v[202:205], v[178:181], v[100:103]
	v_mfma_f32_16x16x32_bf16 v[84:87], v[202:205], v[186:189], v[84:87]
	v_mfma_f32_16x16x32_bf16 v[80:83], v[210:213], v[186:189], v[80:83]
	v_mfma_f32_16x16x32_bf16 v[64:67], v[210:213], v[194:197], v[64:67]
	v_mfma_f32_16x16x32_bf16 v[68:71], v[202:205], v[194:197], v[68:71]
	s_setprio 0
	s_mov_b32 m0, s51
	v_lshl_add_u64 v[218:219], v[222:223], 0, s[6:7]
	s_barrier
	ds_read_b128 v[166:169], v160 offset:49152
	ds_read_b128 v[170:173], v160 offset:50176
	ds_read_b128 v[174:177], v160 offset:51200
	ds_read_b128 v[178:181], v160 offset:52224
	ds_read_b128 v[182:185], v160 offset:53248
	ds_read_b128 v[186:189], v160 offset:54272
	ds_read_b128 v[190:193], v160 offset:55296
	ds_read_b128 v[194:197], v160 offset:56320
	global_load_lds_dwordx4 v[218:219], off
	v_lshl_add_u64 v[218:219], v[224:225], 0, s[6:7]
	s_mov_b32 m0, s52
	s_nop 0
	global_load_lds_dwordx4 v[218:219], off
	s_barrier
	s_waitcnt lgkmcnt(0)
	s_setprio 1
	s_waitcnt lgkmcnt(0)
	v_mfma_f32_16x16x32_bf16 v[60:63], v[128:131], v[166:169], v[60:63]
	v_mfma_f32_16x16x32_bf16 v[56:59], v[152:155], v[166:169], v[56:59]
	v_mfma_f32_16x16x32_bf16 v[40:43], v[152:155], v[174:177], v[40:43]
	v_mfma_f32_16x16x32_bf16 v[44:47], v[128:131], v[174:177], v[44:47]
	v_mfma_f32_16x16x32_bf16 v[28:31], v[128:131], v[182:185], v[28:31]
	v_mfma_f32_16x16x32_bf16 v[24:27], v[152:155], v[182:185], v[24:27]
	v_mfma_f32_16x16x32_bf16 v[8:11], v[152:155], v[190:193], v[8:11]
	v_mfma_f32_16x16x32_bf16 v[12:15], v[128:131], v[190:193], v[12:15]
	v_mfma_f32_16x16x32_bf16 v[60:63], v[148:151], v[170:173], v[60:63]
	v_mfma_f32_16x16x32_bf16 v[56:59], v[162:165], v[170:173], v[56:59]
	v_mfma_f32_16x16x32_bf16 v[40:43], v[162:165], v[178:181], v[40:43]
	v_mfma_f32_16x16x32_bf16 v[44:47], v[148:151], v[178:181], v[44:47]
	v_mfma_f32_16x16x32_bf16 v[28:31], v[148:151], v[186:189], v[28:31]
	v_mfma_f32_16x16x32_bf16 v[24:27], v[162:165], v[186:189], v[24:27]
	v_mfma_f32_16x16x32_bf16 v[8:11], v[162:165], v[194:197], v[8:11]
	v_mfma_f32_16x16x32_bf16 v[12:15], v[148:151], v[194:197], v[12:15]
	s_setprio 0
	s_barrier
	s_add_u32 s30, s30, 0x40080
	s_addc_u32 s31, s31, 0
	s_add_i32 s40, s40, s46
	v_lshl_add_u64 v[128:129], s[30:31], 0, v[134:135]
	s_mov_b32 m0, s40
	s_nop 0
	global_load_lds_dwordx4 v[128:129], off
	v_lshl_add_u64 v[128:129], s[30:31], 0, v[138:139]
	s_add_i32 m0, s40, 0x2000
	s_nop 0
	global_load_lds_dwordx4 v[128:129], off
	s_waitcnt vmcnt(6)
	s_barrier
	s_setprio 1
	v_mfma_f32_16x16x32_bf16 v[52:55], v[198:201], v[166:169], v[52:55]
	v_mfma_f32_16x16x32_bf16 v[48:51], v[206:209], v[166:169], v[48:51]
	v_mfma_f32_16x16x32_bf16 v[32:35], v[206:209], v[174:177], v[32:35]
	v_mfma_f32_16x16x32_bf16 v[36:39], v[198:201], v[174:177], v[36:39]
	v_mfma_f32_16x16x32_bf16 v[20:23], v[198:201], v[182:185], v[20:23]
	v_mfma_f32_16x16x32_bf16 v[16:19], v[206:209], v[182:185], v[16:19]
	v_mfma_f32_16x16x32_bf16 v[0:3], v[206:209], v[190:193], v[0:3]
	v_mfma_f32_16x16x32_bf16 v[4:7], v[198:201], v[190:193], v[4:7]
	v_mfma_f32_16x16x32_bf16 v[52:55], v[202:205], v[170:173], v[52:55]
	v_mfma_f32_16x16x32_bf16 v[48:51], v[210:213], v[170:173], v[48:51]
	v_mfma_f32_16x16x32_bf16 v[32:35], v[210:213], v[178:181], v[32:35]
	v_mfma_f32_16x16x32_bf16 v[36:39], v[202:205], v[178:181], v[36:39]
	v_mfma_f32_16x16x32_bf16 v[20:23], v[202:205], v[186:189], v[20:23]
	v_mfma_f32_16x16x32_bf16 v[16:19], v[210:213], v[186:189], v[16:19]
	v_mfma_f32_16x16x32_bf16 v[0:3], v[210:213], v[194:197], v[0:3]
	v_mfma_f32_16x16x32_bf16 v[4:7], v[202:205], v[194:197], v[4:7]
	s_setprio 0
	s_add_u32 s10, s10, 0x100
	s_addc_u32 s11, s11, 0
	s_add_u32 s64, s64, 0x100
	s_addc_u32 s65, s65, 0
	s_cmp_ge_i32 s66, s50
	s_mov_b32 s30, s66
	s_barrier
	s_cbranch_scc0 .LBB0_1186
	s_branch .LBB0_1177

; #define PG8_STAGE(bufoff, gbase, voff) do { _Pragma("unroll") for (int _i = 0; _i < 2; ++_i) \
;         __builtin_amdgcn_global_load_lds((const unsigned*)((const char*)(gbase) + (voff)[_i]), (LAS unsigned*)(lds + (bufoff) + ldsw + _i * 8192), 16, 0, 0); } while (0)
; #define PG8_LDA(dst, b, h) do { _Pragma("unroll") for (int m = 0; m < 4; ++m) _Pragma("unroll") for (int k = 0; k < 2; ++k) dst[m][k] = *(const LAS bf16x8*)(lds + PG8_SA(b, h) + aoff + m * 2048 + k * 1024); } while (0)
; #define PG8_LDB(dst, b, h) do { _Pragma("unroll") for (int n = 0; n < 2; ++n) _Pragma("unroll") for (int k = 0; k < 2; ++k) dst[n][k] = *(const LAS bf16x8*)(lds + PG8_SB(b, h) + boff + n * 2048 + k * 1024); } while (0)
; #define PG8_MMA(ai, bj, At, Bt) do { __builtin_amdgcn_s_setprio(1); _Pragma("unroll") for (int m = 0; m < 4; ++m) _Pragma("unroll") for (int n = 0; n < 2; ++n) _Pragma("unroll") for (int k = 0; k < 2; ++k) \
;         acc[ai][bj][m][n] = __builtin_amdgcn_mfma_f32_16x16x32_bf16(Bt[n][k], At[m][k], acc[ai][bj][m][n], 0, 0, 0); __builtin_amdgcn_s_setprio(0); } while (0)
; #define PG8_WAIT_L(n) asm volatile("s_waitcnt lgkmcnt(" #n ")" ::: "memory")
; #define PG8_BAR __builtin_amdgcn_s_barrier()
; #define PG8_SCHED __builtin_amdgcn_sched_barrier(0)
; template <class Epi>
; DEVINL void gemm_phase(LAS unsigned char* lds, const Gemm g, const Order& S, const Epi& E) {
;     ...
;         for (int t = 0; t < nt; t += 2) {
;             const bool last = (t == nt - 2);
;             const char* a1 = cA + (size_t)(t + 1) * kstep;
;             const char* a2 = last ? nA : cA + (size_t)(t + 2) * kstep; const char* b2 = last ? nB : cB + (size_t)(t + 2) * kstep;
;             const char* a3 = a2 + kstep; const char* b3 = b2 + kstep;
;             PG8_LDB(B0, 0, 0); PG8_SCHED; PG8_LDA(At, 0, 0); PG8_STAGE(PG8_SA(1, 1), a1 + hstepA, voffA);
;             PG8_WAIT_L(8); PG8_BAR; PG8_WAIT_L(0); PG8_MMA(0, 0, At, B0); PG8_BAR; PG8_SCHED;
;             PG8_LDB(B1, 0, 1); PG8_STAGE(PG8_SB(0, 0), b2, voffB);
;             PG8_BAR; PG8_WAIT_L(0); PG8_MMA(0, 1, At, B1); PG8_BAR;
;             PG8_LDA(At, 0, 1); PG8_STAGE(PG8_SA(0, 0), a2, voffA);
;             PG8_BAR; PG8_WAIT_L(0); PG8_MMA(1, 0, At, B0); PG8_BAR; PG8_SCHED;
.LBB0_1259:
	ds_read_b128 v[128:131], v183
	ds_read_b128 v[132:135], v183 offset:1024
	ds_read_b128 v[136:139], v183 offset:2048
	ds_read_b128 v[140:143], v183 offset:3072
	s_add_i32 s68, s40, 2
	s_add_u32 s41, s8, 0xfffc0080
	s_addc_u32 s42, s9, -1
	s_cmp_eq_u32 s55, s40
	s_cselect_b32 s40, s25, s66
	s_cselect_b32 s43, s2, s42
	s_cselect_b32 s42, s3, s41
	s_cselect_b32 s41, s17, s67
	v_lshl_add_u64 v[198:199], s[8:9], 0, v[160:161]
	s_add_i32 m0, s31, 0xc000
	ds_read_b128 v[144:147], v184
	ds_read_b128 v[148:151], v184 offset:1024
	ds_read_b128 v[168:171], v184 offset:2048
	ds_read_b128 v[172:175], v184 offset:3072
	ds_read_b128 v[176:179], v184 offset:4096
	ds_read_b128 v[186:189], v184 offset:5120
	ds_read_b128 v[190:193], v184 offset:6144
	ds_read_b128 v[194:197], v184 offset:7168
	global_load_lds_dwordx4 v[198:199], off
	v_lshl_add_u64 v[198:199], s[8:9], 0, v[162:163]
	s_add_i32 m0, s31, 0xe000
	s_nop 0
	global_load_lds_dwordx4 v[198:199], off
	s_waitcnt lgkmcnt(8)
	s_barrier
	s_waitcnt lgkmcnt(0)
	s_setprio 1
	s_waitcnt lgkmcnt(0)
	v_mfma_f32_16x16x32_bf16 v[116:119], v[128:131], v[144:147], v[116:119]
	v_mfma_f32_16x16x32_bf16 v[124:127], v[136:139], v[144:147], v[124:127]
	v_mfma_f32_16x16x32_bf16 v[104:107], v[136:139], v[168:171], v[104:107]
	v_mfma_f32_16x16x32_bf16 v[108:111], v[128:131], v[168:171], v[108:111]
	v_mfma_f32_16x16x32_bf16 v[92:95], v[128:131], v[176:179], v[92:95]
	v_mfma_f32_16x16x32_bf16 v[88:91], v[136:139], v[176:179], v[88:91]
	v_mfma_f32_16x16x32_bf16 v[72:75], v[136:139], v[190:193], v[72:75]
	v_mfma_f32_16x16x32_bf16 v[76:79], v[128:131], v[190:193], v[76:79]
	v_mfma_f32_16x16x32_bf16 v[116:119], v[132:135], v[148:151], v[116:119]
	v_mfma_f32_16x16x32_bf16 v[124:127], v[140:143], v[148:151], v[124:127]
	v_mfma_f32_16x16x32_bf16 v[104:107], v[140:143], v[172:175], v[104:107]
	v_mfma_f32_16x16x32_bf16 v[108:111], v[132:135], v[172:175], v[108:111]
	v_mfma_f32_16x16x32_bf16 v[92:95], v[132:135], v[186:189], v[92:95]
	v_mfma_f32_16x16x32_bf16 v[88:91], v[140:143], v[186:189], v[88:91]
	v_mfma_f32_16x16x32_bf16 v[72:75], v[140:143], v[194:197], v[72:75]
	v_mfma_f32_16x16x32_bf16 v[76:79], v[132:135], v[194:197], v[76:79]
	s_setprio 0
	s_barrier
	s_add_i32 s69, s59, s48
	v_lshl_add_u64 v[218:219], s[40:41], 0, v[154:155]
	s_mov_b32 m0, s69
	ds_read_b128 v[198:201], v185
	ds_read_b128 v[202:205], v185 offset:1024
	ds_read_b128 v[206:209], v185 offset:2048
	ds_read_b128 v[210:213], v185 offset:3072
	global_load_lds_dwordx4 v[218:219], off
	v_lshl_add_u64 v[220:221], s[40:41], 0, v[158:159]
	s_add_i32 m0, s69, 0x2000
	s_nop 0
	global_load_lds_dwordx4 v[220:221], off
	s_barrier
	s_waitcnt lgkmcnt(0)
	s_setprio 1
	s_waitcnt lgkmcnt(0)
	v_mfma_f32_16x16x32_bf16 v[120:123], v[198:201], v[144:147], v[120:123]
	v_mfma_f32_16x16x32_bf16 v[112:115], v[206:209], v[144:147], v[112:115]
	v_mfma_f32_16x16x32_bf16 v[96:99], v[206:209], v[168:171], v[96:99]
	v_mfma_f32_16x16x32_bf16 v[100:103], v[198:201], v[168:171], v[100:103]
	v_mfma_f32_16x16x32_bf16 v[84:87], v[198:201], v[176:179], v[84:87]
	v_mfma_f32_16x16x32_bf16 v[80:83], v[206:209], v[176:179], v[80:83]
	v_mfma_f32_16x16x32_bf16 v[64:67], v[206:209], v[190:193], v[64:67]
	v_mfma_f32_16x16x32_bf16 v[68:71], v[198:201], v[190:193], v[68:71]
	v_mfma_f32_16x16x32_bf16 v[120:123], v[202:205], v[148:151], v[120:123]
	v_mfma_f32_16x16x32_bf16 v[112:115], v[210:213], v[148:151], v[112:115]
	v_mfma_f32_16x16x32_bf16 v[96:99], v[210:213], v[172:175], v[96:99]
	v_mfma_f32_16x16x32_bf16 v[100:103], v[202:205], v[172:175], v[100:103]
	v_mfma_f32_16x16x32_bf16 v[84:87], v[202:205], v[186:189], v[84:87]
	v_mfma_f32_16x16x32_bf16 v[80:83], v[210:213], v[186:189], v[80:83]
	v_mfma_f32_16x16x32_bf16 v[64:67], v[210:213], v[194:197], v[64:67]
	v_mfma_f32_16x16x32_bf16 v[68:71], v[202:205], v[194:197], v[68:71]
	s_setprio 0
	s_mov_b32 m0, s31
	v_lshl_add_u64 v[222:223], s[42:43], 0, v[152:153]
	s_barrier
	ds_read_b128 v[144:147], v184 offset:16384
	ds_read_b128 v[148:151], v184 offset:17408
	ds_read_b128 v[168:171], v184 offset:18432
	ds_read_b128 v[172:175], v184 offset:19456
	ds_read_b128 v[176:179], v184 offset:20480
	ds_read_b128 v[186:189], v184 offset:21504
	ds_read_b128 v[190:193], v184 offset:22528
	ds_read_b128 v[194:197], v184 offset:23552
	global_load_lds_dwordx4 v[222:223], off
	v_lshl_add_u64 v[224:225], s[42:43], 0, v[156:157]
	s_mov_b32 m0, s49
	s_nop 0
	global_load_lds_dwordx4 v[224:225], off
	s_barrier
	s_waitcnt lgkmcnt(0)
	s_setprio 1
	s_waitcnt lgkmcnt(0)
	v_mfma_f32_16x16x32_bf16 v[60:63], v[128:131], v[144:147], v[60:63]
	v_mfma_f32_16x16x32_bf16 v[56:59], v[136:139], v[144:147], v[56:59]
	v_mfma_f32_16x16x32_bf16 v[40:43], v[136:139], v[168:171], v[40:43]
	v_mfma_f32_16x16x32_bf16 v[44:47], v[128:131], v[168:171], v[44:47]
	v_mfma_f32_16x16x32_bf16 v[28:31], v[128:131], v[176:179], v[28:31]
	v_mfma_f32_16x16x32_bf16 v[24:27], v[136:139], v[176:179], v[24:27]
	v_mfma_f32_16x16x32_bf16 v[8:11], v[136:139], v[190:193], v[8:11]
	v_mfma_f32_16x16x32_bf16 v[12:15], v[128:131], v[190:193], v[12:15]
	v_mfma_f32_16x16x32_bf16 v[60:63], v[132:135], v[148:151], v[60:63]
	v_mfma_f32_16x16x32_bf16 v[56:59], v[140:143], v[148:151], v[56:59]
	v_mfma_f32_16x16x32_bf16 v[40:43], v[140:143], v[172:175], v[40:43]
	v_mfma_f32_16x16x32_bf16 v[44:47], v[132:135], v[172:175], v[44:47]
	v_mfma_f32_16x16x32_bf16 v[28:31], v[132:135], v[186:189], v[28:31]
	v_mfma_f32_16x16x32_bf16 v[24:27], v[140:143], v[186:189], v[24:27]
	v_mfma_f32_16x16x32_bf16 v[8:11], v[140:143], v[194:197], v[8:11]
	v_mfma_f32_16x16x32_bf16 v[12:15], v[132:135], v[194:197], v[12:15]
	s_setprio 0
	s_barrier
; #define PG8_STAGE(bufoff, gbase, voff) do { _Pragma("unroll") for (int _i = 0; _i < 2; ++_i) \
;         __builtin_amdgcn_global_load_lds((const unsigned*)((const char*)(gbase) + (voff)[_i]), (LAS unsigned*)(lds + (bufoff) + ldsw + _i * 8192), 16, 0, 0); } while (0)
; #define PG8_LDA(dst, b, h) do { _Pragma("unroll") for (int m = 0; m < 4; ++m) _Pragma("unroll") for (int k = 0; k < 2; ++k) dst[m][k] = *(const LAS bf16x8*)(lds + PG8_SA(b, h) + aoff + m * 2048 + k * 1024); } while (0)
; #define PG8_LDB(dst, b, h) do { _Pragma("unroll") for (int n = 0; n < 2; ++n) _Pragma("unroll") for (int k = 0; k < 2; ++k) dst[n][k] = *(const LAS bf16x8*)(lds + PG8_SB(b, h) + boff + n * 2048 + k * 1024); } while (0)
; #define PG8_MMA(ai, bj, At, Bt) do { __builtin_amdgcn_s_setprio(1); _Pragma("unroll") for (int m = 0; m < 4; ++m) _Pragma("unroll") for (int n = 0; n < 2; ++n) _Pragma("unroll") for (int k = 0; k < 2; ++k) \
;         acc[ai][bj][m][n] = __builtin_amdgcn_mfma_f32_16x16x32_bf16(Bt[n][k], At[m][k], acc[ai][bj][m][n], 0, 0, 0); __builtin_amdgcn_s_setprio(0); } while (0)
; #define PG8_WAIT_V(n) asm volatile("s_waitcnt vmcnt(" #n ")" ::: "memory")
; #define PG8_WAIT_L(n) asm volatile("s_waitcnt lgkmcnt(" #n ")" ::: "memory")
; #define PG8_BAR __builtin_amdgcn_s_barrier()
; #define PG8_SCHED __builtin_amdgcn_sched_barrier(0)
; template <class Epi>
; DEVINL void gemm_phase(LAS unsigned char* lds, const Gemm g, const Order& S, const Epi& E) {
;     ...
;             PG8_STAGE(PG8_SB(0, 1), b2 + hstepB, voffB);
;             PG8_WAIT_V(6); PG8_BAR; PG8_MMA(1, 1, At, B1); PG8_BAR;
;             PG8_LDB(B0, 1, 0); PG8_SCHED; PG8_LDA(At, 1, 0); PG8_STAGE(PG8_SA(0, 1), a2 + hstepA, voffA);
;             PG8_WAIT_L(8); PG8_BAR; PG8_WAIT_L(0); PG8_MMA(0, 0, At, B0); PG8_BAR; PG8_SCHED;
;             PG8_LDB(B1, 1, 1); PG8_STAGE(PG8_SB(1, 0), b3, voffB);
;             PG8_BAR; PG8_WAIT_L(0); PG8_MMA(0, 1, At, B1); PG8_BAR;
;             PG8_LDA(At, 1, 1); PG8_STAGE(PG8_SA(1, 0), a3, voffA);
	s_add_u32 s70, s40, 0x40000
	s_addc_u32 s71, s41, 0
	s_add_i32 s69, s64, s48
	v_lshl_add_u64 v[128:129], s[70:71], 0, v[154:155]
	s_mov_b32 m0, s69
	s_nop 0
	global_load_lds_dwordx4 v[128:129], off
	v_lshl_add_u64 v[128:129], s[70:71], 0, v[158:159]
	s_add_i32 m0, s69, 0x2000
	s_nop 0
	global_load_lds_dwordx4 v[128:129], off
	s_waitcnt vmcnt(6)
	s_barrier
	s_setprio 1
	v_mfma_f32_16x16x32_bf16 v[52:55], v[198:201], v[144:147], v[52:55]
	v_mfma_f32_16x16x32_bf16 v[48:51], v[206:209], v[144:147], v[48:51]
	v_mfma_f32_16x16x32_bf16 v[32:35], v[206:209], v[168:171], v[32:35]
	v_mfma_f32_16x16x32_bf16 v[36:39], v[198:201], v[168:171], v[36:39]
	v_mfma_f32_16x16x32_bf16 v[20:23], v[198:201], v[176:179], v[20:23]
	v_mfma_f32_16x16x32_bf16 v[16:19], v[206:209], v[176:179], v[16:19]
	v_mfma_f32_16x16x32_bf16 v[0:3], v[206:209], v[190:193], v[0:3]
	v_mfma_f32_16x16x32_bf16 v[4:7], v[198:201], v[190:193], v[4:7]
	v_mfma_f32_16x16x32_bf16 v[52:55], v[202:205], v[148:151], v[52:55]
	v_mfma_f32_16x16x32_bf16 v[48:51], v[210:213], v[148:151], v[48:51]
	v_mfma_f32_16x16x32_bf16 v[32:35], v[210:213], v[172:175], v[32:35]
	v_mfma_f32_16x16x32_bf16 v[36:39], v[202:205], v[172:175], v[36:39]
	v_mfma_f32_16x16x32_bf16 v[20:23], v[202:205], v[186:189], v[20:23]
	v_mfma_f32_16x16x32_bf16 v[16:19], v[210:213], v[186:189], v[16:19]
	v_mfma_f32_16x16x32_bf16 v[0:3], v[210:213], v[194:197], v[0:3]
	v_mfma_f32_16x16x32_bf16 v[4:7], v[202:205], v[194:197], v[4:7]
	s_setprio 0
	s_add_i32 s69, 16, 0x18000
	v_add_u32_e32 v140, s69, v181
	s_barrier
	ds_read_b128 v[128:131], v140
	ds_read_b128 v[132:135], v140 offset:1024
	ds_read_b128 v[136:139], v140 offset:2048
	ds_read_b128 v[140:143], v140 offset:3072
	s_add_u32 s42, s42, 0x40000
	s_addc_u32 s43, s43, 0
	s_mov_b32 m0, s50
	v_lshl_add_u64 v[198:199], s[42:43], 0, v[152:153]
	ds_read_b128 v[144:147], v184 offset:32768
	ds_read_b128 v[148:151], v184 offset:33792
	ds_read_b128 v[168:171], v184 offset:34816
	ds_read_b128 v[172:175], v184 offset:35840
	ds_read_b128 v[176:179], v184 offset:36864
	ds_read_b128 v[186:189], v184 offset:37888
	ds_read_b128 v[190:193], v184 offset:38912
	ds_read_b128 v[194:197], v184 offset:39936
	global_load_lds_dwordx4 v[198:199], off
	v_lshl_add_u64 v[198:199], s[42:43], 0, v[156:157]
	s_mov_b32 m0, s51
	s_nop 0
	global_load_lds_dwordx4 v[198:199], off
	s_waitcnt lgkmcnt(8)
	s_barrier
	s_waitcnt lgkmcnt(0)
	s_setprio 1
	s_waitcnt lgkmcnt(0)
	v_mfma_f32_16x16x32_bf16 v[116:119], v[128:131], v[144:147], v[116:119]
	v_mfma_f32_16x16x32_bf16 v[124:127], v[136:139], v[144:147], v[124:127]
	v_mfma_f32_16x16x32_bf16 v[104:107], v[136:139], v[168:171], v[104:107]
	v_mfma_f32_16x16x32_bf16 v[108:111], v[128:131], v[168:171], v[108:111]
	v_mfma_f32_16x16x32_bf16 v[92:95], v[128:131], v[176:179], v[92:95]
	v_mfma_f32_16x16x32_bf16 v[88:91], v[136:139], v[176:179], v[88:91]
	v_mfma_f32_16x16x32_bf16 v[72:75], v[136:139], v[190:193], v[72:75]
	v_mfma_f32_16x16x32_bf16 v[76:79], v[128:131], v[190:193], v[76:79]
	v_mfma_f32_16x16x32_bf16 v[116:119], v[132:135], v[148:151], v[116:119]
	v_mfma_f32_16x16x32_bf16 v[124:127], v[140:143], v[148:151], v[124:127]
	v_mfma_f32_16x16x32_bf16 v[104:107], v[140:143], v[172:175], v[104:107]
	v_mfma_f32_16x16x32_bf16 v[108:111], v[132:135], v[172:175], v[108:111]
	v_mfma_f32_16x16x32_bf16 v[92:95], v[132:135], v[186:189], v[92:95]
	v_mfma_f32_16x16x32_bf16 v[88:91], v[140:143], v[186:189], v[88:91]
	v_mfma_f32_16x16x32_bf16 v[72:75], v[140:143], v[194:197], v[72:75]
	v_mfma_f32_16x16x32_bf16 v[76:79], v[132:135], v[194:197], v[76:79]
	s_setprio 0
	s_barrier
	s_add_i32 s42, 16, 0x1c000
	s_add_i32 s43, s69, s48
	v_add_u32_e32 v210, s42, v181
	v_lshl_add_u64 v[218:219], v[218:219], 0, s[10:11]
	s_mov_b32 m0, s43
	ds_read_b128 v[198:201], v210
	ds_read_b128 v[202:205], v210 offset:1024
	ds_read_b128 v[206:209], v210 offset:2048
	ds_read_b128 v[210:213], v210 offset:3072
	global_load_lds_dwordx4 v[218:219], off
	v_lshl_add_u64 v[218:219], v[220:221], 0, s[10:11]
	s_add_i32 m0, s43, 0x2000
	s_nop 0
	global_load_lds_dwordx4 v[218:219], off
	s_barrier
; #define PG8_STAGE(bufoff, gbase, voff) do { _Pragma("unroll") for (int _i = 0; _i < 2; ++_i) \
;         __builtin_amdgcn_global_load_lds((const unsigned*)((const char*)(gbase) + (voff)[_i]), (LAS unsigned*)(lds + (bufoff) + ldsw + _i * 8192), 16, 0, 0); } while (0)
; #define PG8_MMA(ai, bj, At, Bt) do { __builtin_amdgcn_s_setprio(1); _Pragma("unroll") for (int m = 0; m < 4; ++m) _Pragma("unroll") for (int n = 0; n < 2; ++n) _Pragma("unroll") for (int k = 0; k < 2; ++k) \
;         acc[ai][bj][m][n] = __builtin_amdgcn_mfma_f32_16x16x32_bf16(Bt[n][k], At[m][k], acc[ai][bj][m][n], 0, 0, 0); __builtin_amdgcn_s_setprio(0); } while (0)
; #define PG8_WAIT_V(n) asm volatile("s_waitcnt vmcnt(" #n ")" ::: "memory")
; #define PG8_WAIT_L(n) asm volatile("s_waitcnt lgkmcnt(" #n ")" ::: "memory")
; #define PG8_BAR __builtin_amdgcn_s_barrier()
; #define PG8_SCHED __builtin_amdgcn_sched_barrier(0)
; template <class Epi>
; DEVINL void gemm_phase(LAS unsigned char* lds, const Gemm g, const Order& S, const Epi& E) {
;     ...
;             PG8_BAR; PG8_WAIT_L(0); PG8_MMA(1, 0, At, B0); PG8_BAR; PG8_SCHED;
;             PG8_STAGE(PG8_SB(1, 1), b3 + hstepB, voffB);
;             PG8_WAIT_V(6); PG8_BAR; PG8_MMA(1, 1, At, B1); PG8_BAR;
;         }
	s_waitcnt lgkmcnt(0)
	s_setprio 1
	s_waitcnt lgkmcnt(0)
	v_mfma_f32_16x16x32_bf16 v[120:123], v[198:201], v[144:147], v[120:123]
	v_mfma_f32_16x16x32_bf16 v[112:115], v[206:209], v[144:147], v[112:115]
	v_mfma_f32_16x16x32_bf16 v[96:99], v[206:209], v[168:171], v[96:99]
	v_mfma_f32_16x16x32_bf16 v[100:103], v[198:201], v[168:171], v[100:103]
	v_mfma_f32_16x16x32_bf16 v[84:87], v[198:201], v[176:179], v[84:87]
	v_mfma_f32_16x16x32_bf16 v[80:83], v[206:209], v[176:179], v[80:83]
	v_mfma_f32_16x16x32_bf16 v[64:67], v[206:209], v[190:193], v[64:67]
	v_mfma_f32_16x16x32_bf16 v[68:71], v[198:201], v[190:193], v[68:71]
	v_mfma_f32_16x16x32_bf16 v[120:123], v[202:205], v[148:151], v[120:123]
	v_mfma_f32_16x16x32_bf16 v[112:115], v[210:213], v[148:151], v[112:115]
	v_mfma_f32_16x16x32_bf16 v[96:99], v[210:213], v[172:175], v[96:99]
	v_mfma_f32_16x16x32_bf16 v[100:103], v[202:205], v[172:175], v[100:103]
	v_mfma_f32_16x16x32_bf16 v[84:87], v[202:205], v[186:189], v[84:87]
	v_mfma_f32_16x16x32_bf16 v[80:83], v[210:213], v[186:189], v[80:83]
	v_mfma_f32_16x16x32_bf16 v[64:67], v[210:213], v[194:197], v[64:67]
	v_mfma_f32_16x16x32_bf16 v[68:71], v[202:205], v[194:197], v[68:71]
	s_setprio 0
	s_mov_b32 m0, s53
	v_lshl_add_u64 v[218:219], v[222:223], 0, s[10:11]
	s_barrier
	ds_read_b128 v[144:147], v184 offset:49152
	ds_read_b128 v[148:151], v184 offset:50176
	ds_read_b128 v[168:171], v184 offset:51200
	ds_read_b128 v[172:175], v184 offset:52224
	ds_read_b128 v[176:179], v184 offset:53248
	ds_read_b128 v[186:189], v184 offset:54272
	ds_read_b128 v[190:193], v184 offset:55296
	ds_read_b128 v[194:197], v184 offset:56320
	global_load_lds_dwordx4 v[218:219], off
	v_lshl_add_u64 v[218:219], v[224:225], 0, s[10:11]
	s_mov_b32 m0, s54
	s_nop 0
	global_load_lds_dwordx4 v[218:219], off
	s_barrier
	s_waitcnt lgkmcnt(0)
	s_setprio 1
	s_waitcnt lgkmcnt(0)
	v_mfma_f32_16x16x32_bf16 v[60:63], v[128:131], v[144:147], v[60:63]
	v_mfma_f32_16x16x32_bf16 v[56:59], v[136:139], v[144:147], v[56:59]
	v_mfma_f32_16x16x32_bf16 v[40:43], v[136:139], v[168:171], v[40:43]
	v_mfma_f32_16x16x32_bf16 v[44:47], v[128:131], v[168:171], v[44:47]
	v_mfma_f32_16x16x32_bf16 v[28:31], v[128:131], v[176:179], v[28:31]
	v_mfma_f32_16x16x32_bf16 v[24:27], v[136:139], v[176:179], v[24:27]
	v_mfma_f32_16x16x32_bf16 v[8:11], v[136:139], v[190:193], v[8:11]
	v_mfma_f32_16x16x32_bf16 v[12:15], v[128:131], v[190:193], v[12:15]
	v_mfma_f32_16x16x32_bf16 v[60:63], v[132:135], v[148:151], v[60:63]
	v_mfma_f32_16x16x32_bf16 v[56:59], v[140:143], v[148:151], v[56:59]
	v_mfma_f32_16x16x32_bf16 v[40:43], v[140:143], v[172:175], v[40:43]
	v_mfma_f32_16x16x32_bf16 v[44:47], v[132:135], v[172:175], v[44:47]
	v_mfma_f32_16x16x32_bf16 v[28:31], v[132:135], v[186:189], v[28:31]
	v_mfma_f32_16x16x32_bf16 v[24:27], v[140:143], v[186:189], v[24:27]
	v_mfma_f32_16x16x32_bf16 v[8:11], v[140:143], v[194:197], v[8:11]
	v_mfma_f32_16x16x32_bf16 v[12:15], v[132:135], v[194:197], v[12:15]
	s_setprio 0
	s_barrier
	s_add_u32 s40, s40, 0x40080
	s_addc_u32 s41, s41, 0
	s_add_i32 s42, s42, s48
	v_lshl_add_u64 v[128:129], s[40:41], 0, v[154:155]
	s_mov_b32 m0, s42
	s_nop 0
	global_load_lds_dwordx4 v[128:129], off
	v_lshl_add_u64 v[128:129], s[40:41], 0, v[158:159]
	s_add_i32 m0, s42, 0x2000
	s_nop 0
	global_load_lds_dwordx4 v[128:129], off
	s_waitcnt vmcnt(6)
	s_barrier
	s_setprio 1
	v_mfma_f32_16x16x32_bf16 v[52:55], v[198:201], v[144:147], v[52:55]
	v_mfma_f32_16x16x32_bf16 v[48:51], v[206:209], v[144:147], v[48:51]
	v_mfma_f32_16x16x32_bf16 v[32:35], v[206:209], v[168:171], v[32:35]
	v_mfma_f32_16x16x32_bf16 v[36:39], v[198:201], v[168:171], v[36:39]
	v_mfma_f32_16x16x32_bf16 v[20:23], v[198:201], v[176:179], v[20:23]
	v_mfma_f32_16x16x32_bf16 v[16:19], v[206:209], v[176:179], v[16:19]
	v_mfma_f32_16x16x32_bf16 v[0:3], v[206:209], v[190:193], v[0:3]
	v_mfma_f32_16x16x32_bf16 v[4:7], v[198:201], v[190:193], v[4:7]
	v_mfma_f32_16x16x32_bf16 v[52:55], v[202:205], v[148:151], v[52:55]
	v_mfma_f32_16x16x32_bf16 v[48:51], v[210:213], v[148:151], v[48:51]
	v_mfma_f32_16x16x32_bf16 v[32:35], v[210:213], v[172:175], v[32:35]
	v_mfma_f32_16x16x32_bf16 v[36:39], v[202:205], v[172:175], v[36:39]
	v_mfma_f32_16x16x32_bf16 v[20:23], v[202:205], v[186:189], v[20:23]
	v_mfma_f32_16x16x32_bf16 v[16:19], v[210:213], v[186:189], v[16:19]
	v_mfma_f32_16x16x32_bf16 v[0:3], v[210:213], v[194:197], v[0:3]
	v_mfma_f32_16x16x32_bf16 v[4:7], v[202:205], v[194:197], v[4:7]
	s_setprio 0
	s_add_u32 s8, s8, 0x100
	s_addc_u32 s9, s9, 0
	s_add_u32 s66, s66, 0x100
	s_addc_u32 s67, s67, 0
	s_cmp_ge_i32 s68, s52
	s_mov_b32 s40, s68
	s_barrier
	s_cbranch_scc0 .LBB0_1259
	s_branch .LBB0_1250

; #define PG8_STAGE(bufoff, gbase, voff) do { _Pragma("unroll") for (int _i = 0; _i < 2; ++_i) \
;         __builtin_amdgcn_global_load_lds((const unsigned*)((const char*)(gbase) + (voff)[_i]), (LAS unsigned*)(lds + (bufoff) + ldsw + _i * 8192), 16, 0, 0); } while (0)
; #define PG8_LDA(dst, b, h) do { _Pragma("unroll") for (int m = 0; m < 4; ++m) _Pragma("unroll") for (int k = 0; k < 2; ++k) dst[m][k] = *(const LAS bf16x8*)(lds + PG8_SA(b, h) + aoff + m * 2048 + k * 1024); } while (0)
; #define PG8_LDB(dst, b, h) do { _Pragma("unroll") for (int n = 0; n < 2; ++n) _Pragma("unroll") for (int k = 0; k < 2; ++k) dst[n][k] = *(const LAS bf16x8*)(lds + PG8_SB(b, h) + boff + n * 2048 + k * 1024); } while (0)
; #define PG8_MMA(ai, bj, At, Bt) do { __builtin_amdgcn_s_setprio(1); _Pragma("unroll") for (int m = 0; m < 4; ++m) _Pragma("unroll") for (int n = 0; n < 2; ++n) _Pragma("unroll") for (int k = 0; k < 2; ++k) \
;         acc[ai][bj][m][n] = __builtin_amdgcn_mfma_f32_16x16x32_bf16(Bt[n][k], At[m][k], acc[ai][bj][m][n], 0, 0, 0); __builtin_amdgcn_s_setprio(0); } while (0)
; #define PG8_WAIT_L(n) asm volatile("s_waitcnt lgkmcnt(" #n ")" ::: "memory")
; #define PG8_BAR __builtin_amdgcn_s_barrier()
; #define PG8_SCHED __builtin_amdgcn_sched_barrier(0)
; template <class Epi>
; DEVINL void gemm_phase(LAS unsigned char* lds, const Gemm g, const Order& S, const Epi& E) {
;     ...
;         for (int t = 0; t < nt; t += 2) {
;             const bool last = (t == nt - 2);
;             const char* a1 = cA + (size_t)(t + 1) * kstep;
;             const char* a2 = last ? nA : cA + (size_t)(t + 2) * kstep; const char* b2 = last ? nB : cB + (size_t)(t + 2) * kstep;
;             const char* a3 = a2 + kstep; const char* b3 = b2 + kstep;
;             PG8_LDB(B0, 0, 0); PG8_SCHED; PG8_LDA(At, 0, 0); PG8_STAGE(PG8_SA(1, 1), a1 + hstepA, voffA);
;             PG8_WAIT_L(8); PG8_BAR; PG8_WAIT_L(0); PG8_MMA(0, 0, At, B0); PG8_BAR; PG8_SCHED;
;             PG8_LDB(B1, 0, 1); PG8_STAGE(PG8_SB(0, 0), b2, voffB);
;             PG8_BAR; PG8_WAIT_L(0); PG8_MMA(0, 1, At, B1); PG8_BAR;
;             PG8_LDA(At, 0, 1); PG8_STAGE(PG8_SA(0, 0), a2, voffA);
;             PG8_BAR; PG8_WAIT_L(0); PG8_MMA(1, 0, At, B0); PG8_BAR; PG8_SCHED;
.LBB0_1332:
	ds_read_b128 v[150:153], v147
	ds_read_b128 v[154:157], v147 offset:1024
	ds_read_b128 v[158:161], v147 offset:2048
	ds_read_b128 v[162:165], v147 offset:3072
	s_add_i32 s71, s40, 2
	s_add_u32 s41, s8, 0xfff80080
	s_addc_u32 s42, s9, -1
	s_cmp_eq_u32 s55, s40
	s_cselect_b32 s40, s29, s69
	s_cselect_b32 s43, s2, s42
	s_cselect_b32 s42, s3, s41
	s_cselect_b32 s41, s27, s70
	v_lshl_add_u64 v[198:199], s[8:9], 0, v[136:137]
	s_add_i32 m0, s25, 0xc000
	ds_read_b128 v[166:169], v148
	ds_read_b128 v[170:173], v148 offset:1024
	ds_read_b128 v[174:177], v148 offset:2048
	ds_read_b128 v[178:181], v148 offset:3072
	ds_read_b128 v[182:185], v148 offset:4096
	ds_read_b128 v[186:189], v148 offset:5120
	ds_read_b128 v[190:193], v148 offset:6144
	ds_read_b128 v[194:197], v148 offset:7168
	global_load_lds_dwordx4 v[198:199], off
	v_lshl_add_u64 v[198:199], s[8:9], 0, v[138:139]
	s_add_i32 m0, s25, 0xe000
	s_nop 0
	global_load_lds_dwordx4 v[198:199], off
	s_waitcnt lgkmcnt(8)
	s_barrier
	s_waitcnt lgkmcnt(0)
	s_setprio 1
	s_waitcnt lgkmcnt(0)
	v_mfma_f32_16x16x32_bf16 v[120:123], v[150:153], v[166:169], v[120:123]
	v_mfma_f32_16x16x32_bf16 v[124:127], v[158:161], v[166:169], v[124:127]
	v_mfma_f32_16x16x32_bf16 v[104:107], v[158:161], v[174:177], v[104:107]
	v_mfma_f32_16x16x32_bf16 v[108:111], v[150:153], v[174:177], v[108:111]
	v_mfma_f32_16x16x32_bf16 v[92:95], v[150:153], v[182:185], v[92:95]
	v_mfma_f32_16x16x32_bf16 v[88:91], v[158:161], v[182:185], v[88:91]
	v_mfma_f32_16x16x32_bf16 v[72:75], v[158:161], v[190:193], v[72:75]
	v_mfma_f32_16x16x32_bf16 v[76:79], v[150:153], v[190:193], v[76:79]
	v_mfma_f32_16x16x32_bf16 v[120:123], v[154:157], v[170:173], v[120:123]
	v_mfma_f32_16x16x32_bf16 v[124:127], v[162:165], v[170:173], v[124:127]
	v_mfma_f32_16x16x32_bf16 v[104:107], v[162:165], v[178:181], v[104:107]
	v_mfma_f32_16x16x32_bf16 v[108:111], v[154:157], v[178:181], v[108:111]
	v_mfma_f32_16x16x32_bf16 v[92:95], v[154:157], v[186:189], v[92:95]
	v_mfma_f32_16x16x32_bf16 v[88:91], v[162:165], v[186:189], v[88:91]
	v_mfma_f32_16x16x32_bf16 v[72:75], v[162:165], v[194:197], v[72:75]
	v_mfma_f32_16x16x32_bf16 v[76:79], v[154:157], v[194:197], v[76:79]
	s_setprio 0
	s_barrier
	s_add_i32 s72, s59, s48
	v_lshl_add_u64 v[218:219], s[40:41], 0, v[130:131]
	s_mov_b32 m0, s72
	ds_read_b128 v[198:201], v149
	ds_read_b128 v[202:205], v149 offset:1024
	ds_read_b128 v[206:209], v149 offset:2048
	ds_read_b128 v[210:213], v149 offset:3072
	global_load_lds_dwordx4 v[218:219], off
	v_lshl_add_u64 v[220:221], s[40:41], 0, v[134:135]
	s_add_i32 m0, s72, 0x2000
	s_nop 0
	global_load_lds_dwordx4 v[220:221], off
	s_barrier
	s_waitcnt lgkmcnt(0)
	s_setprio 1
	s_waitcnt lgkmcnt(0)
	v_mfma_f32_16x16x32_bf16 v[116:119], v[198:201], v[166:169], v[116:119]
	v_mfma_f32_16x16x32_bf16 v[112:115], v[206:209], v[166:169], v[112:115]
	v_mfma_f32_16x16x32_bf16 v[96:99], v[206:209], v[174:177], v[96:99]
	v_mfma_f32_16x16x32_bf16 v[100:103], v[198:201], v[174:177], v[100:103]
	v_mfma_f32_16x16x32_bf16 v[84:87], v[198:201], v[182:185], v[84:87]
	v_mfma_f32_16x16x32_bf16 v[80:83], v[206:209], v[182:185], v[80:83]
	v_mfma_f32_16x16x32_bf16 v[64:67], v[206:209], v[190:193], v[64:67]
	v_mfma_f32_16x16x32_bf16 v[68:71], v[198:201], v[190:193], v[68:71]
	v_mfma_f32_16x16x32_bf16 v[116:119], v[202:205], v[170:173], v[116:119]
	v_mfma_f32_16x16x32_bf16 v[112:115], v[210:213], v[170:173], v[112:115]
	v_mfma_f32_16x16x32_bf16 v[96:99], v[210:213], v[178:181], v[96:99]
	v_mfma_f32_16x16x32_bf16 v[100:103], v[202:205], v[178:181], v[100:103]
	v_mfma_f32_16x16x32_bf16 v[84:87], v[202:205], v[186:189], v[84:87]
	v_mfma_f32_16x16x32_bf16 v[80:83], v[210:213], v[186:189], v[80:83]
	v_mfma_f32_16x16x32_bf16 v[64:67], v[210:213], v[194:197], v[64:67]
	v_mfma_f32_16x16x32_bf16 v[68:71], v[202:205], v[194:197], v[68:71]
	s_setprio 0
	s_mov_b32 m0, s25
	v_lshl_add_u64 v[222:223], s[42:43], 0, v[128:129]
	s_barrier
	ds_read_b128 v[166:169], v148 offset:16384
	ds_read_b128 v[170:173], v148 offset:17408
	ds_read_b128 v[174:177], v148 offset:18432
	ds_read_b128 v[178:181], v148 offset:19456
	ds_read_b128 v[182:185], v148 offset:20480
	ds_read_b128 v[186:189], v148 offset:21504
	ds_read_b128 v[190:193], v148 offset:22528
	ds_read_b128 v[194:197], v148 offset:23552
	global_load_lds_dwordx4 v[222:223], off
	v_lshl_add_u64 v[224:225], s[42:43], 0, v[132:133]
	s_mov_b32 m0, s49
	s_nop 0
	global_load_lds_dwordx4 v[224:225], off
	s_barrier
	s_waitcnt lgkmcnt(0)
	s_setprio 1
	s_waitcnt lgkmcnt(0)
	v_mfma_f32_16x16x32_bf16 v[60:63], v[150:153], v[166:169], v[60:63]
	v_mfma_f32_16x16x32_bf16 v[56:59], v[158:161], v[166:169], v[56:59]
	v_mfma_f32_16x16x32_bf16 v[40:43], v[158:161], v[174:177], v[40:43]
	v_mfma_f32_16x16x32_bf16 v[44:47], v[150:153], v[174:177], v[44:47]
	v_mfma_f32_16x16x32_bf16 v[28:31], v[150:153], v[182:185], v[28:31]
	v_mfma_f32_16x16x32_bf16 v[24:27], v[158:161], v[182:185], v[24:27]
	v_mfma_f32_16x16x32_bf16 v[8:11], v[158:161], v[190:193], v[8:11]
	v_mfma_f32_16x16x32_bf16 v[12:15], v[150:153], v[190:193], v[12:15]
	v_mfma_f32_16x16x32_bf16 v[60:63], v[154:157], v[170:173], v[60:63]
	v_mfma_f32_16x16x32_bf16 v[56:59], v[162:165], v[170:173], v[56:59]
	v_mfma_f32_16x16x32_bf16 v[40:43], v[162:165], v[178:181], v[40:43]
	v_mfma_f32_16x16x32_bf16 v[44:47], v[154:157], v[178:181], v[44:47]
	v_mfma_f32_16x16x32_bf16 v[28:31], v[154:157], v[186:189], v[28:31]
	v_mfma_f32_16x16x32_bf16 v[24:27], v[162:165], v[186:189], v[24:27]
	v_mfma_f32_16x16x32_bf16 v[8:11], v[162:165], v[194:197], v[8:11]
	v_mfma_f32_16x16x32_bf16 v[12:15], v[154:157], v[194:197], v[12:15]
	s_setprio 0
	s_barrier
; #define PG8_STAGE(bufoff, gbase, voff) do { _Pragma("unroll") for (int _i = 0; _i < 2; ++_i) \
;         __builtin_amdgcn_global_load_lds((const unsigned*)((const char*)(gbase) + (voff)[_i]), (LAS unsigned*)(lds + (bufoff) + ldsw + _i * 8192), 16, 0, 0); } while (0)
; #define PG8_LDA(dst, b, h) do { _Pragma("unroll") for (int m = 0; m < 4; ++m) _Pragma("unroll") for (int k = 0; k < 2; ++k) dst[m][k] = *(const LAS bf16x8*)(lds + PG8_SA(b, h) + aoff + m * 2048 + k * 1024); } while (0)
; #define PG8_LDB(dst, b, h) do { _Pragma("unroll") for (int n = 0; n < 2; ++n) _Pragma("unroll") for (int k = 0; k < 2; ++k) dst[n][k] = *(const LAS bf16x8*)(lds + PG8_SB(b, h) + boff + n * 2048 + k * 1024); } while (0)
; #define PG8_MMA(ai, bj, At, Bt) do { __builtin_amdgcn_s_setprio(1); _Pragma("unroll") for (int m = 0; m < 4; ++m) _Pragma("unroll") for (int n = 0; n < 2; ++n) _Pragma("unroll") for (int k = 0; k < 2; ++k) \
;         acc[ai][bj][m][n] = __builtin_amdgcn_mfma_f32_16x16x32_bf16(Bt[n][k], At[m][k], acc[ai][bj][m][n], 0, 0, 0); __builtin_amdgcn_s_setprio(0); } while (0)
; #define PG8_WAIT_V(n) asm volatile("s_waitcnt vmcnt(" #n ")" ::: "memory")
; #define PG8_WAIT_L(n) asm volatile("s_waitcnt lgkmcnt(" #n ")" ::: "memory")
; #define PG8_BAR __builtin_amdgcn_s_barrier()
; #define PG8_SCHED __builtin_amdgcn_sched_barrier(0)
; template <class Epi>
; DEVINL void gemm_phase(LAS unsigned char* lds, const Gemm g, const Order& S, const Epi& E) {
;     ...
;             PG8_STAGE(PG8_SB(0, 1), b2 + hstepB, voffB);
;             PG8_WAIT_V(6); PG8_BAR; PG8_MMA(1, 1, At, B1); PG8_BAR;
;             PG8_LDB(B0, 1, 0); PG8_SCHED; PG8_LDA(At, 1, 0); PG8_STAGE(PG8_SA(0, 1), a2 + hstepA, voffA);
;             PG8_WAIT_L(8); PG8_BAR; PG8_WAIT_L(0); PG8_MMA(0, 0, At, B0); PG8_BAR; PG8_SCHED;
;             PG8_LDB(B1, 1, 1); PG8_STAGE(PG8_SB(1, 0), b3, voffB);
;             PG8_BAR; PG8_WAIT_L(0); PG8_MMA(0, 1, At, B1); PG8_BAR;
;             PG8_LDA(At, 1, 1); PG8_STAGE(PG8_SA(1, 0), a3, voffA);
	s_add_u32 s72, s40, 0x80000
	s_addc_u32 s73, s41, 0
	s_add_i32 s74, s64, s48
	v_lshl_add_u64 v[150:151], s[72:73], 0, v[130:131]
	s_mov_b32 m0, s74
	s_nop 0
	global_load_lds_dwordx4 v[150:151], off
	v_lshl_add_u64 v[150:151], s[72:73], 0, v[134:135]
	s_add_i32 m0, s74, 0x2000
	s_nop 0
	global_load_lds_dwordx4 v[150:151], off
	s_waitcnt vmcnt(6)
	s_barrier
	s_setprio 1
	v_mfma_f32_16x16x32_bf16 v[52:55], v[198:201], v[166:169], v[52:55]
	v_mfma_f32_16x16x32_bf16 v[48:51], v[206:209], v[166:169], v[48:51]
	v_mfma_f32_16x16x32_bf16 v[32:35], v[206:209], v[174:177], v[32:35]
	v_mfma_f32_16x16x32_bf16 v[36:39], v[198:201], v[174:177], v[36:39]
	v_mfma_f32_16x16x32_bf16 v[20:23], v[198:201], v[182:185], v[20:23]
	v_mfma_f32_16x16x32_bf16 v[16:19], v[206:209], v[182:185], v[16:19]
	v_mfma_f32_16x16x32_bf16 v[0:3], v[206:209], v[190:193], v[0:3]
	v_mfma_f32_16x16x32_bf16 v[4:7], v[198:201], v[190:193], v[4:7]
	v_mfma_f32_16x16x32_bf16 v[52:55], v[202:205], v[170:173], v[52:55]
	v_mfma_f32_16x16x32_bf16 v[48:51], v[210:213], v[170:173], v[48:51]
	v_mfma_f32_16x16x32_bf16 v[32:35], v[210:213], v[178:181], v[32:35]
	v_mfma_f32_16x16x32_bf16 v[36:39], v[202:205], v[178:181], v[36:39]
	v_mfma_f32_16x16x32_bf16 v[20:23], v[202:205], v[186:189], v[20:23]
	v_mfma_f32_16x16x32_bf16 v[16:19], v[210:213], v[186:189], v[16:19]
	v_mfma_f32_16x16x32_bf16 v[0:3], v[210:213], v[194:197], v[0:3]
	v_mfma_f32_16x16x32_bf16 v[4:7], v[202:205], v[194:197], v[4:7]
	s_setprio 0
	s_add_i32 s72, 16, 0x18000
	v_add_u32_e32 v162, s72, v145
	s_barrier
	ds_read_b128 v[150:153], v162
	ds_read_b128 v[154:157], v162 offset:1024
	ds_read_b128 v[158:161], v162 offset:2048
	ds_read_b128 v[162:165], v162 offset:3072
	s_add_u32 s42, s42, 0x80000
	s_addc_u32 s43, s43, 0
	s_mov_b32 m0, s50
	v_lshl_add_u64 v[198:199], s[42:43], 0, v[128:129]
	ds_read_b128 v[166:169], v148 offset:32768
	ds_read_b128 v[170:173], v148 offset:33792
	ds_read_b128 v[174:177], v148 offset:34816
	ds_read_b128 v[178:181], v148 offset:35840
	ds_read_b128 v[182:185], v148 offset:36864
	ds_read_b128 v[186:189], v148 offset:37888
	ds_read_b128 v[190:193], v148 offset:38912
	ds_read_b128 v[194:197], v148 offset:39936
	global_load_lds_dwordx4 v[198:199], off
	v_lshl_add_u64 v[198:199], s[42:43], 0, v[132:133]
	s_mov_b32 m0, s51
	s_nop 0
	global_load_lds_dwordx4 v[198:199], off
	s_waitcnt lgkmcnt(8)
	s_barrier
	s_waitcnt lgkmcnt(0)
	s_setprio 1
	s_waitcnt lgkmcnt(0)
	v_mfma_f32_16x16x32_bf16 v[120:123], v[150:153], v[166:169], v[120:123]
	v_mfma_f32_16x16x32_bf16 v[124:127], v[158:161], v[166:169], v[124:127]
	v_mfma_f32_16x16x32_bf16 v[104:107], v[158:161], v[174:177], v[104:107]
	v_mfma_f32_16x16x32_bf16 v[108:111], v[150:153], v[174:177], v[108:111]
	v_mfma_f32_16x16x32_bf16 v[92:95], v[150:153], v[182:185], v[92:95]
	v_mfma_f32_16x16x32_bf16 v[88:91], v[158:161], v[182:185], v[88:91]
	v_mfma_f32_16x16x32_bf16 v[72:75], v[158:161], v[190:193], v[72:75]
	v_mfma_f32_16x16x32_bf16 v[76:79], v[150:153], v[190:193], v[76:79]
	v_mfma_f32_16x16x32_bf16 v[120:123], v[154:157], v[170:173], v[120:123]
	v_mfma_f32_16x16x32_bf16 v[124:127], v[162:165], v[170:173], v[124:127]
	v_mfma_f32_16x16x32_bf16 v[104:107], v[162:165], v[178:181], v[104:107]
	v_mfma_f32_16x16x32_bf16 v[108:111], v[154:157], v[178:181], v[108:111]
	v_mfma_f32_16x16x32_bf16 v[92:95], v[154:157], v[186:189], v[92:95]
	v_mfma_f32_16x16x32_bf16 v[88:91], v[162:165], v[186:189], v[88:91]
	v_mfma_f32_16x16x32_bf16 v[72:75], v[162:165], v[194:197], v[72:75]
	v_mfma_f32_16x16x32_bf16 v[76:79], v[154:157], v[194:197], v[76:79]
	s_setprio 0
	s_barrier
	s_add_i32 s42, 16, 0x1c000
	s_add_i32 s43, s72, s48
	v_add_u32_e32 v210, s42, v145
	v_lshl_add_u64 v[218:219], v[218:219], 0, s[6:7]
	s_mov_b32 m0, s43
	ds_read_b128 v[198:201], v210
	ds_read_b128 v[202:205], v210 offset:1024
	ds_read_b128 v[206:209], v210 offset:2048
	ds_read_b128 v[210:213], v210 offset:3072
	global_load_lds_dwordx4 v[218:219], off
	v_lshl_add_u64 v[218:219], v[220:221], 0, s[6:7]
	s_add_i32 m0, s43, 0x2000
	s_nop 0
	global_load_lds_dwordx4 v[218:219], off
	s_barrier
; #define PG8_STAGE(bufoff, gbase, voff) do { _Pragma("unroll") for (int _i = 0; _i < 2; ++_i) \
;         __builtin_amdgcn_global_load_lds((const unsigned*)((const char*)(gbase) + (voff)[_i]), (LAS unsigned*)(lds + (bufoff) + ldsw + _i * 8192), 16, 0, 0); } while (0)
; #define PG8_MMA(ai, bj, At, Bt) do { __builtin_amdgcn_s_setprio(1); _Pragma("unroll") for (int m = 0; m < 4; ++m) _Pragma("unroll") for (int n = 0; n < 2; ++n) _Pragma("unroll") for (int k = 0; k < 2; ++k) \
;         acc[ai][bj][m][n] = __builtin_amdgcn_mfma_f32_16x16x32_bf16(Bt[n][k], At[m][k], acc[ai][bj][m][n], 0, 0, 0); __builtin_amdgcn_s_setprio(0); } while (0)
; #define PG8_WAIT_V(n) asm volatile("s_waitcnt vmcnt(" #n ")" ::: "memory")
; #define PG8_WAIT_L(n) asm volatile("s_waitcnt lgkmcnt(" #n ")" ::: "memory")
; #define PG8_BAR __builtin_amdgcn_s_barrier()
; #define PG8_SCHED __builtin_amdgcn_sched_barrier(0)
; template <class Epi>
; DEVINL void gemm_phase(LAS unsigned char* lds, const Gemm g, const Order& S, const Epi& E) {
;     ...
;             PG8_BAR; PG8_WAIT_L(0); PG8_MMA(1, 0, At, B0); PG8_BAR; PG8_SCHED;
;             PG8_STAGE(PG8_SB(1, 1), b3 + hstepB, voffB);
;             PG8_WAIT_V(6); PG8_BAR; PG8_MMA(1, 1, At, B1); PG8_BAR;
;         }
	s_waitcnt lgkmcnt(0)
	s_setprio 1
	s_waitcnt lgkmcnt(0)
	v_mfma_f32_16x16x32_bf16 v[116:119], v[198:201], v[166:169], v[116:119]
	v_mfma_f32_16x16x32_bf16 v[112:115], v[206:209], v[166:169], v[112:115]
	v_mfma_f32_16x16x32_bf16 v[96:99], v[206:209], v[174:177], v[96:99]
	v_mfma_f32_16x16x32_bf16 v[100:103], v[198:201], v[174:177], v[100:103]
	v_mfma_f32_16x16x32_bf16 v[84:87], v[198:201], v[182:185], v[84:87]
	v_mfma_f32_16x16x32_bf16 v[80:83], v[206:209], v[182:185], v[80:83]
	v_mfma_f32_16x16x32_bf16 v[64:67], v[206:209], v[190:193], v[64:67]
	v_mfma_f32_16x16x32_bf16 v[68:71], v[198:201], v[190:193], v[68:71]
	v_mfma_f32_16x16x32_bf16 v[116:119], v[202:205], v[170:173], v[116:119]
	v_mfma_f32_16x16x32_bf16 v[112:115], v[210:213], v[170:173], v[112:115]
	v_mfma_f32_16x16x32_bf16 v[96:99], v[210:213], v[178:181], v[96:99]
	v_mfma_f32_16x16x32_bf16 v[100:103], v[202:205], v[178:181], v[100:103]
	v_mfma_f32_16x16x32_bf16 v[84:87], v[202:205], v[186:189], v[84:87]
	v_mfma_f32_16x16x32_bf16 v[80:83], v[210:213], v[186:189], v[80:83]
	v_mfma_f32_16x16x32_bf16 v[64:67], v[210:213], v[194:197], v[64:67]
	v_mfma_f32_16x16x32_bf16 v[68:71], v[202:205], v[194:197], v[68:71]
	s_setprio 0
	s_mov_b32 m0, s53
	v_lshl_add_u64 v[218:219], v[222:223], 0, s[6:7]
	s_barrier
	ds_read_b128 v[166:169], v148 offset:49152
	ds_read_b128 v[170:173], v148 offset:50176
	ds_read_b128 v[174:177], v148 offset:51200
	ds_read_b128 v[178:181], v148 offset:52224
	ds_read_b128 v[182:185], v148 offset:53248
	ds_read_b128 v[186:189], v148 offset:54272
	ds_read_b128 v[190:193], v148 offset:55296
	ds_read_b128 v[194:197], v148 offset:56320
	global_load_lds_dwordx4 v[218:219], off
	v_lshl_add_u64 v[218:219], v[224:225], 0, s[6:7]
	s_mov_b32 m0, s54
	s_nop 0
	global_load_lds_dwordx4 v[218:219], off
	s_barrier
	s_waitcnt lgkmcnt(0)
	s_setprio 1
	s_waitcnt lgkmcnt(0)
	v_mfma_f32_16x16x32_bf16 v[60:63], v[150:153], v[166:169], v[60:63]
	v_mfma_f32_16x16x32_bf16 v[56:59], v[158:161], v[166:169], v[56:59]
	v_mfma_f32_16x16x32_bf16 v[40:43], v[158:161], v[174:177], v[40:43]
	v_mfma_f32_16x16x32_bf16 v[44:47], v[150:153], v[174:177], v[44:47]
	v_mfma_f32_16x16x32_bf16 v[28:31], v[150:153], v[182:185], v[28:31]
	v_mfma_f32_16x16x32_bf16 v[24:27], v[158:161], v[182:185], v[24:27]
	v_mfma_f32_16x16x32_bf16 v[8:11], v[158:161], v[190:193], v[8:11]
	v_mfma_f32_16x16x32_bf16 v[12:15], v[150:153], v[190:193], v[12:15]
	v_mfma_f32_16x16x32_bf16 v[60:63], v[154:157], v[170:173], v[60:63]
	v_mfma_f32_16x16x32_bf16 v[56:59], v[162:165], v[170:173], v[56:59]
	v_mfma_f32_16x16x32_bf16 v[40:43], v[162:165], v[178:181], v[40:43]
	v_mfma_f32_16x16x32_bf16 v[44:47], v[154:157], v[178:181], v[44:47]
	v_mfma_f32_16x16x32_bf16 v[28:31], v[154:157], v[186:189], v[28:31]
	v_mfma_f32_16x16x32_bf16 v[24:27], v[162:165], v[186:189], v[24:27]
	v_mfma_f32_16x16x32_bf16 v[8:11], v[162:165], v[194:197], v[8:11]
	v_mfma_f32_16x16x32_bf16 v[12:15], v[154:157], v[194:197], v[12:15]
	s_setprio 0
	s_barrier
	s_add_u32 s40, s40, 0x80080
	s_addc_u32 s41, s41, 0
	s_add_i32 s42, s42, s48
	v_lshl_add_u64 v[150:151], s[40:41], 0, v[130:131]
	s_mov_b32 m0, s42
	s_nop 0
	global_load_lds_dwordx4 v[150:151], off
	v_lshl_add_u64 v[150:151], s[40:41], 0, v[134:135]
	s_add_i32 m0, s42, 0x2000
	s_nop 0
	global_load_lds_dwordx4 v[150:151], off
	s_waitcnt vmcnt(6)
	s_barrier
	s_setprio 1
	v_mfma_f32_16x16x32_bf16 v[52:55], v[198:201], v[166:169], v[52:55]
	v_mfma_f32_16x16x32_bf16 v[48:51], v[206:209], v[166:169], v[48:51]
	v_mfma_f32_16x16x32_bf16 v[32:35], v[206:209], v[174:177], v[32:35]
	v_mfma_f32_16x16x32_bf16 v[36:39], v[198:201], v[174:177], v[36:39]
	v_mfma_f32_16x16x32_bf16 v[20:23], v[198:201], v[182:185], v[20:23]
	v_mfma_f32_16x16x32_bf16 v[16:19], v[206:209], v[182:185], v[16:19]
	v_mfma_f32_16x16x32_bf16 v[0:3], v[206:209], v[190:193], v[0:3]
	v_mfma_f32_16x16x32_bf16 v[4:7], v[198:201], v[190:193], v[4:7]
	v_mfma_f32_16x16x32_bf16 v[52:55], v[202:205], v[170:173], v[52:55]
	v_mfma_f32_16x16x32_bf16 v[48:51], v[210:213], v[170:173], v[48:51]
	v_mfma_f32_16x16x32_bf16 v[32:35], v[210:213], v[178:181], v[32:35]
	v_mfma_f32_16x16x32_bf16 v[36:39], v[202:205], v[178:181], v[36:39]
	v_mfma_f32_16x16x32_bf16 v[20:23], v[202:205], v[186:189], v[20:23]
	v_mfma_f32_16x16x32_bf16 v[16:19], v[210:213], v[186:189], v[16:19]
	v_mfma_f32_16x16x32_bf16 v[0:3], v[210:213], v[194:197], v[0:3]
	v_mfma_f32_16x16x32_bf16 v[4:7], v[202:205], v[194:197], v[4:7]
	s_setprio 0
	s_add_u32 s8, s8, 0x100
	s_addc_u32 s9, s9, 0
	s_add_u32 s69, s69, 0x100
	s_addc_u32 s70, s70, 0
	s_cmp_ge_i32 s71, s52
	s_mov_b32 s40, s71
	s_barrier
	s_cbranch_scc0 .LBB0_1332
	s_branch .LBB0_1323

; #define PG8_STAGE(bufoff, gbase, voff) do { _Pragma("unroll") for (int _i = 0; _i < 2; ++_i) \
;         __builtin_amdgcn_global_load_lds((const unsigned*)((const char*)(gbase) + (voff)[_i]), (LAS unsigned*)(lds + (bufoff) + ldsw + _i * 8192), 16, 0, 0); } while (0)
; #define PG8_LDA(dst, b, h) do { _Pragma("unroll") for (int m = 0; m < 4; ++m) _Pragma("unroll") for (int k = 0; k < 2; ++k) dst[m][k] = *(const LAS bf16x8*)(lds + PG8_SA(b, h) + aoff + m * 2048 + k * 1024); } while (0)
; #define PG8_LDB(dst, b, h) do { _Pragma("unroll") for (int n = 0; n < 2; ++n) _Pragma("unroll") for (int k = 0; k < 2; ++k) dst[n][k] = *(const LAS bf16x8*)(lds + PG8_SB(b, h) + boff + n * 2048 + k * 1024); } while (0)
; #define PG8_MMA(ai, bj, At, Bt) do { __builtin_amdgcn_s_setprio(1); _Pragma("unroll") for (int m = 0; m < 4; ++m) _Pragma("unroll") for (int n = 0; n < 2; ++n) _Pragma("unroll") for (int k = 0; k < 2; ++k) \
;         acc[ai][bj][m][n] = __builtin_amdgcn_mfma_f32_16x16x32_bf16(Bt[n][k], At[m][k], acc[ai][bj][m][n], 0, 0, 0); __builtin_amdgcn_s_setprio(0); } while (0)
; #define PG8_WAIT_L(n) asm volatile("s_waitcnt lgkmcnt(" #n ")" ::: "memory")
; #define PG8_BAR __builtin_amdgcn_s_barrier()
; #define PG8_SCHED __builtin_amdgcn_sched_barrier(0)
; template <class Epi>
; DEVINL void gemm_phase(LAS unsigned char* lds, const Gemm g, const Order& S, const Epi& E) {
;     ...
;         for (int t = 0; t < nt; t += 2) {
;             const bool last = (t == nt - 2);
;             const char* a1 = cA + (size_t)(t + 1) * kstep;
;             const char* a2 = last ? nA : cA + (size_t)(t + 2) * kstep; const char* b2 = last ? nB : cB + (size_t)(t + 2) * kstep;
;             const char* a3 = a2 + kstep; const char* b3 = b2 + kstep;
;             PG8_LDB(B0, 0, 0); PG8_SCHED; PG8_LDA(At, 0, 0); PG8_STAGE(PG8_SA(1, 1), a1 + hstepA, voffA);
;             PG8_WAIT_L(8); PG8_BAR; PG8_WAIT_L(0); PG8_MMA(0, 0, At, B0); PG8_BAR; PG8_SCHED;
;             PG8_LDB(B1, 0, 1); PG8_STAGE(PG8_SB(0, 0), b2, voffB);
;             PG8_BAR; PG8_WAIT_L(0); PG8_MMA(0, 1, At, B1); PG8_BAR;
;             PG8_LDA(At, 0, 1); PG8_STAGE(PG8_SA(0, 0), a2, voffA);
;             PG8_BAR; PG8_WAIT_L(0); PG8_MMA(1, 0, At, B0); PG8_BAR; PG8_SCHED;
.LBB0_1492:
	ds_read_b128 v[150:153], v147
	ds_read_b128 v[154:157], v147 offset:1024
	ds_read_b128 v[158:161], v147 offset:2048
	ds_read_b128 v[162:165], v147 offset:3072
	s_add_i32 s74, s42, 2
	s_add_u32 s43, s8, 0xfff80080
	s_addc_u32 s44, s9, -1
	s_cmp_eq_u32 s57, s42
	s_cselect_b32 s42, s37, s72
	s_cselect_b32 s45, s2, s44
	s_cselect_b32 s44, s3, s43
	s_cselect_b32 s43, s31, s73
	v_lshl_add_u64 v[198:199], s[8:9], 0, v[136:137]
	s_add_i32 m0, s29, 0xc000
	ds_read_b128 v[166:169], v148
	ds_read_b128 v[170:173], v148 offset:1024
	ds_read_b128 v[174:177], v148 offset:2048
	ds_read_b128 v[178:181], v148 offset:3072
	ds_read_b128 v[182:185], v148 offset:4096
	ds_read_b128 v[186:189], v148 offset:5120
	ds_read_b128 v[190:193], v148 offset:6144
	ds_read_b128 v[194:197], v148 offset:7168
	global_load_lds_dwordx4 v[198:199], off
	v_lshl_add_u64 v[198:199], s[8:9], 0, v[138:139]
	s_add_i32 m0, s29, 0xe000
	s_nop 0
	global_load_lds_dwordx4 v[198:199], off
	s_waitcnt lgkmcnt(8)
	s_barrier
	s_waitcnt lgkmcnt(0)
	s_setprio 1
	s_waitcnt lgkmcnt(0)
	v_mfma_f32_16x16x32_bf16 v[120:123], v[150:153], v[166:169], v[120:123]
	v_mfma_f32_16x16x32_bf16 v[124:127], v[158:161], v[166:169], v[124:127]
	v_mfma_f32_16x16x32_bf16 v[104:107], v[158:161], v[174:177], v[104:107]
	v_mfma_f32_16x16x32_bf16 v[108:111], v[150:153], v[174:177], v[108:111]
	v_mfma_f32_16x16x32_bf16 v[92:95], v[150:153], v[182:185], v[92:95]
	v_mfma_f32_16x16x32_bf16 v[88:91], v[158:161], v[182:185], v[88:91]
	v_mfma_f32_16x16x32_bf16 v[72:75], v[158:161], v[190:193], v[72:75]
	v_mfma_f32_16x16x32_bf16 v[76:79], v[150:153], v[190:193], v[76:79]
	v_mfma_f32_16x16x32_bf16 v[120:123], v[154:157], v[170:173], v[120:123]
	v_mfma_f32_16x16x32_bf16 v[124:127], v[162:165], v[170:173], v[124:127]
	v_mfma_f32_16x16x32_bf16 v[104:107], v[162:165], v[178:181], v[104:107]
	v_mfma_f32_16x16x32_bf16 v[108:111], v[154:157], v[178:181], v[108:111]
	v_mfma_f32_16x16x32_bf16 v[92:95], v[154:157], v[186:189], v[92:95]
	v_mfma_f32_16x16x32_bf16 v[88:91], v[162:165], v[186:189], v[88:91]
	v_mfma_f32_16x16x32_bf16 v[72:75], v[162:165], v[194:197], v[72:75]
	v_mfma_f32_16x16x32_bf16 v[76:79], v[154:157], v[194:197], v[76:79]
	s_setprio 0
	s_barrier
	s_add_i32 s75, s65, s50
	v_lshl_add_u64 v[218:219], s[42:43], 0, v[130:131]
	s_mov_b32 m0, s75
	ds_read_b128 v[198:201], v149
	ds_read_b128 v[202:205], v149 offset:1024
	ds_read_b128 v[206:209], v149 offset:2048
	ds_read_b128 v[210:213], v149 offset:3072
	global_load_lds_dwordx4 v[218:219], off
	v_lshl_add_u64 v[220:221], s[42:43], 0, v[134:135]
	s_add_i32 m0, s75, 0x2000
	s_nop 0
	global_load_lds_dwordx4 v[220:221], off
	s_barrier
	s_waitcnt lgkmcnt(0)
	s_setprio 1
	s_waitcnt lgkmcnt(0)
	v_mfma_f32_16x16x32_bf16 v[116:119], v[198:201], v[166:169], v[116:119]
	v_mfma_f32_16x16x32_bf16 v[112:115], v[206:209], v[166:169], v[112:115]
	v_mfma_f32_16x16x32_bf16 v[96:99], v[206:209], v[174:177], v[96:99]
	v_mfma_f32_16x16x32_bf16 v[100:103], v[198:201], v[174:177], v[100:103]
	v_mfma_f32_16x16x32_bf16 v[84:87], v[198:201], v[182:185], v[84:87]
	v_mfma_f32_16x16x32_bf16 v[80:83], v[206:209], v[182:185], v[80:83]
	v_mfma_f32_16x16x32_bf16 v[64:67], v[206:209], v[190:193], v[64:67]
	v_mfma_f32_16x16x32_bf16 v[68:71], v[198:201], v[190:193], v[68:71]
	v_mfma_f32_16x16x32_bf16 v[116:119], v[202:205], v[170:173], v[116:119]
	v_mfma_f32_16x16x32_bf16 v[112:115], v[210:213], v[170:173], v[112:115]
	v_mfma_f32_16x16x32_bf16 v[96:99], v[210:213], v[178:181], v[96:99]
	v_mfma_f32_16x16x32_bf16 v[100:103], v[202:205], v[178:181], v[100:103]
	v_mfma_f32_16x16x32_bf16 v[84:87], v[202:205], v[186:189], v[84:87]
	v_mfma_f32_16x16x32_bf16 v[80:83], v[210:213], v[186:189], v[80:83]
	v_mfma_f32_16x16x32_bf16 v[64:67], v[210:213], v[194:197], v[64:67]
	v_mfma_f32_16x16x32_bf16 v[68:71], v[202:205], v[194:197], v[68:71]
	s_setprio 0
	s_mov_b32 m0, s29
	v_lshl_add_u64 v[222:223], s[44:45], 0, v[128:129]
	s_barrier
	ds_read_b128 v[166:169], v148 offset:16384
	ds_read_b128 v[170:173], v148 offset:17408
	ds_read_b128 v[174:177], v148 offset:18432
	ds_read_b128 v[178:181], v148 offset:19456
	ds_read_b128 v[182:185], v148 offset:20480
	ds_read_b128 v[186:189], v148 offset:21504
	ds_read_b128 v[190:193], v148 offset:22528
	ds_read_b128 v[194:197], v148 offset:23552
	global_load_lds_dwordx4 v[222:223], off
	v_lshl_add_u64 v[224:225], s[44:45], 0, v[132:133]
	s_mov_b32 m0, s51
	s_nop 0
	global_load_lds_dwordx4 v[224:225], off
	s_barrier
	s_waitcnt lgkmcnt(0)
	s_setprio 1
	s_waitcnt lgkmcnt(0)
	v_mfma_f32_16x16x32_bf16 v[60:63], v[150:153], v[166:169], v[60:63]
	v_mfma_f32_16x16x32_bf16 v[56:59], v[158:161], v[166:169], v[56:59]
	v_mfma_f32_16x16x32_bf16 v[40:43], v[158:161], v[174:177], v[40:43]
	v_mfma_f32_16x16x32_bf16 v[44:47], v[150:153], v[174:177], v[44:47]
	v_mfma_f32_16x16x32_bf16 v[28:31], v[150:153], v[182:185], v[28:31]
	v_mfma_f32_16x16x32_bf16 v[24:27], v[158:161], v[182:185], v[24:27]
	v_mfma_f32_16x16x32_bf16 v[8:11], v[158:161], v[190:193], v[8:11]
	v_mfma_f32_16x16x32_bf16 v[12:15], v[150:153], v[190:193], v[12:15]
	v_mfma_f32_16x16x32_bf16 v[60:63], v[154:157], v[170:173], v[60:63]
	v_mfma_f32_16x16x32_bf16 v[56:59], v[162:165], v[170:173], v[56:59]
	v_mfma_f32_16x16x32_bf16 v[40:43], v[162:165], v[178:181], v[40:43]
	v_mfma_f32_16x16x32_bf16 v[44:47], v[154:157], v[178:181], v[44:47]
	v_mfma_f32_16x16x32_bf16 v[28:31], v[154:157], v[186:189], v[28:31]
	v_mfma_f32_16x16x32_bf16 v[24:27], v[162:165], v[186:189], v[24:27]
	v_mfma_f32_16x16x32_bf16 v[8:11], v[162:165], v[194:197], v[8:11]
	v_mfma_f32_16x16x32_bf16 v[12:15], v[154:157], v[194:197], v[12:15]
	s_setprio 0
	s_barrier
; #define PG8_STAGE(bufoff, gbase, voff) do { _Pragma("unroll") for (int _i = 0; _i < 2; ++_i) \
;         __builtin_amdgcn_global_load_lds((const unsigned*)((const char*)(gbase) + (voff)[_i]), (LAS unsigned*)(lds + (bufoff) + ldsw + _i * 8192), 16, 0, 0); } while (0)
; #define PG8_LDA(dst, b, h) do { _Pragma("unroll") for (int m = 0; m < 4; ++m) _Pragma("unroll") for (int k = 0; k < 2; ++k) dst[m][k] = *(const LAS bf16x8*)(lds + PG8_SA(b, h) + aoff + m * 2048 + k * 1024); } while (0)
; #define PG8_LDB(dst, b, h) do { _Pragma("unroll") for (int n = 0; n < 2; ++n) _Pragma("unroll") for (int k = 0; k < 2; ++k) dst[n][k] = *(const LAS bf16x8*)(lds + PG8_SB(b, h) + boff + n * 2048 + k * 1024); } while (0)
; #define PG8_MMA(ai, bj, At, Bt) do { __builtin_amdgcn_s_setprio(1); _Pragma("unroll") for (int m = 0; m < 4; ++m) _Pragma("unroll") for (int n = 0; n < 2; ++n) _Pragma("unroll") for (int k = 0; k < 2; ++k) \
;         acc[ai][bj][m][n] = __builtin_amdgcn_mfma_f32_16x16x32_bf16(Bt[n][k], At[m][k], acc[ai][bj][m][n], 0, 0, 0); __builtin_amdgcn_s_setprio(0); } while (0)
; #define PG8_WAIT_V(n) asm volatile("s_waitcnt vmcnt(" #n ")" ::: "memory")
; #define PG8_WAIT_L(n) asm volatile("s_waitcnt lgkmcnt(" #n ")" ::: "memory")
; #define PG8_BAR __builtin_amdgcn_s_barrier()
; #define PG8_SCHED __builtin_amdgcn_sched_barrier(0)
; template <class Epi>
; DEVINL void gemm_phase(LAS unsigned char* lds, const Gemm g, const Order& S, const Epi& E) {
;     ...
;             PG8_STAGE(PG8_SB(0, 1), b2 + hstepB, voffB);
;             PG8_WAIT_V(6); PG8_BAR; PG8_MMA(1, 1, At, B1); PG8_BAR;
;             PG8_LDB(B0, 1, 0); PG8_SCHED; PG8_LDA(At, 1, 0); PG8_STAGE(PG8_SA(0, 1), a2 + hstepA, voffA);
;             PG8_WAIT_L(8); PG8_BAR; PG8_WAIT_L(0); PG8_MMA(0, 0, At, B0); PG8_BAR; PG8_SCHED;
;             PG8_LDB(B1, 1, 1); PG8_STAGE(PG8_SB(1, 0), b3, voffB);
;             PG8_BAR; PG8_WAIT_L(0); PG8_MMA(0, 1, At, B1); PG8_BAR;
;             PG8_LDA(At, 1, 1); PG8_STAGE(PG8_SA(1, 0), a3, voffA);
	s_add_u32 s76, s42, 0x80000
	s_addc_u32 s77, s43, 0
	s_add_i32 s75, s66, s50
	v_lshl_add_u64 v[150:151], s[76:77], 0, v[130:131]
	s_mov_b32 m0, s75
	s_nop 0
	global_load_lds_dwordx4 v[150:151], off
	v_lshl_add_u64 v[150:151], s[76:77], 0, v[134:135]
	s_add_i32 m0, s75, 0x2000
	s_nop 0
	global_load_lds_dwordx4 v[150:151], off
	s_waitcnt vmcnt(6)
	s_barrier
	s_setprio 1
	v_mfma_f32_16x16x32_bf16 v[52:55], v[198:201], v[166:169], v[52:55]
	v_mfma_f32_16x16x32_bf16 v[48:51], v[206:209], v[166:169], v[48:51]
	v_mfma_f32_16x16x32_bf16 v[32:35], v[206:209], v[174:177], v[32:35]
	v_mfma_f32_16x16x32_bf16 v[36:39], v[198:201], v[174:177], v[36:39]
	v_mfma_f32_16x16x32_bf16 v[20:23], v[198:201], v[182:185], v[20:23]
	v_mfma_f32_16x16x32_bf16 v[16:19], v[206:209], v[182:185], v[16:19]
	v_mfma_f32_16x16x32_bf16 v[0:3], v[206:209], v[190:193], v[0:3]
	v_mfma_f32_16x16x32_bf16 v[4:7], v[198:201], v[190:193], v[4:7]
	v_mfma_f32_16x16x32_bf16 v[52:55], v[202:205], v[170:173], v[52:55]
	v_mfma_f32_16x16x32_bf16 v[48:51], v[210:213], v[170:173], v[48:51]
	v_mfma_f32_16x16x32_bf16 v[32:35], v[210:213], v[178:181], v[32:35]
	v_mfma_f32_16x16x32_bf16 v[36:39], v[202:205], v[178:181], v[36:39]
	v_mfma_f32_16x16x32_bf16 v[20:23], v[202:205], v[186:189], v[20:23]
	v_mfma_f32_16x16x32_bf16 v[16:19], v[210:213], v[186:189], v[16:19]
	v_mfma_f32_16x16x32_bf16 v[0:3], v[210:213], v[194:197], v[0:3]
	v_mfma_f32_16x16x32_bf16 v[4:7], v[202:205], v[194:197], v[4:7]
	s_setprio 0
	s_add_i32 s75, 16, 0x18000
	v_add_u32_e32 v162, s75, v145
	s_barrier
	ds_read_b128 v[150:153], v162
	ds_read_b128 v[154:157], v162 offset:1024
	ds_read_b128 v[158:161], v162 offset:2048
	ds_read_b128 v[162:165], v162 offset:3072
	s_add_u32 s44, s44, 0x80000
	s_addc_u32 s45, s45, 0
	s_mov_b32 m0, s52
	v_lshl_add_u64 v[198:199], s[44:45], 0, v[128:129]
	ds_read_b128 v[166:169], v148 offset:32768
	ds_read_b128 v[170:173], v148 offset:33792
	ds_read_b128 v[174:177], v148 offset:34816
	ds_read_b128 v[178:181], v148 offset:35840
	ds_read_b128 v[182:185], v148 offset:36864
	ds_read_b128 v[186:189], v148 offset:37888
	ds_read_b128 v[190:193], v148 offset:38912
	ds_read_b128 v[194:197], v148 offset:39936
	global_load_lds_dwordx4 v[198:199], off
	v_lshl_add_u64 v[198:199], s[44:45], 0, v[132:133]
	s_mov_b32 m0, s53
	s_nop 0
	global_load_lds_dwordx4 v[198:199], off
	s_waitcnt lgkmcnt(8)
	s_barrier
	s_waitcnt lgkmcnt(0)
	s_setprio 1
	s_waitcnt lgkmcnt(0)
	v_mfma_f32_16x16x32_bf16 v[120:123], v[150:153], v[166:169], v[120:123]
	v_mfma_f32_16x16x32_bf16 v[124:127], v[158:161], v[166:169], v[124:127]
	v_mfma_f32_16x16x32_bf16 v[104:107], v[158:161], v[174:177], v[104:107]
	v_mfma_f32_16x16x32_bf16 v[108:111], v[150:153], v[174:177], v[108:111]
	v_mfma_f32_16x16x32_bf16 v[92:95], v[150:153], v[182:185], v[92:95]
	v_mfma_f32_16x16x32_bf16 v[88:91], v[158:161], v[182:185], v[88:91]
	v_mfma_f32_16x16x32_bf16 v[72:75], v[158:161], v[190:193], v[72:75]
	v_mfma_f32_16x16x32_bf16 v[76:79], v[150:153], v[190:193], v[76:79]
	v_mfma_f32_16x16x32_bf16 v[120:123], v[154:157], v[170:173], v[120:123]
	v_mfma_f32_16x16x32_bf16 v[124:127], v[162:165], v[170:173], v[124:127]
	v_mfma_f32_16x16x32_bf16 v[104:107], v[162:165], v[178:181], v[104:107]
	v_mfma_f32_16x16x32_bf16 v[108:111], v[154:157], v[178:181], v[108:111]
	v_mfma_f32_16x16x32_bf16 v[92:95], v[154:157], v[186:189], v[92:95]
	v_mfma_f32_16x16x32_bf16 v[88:91], v[162:165], v[186:189], v[88:91]
	v_mfma_f32_16x16x32_bf16 v[72:75], v[162:165], v[194:197], v[72:75]
	v_mfma_f32_16x16x32_bf16 v[76:79], v[154:157], v[194:197], v[76:79]
	s_setprio 0
	s_barrier
	s_add_i32 s44, 16, 0x1c000
	s_add_i32 s45, s75, s50
	v_add_u32_e32 v210, s44, v145
	v_lshl_add_u64 v[218:219], v[218:219], 0, s[6:7]
	s_mov_b32 m0, s45
	ds_read_b128 v[198:201], v210
	ds_read_b128 v[202:205], v210 offset:1024
	ds_read_b128 v[206:209], v210 offset:2048
	ds_read_b128 v[210:213], v210 offset:3072
	global_load_lds_dwordx4 v[218:219], off
	v_lshl_add_u64 v[218:219], v[220:221], 0, s[6:7]
	s_add_i32 m0, s45, 0x2000
	s_nop 0
	global_load_lds_dwordx4 v[218:219], off
	s_barrier
; #define PG8_STAGE(bufoff, gbase, voff) do { _Pragma("unroll") for (int _i = 0; _i < 2; ++_i) \
;         __builtin_amdgcn_global_load_lds((const unsigned*)((const char*)(gbase) + (voff)[_i]), (LAS unsigned*)(lds + (bufoff) + ldsw + _i * 8192), 16, 0, 0); } while (0)
; #define PG8_MMA(ai, bj, At, Bt) do { __builtin_amdgcn_s_setprio(1); _Pragma("unroll") for (int m = 0; m < 4; ++m) _Pragma("unroll") for (int n = 0; n < 2; ++n) _Pragma("unroll") for (int k = 0; k < 2; ++k) \
;         acc[ai][bj][m][n] = __builtin_amdgcn_mfma_f32_16x16x32_bf16(Bt[n][k], At[m][k], acc[ai][bj][m][n], 0, 0, 0); __builtin_amdgcn_s_setprio(0); } while (0)
; #define PG8_WAIT_V(n) asm volatile("s_waitcnt vmcnt(" #n ")" ::: "memory")
; #define PG8_WAIT_L(n) asm volatile("s_waitcnt lgkmcnt(" #n ")" ::: "memory")
; #define PG8_BAR __builtin_amdgcn_s_barrier()
; #define PG8_SCHED __builtin_amdgcn_sched_barrier(0)
; template <class Epi>
; DEVINL void gemm_phase(LAS unsigned char* lds, const Gemm g, const Order& S, const Epi& E) {
;     ...
;             PG8_BAR; PG8_WAIT_L(0); PG8_MMA(1, 0, At, B0); PG8_BAR; PG8_SCHED;
;             PG8_STAGE(PG8_SB(1, 1), b3 + hstepB, voffB);
;             PG8_WAIT_V(6); PG8_BAR; PG8_MMA(1, 1, At, B1); PG8_BAR;
;         }
	s_waitcnt lgkmcnt(0)
	s_setprio 1
	s_waitcnt lgkmcnt(0)
	v_mfma_f32_16x16x32_bf16 v[116:119], v[198:201], v[166:169], v[116:119]
	v_mfma_f32_16x16x32_bf16 v[112:115], v[206:209], v[166:169], v[112:115]
	v_mfma_f32_16x16x32_bf16 v[96:99], v[206:209], v[174:177], v[96:99]
	v_mfma_f32_16x16x32_bf16 v[100:103], v[198:201], v[174:177], v[100:103]
	v_mfma_f32_16x16x32_bf16 v[84:87], v[198:201], v[182:185], v[84:87]
	v_mfma_f32_16x16x32_bf16 v[80:83], v[206:209], v[182:185], v[80:83]
	v_mfma_f32_16x16x32_bf16 v[64:67], v[206:209], v[190:193], v[64:67]
	v_mfma_f32_16x16x32_bf16 v[68:71], v[198:201], v[190:193], v[68:71]
	v_mfma_f32_16x16x32_bf16 v[116:119], v[202:205], v[170:173], v[116:119]
	v_mfma_f32_16x16x32_bf16 v[112:115], v[210:213], v[170:173], v[112:115]
	v_mfma_f32_16x16x32_bf16 v[96:99], v[210:213], v[178:181], v[96:99]
	v_mfma_f32_16x16x32_bf16 v[100:103], v[202:205], v[178:181], v[100:103]
	v_mfma_f32_16x16x32_bf16 v[84:87], v[202:205], v[186:189], v[84:87]
	v_mfma_f32_16x16x32_bf16 v[80:83], v[210:213], v[186:189], v[80:83]
	v_mfma_f32_16x16x32_bf16 v[64:67], v[210:213], v[194:197], v[64:67]
	v_mfma_f32_16x16x32_bf16 v[68:71], v[202:205], v[194:197], v[68:71]
	s_setprio 0
	s_mov_b32 m0, s55
	v_lshl_add_u64 v[218:219], v[222:223], 0, s[6:7]
	s_barrier
	ds_read_b128 v[166:169], v148 offset:49152
	ds_read_b128 v[170:173], v148 offset:50176
	ds_read_b128 v[174:177], v148 offset:51200
	ds_read_b128 v[178:181], v148 offset:52224
	ds_read_b128 v[182:185], v148 offset:53248
	ds_read_b128 v[186:189], v148 offset:54272
	ds_read_b128 v[190:193], v148 offset:55296
	ds_read_b128 v[194:197], v148 offset:56320
	global_load_lds_dwordx4 v[218:219], off
	v_lshl_add_u64 v[218:219], v[224:225], 0, s[6:7]
	s_mov_b32 m0, s56
	s_nop 0
	global_load_lds_dwordx4 v[218:219], off
	s_barrier
	s_waitcnt lgkmcnt(0)
	s_setprio 1
	s_waitcnt lgkmcnt(0)
	v_mfma_f32_16x16x32_bf16 v[60:63], v[150:153], v[166:169], v[60:63]
	v_mfma_f32_16x16x32_bf16 v[56:59], v[158:161], v[166:169], v[56:59]
	v_mfma_f32_16x16x32_bf16 v[40:43], v[158:161], v[174:177], v[40:43]
	v_mfma_f32_16x16x32_bf16 v[44:47], v[150:153], v[174:177], v[44:47]
	v_mfma_f32_16x16x32_bf16 v[28:31], v[150:153], v[182:185], v[28:31]
	v_mfma_f32_16x16x32_bf16 v[24:27], v[158:161], v[182:185], v[24:27]
	v_mfma_f32_16x16x32_bf16 v[8:11], v[158:161], v[190:193], v[8:11]
	v_mfma_f32_16x16x32_bf16 v[12:15], v[150:153], v[190:193], v[12:15]
	v_mfma_f32_16x16x32_bf16 v[60:63], v[154:157], v[170:173], v[60:63]
	v_mfma_f32_16x16x32_bf16 v[56:59], v[162:165], v[170:173], v[56:59]
	v_mfma_f32_16x16x32_bf16 v[40:43], v[162:165], v[178:181], v[40:43]
	v_mfma_f32_16x16x32_bf16 v[44:47], v[154:157], v[178:181], v[44:47]
	v_mfma_f32_16x16x32_bf16 v[28:31], v[154:157], v[186:189], v[28:31]
	v_mfma_f32_16x16x32_bf16 v[24:27], v[162:165], v[186:189], v[24:27]
	v_mfma_f32_16x16x32_bf16 v[8:11], v[162:165], v[194:197], v[8:11]
	v_mfma_f32_16x16x32_bf16 v[12:15], v[154:157], v[194:197], v[12:15]
	s_setprio 0
	s_barrier
	s_add_u32 s42, s42, 0x80080
	s_addc_u32 s43, s43, 0
	s_add_i32 s44, s44, s50
	v_lshl_add_u64 v[150:151], s[42:43], 0, v[130:131]
	s_mov_b32 m0, s44
	s_nop 0
	global_load_lds_dwordx4 v[150:151], off
	v_lshl_add_u64 v[150:151], s[42:43], 0, v[134:135]
	s_add_i32 m0, s44, 0x2000
	s_nop 0
	global_load_lds_dwordx4 v[150:151], off
	s_waitcnt vmcnt(6)
	s_barrier
	s_setprio 1
	v_mfma_f32_16x16x32_bf16 v[52:55], v[198:201], v[166:169], v[52:55]
	v_mfma_f32_16x16x32_bf16 v[48:51], v[206:209], v[166:169], v[48:51]
	v_mfma_f32_16x16x32_bf16 v[32:35], v[206:209], v[174:177], v[32:35]
	v_mfma_f32_16x16x32_bf16 v[36:39], v[198:201], v[174:177], v[36:39]
	v_mfma_f32_16x16x32_bf16 v[20:23], v[198:201], v[182:185], v[20:23]
	v_mfma_f32_16x16x32_bf16 v[16:19], v[206:209], v[182:185], v[16:19]
	v_mfma_f32_16x16x32_bf16 v[0:3], v[206:209], v[190:193], v[0:3]
	v_mfma_f32_16x16x32_bf16 v[4:7], v[198:201], v[190:193], v[4:7]
	v_mfma_f32_16x16x32_bf16 v[52:55], v[202:205], v[170:173], v[52:55]
	v_mfma_f32_16x16x32_bf16 v[48:51], v[210:213], v[170:173], v[48:51]
	v_mfma_f32_16x16x32_bf16 v[32:35], v[210:213], v[178:181], v[32:35]
	v_mfma_f32_16x16x32_bf16 v[36:39], v[202:205], v[178:181], v[36:39]
	v_mfma_f32_16x16x32_bf16 v[20:23], v[202:205], v[186:189], v[20:23]
	v_mfma_f32_16x16x32_bf16 v[16:19], v[210:213], v[186:189], v[16:19]
	v_mfma_f32_16x16x32_bf16 v[0:3], v[210:213], v[194:197], v[0:3]
	v_mfma_f32_16x16x32_bf16 v[4:7], v[202:205], v[194:197], v[4:7]
	s_setprio 0
	s_add_u32 s8, s8, 0x100
	s_addc_u32 s9, s9, 0
	s_add_u32 s72, s72, 0x100
	s_addc_u32 s73, s73, 0
	s_cmp_ge_i32 s74, s54
	s_mov_b32 s42, s74
	s_barrier
	s_cbranch_scc0 .LBB0_1492
	v_readlane_b32 s75, v250, 1
	s_branch .LBB0_1483

; #define PG8_STAGE(bufoff, gbase, voff) do { _Pragma("unroll") for (int _i = 0; _i < 2; ++_i) \
;         __builtin_amdgcn_global_load_lds((const unsigned*)((const char*)(gbase) + (voff)[_i]), (LAS unsigned*)(lds + (bufoff) + ldsw + _i * 8192), 16, 0, 0); } while (0)
; #define PG8_LDA(dst, b, h) do { _Pragma("unroll") for (int m = 0; m < 4; ++m) _Pragma("unroll") for (int k = 0; k < 2; ++k) dst[m][k] = *(const LAS bf16x8*)(lds + PG8_SA(b, h) + aoff + m * 2048 + k * 1024); } while (0)
; #define PG8_LDB(dst, b, h) do { _Pragma("unroll") for (int n = 0; n < 2; ++n) _Pragma("unroll") for (int k = 0; k < 2; ++k) dst[n][k] = *(const LAS bf16x8*)(lds + PG8_SB(b, h) + boff + n * 2048 + k * 1024); } while (0)
; #define PG8_MMA(ai, bj, At, Bt) do { __builtin_amdgcn_s_setprio(1); _Pragma("unroll") for (int m = 0; m < 4; ++m) _Pragma("unroll") for (int n = 0; n < 2; ++n) _Pragma("unroll") for (int k = 0; k < 2; ++k) \
;         acc[ai][bj][m][n] = __builtin_amdgcn_mfma_f32_16x16x32_bf16(Bt[n][k], At[m][k], acc[ai][bj][m][n], 0, 0, 0); __builtin_amdgcn_s_setprio(0); } while (0)
; #define PG8_WAIT_L(n) asm volatile("s_waitcnt lgkmcnt(" #n ")" ::: "memory")
; #define PG8_BAR __builtin_amdgcn_s_barrier()
; #define PG8_SCHED __builtin_amdgcn_sched_barrier(0)
; template <class Epi>
; DEVINL void gemm_phase(LAS unsigned char* lds, const Gemm g, const Order& S, const Epi& E) {
;     ...
;         for (int t = 0; t < nt; t += 2) {
;             const bool last = (t == nt - 2);
;             const char* a1 = cA + (size_t)(t + 1) * kstep;
;             const char* a2 = last ? nA : cA + (size_t)(t + 2) * kstep; const char* b2 = last ? nB : cB + (size_t)(t + 2) * kstep;
;             const char* a3 = a2 + kstep; const char* b3 = b2 + kstep;
;             PG8_LDB(B0, 0, 0); PG8_SCHED; PG8_LDA(At, 0, 0); PG8_STAGE(PG8_SA(1, 1), a1 + hstepA, voffA);
;             PG8_WAIT_L(8); PG8_BAR; PG8_WAIT_L(0); PG8_MMA(0, 0, At, B0); PG8_BAR; PG8_SCHED;
;             PG8_LDB(B1, 0, 1); PG8_STAGE(PG8_SB(0, 0), b2, voffB);
;             PG8_BAR; PG8_WAIT_L(0); PG8_MMA(0, 1, At, B1); PG8_BAR;
;             PG8_LDA(At, 0, 1); PG8_STAGE(PG8_SA(0, 0), a2, voffA);
;             PG8_BAR; PG8_WAIT_L(0); PG8_MMA(1, 0, At, B0); PG8_BAR; PG8_SCHED;
.LBB0_1623:
	ds_read_b128 v[150:153], v147
	ds_read_b128 v[154:157], v147 offset:1024
	ds_read_b128 v[158:161], v147 offset:2048
	ds_read_b128 v[162:165], v147 offset:3072
	s_add_i32 s69, s38, 2
	s_add_u32 s39, s2, 0xfffc0080
	s_addc_u32 s40, s3, -1
	s_cmp_eq_u32 s52, s38
	s_cselect_b32 s38, s66, s67
	s_cselect_b32 s41, s27, s40
	s_cselect_b32 s40, s29, s39
	s_cselect_b32 s39, s65, s68
	v_lshl_add_u64 v[198:199], s[2:3], 0, v[136:137]
	s_add_i32 m0, s25, 0xc000
	ds_read_b128 v[166:169], v148
	ds_read_b128 v[170:173], v148 offset:1024
	ds_read_b128 v[174:177], v148 offset:2048
	ds_read_b128 v[178:181], v148 offset:3072
	ds_read_b128 v[182:185], v148 offset:4096
	ds_read_b128 v[186:189], v148 offset:5120
	ds_read_b128 v[190:193], v148 offset:6144
	ds_read_b128 v[194:197], v148 offset:7168
	global_load_lds_dwordx4 v[198:199], off
	v_lshl_add_u64 v[198:199], s[2:3], 0, v[138:139]
	s_add_i32 m0, s25, 0xe000
	s_nop 0
	global_load_lds_dwordx4 v[198:199], off
	s_waitcnt lgkmcnt(8)
	s_barrier
	s_waitcnt lgkmcnt(0)
	s_setprio 1
	s_waitcnt lgkmcnt(0)
	v_mfma_f32_16x16x32_bf16 v[120:123], v[150:153], v[166:169], v[120:123]
	v_mfma_f32_16x16x32_bf16 v[124:127], v[158:161], v[166:169], v[124:127]
	v_mfma_f32_16x16x32_bf16 v[104:107], v[158:161], v[174:177], v[104:107]
	v_mfma_f32_16x16x32_bf16 v[108:111], v[150:153], v[174:177], v[108:111]
	v_mfma_f32_16x16x32_bf16 v[92:95], v[150:153], v[182:185], v[92:95]
	v_mfma_f32_16x16x32_bf16 v[88:91], v[158:161], v[182:185], v[88:91]
	v_mfma_f32_16x16x32_bf16 v[72:75], v[158:161], v[190:193], v[72:75]
	v_mfma_f32_16x16x32_bf16 v[76:79], v[150:153], v[190:193], v[76:79]
	v_mfma_f32_16x16x32_bf16 v[120:123], v[154:157], v[170:173], v[120:123]
	v_mfma_f32_16x16x32_bf16 v[124:127], v[162:165], v[170:173], v[124:127]
	v_mfma_f32_16x16x32_bf16 v[104:107], v[162:165], v[178:181], v[104:107]
	v_mfma_f32_16x16x32_bf16 v[108:111], v[154:157], v[178:181], v[108:111]
	v_mfma_f32_16x16x32_bf16 v[92:95], v[154:157], v[186:189], v[92:95]
	v_mfma_f32_16x16x32_bf16 v[88:91], v[162:165], v[186:189], v[88:91]
	v_mfma_f32_16x16x32_bf16 v[72:75], v[162:165], v[194:197], v[72:75]
	v_mfma_f32_16x16x32_bf16 v[76:79], v[154:157], v[194:197], v[76:79]
	s_setprio 0
	s_barrier
	s_add_i32 s70, s58, s45
	v_lshl_add_u64 v[218:219], s[38:39], 0, v[130:131]
	s_mov_b32 m0, s70
	ds_read_b128 v[198:201], v149
	ds_read_b128 v[202:205], v149 offset:1024
	ds_read_b128 v[206:209], v149 offset:2048
	ds_read_b128 v[210:213], v149 offset:3072
	global_load_lds_dwordx4 v[218:219], off
	v_lshl_add_u64 v[220:221], s[38:39], 0, v[134:135]
	s_add_i32 m0, s70, 0x2000
	s_nop 0
	global_load_lds_dwordx4 v[220:221], off
	s_barrier
	s_waitcnt lgkmcnt(0)
	s_setprio 1
	s_waitcnt lgkmcnt(0)
	v_mfma_f32_16x16x32_bf16 v[116:119], v[198:201], v[166:169], v[116:119]
	v_mfma_f32_16x16x32_bf16 v[112:115], v[206:209], v[166:169], v[112:115]
	v_mfma_f32_16x16x32_bf16 v[96:99], v[206:209], v[174:177], v[96:99]
	v_mfma_f32_16x16x32_bf16 v[100:103], v[198:201], v[174:177], v[100:103]
	v_mfma_f32_16x16x32_bf16 v[84:87], v[198:201], v[182:185], v[84:87]
	v_mfma_f32_16x16x32_bf16 v[80:83], v[206:209], v[182:185], v[80:83]
	v_mfma_f32_16x16x32_bf16 v[64:67], v[206:209], v[190:193], v[64:67]
	v_mfma_f32_16x16x32_bf16 v[68:71], v[198:201], v[190:193], v[68:71]
	v_mfma_f32_16x16x32_bf16 v[116:119], v[202:205], v[170:173], v[116:119]
	v_mfma_f32_16x16x32_bf16 v[112:115], v[210:213], v[170:173], v[112:115]
	v_mfma_f32_16x16x32_bf16 v[96:99], v[210:213], v[178:181], v[96:99]
	v_mfma_f32_16x16x32_bf16 v[100:103], v[202:205], v[178:181], v[100:103]
	v_mfma_f32_16x16x32_bf16 v[84:87], v[202:205], v[186:189], v[84:87]
	v_mfma_f32_16x16x32_bf16 v[80:83], v[210:213], v[186:189], v[80:83]
	v_mfma_f32_16x16x32_bf16 v[64:67], v[210:213], v[194:197], v[64:67]
	v_mfma_f32_16x16x32_bf16 v[68:71], v[202:205], v[194:197], v[68:71]
	s_setprio 0
	s_mov_b32 m0, s25
	v_lshl_add_u64 v[222:223], s[40:41], 0, v[128:129]
	s_barrier
	ds_read_b128 v[166:169], v148 offset:16384
	ds_read_b128 v[170:173], v148 offset:17408
	ds_read_b128 v[174:177], v148 offset:18432
	ds_read_b128 v[178:181], v148 offset:19456
	ds_read_b128 v[182:185], v148 offset:20480
	ds_read_b128 v[186:189], v148 offset:21504
	ds_read_b128 v[190:193], v148 offset:22528
	ds_read_b128 v[194:197], v148 offset:23552
	global_load_lds_dwordx4 v[222:223], off
	v_lshl_add_u64 v[224:225], s[40:41], 0, v[132:133]
	s_mov_b32 m0, s46
	s_nop 0
	global_load_lds_dwordx4 v[224:225], off
	s_barrier
	s_waitcnt lgkmcnt(0)
	s_setprio 1
	s_waitcnt lgkmcnt(0)
	v_mfma_f32_16x16x32_bf16 v[60:63], v[150:153], v[166:169], v[60:63]
	v_mfma_f32_16x16x32_bf16 v[56:59], v[158:161], v[166:169], v[56:59]
	v_mfma_f32_16x16x32_bf16 v[40:43], v[158:161], v[174:177], v[40:43]
	v_mfma_f32_16x16x32_bf16 v[44:47], v[150:153], v[174:177], v[44:47]
	v_mfma_f32_16x16x32_bf16 v[28:31], v[150:153], v[182:185], v[28:31]
	v_mfma_f32_16x16x32_bf16 v[24:27], v[158:161], v[182:185], v[24:27]
	v_mfma_f32_16x16x32_bf16 v[8:11], v[158:161], v[190:193], v[8:11]
	v_mfma_f32_16x16x32_bf16 v[12:15], v[150:153], v[190:193], v[12:15]
	v_mfma_f32_16x16x32_bf16 v[60:63], v[154:157], v[170:173], v[60:63]
	v_mfma_f32_16x16x32_bf16 v[56:59], v[162:165], v[170:173], v[56:59]
	v_mfma_f32_16x16x32_bf16 v[40:43], v[162:165], v[178:181], v[40:43]
	v_mfma_f32_16x16x32_bf16 v[44:47], v[154:157], v[178:181], v[44:47]
	v_mfma_f32_16x16x32_bf16 v[28:31], v[154:157], v[186:189], v[28:31]
	v_mfma_f32_16x16x32_bf16 v[24:27], v[162:165], v[186:189], v[24:27]
	v_mfma_f32_16x16x32_bf16 v[8:11], v[162:165], v[194:197], v[8:11]
	v_mfma_f32_16x16x32_bf16 v[12:15], v[154:157], v[194:197], v[12:15]
	s_setprio 0
	s_barrier
; #define PG8_STAGE(bufoff, gbase, voff) do { _Pragma("unroll") for (int _i = 0; _i < 2; ++_i) \
;         __builtin_amdgcn_global_load_lds((const unsigned*)((const char*)(gbase) + (voff)[_i]), (LAS unsigned*)(lds + (bufoff) + ldsw + _i * 8192), 16, 0, 0); } while (0)
; #define PG8_LDA(dst, b, h) do { _Pragma("unroll") for (int m = 0; m < 4; ++m) _Pragma("unroll") for (int k = 0; k < 2; ++k) dst[m][k] = *(const LAS bf16x8*)(lds + PG8_SA(b, h) + aoff + m * 2048 + k * 1024); } while (0)
; #define PG8_LDB(dst, b, h) do { _Pragma("unroll") for (int n = 0; n < 2; ++n) _Pragma("unroll") for (int k = 0; k < 2; ++k) dst[n][k] = *(const LAS bf16x8*)(lds + PG8_SB(b, h) + boff + n * 2048 + k * 1024); } while (0)
; #define PG8_MMA(ai, bj, At, Bt) do { __builtin_amdgcn_s_setprio(1); _Pragma("unroll") for (int m = 0; m < 4; ++m) _Pragma("unroll") for (int n = 0; n < 2; ++n) _Pragma("unroll") for (int k = 0; k < 2; ++k) \
;         acc[ai][bj][m][n] = __builtin_amdgcn_mfma_f32_16x16x32_bf16(Bt[n][k], At[m][k], acc[ai][bj][m][n], 0, 0, 0); __builtin_amdgcn_s_setprio(0); } while (0)
; #define PG8_WAIT_V(n) asm volatile("s_waitcnt vmcnt(" #n ")" ::: "memory")
; #define PG8_WAIT_L(n) asm volatile("s_waitcnt lgkmcnt(" #n ")" ::: "memory")
; #define PG8_BAR __builtin_amdgcn_s_barrier()
; #define PG8_SCHED __builtin_amdgcn_sched_barrier(0)
; template <class Epi>
; DEVINL void gemm_phase(LAS unsigned char* lds, const Gemm g, const Order& S, const Epi& E) {
;     ...
;             PG8_STAGE(PG8_SB(0, 1), b2 + hstepB, voffB);
;             PG8_WAIT_V(6); PG8_BAR; PG8_MMA(1, 1, At, B1); PG8_BAR;
;             PG8_LDB(B0, 1, 0); PG8_SCHED; PG8_LDA(At, 1, 0); PG8_STAGE(PG8_SA(0, 1), a2 + hstepA, voffA);
;             PG8_WAIT_L(8); PG8_BAR; PG8_WAIT_L(0); PG8_MMA(0, 0, At, B0); PG8_BAR; PG8_SCHED;
;             PG8_LDB(B1, 1, 1); PG8_STAGE(PG8_SB(1, 0), b3, voffB);
;             PG8_BAR; PG8_WAIT_L(0); PG8_MMA(0, 1, At, B1); PG8_BAR;
;             PG8_LDA(At, 1, 1); PG8_STAGE(PG8_SA(1, 0), a3, voffA);
	s_add_u32 s70, s38, 0x40000
	s_addc_u32 s71, s39, 0
	s_add_i32 s72, s59, s45
	v_lshl_add_u64 v[150:151], s[70:71], 0, v[130:131]
	s_mov_b32 m0, s72
	s_nop 0
	global_load_lds_dwordx4 v[150:151], off
	v_lshl_add_u64 v[150:151], s[70:71], 0, v[134:135]
	s_add_i32 m0, s72, 0x2000
	s_nop 0
	global_load_lds_dwordx4 v[150:151], off
	s_waitcnt vmcnt(6)
	s_barrier
	s_setprio 1
	v_mfma_f32_16x16x32_bf16 v[52:55], v[198:201], v[166:169], v[52:55]
	v_mfma_f32_16x16x32_bf16 v[48:51], v[206:209], v[166:169], v[48:51]
	v_mfma_f32_16x16x32_bf16 v[32:35], v[206:209], v[174:177], v[32:35]
	v_mfma_f32_16x16x32_bf16 v[36:39], v[198:201], v[174:177], v[36:39]
	v_mfma_f32_16x16x32_bf16 v[20:23], v[198:201], v[182:185], v[20:23]
	v_mfma_f32_16x16x32_bf16 v[16:19], v[206:209], v[182:185], v[16:19]
	v_mfma_f32_16x16x32_bf16 v[0:3], v[206:209], v[190:193], v[0:3]
	v_mfma_f32_16x16x32_bf16 v[4:7], v[198:201], v[190:193], v[4:7]
	v_mfma_f32_16x16x32_bf16 v[52:55], v[202:205], v[170:173], v[52:55]
	v_mfma_f32_16x16x32_bf16 v[48:51], v[210:213], v[170:173], v[48:51]
	v_mfma_f32_16x16x32_bf16 v[32:35], v[210:213], v[178:181], v[32:35]
	v_mfma_f32_16x16x32_bf16 v[36:39], v[202:205], v[178:181], v[36:39]
	v_mfma_f32_16x16x32_bf16 v[20:23], v[202:205], v[186:189], v[20:23]
	v_mfma_f32_16x16x32_bf16 v[16:19], v[210:213], v[186:189], v[16:19]
	v_mfma_f32_16x16x32_bf16 v[0:3], v[210:213], v[194:197], v[0:3]
	v_mfma_f32_16x16x32_bf16 v[4:7], v[202:205], v[194:197], v[4:7]
	s_setprio 0
	s_add_i32 s70, 16, 0x18000
	v_add_u32_e32 v162, s70, v145
	s_barrier
	ds_read_b128 v[150:153], v162
	ds_read_b128 v[154:157], v162 offset:1024
	ds_read_b128 v[158:161], v162 offset:2048
	ds_read_b128 v[162:165], v162 offset:3072
	s_add_u32 s40, s40, 0x40000
	s_addc_u32 s41, s41, 0
	s_mov_b32 m0, s47
	v_lshl_add_u64 v[198:199], s[40:41], 0, v[128:129]
	ds_read_b128 v[166:169], v148 offset:32768
	ds_read_b128 v[170:173], v148 offset:33792
	ds_read_b128 v[174:177], v148 offset:34816
	ds_read_b128 v[178:181], v148 offset:35840
	ds_read_b128 v[182:185], v148 offset:36864
	ds_read_b128 v[186:189], v148 offset:37888
	ds_read_b128 v[190:193], v148 offset:38912
	ds_read_b128 v[194:197], v148 offset:39936
	global_load_lds_dwordx4 v[198:199], off
	v_lshl_add_u64 v[198:199], s[40:41], 0, v[132:133]
	s_mov_b32 m0, s48
	s_nop 0
	global_load_lds_dwordx4 v[198:199], off
	s_waitcnt lgkmcnt(8)
	s_barrier
	s_waitcnt lgkmcnt(0)
	s_setprio 1
	s_waitcnt lgkmcnt(0)
	v_mfma_f32_16x16x32_bf16 v[120:123], v[150:153], v[166:169], v[120:123]
	v_mfma_f32_16x16x32_bf16 v[124:127], v[158:161], v[166:169], v[124:127]
	v_mfma_f32_16x16x32_bf16 v[104:107], v[158:161], v[174:177], v[104:107]
	v_mfma_f32_16x16x32_bf16 v[108:111], v[150:153], v[174:177], v[108:111]
	v_mfma_f32_16x16x32_bf16 v[92:95], v[150:153], v[182:185], v[92:95]
	v_mfma_f32_16x16x32_bf16 v[88:91], v[158:161], v[182:185], v[88:91]
	v_mfma_f32_16x16x32_bf16 v[72:75], v[158:161], v[190:193], v[72:75]
	v_mfma_f32_16x16x32_bf16 v[76:79], v[150:153], v[190:193], v[76:79]
	v_mfma_f32_16x16x32_bf16 v[120:123], v[154:157], v[170:173], v[120:123]
	v_mfma_f32_16x16x32_bf16 v[124:127], v[162:165], v[170:173], v[124:127]
	v_mfma_f32_16x16x32_bf16 v[104:107], v[162:165], v[178:181], v[104:107]
	v_mfma_f32_16x16x32_bf16 v[108:111], v[154:157], v[178:181], v[108:111]
	v_mfma_f32_16x16x32_bf16 v[92:95], v[154:157], v[186:189], v[92:95]
	v_mfma_f32_16x16x32_bf16 v[88:91], v[162:165], v[186:189], v[88:91]
	v_mfma_f32_16x16x32_bf16 v[72:75], v[162:165], v[194:197], v[72:75]
	v_mfma_f32_16x16x32_bf16 v[76:79], v[154:157], v[194:197], v[76:79]
	s_setprio 0
	s_barrier
	s_add_i32 s40, 16, 0x1c000
	s_add_i32 s41, s70, s45
	v_add_u32_e32 v210, s40, v145
	v_lshl_add_u64 v[218:219], v[218:219], 0, s[6:7]
	s_mov_b32 m0, s41
	ds_read_b128 v[198:201], v210
	ds_read_b128 v[202:205], v210 offset:1024
	ds_read_b128 v[206:209], v210 offset:2048
	ds_read_b128 v[210:213], v210 offset:3072
	global_load_lds_dwordx4 v[218:219], off
	v_lshl_add_u64 v[218:219], v[220:221], 0, s[6:7]
	s_add_i32 m0, s41, 0x2000
	s_nop 0
	global_load_lds_dwordx4 v[218:219], off
	s_barrier
; #define PG8_STAGE(bufoff, gbase, voff) do { _Pragma("unroll") for (int _i = 0; _i < 2; ++_i) \
;         __builtin_amdgcn_global_load_lds((const unsigned*)((const char*)(gbase) + (voff)[_i]), (LAS unsigned*)(lds + (bufoff) + ldsw + _i * 8192), 16, 0, 0); } while (0)
; #define PG8_MMA(ai, bj, At, Bt) do { __builtin_amdgcn_s_setprio(1); _Pragma("unroll") for (int m = 0; m < 4; ++m) _Pragma("unroll") for (int n = 0; n < 2; ++n) _Pragma("unroll") for (int k = 0; k < 2; ++k) \
;         acc[ai][bj][m][n] = __builtin_amdgcn_mfma_f32_16x16x32_bf16(Bt[n][k], At[m][k], acc[ai][bj][m][n], 0, 0, 0); __builtin_amdgcn_s_setprio(0); } while (0)
; #define PG8_WAIT_V(n) asm volatile("s_waitcnt vmcnt(" #n ")" ::: "memory")
; #define PG8_WAIT_L(n) asm volatile("s_waitcnt lgkmcnt(" #n ")" ::: "memory")
; #define PG8_BAR __builtin_amdgcn_s_barrier()
; #define PG8_SCHED __builtin_amdgcn_sched_barrier(0)
; template <class Epi>
; DEVINL void gemm_phase(LAS unsigned char* lds, const Gemm g, const Order& S, const Epi& E) {
;     ...
;             PG8_BAR; PG8_WAIT_L(0); PG8_MMA(1, 0, At, B0); PG8_BAR; PG8_SCHED;
;             PG8_STAGE(PG8_SB(1, 1), b3 + hstepB, voffB);
;             PG8_WAIT_V(6); PG8_BAR; PG8_MMA(1, 1, At, B1); PG8_BAR;
;         }
	s_waitcnt lgkmcnt(0)
	s_setprio 1
	s_waitcnt lgkmcnt(0)
	v_mfma_f32_16x16x32_bf16 v[116:119], v[198:201], v[166:169], v[116:119]
	v_mfma_f32_16x16x32_bf16 v[112:115], v[206:209], v[166:169], v[112:115]
	v_mfma_f32_16x16x32_bf16 v[96:99], v[206:209], v[174:177], v[96:99]
	v_mfma_f32_16x16x32_bf16 v[100:103], v[198:201], v[174:177], v[100:103]
	v_mfma_f32_16x16x32_bf16 v[84:87], v[198:201], v[182:185], v[84:87]
	v_mfma_f32_16x16x32_bf16 v[80:83], v[206:209], v[182:185], v[80:83]
	v_mfma_f32_16x16x32_bf16 v[64:67], v[206:209], v[190:193], v[64:67]
	v_mfma_f32_16x16x32_bf16 v[68:71], v[198:201], v[190:193], v[68:71]
	v_mfma_f32_16x16x32_bf16 v[116:119], v[202:205], v[170:173], v[116:119]
	v_mfma_f32_16x16x32_bf16 v[112:115], v[210:213], v[170:173], v[112:115]
	v_mfma_f32_16x16x32_bf16 v[96:99], v[210:213], v[178:181], v[96:99]
	v_mfma_f32_16x16x32_bf16 v[100:103], v[202:205], v[178:181], v[100:103]
	v_mfma_f32_16x16x32_bf16 v[84:87], v[202:205], v[186:189], v[84:87]
	v_mfma_f32_16x16x32_bf16 v[80:83], v[210:213], v[186:189], v[80:83]
	v_mfma_f32_16x16x32_bf16 v[64:67], v[210:213], v[194:197], v[64:67]
	v_mfma_f32_16x16x32_bf16 v[68:71], v[202:205], v[194:197], v[68:71]
	s_setprio 0
	s_mov_b32 m0, s50
	v_lshl_add_u64 v[218:219], v[222:223], 0, s[6:7]
	s_barrier
	ds_read_b128 v[166:169], v148 offset:49152
	ds_read_b128 v[170:173], v148 offset:50176
	ds_read_b128 v[174:177], v148 offset:51200
	ds_read_b128 v[178:181], v148 offset:52224
	ds_read_b128 v[182:185], v148 offset:53248
	ds_read_b128 v[186:189], v148 offset:54272
	ds_read_b128 v[190:193], v148 offset:55296
	ds_read_b128 v[194:197], v148 offset:56320
	global_load_lds_dwordx4 v[218:219], off
	v_lshl_add_u64 v[218:219], v[224:225], 0, s[6:7]
	s_mov_b32 m0, s51
	s_nop 0
	global_load_lds_dwordx4 v[218:219], off
	s_barrier
	s_waitcnt lgkmcnt(0)
	s_setprio 1
	s_waitcnt lgkmcnt(0)
	v_mfma_f32_16x16x32_bf16 v[60:63], v[150:153], v[166:169], v[60:63]
	v_mfma_f32_16x16x32_bf16 v[56:59], v[158:161], v[166:169], v[56:59]
	v_mfma_f32_16x16x32_bf16 v[40:43], v[158:161], v[174:177], v[40:43]
	v_mfma_f32_16x16x32_bf16 v[44:47], v[150:153], v[174:177], v[44:47]
	v_mfma_f32_16x16x32_bf16 v[28:31], v[150:153], v[182:185], v[28:31]
	v_mfma_f32_16x16x32_bf16 v[24:27], v[158:161], v[182:185], v[24:27]
	v_mfma_f32_16x16x32_bf16 v[8:11], v[158:161], v[190:193], v[8:11]
	v_mfma_f32_16x16x32_bf16 v[12:15], v[150:153], v[190:193], v[12:15]
	v_mfma_f32_16x16x32_bf16 v[60:63], v[154:157], v[170:173], v[60:63]
	v_mfma_f32_16x16x32_bf16 v[56:59], v[162:165], v[170:173], v[56:59]
	v_mfma_f32_16x16x32_bf16 v[40:43], v[162:165], v[178:181], v[40:43]
	v_mfma_f32_16x16x32_bf16 v[44:47], v[154:157], v[178:181], v[44:47]
	v_mfma_f32_16x16x32_bf16 v[28:31], v[154:157], v[186:189], v[28:31]
	v_mfma_f32_16x16x32_bf16 v[24:27], v[162:165], v[186:189], v[24:27]
	v_mfma_f32_16x16x32_bf16 v[8:11], v[162:165], v[194:197], v[8:11]
	v_mfma_f32_16x16x32_bf16 v[12:15], v[154:157], v[194:197], v[12:15]
	s_setprio 0
	s_barrier
	s_add_u32 s38, s38, 0x40080
	s_addc_u32 s39, s39, 0
	s_add_i32 s40, s40, s45
	v_lshl_add_u64 v[150:151], s[38:39], 0, v[130:131]
	s_mov_b32 m0, s40
	s_nop 0
	global_load_lds_dwordx4 v[150:151], off
	v_lshl_add_u64 v[150:151], s[38:39], 0, v[134:135]
	s_add_i32 m0, s40, 0x2000
	s_nop 0
	global_load_lds_dwordx4 v[150:151], off
	s_waitcnt vmcnt(6)
	s_barrier
	s_setprio 1
	v_mfma_f32_16x16x32_bf16 v[52:55], v[198:201], v[166:169], v[52:55]
	v_mfma_f32_16x16x32_bf16 v[48:51], v[206:209], v[166:169], v[48:51]
	v_mfma_f32_16x16x32_bf16 v[32:35], v[206:209], v[174:177], v[32:35]
	v_mfma_f32_16x16x32_bf16 v[36:39], v[198:201], v[174:177], v[36:39]
	v_mfma_f32_16x16x32_bf16 v[20:23], v[198:201], v[182:185], v[20:23]
	v_mfma_f32_16x16x32_bf16 v[16:19], v[206:209], v[182:185], v[16:19]
	v_mfma_f32_16x16x32_bf16 v[0:3], v[206:209], v[190:193], v[0:3]
	v_mfma_f32_16x16x32_bf16 v[4:7], v[198:201], v[190:193], v[4:7]
	v_mfma_f32_16x16x32_bf16 v[52:55], v[202:205], v[170:173], v[52:55]
	v_mfma_f32_16x16x32_bf16 v[48:51], v[210:213], v[170:173], v[48:51]
	v_mfma_f32_16x16x32_bf16 v[32:35], v[210:213], v[178:181], v[32:35]
	v_mfma_f32_16x16x32_bf16 v[36:39], v[202:205], v[178:181], v[36:39]
	v_mfma_f32_16x16x32_bf16 v[20:23], v[202:205], v[186:189], v[20:23]
	v_mfma_f32_16x16x32_bf16 v[16:19], v[210:213], v[186:189], v[16:19]
	v_mfma_f32_16x16x32_bf16 v[0:3], v[210:213], v[194:197], v[0:3]
	v_mfma_f32_16x16x32_bf16 v[4:7], v[202:205], v[194:197], v[4:7]
	s_setprio 0
	s_add_u32 s2, s2, 0x100
	s_addc_u32 s3, s3, 0
	s_add_u32 s67, s67, 0x100
	s_addc_u32 s68, s68, 0
	s_cmp_ge_i32 s69, s49
	s_mov_b32 s38, s69
	s_barrier
	s_cbranch_scc0 .LBB0_1623
	s_branch .LBB0_1614

; #define PG8_STAGE(bufoff, gbase, voff) do { _Pragma("unroll") for (int _i = 0; _i < 2; ++_i) \
;         __builtin_amdgcn_global_load_lds((const unsigned*)((const char*)(gbase) + (voff)[_i]), (LAS unsigned*)(lds + (bufoff) + ldsw + _i * 8192), 16, 0, 0); } while (0)
; #define PG8_LDA(dst, b, h) do { _Pragma("unroll") for (int m = 0; m < 4; ++m) _Pragma("unroll") for (int k = 0; k < 2; ++k) dst[m][k] = *(const LAS bf16x8*)(lds + PG8_SA(b, h) + aoff + m * 2048 + k * 1024); } while (0)
; #define PG8_LDB(dst, b, h) do { _Pragma("unroll") for (int n = 0; n < 2; ++n) _Pragma("unroll") for (int k = 0; k < 2; ++k) dst[n][k] = *(const LAS bf16x8*)(lds + PG8_SB(b, h) + boff + n * 2048 + k * 1024); } while (0)
; #define PG8_MMA(ai, bj, At, Bt) do { __builtin_amdgcn_s_setprio(1); _Pragma("unroll") for (int m = 0; m < 4; ++m) _Pragma("unroll") for (int n = 0; n < 2; ++n) _Pragma("unroll") for (int k = 0; k < 2; ++k) \
;         acc[ai][bj][m][n] = __builtin_amdgcn_mfma_f32_16x16x32_bf16(Bt[n][k], At[m][k], acc[ai][bj][m][n], 0, 0, 0); __builtin_amdgcn_s_setprio(0); } while (0)
; #define PG8_WAIT_L(n) asm volatile("s_waitcnt lgkmcnt(" #n ")" ::: "memory")
; #define PG8_BAR __builtin_amdgcn_s_barrier()
; #define PG8_SCHED __builtin_amdgcn_sched_barrier(0)
; template <class Epi>
; DEVINL void gemm_phase(LAS unsigned char* lds, const Gemm g, const Order& S, const Epi& E) {
;     ...
;         for (int t = 0; t < nt; t += 2) {
;             const bool last = (t == nt - 2);
;             const char* a1 = cA + (size_t)(t + 1) * kstep;
;             const char* a2 = last ? nA : cA + (size_t)(t + 2) * kstep; const char* b2 = last ? nB : cB + (size_t)(t + 2) * kstep;
;             const char* a3 = a2 + kstep; const char* b3 = b2 + kstep;
;             PG8_LDB(B0, 0, 0); PG8_SCHED; PG8_LDA(At, 0, 0); PG8_STAGE(PG8_SA(1, 1), a1 + hstepA, voffA);
;             PG8_WAIT_L(8); PG8_BAR; PG8_WAIT_L(0); PG8_MMA(0, 0, At, B0); PG8_BAR; PG8_SCHED;
;             PG8_LDB(B1, 0, 1); PG8_STAGE(PG8_SB(0, 0), b2, voffB);
;             PG8_BAR; PG8_WAIT_L(0); PG8_MMA(0, 1, At, B1); PG8_BAR;
;             PG8_LDA(At, 0, 1); PG8_STAGE(PG8_SA(0, 0), a2, voffA);
;             PG8_BAR; PG8_WAIT_L(0); PG8_MMA(1, 0, At, B0); PG8_BAR; PG8_SCHED;
.LBB0_1775:
	ds_read_b128 v[152:155], v149
	ds_read_b128 v[156:159], v149 offset:1024
	ds_read_b128 v[160:163], v149 offset:2048
	ds_read_b128 v[164:167], v149 offset:3072
	s_add_i32 s55, s26, 2
	s_add_u32 s27, s24, 0xfff80080
	s_addc_u32 s28, s25, -1
	s_cmp_eq_u32 s44, s26
	s_cselect_b32 s26, s52, s53
	s_cselect_b32 s29, s9, s28
	s_cselect_b32 s28, s11, s27
	s_cselect_b32 s27, s51, s54
	v_lshl_add_u64 v[144:145], s[24:25], 0, v[136:137]
	s_add_i32 m0, s17, 0xc000
	ds_read_b128 v[168:171], v150
	ds_read_b128 v[172:175], v150 offset:1024
	ds_read_b128 v[176:179], v150 offset:2048
	ds_read_b128 v[180:183], v150 offset:3072
	ds_read_b128 v[184:187], v150 offset:4096
	ds_read_b128 v[188:191], v150 offset:5120
	ds_read_b128 v[192:195], v150 offset:6144
	ds_read_b128 v[196:199], v150 offset:7168
	global_load_lds_dwordx4 v[144:145], off
	v_lshl_add_u64 v[144:145], s[24:25], 0, v[138:139]
	s_add_i32 m0, s17, 0xe000
	s_nop 0
	global_load_lds_dwordx4 v[144:145], off
	s_waitcnt lgkmcnt(8)
	s_barrier
	s_waitcnt lgkmcnt(0)
	s_setprio 1
	s_waitcnt lgkmcnt(0)
	v_mfma_f32_16x16x32_bf16 v[124:127], v[152:155], v[168:171], v[124:127]
	v_mfma_f32_16x16x32_bf16 v[116:119], v[160:163], v[168:171], v[116:119]
	v_mfma_f32_16x16x32_bf16 v[100:103], v[160:163], v[176:179], v[100:103]
	v_mfma_f32_16x16x32_bf16 v[108:111], v[152:155], v[176:179], v[108:111]
	v_mfma_f32_16x16x32_bf16 v[92:95], v[152:155], v[184:187], v[92:95]
	v_mfma_f32_16x16x32_bf16 v[84:87], v[160:163], v[184:187], v[84:87]
	v_mfma_f32_16x16x32_bf16 v[68:71], v[160:163], v[192:195], v[68:71]
	v_mfma_f32_16x16x32_bf16 v[76:79], v[152:155], v[192:195], v[76:79]
	v_mfma_f32_16x16x32_bf16 v[124:127], v[156:159], v[172:175], v[124:127]
	v_mfma_f32_16x16x32_bf16 v[116:119], v[164:167], v[172:175], v[116:119]
	v_mfma_f32_16x16x32_bf16 v[100:103], v[164:167], v[180:183], v[100:103]
	v_mfma_f32_16x16x32_bf16 v[108:111], v[156:159], v[180:183], v[108:111]
	v_mfma_f32_16x16x32_bf16 v[92:95], v[156:159], v[188:191], v[92:95]
	v_mfma_f32_16x16x32_bf16 v[84:87], v[164:167], v[188:191], v[84:87]
	v_mfma_f32_16x16x32_bf16 v[68:71], v[164:167], v[196:199], v[68:71]
	v_mfma_f32_16x16x32_bf16 v[76:79], v[156:159], v[196:199], v[76:79]
	s_setprio 0
	s_barrier
	s_add_i32 s56, s47, s30
	v_lshl_add_u64 v[144:145], s[26:27], 0, v[132:133]
	s_mov_b32 m0, s56
	ds_read_b128 v[200:203], v151
	ds_read_b128 v[204:207], v151 offset:1024
	ds_read_b128 v[208:211], v151 offset:2048
	ds_read_b128 v[218:221], v151 offset:3072
	global_load_lds_dwordx4 v[144:145], off
	v_lshl_add_u64 v[212:213], s[26:27], 0, v[128:129]
	s_add_i32 m0, s56, 0x2000
	s_nop 0
	global_load_lds_dwordx4 v[212:213], off
	s_barrier
	s_waitcnt lgkmcnt(0)
	s_setprio 1
	s_waitcnt lgkmcnt(0)
	v_mfma_f32_16x16x32_bf16 v[120:123], v[200:203], v[168:171], v[120:123]
	v_mfma_f32_16x16x32_bf16 v[112:115], v[208:211], v[168:171], v[112:115]
	v_mfma_f32_16x16x32_bf16 v[96:99], v[208:211], v[176:179], v[96:99]
	v_mfma_f32_16x16x32_bf16 v[104:107], v[200:203], v[176:179], v[104:107]
	v_mfma_f32_16x16x32_bf16 v[88:91], v[200:203], v[184:187], v[88:91]
	v_mfma_f32_16x16x32_bf16 v[80:83], v[208:211], v[184:187], v[80:83]
	v_mfma_f32_16x16x32_bf16 v[64:67], v[208:211], v[192:195], v[64:67]
	v_mfma_f32_16x16x32_bf16 v[72:75], v[200:203], v[192:195], v[72:75]
	v_mfma_f32_16x16x32_bf16 v[120:123], v[204:207], v[172:175], v[120:123]
	v_mfma_f32_16x16x32_bf16 v[112:115], v[218:221], v[172:175], v[112:115]
	v_mfma_f32_16x16x32_bf16 v[96:99], v[218:221], v[180:183], v[96:99]
	v_mfma_f32_16x16x32_bf16 v[104:107], v[204:207], v[180:183], v[104:107]
	v_mfma_f32_16x16x32_bf16 v[88:91], v[204:207], v[188:191], v[88:91]
	v_mfma_f32_16x16x32_bf16 v[80:83], v[218:221], v[188:191], v[80:83]
	v_mfma_f32_16x16x32_bf16 v[64:67], v[218:221], v[196:199], v[64:67]
	v_mfma_f32_16x16x32_bf16 v[72:75], v[204:207], v[196:199], v[72:75]
	s_setprio 0
	s_mov_b32 m0, s17
	v_lshl_add_u64 v[222:223], s[28:29], 0, v[134:135]
	s_barrier
	ds_read_b128 v[168:171], v150 offset:16384
	ds_read_b128 v[172:175], v150 offset:17408
	ds_read_b128 v[176:179], v150 offset:18432
	ds_read_b128 v[180:183], v150 offset:19456
	ds_read_b128 v[184:187], v150 offset:20480
	ds_read_b128 v[188:191], v150 offset:21504
	ds_read_b128 v[192:195], v150 offset:22528
	ds_read_b128 v[196:199], v150 offset:23552
	global_load_lds_dwordx4 v[222:223], off
	v_lshl_add_u64 v[224:225], s[28:29], 0, v[130:131]
	s_mov_b32 m0, s37
	s_nop 0
	global_load_lds_dwordx4 v[224:225], off
	s_barrier
	s_waitcnt lgkmcnt(0)
	s_setprio 1
	s_waitcnt lgkmcnt(0)
	v_mfma_f32_16x16x32_bf16 v[60:63], v[152:155], v[168:171], v[60:63]
	v_mfma_f32_16x16x32_bf16 v[52:55], v[160:163], v[168:171], v[52:55]
	v_mfma_f32_16x16x32_bf16 v[36:39], v[160:163], v[176:179], v[36:39]
	v_mfma_f32_16x16x32_bf16 v[44:47], v[152:155], v[176:179], v[44:47]
	v_mfma_f32_16x16x32_bf16 v[28:31], v[152:155], v[184:187], v[28:31]
	v_mfma_f32_16x16x32_bf16 v[20:23], v[160:163], v[184:187], v[20:23]
	v_mfma_f32_16x16x32_bf16 v[4:7], v[160:163], v[192:195], v[4:7]
	v_mfma_f32_16x16x32_bf16 v[12:15], v[152:155], v[192:195], v[12:15]
	v_mfma_f32_16x16x32_bf16 v[60:63], v[156:159], v[172:175], v[60:63]
	v_mfma_f32_16x16x32_bf16 v[52:55], v[164:167], v[172:175], v[52:55]
	v_mfma_f32_16x16x32_bf16 v[36:39], v[164:167], v[180:183], v[36:39]
	v_mfma_f32_16x16x32_bf16 v[44:47], v[156:159], v[180:183], v[44:47]
	v_mfma_f32_16x16x32_bf16 v[28:31], v[156:159], v[188:191], v[28:31]
	v_mfma_f32_16x16x32_bf16 v[20:23], v[164:167], v[188:191], v[20:23]
	v_mfma_f32_16x16x32_bf16 v[4:7], v[164:167], v[196:199], v[4:7]
	v_mfma_f32_16x16x32_bf16 v[12:15], v[156:159], v[196:199], v[12:15]
	s_setprio 0
	s_barrier
; #define PG8_STAGE(bufoff, gbase, voff) do { _Pragma("unroll") for (int _i = 0; _i < 2; ++_i) \
;         __builtin_amdgcn_global_load_lds((const unsigned*)((const char*)(gbase) + (voff)[_i]), (LAS unsigned*)(lds + (bufoff) + ldsw + _i * 8192), 16, 0, 0); } while (0)
; #define PG8_LDA(dst, b, h) do { _Pragma("unroll") for (int m = 0; m < 4; ++m) _Pragma("unroll") for (int k = 0; k < 2; ++k) dst[m][k] = *(const LAS bf16x8*)(lds + PG8_SA(b, h) + aoff + m * 2048 + k * 1024); } while (0)
; #define PG8_LDB(dst, b, h) do { _Pragma("unroll") for (int n = 0; n < 2; ++n) _Pragma("unroll") for (int k = 0; k < 2; ++k) dst[n][k] = *(const LAS bf16x8*)(lds + PG8_SB(b, h) + boff + n * 2048 + k * 1024); } while (0)
; #define PG8_MMA(ai, bj, At, Bt) do { __builtin_amdgcn_s_setprio(1); _Pragma("unroll") for (int m = 0; m < 4; ++m) _Pragma("unroll") for (int n = 0; n < 2; ++n) _Pragma("unroll") for (int k = 0; k < 2; ++k) \
;         acc[ai][bj][m][n] = __builtin_amdgcn_mfma_f32_16x16x32_bf16(Bt[n][k], At[m][k], acc[ai][bj][m][n], 0, 0, 0); __builtin_amdgcn_s_setprio(0); } while (0)
; #define PG8_WAIT_V(n) asm volatile("s_waitcnt vmcnt(" #n ")" ::: "memory")
; #define PG8_WAIT_L(n) asm volatile("s_waitcnt lgkmcnt(" #n ")" ::: "memory")
; #define PG8_BAR __builtin_amdgcn_s_barrier()
; #define PG8_SCHED __builtin_amdgcn_sched_barrier(0)
; template <class Epi>
; DEVINL void gemm_phase(LAS unsigned char* lds, const Gemm g, const Order& S, const Epi& E) {
;     ...
;             PG8_STAGE(PG8_SB(0, 1), b2 + hstepB, voffB);
;             PG8_WAIT_V(6); PG8_BAR; PG8_MMA(1, 1, At, B1); PG8_BAR;
;             PG8_LDB(B0, 1, 0); PG8_SCHED; PG8_LDA(At, 1, 0); PG8_STAGE(PG8_SA(0, 1), a2 + hstepA, voffA);
;             PG8_WAIT_L(8); PG8_BAR; PG8_WAIT_L(0); PG8_MMA(0, 0, At, B0); PG8_BAR; PG8_SCHED;
;             PG8_LDB(B1, 1, 1); PG8_STAGE(PG8_SB(1, 0), b3, voffB);
;             PG8_BAR; PG8_WAIT_L(0); PG8_MMA(0, 1, At, B1); PG8_BAR;
;             PG8_LDA(At, 1, 1); PG8_STAGE(PG8_SA(1, 0), a3, voffA);
	s_add_u32 s56, s26, 0x80000
	s_addc_u32 s57, s27, 0
	s_add_i32 s58, s48, s30
	v_lshl_add_u64 v[152:153], s[56:57], 0, v[132:133]
	s_mov_b32 m0, s58
	s_nop 0
	global_load_lds_dwordx4 v[152:153], off
	v_lshl_add_u64 v[152:153], s[56:57], 0, v[128:129]
	s_add_i32 m0, s58, 0x2000
	s_nop 0
	global_load_lds_dwordx4 v[152:153], off
	s_waitcnt vmcnt(6)
	s_barrier
	s_setprio 1
	v_mfma_f32_16x16x32_bf16 v[56:59], v[200:203], v[168:171], v[56:59]
	v_mfma_f32_16x16x32_bf16 v[48:51], v[208:211], v[168:171], v[48:51]
	v_mfma_f32_16x16x32_bf16 v[32:35], v[208:211], v[176:179], v[32:35]
	v_mfma_f32_16x16x32_bf16 v[40:43], v[200:203], v[176:179], v[40:43]
	v_mfma_f32_16x16x32_bf16 v[24:27], v[200:203], v[184:187], v[24:27]
	v_mfma_f32_16x16x32_bf16 v[16:19], v[208:211], v[184:187], v[16:19]
	v_mfma_f32_16x16x32_bf16 v[0:3], v[208:211], v[192:195], v[0:3]
	v_mfma_f32_16x16x32_bf16 v[8:11], v[200:203], v[192:195], v[8:11]
	v_mfma_f32_16x16x32_bf16 v[56:59], v[204:207], v[172:175], v[56:59]
	v_mfma_f32_16x16x32_bf16 v[48:51], v[218:221], v[172:175], v[48:51]
	v_mfma_f32_16x16x32_bf16 v[32:35], v[218:221], v[180:183], v[32:35]
	v_mfma_f32_16x16x32_bf16 v[40:43], v[204:207], v[180:183], v[40:43]
	v_mfma_f32_16x16x32_bf16 v[24:27], v[204:207], v[188:191], v[24:27]
	v_mfma_f32_16x16x32_bf16 v[16:19], v[218:221], v[188:191], v[16:19]
	v_mfma_f32_16x16x32_bf16 v[0:3], v[218:221], v[196:199], v[0:3]
	v_mfma_f32_16x16x32_bf16 v[8:11], v[204:207], v[196:199], v[8:11]
	s_setprio 0
	s_add_i32 s56, 16, 0x18000
	v_add_u32_e32 v164, s56, v147
	s_barrier
	ds_read_b128 v[152:155], v164
	ds_read_b128 v[156:159], v164 offset:1024
	ds_read_b128 v[160:163], v164 offset:2048
	ds_read_b128 v[164:167], v164 offset:3072
	s_add_u32 s28, s28, 0x80000
	s_addc_u32 s29, s29, 0
	s_mov_b32 m0, s38
	v_lshl_add_u64 v[200:201], s[28:29], 0, v[134:135]
	ds_read_b128 v[168:171], v150 offset:32768
	ds_read_b128 v[172:175], v150 offset:33792
	ds_read_b128 v[176:179], v150 offset:34816
	ds_read_b128 v[180:183], v150 offset:35840
	ds_read_b128 v[184:187], v150 offset:36864
	ds_read_b128 v[188:191], v150 offset:37888
	ds_read_b128 v[192:195], v150 offset:38912
	ds_read_b128 v[196:199], v150 offset:39936
	global_load_lds_dwordx4 v[200:201], off
	v_lshl_add_u64 v[200:201], s[28:29], 0, v[130:131]
	s_mov_b32 m0, s39
	s_nop 0
	global_load_lds_dwordx4 v[200:201], off
	s_waitcnt lgkmcnt(8)
	s_barrier
	s_waitcnt lgkmcnt(0)
	s_setprio 1
	s_waitcnt lgkmcnt(0)
	v_mfma_f32_16x16x32_bf16 v[124:127], v[152:155], v[168:171], v[124:127]
	v_mfma_f32_16x16x32_bf16 v[116:119], v[160:163], v[168:171], v[116:119]
	v_mfma_f32_16x16x32_bf16 v[100:103], v[160:163], v[176:179], v[100:103]
	v_mfma_f32_16x16x32_bf16 v[108:111], v[152:155], v[176:179], v[108:111]
	v_mfma_f32_16x16x32_bf16 v[92:95], v[152:155], v[184:187], v[92:95]
	v_mfma_f32_16x16x32_bf16 v[84:87], v[160:163], v[184:187], v[84:87]
	v_mfma_f32_16x16x32_bf16 v[68:71], v[160:163], v[192:195], v[68:71]
	v_mfma_f32_16x16x32_bf16 v[76:79], v[152:155], v[192:195], v[76:79]
	v_mfma_f32_16x16x32_bf16 v[124:127], v[156:159], v[172:175], v[124:127]
	v_mfma_f32_16x16x32_bf16 v[116:119], v[164:167], v[172:175], v[116:119]
	v_mfma_f32_16x16x32_bf16 v[100:103], v[164:167], v[180:183], v[100:103]
	v_mfma_f32_16x16x32_bf16 v[108:111], v[156:159], v[180:183], v[108:111]
	v_mfma_f32_16x16x32_bf16 v[92:95], v[156:159], v[188:191], v[92:95]
	v_mfma_f32_16x16x32_bf16 v[84:87], v[164:167], v[188:191], v[84:87]
	v_mfma_f32_16x16x32_bf16 v[68:71], v[164:167], v[196:199], v[68:71]
	v_mfma_f32_16x16x32_bf16 v[76:79], v[156:159], v[196:199], v[76:79]
	s_setprio 0
	s_barrier
	s_add_i32 s28, 16, 0x1c000
	s_add_i32 s29, s56, s30
	v_add_u32_e32 v214, s28, v147
	v_lshl_add_u64 v[144:145], v[144:145], 0, s[6:7]
	s_mov_b32 m0, s29
	ds_read_b128 v[200:203], v214
	ds_read_b128 v[204:207], v214 offset:1024
	ds_read_b128 v[208:211], v214 offset:2048
	ds_read_b128 v[218:221], v214 offset:3072
	global_load_lds_dwordx4 v[144:145], off
	v_lshl_add_u64 v[144:145], v[212:213], 0, s[6:7]
	s_add_i32 m0, s29, 0x2000
	s_nop 0
	global_load_lds_dwordx4 v[144:145], off
	s_barrier
; #define PG8_STAGE(bufoff, gbase, voff) do { _Pragma("unroll") for (int _i = 0; _i < 2; ++_i) \
;         __builtin_amdgcn_global_load_lds((const unsigned*)((const char*)(gbase) + (voff)[_i]), (LAS unsigned*)(lds + (bufoff) + ldsw + _i * 8192), 16, 0, 0); } while (0)
; #define PG8_LDA(dst, b, h) do { _Pragma("unroll") for (int m = 0; m < 4; ++m) _Pragma("unroll") for (int k = 0; k < 2; ++k) dst[m][k] = *(const LAS bf16x8*)(lds + PG8_SA(b, h) + aoff + m * 2048 + k * 1024); } while (0)
; #define PG8_MMA(ai, bj, At, Bt) do { __builtin_amdgcn_s_setprio(1); _Pragma("unroll") for (int m = 0; m < 4; ++m) _Pragma("unroll") for (int n = 0; n < 2; ++n) _Pragma("unroll") for (int k = 0; k < 2; ++k) \
;         acc[ai][bj][m][n] = __builtin_amdgcn_mfma_f32_16x16x32_bf16(Bt[n][k], At[m][k], acc[ai][bj][m][n], 0, 0, 0); __builtin_amdgcn_s_setprio(0); } while (0)
; #define PG8_WAIT_V(n) asm volatile("s_waitcnt vmcnt(" #n ")" ::: "memory")
; #define PG8_WAIT_L(n) asm volatile("s_waitcnt lgkmcnt(" #n ")" ::: "memory")
; #define PG8_BAR __builtin_amdgcn_s_barrier()
; #define PG8_SCHED __builtin_amdgcn_sched_barrier(0)
; template <class Epi>
; DEVINL void gemm_phase(LAS unsigned char* lds, const Gemm g, const Order& S, const Epi& E) {
;     ...
;             PG8_BAR; PG8_WAIT_L(0); PG8_MMA(0, 1, At, B1); PG8_BAR;
;             PG8_LDA(At, 1, 1); PG8_STAGE(PG8_SA(1, 0), a3, voffA);
;             PG8_BAR; PG8_WAIT_L(0); PG8_MMA(1, 0, At, B0); PG8_BAR; PG8_SCHED;
;             PG8_STAGE(PG8_SB(1, 1), b3 + hstepB, voffB);
;             PG8_WAIT_V(6); PG8_BAR; PG8_MMA(1, 1, At, B1); PG8_BAR;
	s_waitcnt lgkmcnt(0)
	s_setprio 1
	s_waitcnt lgkmcnt(0)
	v_mfma_f32_16x16x32_bf16 v[120:123], v[200:203], v[168:171], v[120:123]
	v_mfma_f32_16x16x32_bf16 v[112:115], v[208:211], v[168:171], v[112:115]
	v_mfma_f32_16x16x32_bf16 v[96:99], v[208:211], v[176:179], v[96:99]
	v_mfma_f32_16x16x32_bf16 v[104:107], v[200:203], v[176:179], v[104:107]
	v_mfma_f32_16x16x32_bf16 v[88:91], v[200:203], v[184:187], v[88:91]
	v_mfma_f32_16x16x32_bf16 v[80:83], v[208:211], v[184:187], v[80:83]
	v_mfma_f32_16x16x32_bf16 v[64:67], v[208:211], v[192:195], v[64:67]
	v_mfma_f32_16x16x32_bf16 v[72:75], v[200:203], v[192:195], v[72:75]
	v_mfma_f32_16x16x32_bf16 v[120:123], v[204:207], v[172:175], v[120:123]
	v_mfma_f32_16x16x32_bf16 v[112:115], v[218:221], v[172:175], v[112:115]
	v_mfma_f32_16x16x32_bf16 v[96:99], v[218:221], v[180:183], v[96:99]
	v_mfma_f32_16x16x32_bf16 v[104:107], v[204:207], v[180:183], v[104:107]
	v_mfma_f32_16x16x32_bf16 v[88:91], v[204:207], v[188:191], v[88:91]
	v_mfma_f32_16x16x32_bf16 v[80:83], v[218:221], v[188:191], v[80:83]
	v_mfma_f32_16x16x32_bf16 v[64:67], v[218:221], v[196:199], v[64:67]
	v_mfma_f32_16x16x32_bf16 v[72:75], v[204:207], v[196:199], v[72:75]
	s_setprio 0
	s_mov_b32 m0, s42
	v_lshl_add_u64 v[144:145], v[222:223], 0, s[6:7]
	s_barrier
	ds_read_b128 v[168:171], v150 offset:49152
	ds_read_b128 v[172:175], v150 offset:50176
	ds_read_b128 v[176:179], v150 offset:51200
	ds_read_b128 v[180:183], v150 offset:52224
	ds_read_b128 v[184:187], v150 offset:53248
	ds_read_b128 v[188:191], v150 offset:54272
	ds_read_b128 v[192:195], v150 offset:55296
	ds_read_b128 v[196:199], v150 offset:56320
	global_load_lds_dwordx4 v[144:145], off
	v_lshl_add_u64 v[144:145], v[224:225], 0, s[6:7]
	s_mov_b32 m0, s43
	s_nop 0
	global_load_lds_dwordx4 v[144:145], off
	s_barrier
	s_waitcnt lgkmcnt(0)
	s_setprio 1
	s_waitcnt lgkmcnt(0)
	v_mfma_f32_16x16x32_bf16 v[60:63], v[152:155], v[168:171], v[60:63]
	v_mfma_f32_16x16x32_bf16 v[52:55], v[160:163], v[168:171], v[52:55]
	v_mfma_f32_16x16x32_bf16 v[36:39], v[160:163], v[176:179], v[36:39]
	v_mfma_f32_16x16x32_bf16 v[44:47], v[152:155], v[176:179], v[44:47]
	v_mfma_f32_16x16x32_bf16 v[28:31], v[152:155], v[184:187], v[28:31]
	v_mfma_f32_16x16x32_bf16 v[20:23], v[160:163], v[184:187], v[20:23]
	v_mfma_f32_16x16x32_bf16 v[4:7], v[160:163], v[192:195], v[4:7]
	v_mfma_f32_16x16x32_bf16 v[12:15], v[152:155], v[192:195], v[12:15]
	v_mfma_f32_16x16x32_bf16 v[60:63], v[156:159], v[172:175], v[60:63]
	v_mfma_f32_16x16x32_bf16 v[52:55], v[164:167], v[172:175], v[52:55]
	v_mfma_f32_16x16x32_bf16 v[36:39], v[164:167], v[180:183], v[36:39]
	v_mfma_f32_16x16x32_bf16 v[44:47], v[156:159], v[180:183], v[44:47]
	v_mfma_f32_16x16x32_bf16 v[28:31], v[156:159], v[188:191], v[28:31]
	v_mfma_f32_16x16x32_bf16 v[20:23], v[164:167], v[188:191], v[20:23]
	v_mfma_f32_16x16x32_bf16 v[4:7], v[164:167], v[196:199], v[4:7]
	v_mfma_f32_16x16x32_bf16 v[12:15], v[156:159], v[196:199], v[12:15]
	s_setprio 0
	s_barrier
	s_add_u32 s26, s26, 0x80080
	s_addc_u32 s27, s27, 0
	s_add_i32 s28, s28, s30
	v_lshl_add_u64 v[144:145], s[26:27], 0, v[132:133]
	s_mov_b32 m0, s28
	s_nop 0
	global_load_lds_dwordx4 v[144:145], off
	v_lshl_add_u64 v[144:145], s[26:27], 0, v[128:129]
	s_add_i32 m0, s28, 0x2000
	s_nop 0
	global_load_lds_dwordx4 v[144:145], off
	s_waitcnt vmcnt(6)
	s_barrier
	s_setprio 1
	v_mfma_f32_16x16x32_bf16 v[56:59], v[200:203], v[168:171], v[56:59]
	v_mfma_f32_16x16x32_bf16 v[48:51], v[208:211], v[168:171], v[48:51]
	v_mfma_f32_16x16x32_bf16 v[32:35], v[208:211], v[176:179], v[32:35]
	v_mfma_f32_16x16x32_bf16 v[40:43], v[200:203], v[176:179], v[40:43]
	v_mfma_f32_16x16x32_bf16 v[24:27], v[200:203], v[184:187], v[24:27]
	v_mfma_f32_16x16x32_bf16 v[16:19], v[208:211], v[184:187], v[16:19]
	v_mfma_f32_16x16x32_bf16 v[0:3], v[208:211], v[192:195], v[0:3]
	v_mfma_f32_16x16x32_bf16 v[8:11], v[200:203], v[192:195], v[8:11]
	v_mfma_f32_16x16x32_bf16 v[56:59], v[204:207], v[172:175], v[56:59]
	v_mfma_f32_16x16x32_bf16 v[48:51], v[218:221], v[172:175], v[48:51]
	v_mfma_f32_16x16x32_bf16 v[32:35], v[218:221], v[180:183], v[32:35]
	v_mfma_f32_16x16x32_bf16 v[40:43], v[204:207], v[180:183], v[40:43]
	v_mfma_f32_16x16x32_bf16 v[24:27], v[204:207], v[188:191], v[24:27]
	v_mfma_f32_16x16x32_bf16 v[16:19], v[218:221], v[188:191], v[16:19]
	v_mfma_f32_16x16x32_bf16 v[0:3], v[218:221], v[196:199], v[0:3]
	v_mfma_f32_16x16x32_bf16 v[8:11], v[204:207], v[196:199], v[8:11]
	s_setprio 0
	s_add_u32 s24, s24, 0x100
	s_addc_u32 s25, s25, 0
	s_add_u32 s53, s53, 0x100
	s_addc_u32 s54, s54, 0
	s_cmp_ge_i32 s55, s41
	s_mov_b32 s26, s55
	s_barrier
	s_cbranch_scc0 .LBB0_1775
	s_branch .LBB0_1770

; #define PG8_STAGE(bufoff, gbase, voff) do { _Pragma("unroll") for (int _i = 0; _i < 2; ++_i) \
;         __builtin_amdgcn_global_load_lds((const unsigned*)((const char*)(gbase) + (voff)[_i]), (LAS unsigned*)(lds + (bufoff) + ldsw + _i * 8192), 16, 0, 0); } while (0)
; #define PG8_LDA(dst, b, h) do { _Pragma("unroll") for (int m = 0; m < 4; ++m) _Pragma("unroll") for (int k = 0; k < 2; ++k) dst[m][k] = *(const LAS bf16x8*)(lds + PG8_SA(b, h) + aoff + m * 2048 + k * 1024); } while (0)
; #define PG8_LDB(dst, b, h) do { _Pragma("unroll") for (int n = 0; n < 2; ++n) _Pragma("unroll") for (int k = 0; k < 2; ++k) dst[n][k] = *(const LAS bf16x8*)(lds + PG8_SB(b, h) + boff + n * 2048 + k * 1024); } while (0)
; #define PG8_MMA(ai, bj, At, Bt) do { __builtin_amdgcn_s_setprio(1); _Pragma("unroll") for (int m = 0; m < 4; ++m) _Pragma("unroll") for (int n = 0; n < 2; ++n) _Pragma("unroll") for (int k = 0; k < 2; ++k) \
;         acc[ai][bj][m][n] = __builtin_amdgcn_mfma_f32_16x16x32_bf16(Bt[n][k], At[m][k], acc[ai][bj][m][n], 0, 0, 0); __builtin_amdgcn_s_setprio(0); } while (0)
; #define PG8_WAIT_L(n) asm volatile("s_waitcnt lgkmcnt(" #n ")" ::: "memory")
; #define PG8_BAR __builtin_amdgcn_s_barrier()
; #define PG8_SCHED __builtin_amdgcn_sched_barrier(0)
; template <class Epi>
; DEVINL void gemm_phase(LAS unsigned char* lds, const Gemm g, const Order& S, const Epi& E) {
;     ...
;         for (int t = 0; t < nt; t += 2) {
;             const bool last = (t == nt - 2);
;             const char* a1 = cA + (size_t)(t + 1) * kstep;
;             const char* a2 = last ? nA : cA + (size_t)(t + 2) * kstep; const char* b2 = last ? nB : cB + (size_t)(t + 2) * kstep;
;             const char* a3 = a2 + kstep; const char* b3 = b2 + kstep;
;             PG8_LDB(B0, 0, 0); PG8_SCHED; PG8_LDA(At, 0, 0); PG8_STAGE(PG8_SA(1, 1), a1 + hstepA, voffA);
;             PG8_WAIT_L(8); PG8_BAR; PG8_WAIT_L(0); PG8_MMA(0, 0, At, B0); PG8_BAR; PG8_SCHED;
;             PG8_LDB(B1, 0, 1); PG8_STAGE(PG8_SB(0, 0), b2, voffB);
;             PG8_BAR; PG8_WAIT_L(0); PG8_MMA(0, 1, At, B1); PG8_BAR;
;             PG8_LDA(At, 0, 1); PG8_STAGE(PG8_SA(0, 0), a2, voffA);
;             PG8_BAR; PG8_WAIT_L(0); PG8_MMA(1, 0, At, B0); PG8_BAR; PG8_SCHED;
.LBB0_1852:
	ds_read_b128 v[150:153], v147
	ds_read_b128 v[154:157], v147 offset:1024
	ds_read_b128 v[158:161], v147 offset:2048
	ds_read_b128 v[162:165], v147 offset:3072
	s_add_i32 s61, s28, 2
	s_add_u32 s26, s24, 0x100
	s_addc_u32 s27, s25, 0
	s_cmp_eq_u32 s45, s28
	s_cselect_b32 s28, s4, s59
	s_cselect_b32 s31, s3, s27
	s_cselect_b32 s30, s2, s26
	s_cselect_b32 s29, s5, s60
	v_lshl_add_u64 v[198:199], s[24:25], 0, v[136:137]
	s_add_i32 m0, s38, 0xc000
	ds_read_b128 v[166:169], v148
	ds_read_b128 v[170:173], v148 offset:1024
	ds_read_b128 v[174:177], v148 offset:2048
	ds_read_b128 v[178:181], v148 offset:3072
	ds_read_b128 v[182:185], v148 offset:4096
	ds_read_b128 v[186:189], v148 offset:5120
	ds_read_b128 v[190:193], v148 offset:6144
	ds_read_b128 v[194:197], v148 offset:7168
	global_load_lds_dwordx4 v[198:199], off
	v_lshl_add_u64 v[198:199], s[24:25], 0, v[138:139]
	s_add_i32 m0, s38, 0xe000
	s_nop 0
	global_load_lds_dwordx4 v[198:199], off
	s_waitcnt lgkmcnt(8)
	s_barrier
	s_waitcnt lgkmcnt(0)
	s_setprio 1
	s_waitcnt lgkmcnt(0)
	v_mfma_f32_16x16x32_bf16 v[120:123], v[150:153], v[166:169], v[120:123]
	v_mfma_f32_16x16x32_bf16 v[124:127], v[158:161], v[166:169], v[124:127]
	v_mfma_f32_16x16x32_bf16 v[104:107], v[158:161], v[174:177], v[104:107]
	v_mfma_f32_16x16x32_bf16 v[108:111], v[150:153], v[174:177], v[108:111]
	v_mfma_f32_16x16x32_bf16 v[92:95], v[150:153], v[182:185], v[92:95]
	v_mfma_f32_16x16x32_bf16 v[88:91], v[158:161], v[182:185], v[88:91]
	v_mfma_f32_16x16x32_bf16 v[72:75], v[158:161], v[190:193], v[72:75]
	v_mfma_f32_16x16x32_bf16 v[76:79], v[150:153], v[190:193], v[76:79]
	v_mfma_f32_16x16x32_bf16 v[120:123], v[154:157], v[170:173], v[120:123]
	v_mfma_f32_16x16x32_bf16 v[124:127], v[162:165], v[170:173], v[124:127]
	v_mfma_f32_16x16x32_bf16 v[104:107], v[162:165], v[178:181], v[104:107]
	v_mfma_f32_16x16x32_bf16 v[108:111], v[154:157], v[178:181], v[108:111]
	v_mfma_f32_16x16x32_bf16 v[92:95], v[154:157], v[186:189], v[92:95]
	v_mfma_f32_16x16x32_bf16 v[88:91], v[162:165], v[186:189], v[88:91]
	v_mfma_f32_16x16x32_bf16 v[72:75], v[162:165], v[194:197], v[72:75]
	v_mfma_f32_16x16x32_bf16 v[76:79], v[154:157], v[194:197], v[76:79]
	s_setprio 0
	s_barrier
	s_add_i32 s24, s49, s37
	v_lshl_add_u64 v[218:219], s[28:29], 0, v[130:131]
	s_mov_b32 m0, s24
	ds_read_b128 v[198:201], v149
	ds_read_b128 v[202:205], v149 offset:1024
	ds_read_b128 v[206:209], v149 offset:2048
	ds_read_b128 v[210:213], v149 offset:3072
	global_load_lds_dwordx4 v[218:219], off
	v_lshl_add_u64 v[220:221], s[28:29], 0, v[134:135]
	s_add_i32 m0, s24, 0x2000
	s_nop 0
	global_load_lds_dwordx4 v[220:221], off
	s_barrier
	s_waitcnt lgkmcnt(0)
	s_setprio 1
	s_waitcnt lgkmcnt(0)
	v_mfma_f32_16x16x32_bf16 v[116:119], v[198:201], v[166:169], v[116:119]
	v_mfma_f32_16x16x32_bf16 v[112:115], v[206:209], v[166:169], v[112:115]
	v_mfma_f32_16x16x32_bf16 v[96:99], v[206:209], v[174:177], v[96:99]
	v_mfma_f32_16x16x32_bf16 v[100:103], v[198:201], v[174:177], v[100:103]
	v_mfma_f32_16x16x32_bf16 v[84:87], v[198:201], v[182:185], v[84:87]
	v_mfma_f32_16x16x32_bf16 v[80:83], v[206:209], v[182:185], v[80:83]
	v_mfma_f32_16x16x32_bf16 v[64:67], v[206:209], v[190:193], v[64:67]
	v_mfma_f32_16x16x32_bf16 v[68:71], v[198:201], v[190:193], v[68:71]
	v_mfma_f32_16x16x32_bf16 v[116:119], v[202:205], v[170:173], v[116:119]
	v_mfma_f32_16x16x32_bf16 v[112:115], v[210:213], v[170:173], v[112:115]
	v_mfma_f32_16x16x32_bf16 v[96:99], v[210:213], v[178:181], v[96:99]
	v_mfma_f32_16x16x32_bf16 v[100:103], v[202:205], v[178:181], v[100:103]
	v_mfma_f32_16x16x32_bf16 v[84:87], v[202:205], v[186:189], v[84:87]
	v_mfma_f32_16x16x32_bf16 v[80:83], v[210:213], v[186:189], v[80:83]
	v_mfma_f32_16x16x32_bf16 v[64:67], v[210:213], v[194:197], v[64:67]
	v_mfma_f32_16x16x32_bf16 v[68:71], v[202:205], v[194:197], v[68:71]
	s_setprio 0
	s_mov_b32 m0, s38
	v_lshl_add_u64 v[222:223], s[30:31], 0, v[128:129]
	s_barrier
	ds_read_b128 v[166:169], v148 offset:16384
	ds_read_b128 v[170:173], v148 offset:17408
	ds_read_b128 v[174:177], v148 offset:18432
	ds_read_b128 v[178:181], v148 offset:19456
	ds_read_b128 v[182:185], v148 offset:20480
	ds_read_b128 v[186:189], v148 offset:21504
	ds_read_b128 v[190:193], v148 offset:22528
	ds_read_b128 v[194:197], v148 offset:23552
	global_load_lds_dwordx4 v[222:223], off
	v_lshl_add_u64 v[224:225], s[30:31], 0, v[132:133]
	s_mov_b32 m0, s39
	s_nop 0
	global_load_lds_dwordx4 v[224:225], off
	s_barrier
	s_waitcnt lgkmcnt(0)
	s_setprio 1
	s_waitcnt lgkmcnt(0)
	v_mfma_f32_16x16x32_bf16 v[60:63], v[150:153], v[166:169], v[60:63]
	v_mfma_f32_16x16x32_bf16 v[56:59], v[158:161], v[166:169], v[56:59]
	v_mfma_f32_16x16x32_bf16 v[40:43], v[158:161], v[174:177], v[40:43]
	v_mfma_f32_16x16x32_bf16 v[44:47], v[150:153], v[174:177], v[44:47]
	v_mfma_f32_16x16x32_bf16 v[28:31], v[150:153], v[182:185], v[28:31]
	v_mfma_f32_16x16x32_bf16 v[24:27], v[158:161], v[182:185], v[24:27]
	v_mfma_f32_16x16x32_bf16 v[8:11], v[158:161], v[190:193], v[8:11]
	v_mfma_f32_16x16x32_bf16 v[12:15], v[150:153], v[190:193], v[12:15]
	v_mfma_f32_16x16x32_bf16 v[60:63], v[154:157], v[170:173], v[60:63]
	v_mfma_f32_16x16x32_bf16 v[56:59], v[162:165], v[170:173], v[56:59]
	v_mfma_f32_16x16x32_bf16 v[40:43], v[162:165], v[178:181], v[40:43]
	v_mfma_f32_16x16x32_bf16 v[44:47], v[154:157], v[178:181], v[44:47]
	v_mfma_f32_16x16x32_bf16 v[28:31], v[154:157], v[186:189], v[28:31]
	v_mfma_f32_16x16x32_bf16 v[24:27], v[162:165], v[186:189], v[24:27]
	v_mfma_f32_16x16x32_bf16 v[8:11], v[162:165], v[194:197], v[8:11]
	v_mfma_f32_16x16x32_bf16 v[12:15], v[154:157], v[194:197], v[12:15]
	s_setprio 0
	s_barrier
; #define PG8_STAGE(bufoff, gbase, voff) do { _Pragma("unroll") for (int _i = 0; _i < 2; ++_i) \
;         __builtin_amdgcn_global_load_lds((const unsigned*)((const char*)(gbase) + (voff)[_i]), (LAS unsigned*)(lds + (bufoff) + ldsw + _i * 8192), 16, 0, 0); } while (0)
; #define PG8_LDA(dst, b, h) do { _Pragma("unroll") for (int m = 0; m < 4; ++m) _Pragma("unroll") for (int k = 0; k < 2; ++k) dst[m][k] = *(const LAS bf16x8*)(lds + PG8_SA(b, h) + aoff + m * 2048 + k * 1024); } while (0)
; #define PG8_LDB(dst, b, h) do { _Pragma("unroll") for (int n = 0; n < 2; ++n) _Pragma("unroll") for (int k = 0; k < 2; ++k) dst[n][k] = *(const LAS bf16x8*)(lds + PG8_SB(b, h) + boff + n * 2048 + k * 1024); } while (0)
; #define PG8_MMA(ai, bj, At, Bt) do { __builtin_amdgcn_s_setprio(1); _Pragma("unroll") for (int m = 0; m < 4; ++m) _Pragma("unroll") for (int n = 0; n < 2; ++n) _Pragma("unroll") for (int k = 0; k < 2; ++k) \
;         acc[ai][bj][m][n] = __builtin_amdgcn_mfma_f32_16x16x32_bf16(Bt[n][k], At[m][k], acc[ai][bj][m][n], 0, 0, 0); __builtin_amdgcn_s_setprio(0); } while (0)
; #define PG8_WAIT_V(n) asm volatile("s_waitcnt vmcnt(" #n ")" ::: "memory")
; #define PG8_WAIT_L(n) asm volatile("s_waitcnt lgkmcnt(" #n ")" ::: "memory")
; #define PG8_BAR __builtin_amdgcn_s_barrier()
; #define PG8_SCHED __builtin_amdgcn_sched_barrier(0)
; template <class Epi>
; DEVINL void gemm_phase(LAS unsigned char* lds, const Gemm g, const Order& S, const Epi& E) {
;     ...
;             PG8_STAGE(PG8_SB(0, 1), b2 + hstepB, voffB);
;             PG8_WAIT_V(6); PG8_BAR; PG8_MMA(1, 1, At, B1); PG8_BAR;
;             PG8_LDB(B0, 1, 0); PG8_SCHED; PG8_LDA(At, 1, 0); PG8_STAGE(PG8_SA(0, 1), a2 + hstepA, voffA);
;             PG8_WAIT_L(8); PG8_BAR; PG8_WAIT_L(0); PG8_MMA(0, 0, At, B0); PG8_BAR; PG8_SCHED;
;             PG8_LDB(B1, 1, 1); PG8_STAGE(PG8_SB(1, 0), b3, voffB);
	s_add_u32 s24, s28, 0x158000
	s_addc_u32 s25, s29, 0
	s_add_i32 s62, s50, s37
	v_lshl_add_u64 v[150:151], s[24:25], 0, v[130:131]
	s_mov_b32 m0, s62
	s_nop 0
	global_load_lds_dwordx4 v[150:151], off
	v_lshl_add_u64 v[150:151], s[24:25], 0, v[134:135]
	s_add_i32 m0, s62, 0x2000
	s_nop 0
	global_load_lds_dwordx4 v[150:151], off
	s_waitcnt vmcnt(6)
	s_barrier
	s_setprio 1
	v_mfma_f32_16x16x32_bf16 v[52:55], v[198:201], v[166:169], v[52:55]
	v_mfma_f32_16x16x32_bf16 v[48:51], v[206:209], v[166:169], v[48:51]
	v_mfma_f32_16x16x32_bf16 v[32:35], v[206:209], v[174:177], v[32:35]
	v_mfma_f32_16x16x32_bf16 v[36:39], v[198:201], v[174:177], v[36:39]
	v_mfma_f32_16x16x32_bf16 v[20:23], v[198:201], v[182:185], v[20:23]
	v_mfma_f32_16x16x32_bf16 v[16:19], v[206:209], v[182:185], v[16:19]
	v_mfma_f32_16x16x32_bf16 v[0:3], v[206:209], v[190:193], v[0:3]
	v_mfma_f32_16x16x32_bf16 v[4:7], v[198:201], v[190:193], v[4:7]
	v_mfma_f32_16x16x32_bf16 v[52:55], v[202:205], v[170:173], v[52:55]
	v_mfma_f32_16x16x32_bf16 v[48:51], v[210:213], v[170:173], v[48:51]
	v_mfma_f32_16x16x32_bf16 v[32:35], v[210:213], v[178:181], v[32:35]
	v_mfma_f32_16x16x32_bf16 v[36:39], v[202:205], v[178:181], v[36:39]
	v_mfma_f32_16x16x32_bf16 v[20:23], v[202:205], v[186:189], v[20:23]
	v_mfma_f32_16x16x32_bf16 v[16:19], v[210:213], v[186:189], v[16:19]
	v_mfma_f32_16x16x32_bf16 v[0:3], v[210:213], v[194:197], v[0:3]
	v_mfma_f32_16x16x32_bf16 v[4:7], v[202:205], v[194:197], v[4:7]
	s_setprio 0
	s_add_i32 s62, 16, 0x18000
	v_add_u32_e32 v162, s62, v145
	s_barrier
	ds_read_b128 v[150:153], v162
	ds_read_b128 v[154:157], v162 offset:1024
	ds_read_b128 v[158:161], v162 offset:2048
	ds_read_b128 v[162:165], v162 offset:3072
	s_add_u32 s24, s30, 0x158000
	s_addc_u32 s25, s31, 0
	s_mov_b32 m0, s40
	v_lshl_add_u64 v[198:199], s[24:25], 0, v[128:129]
	ds_read_b128 v[166:169], v148 offset:32768
	ds_read_b128 v[170:173], v148 offset:33792
	ds_read_b128 v[174:177], v148 offset:34816
	ds_read_b128 v[178:181], v148 offset:35840
	ds_read_b128 v[182:185], v148 offset:36864
	ds_read_b128 v[186:189], v148 offset:37888
	ds_read_b128 v[190:193], v148 offset:38912
	ds_read_b128 v[194:197], v148 offset:39936
	global_load_lds_dwordx4 v[198:199], off
	v_lshl_add_u64 v[198:199], s[24:25], 0, v[132:133]
	s_mov_b32 m0, s41
	s_nop 0
	global_load_lds_dwordx4 v[198:199], off
	s_waitcnt lgkmcnt(8)
	s_barrier
	s_waitcnt lgkmcnt(0)
	s_setprio 1
	s_waitcnt lgkmcnt(0)
	v_mfma_f32_16x16x32_bf16 v[120:123], v[150:153], v[166:169], v[120:123]
	v_mfma_f32_16x16x32_bf16 v[124:127], v[158:161], v[166:169], v[124:127]
	v_mfma_f32_16x16x32_bf16 v[104:107], v[158:161], v[174:177], v[104:107]
	v_mfma_f32_16x16x32_bf16 v[108:111], v[150:153], v[174:177], v[108:111]
	v_mfma_f32_16x16x32_bf16 v[92:95], v[150:153], v[182:185], v[92:95]
	v_mfma_f32_16x16x32_bf16 v[88:91], v[158:161], v[182:185], v[88:91]
	v_mfma_f32_16x16x32_bf16 v[72:75], v[158:161], v[190:193], v[72:75]
	v_mfma_f32_16x16x32_bf16 v[76:79], v[150:153], v[190:193], v[76:79]
	v_mfma_f32_16x16x32_bf16 v[120:123], v[154:157], v[170:173], v[120:123]
	v_mfma_f32_16x16x32_bf16 v[124:127], v[162:165], v[170:173], v[124:127]
	v_mfma_f32_16x16x32_bf16 v[104:107], v[162:165], v[178:181], v[104:107]
	v_mfma_f32_16x16x32_bf16 v[108:111], v[154:157], v[178:181], v[108:111]
	v_mfma_f32_16x16x32_bf16 v[92:95], v[154:157], v[186:189], v[92:95]
	v_mfma_f32_16x16x32_bf16 v[88:91], v[162:165], v[186:189], v[88:91]
	v_mfma_f32_16x16x32_bf16 v[72:75], v[162:165], v[194:197], v[72:75]
	v_mfma_f32_16x16x32_bf16 v[76:79], v[154:157], v[194:197], v[76:79]
	s_setprio 0
	s_barrier
	s_add_i32 s30, 16, 0x1c000
	s_add_i32 s24, s62, s37
	v_add_u32_e32 v210, s30, v145
	v_lshl_add_u64 v[218:219], v[218:219], 0, s[6:7]
	s_mov_b32 m0, s24
	ds_read_b128 v[198:201], v210
	ds_read_b128 v[202:205], v210 offset:1024
	ds_read_b128 v[206:209], v210 offset:2048
	ds_read_b128 v[210:213], v210 offset:3072
	global_load_lds_dwordx4 v[218:219], off
	v_lshl_add_u64 v[218:219], v[220:221], 0, s[6:7]
	s_add_i32 m0, s24, 0x2000
	s_nop 0
	global_load_lds_dwordx4 v[218:219], off
	s_barrier
; #define PG8_STAGE(bufoff, gbase, voff) do { _Pragma("unroll") for (int _i = 0; _i < 2; ++_i) \
;         __builtin_amdgcn_global_load_lds((const unsigned*)((const char*)(gbase) + (voff)[_i]), (LAS unsigned*)(lds + (bufoff) + ldsw + _i * 8192), 16, 0, 0); } while (0)
; #define PG8_LDA(dst, b, h) do { _Pragma("unroll") for (int m = 0; m < 4; ++m) _Pragma("unroll") for (int k = 0; k < 2; ++k) dst[m][k] = *(const LAS bf16x8*)(lds + PG8_SA(b, h) + aoff + m * 2048 + k * 1024); } while (0)
; #define PG8_MMA(ai, bj, At, Bt) do { __builtin_amdgcn_s_setprio(1); _Pragma("unroll") for (int m = 0; m < 4; ++m) _Pragma("unroll") for (int n = 0; n < 2; ++n) _Pragma("unroll") for (int k = 0; k < 2; ++k) \
;         acc[ai][bj][m][n] = __builtin_amdgcn_mfma_f32_16x16x32_bf16(Bt[n][k], At[m][k], acc[ai][bj][m][n], 0, 0, 0); __builtin_amdgcn_s_setprio(0); } while (0)
; #define PG8_WAIT_V(n) asm volatile("s_waitcnt vmcnt(" #n ")" ::: "memory")
; #define PG8_WAIT_L(n) asm volatile("s_waitcnt lgkmcnt(" #n ")" ::: "memory")
; #define PG8_BAR __builtin_amdgcn_s_barrier()
; #define PG8_SCHED __builtin_amdgcn_sched_barrier(0)
; template <class Epi>
; DEVINL void gemm_phase(LAS unsigned char* lds, const Gemm g, const Order& S, const Epi& E) {
;     ...
;             PG8_BAR; PG8_WAIT_L(0); PG8_MMA(0, 1, At, B1); PG8_BAR;
;             PG8_LDA(At, 1, 1); PG8_STAGE(PG8_SA(1, 0), a3, voffA);
;             PG8_BAR; PG8_WAIT_L(0); PG8_MMA(1, 0, At, B0); PG8_BAR; PG8_SCHED;
;             PG8_STAGE(PG8_SB(1, 1), b3 + hstepB, voffB);
;             PG8_WAIT_V(6); PG8_BAR; PG8_MMA(1, 1, At, B1); PG8_BAR;
	s_waitcnt lgkmcnt(0)
	s_setprio 1
	s_waitcnt lgkmcnt(0)
	v_mfma_f32_16x16x32_bf16 v[116:119], v[198:201], v[166:169], v[116:119]
	v_mfma_f32_16x16x32_bf16 v[112:115], v[206:209], v[166:169], v[112:115]
	v_mfma_f32_16x16x32_bf16 v[96:99], v[206:209], v[174:177], v[96:99]
	v_mfma_f32_16x16x32_bf16 v[100:103], v[198:201], v[174:177], v[100:103]
	v_mfma_f32_16x16x32_bf16 v[84:87], v[198:201], v[182:185], v[84:87]
	v_mfma_f32_16x16x32_bf16 v[80:83], v[206:209], v[182:185], v[80:83]
	v_mfma_f32_16x16x32_bf16 v[64:67], v[206:209], v[190:193], v[64:67]
	v_mfma_f32_16x16x32_bf16 v[68:71], v[198:201], v[190:193], v[68:71]
	v_mfma_f32_16x16x32_bf16 v[116:119], v[202:205], v[170:173], v[116:119]
	v_mfma_f32_16x16x32_bf16 v[112:115], v[210:213], v[170:173], v[112:115]
	v_mfma_f32_16x16x32_bf16 v[96:99], v[210:213], v[178:181], v[96:99]
	v_mfma_f32_16x16x32_bf16 v[100:103], v[202:205], v[178:181], v[100:103]
	v_mfma_f32_16x16x32_bf16 v[84:87], v[202:205], v[186:189], v[84:87]
	v_mfma_f32_16x16x32_bf16 v[80:83], v[210:213], v[186:189], v[80:83]
	v_mfma_f32_16x16x32_bf16 v[64:67], v[210:213], v[194:197], v[64:67]
	v_mfma_f32_16x16x32_bf16 v[68:71], v[202:205], v[194:197], v[68:71]
	s_setprio 0
	s_mov_b32 m0, s43
	v_lshl_add_u64 v[218:219], v[222:223], 0, s[6:7]
	s_barrier
	ds_read_b128 v[166:169], v148 offset:49152
	ds_read_b128 v[170:173], v148 offset:50176
	ds_read_b128 v[174:177], v148 offset:51200
	ds_read_b128 v[178:181], v148 offset:52224
	ds_read_b128 v[182:185], v148 offset:53248
	ds_read_b128 v[186:189], v148 offset:54272
	ds_read_b128 v[190:193], v148 offset:55296
	ds_read_b128 v[194:197], v148 offset:56320
	global_load_lds_dwordx4 v[218:219], off
	v_lshl_add_u64 v[218:219], v[224:225], 0, s[6:7]
	s_mov_b32 m0, s44
	s_nop 0
	global_load_lds_dwordx4 v[218:219], off
	s_barrier
	s_waitcnt lgkmcnt(0)
	s_setprio 1
	s_waitcnt lgkmcnt(0)
	v_mfma_f32_16x16x32_bf16 v[60:63], v[150:153], v[166:169], v[60:63]
	v_mfma_f32_16x16x32_bf16 v[56:59], v[158:161], v[166:169], v[56:59]
	v_mfma_f32_16x16x32_bf16 v[40:43], v[158:161], v[174:177], v[40:43]
	v_mfma_f32_16x16x32_bf16 v[44:47], v[150:153], v[174:177], v[44:47]
	v_mfma_f32_16x16x32_bf16 v[28:31], v[150:153], v[182:185], v[28:31]
	v_mfma_f32_16x16x32_bf16 v[24:27], v[158:161], v[182:185], v[24:27]
	v_mfma_f32_16x16x32_bf16 v[8:11], v[158:161], v[190:193], v[8:11]
	v_mfma_f32_16x16x32_bf16 v[12:15], v[150:153], v[190:193], v[12:15]
	v_mfma_f32_16x16x32_bf16 v[60:63], v[154:157], v[170:173], v[60:63]
	v_mfma_f32_16x16x32_bf16 v[56:59], v[162:165], v[170:173], v[56:59]
	v_mfma_f32_16x16x32_bf16 v[40:43], v[162:165], v[178:181], v[40:43]
	v_mfma_f32_16x16x32_bf16 v[44:47], v[154:157], v[178:181], v[44:47]
	v_mfma_f32_16x16x32_bf16 v[28:31], v[154:157], v[186:189], v[28:31]
	v_mfma_f32_16x16x32_bf16 v[24:27], v[162:165], v[186:189], v[24:27]
	v_mfma_f32_16x16x32_bf16 v[8:11], v[162:165], v[194:197], v[8:11]
	v_mfma_f32_16x16x32_bf16 v[12:15], v[154:157], v[194:197], v[12:15]
	s_setprio 0
	s_barrier
	s_add_u32 s24, s28, 0x158080
	s_addc_u32 s25, s29, 0
	s_add_i32 s28, s30, s37
	v_lshl_add_u64 v[150:151], s[24:25], 0, v[130:131]
	s_mov_b32 m0, s28
	s_nop 0
	global_load_lds_dwordx4 v[150:151], off
	v_lshl_add_u64 v[150:151], s[24:25], 0, v[134:135]
	s_add_i32 m0, s28, 0x2000
	s_nop 0
	global_load_lds_dwordx4 v[150:151], off
	s_waitcnt vmcnt(6)
	s_barrier
	s_setprio 1
	v_mfma_f32_16x16x32_bf16 v[52:55], v[198:201], v[166:169], v[52:55]
	v_mfma_f32_16x16x32_bf16 v[48:51], v[206:209], v[166:169], v[48:51]
	v_mfma_f32_16x16x32_bf16 v[32:35], v[206:209], v[174:177], v[32:35]
	v_mfma_f32_16x16x32_bf16 v[36:39], v[198:201], v[174:177], v[36:39]
	v_mfma_f32_16x16x32_bf16 v[20:23], v[198:201], v[182:185], v[20:23]
	v_mfma_f32_16x16x32_bf16 v[16:19], v[206:209], v[182:185], v[16:19]
	v_mfma_f32_16x16x32_bf16 v[0:3], v[206:209], v[190:193], v[0:3]
	v_mfma_f32_16x16x32_bf16 v[4:7], v[198:201], v[190:193], v[4:7]
	v_mfma_f32_16x16x32_bf16 v[52:55], v[202:205], v[170:173], v[52:55]
	v_mfma_f32_16x16x32_bf16 v[48:51], v[210:213], v[170:173], v[48:51]
	v_mfma_f32_16x16x32_bf16 v[32:35], v[210:213], v[178:181], v[32:35]
	v_mfma_f32_16x16x32_bf16 v[36:39], v[202:205], v[178:181], v[36:39]
	v_mfma_f32_16x16x32_bf16 v[20:23], v[202:205], v[186:189], v[20:23]
	v_mfma_f32_16x16x32_bf16 v[16:19], v[210:213], v[186:189], v[16:19]
	v_mfma_f32_16x16x32_bf16 v[0:3], v[210:213], v[194:197], v[0:3]
	v_mfma_f32_16x16x32_bf16 v[4:7], v[202:205], v[194:197], v[4:7]
	s_setprio 0
	s_add_u32 s59, s59, 0x100
	s_addc_u32 s60, s60, 0
	s_cmp_ge_i32 s61, s42
	s_mov_b64 s[24:25], s[26:27]
	s_mov_b32 s28, s61
	s_barrier
	s_cbranch_scc0 .LBB0_1852
	s_branch .LBB0_1839
